# K-loops: the m0->LDS-DMA wait state is now filled by the segment's own trailing ds_reads instead of s_nop 0 (10 s_nops per iteration removed); on top of v40
# baseline (speedup 1.0000x reference)
; #define PG8_STAGE(bufoff, gbase, voff) do { _Pragma("unroll") for (int _i = 0; _i < 2; ++_i) \
;         __builtin_amdgcn_global_load_lds((const unsigned*)((const char*)(gbase) + (voff)[_i]), (PG8_LAS unsigned*)(lds + (bufoff) + ldsw + _i * 8192), 16, 0, 0); } while (0)
; #define PG8_LDA(dst, b, h) do { _Pragma("unroll") for (int m = 0; m < 4; ++m) _Pragma("unroll") for (int k = 0; k < 2; ++k) dst[m][k] = *(const PG8_LAS bf16x8*)(lds + PG8_SA(b, h) + aoff + m * 2048 + k * 1024); } while (0)
; #define PG8_LDB(dst, b, h) do { _Pragma("unroll") for (int n = 0; n < 2; ++n) _Pragma("unroll") for (int k = 0; k < 2; ++k) dst[n][k] = *(const PG8_LAS bf16x8*)(lds + PG8_SB(b, h) + boff + n * 2048 + k * 1024); } while (0)
; #define PG8_SCHED __builtin_amdgcn_sched_barrier(0)
; template <class Epi, class Sched, bool ALIGN_EPI = false, bool SP2 = false>
; __device__ __forceinline__ void gemm_phase(PG8_LAS unsigned char* lds, const Gemm g, const Sched& S, const Epi& E) {
;     ...
;             const char* a1 = cA + (size_t)(t + 1) * kstep;
;             const char* a2 = last ? nA : cA + (size_t)(t + 2) * kstep; const char* b2 = last ? nB : cB + (size_t)(t + 2) * kstep;
;             const char* a3 = a2 + kstep; const char* b3 = b2 + kstep;
;             if (last && has_next) S.a_ready(nxt);
;             if constexpr (SP2) {
;             PG8_LDB(B0, 0, 0); PG8_LDB(B1, 0, 1); PG8_SCHED; PG8_LDA(At, 0, 0); PG8_STAGE(PG8_SA(1, 1), a1 + hstep, voffA);
.LBB0_66:
	ds_read_b128 v[152:155], v149
	ds_read_b128 v[156:159], v149 offset:1024
	ds_read_b128 v[160:163], v149 offset:2048
	ds_read_b128 v[164:167], v149 offset:3072
	ds_read_b128 v[168:171], v150
	ds_read_b128 v[172:175], v150 offset:1024
	ds_read_b128 v[176:179], v150 offset:2048
	ds_read_b128 v[180:183], v150 offset:3072
	s_add_u32 s42, s40, 0xfff80080
	s_addc_u32 s43, s41, -1
	s_cmp_eq_u32 s68, 28
	s_cselect_b32 s45, s35, s43
	s_cselect_b32 s44, s63, s42
	s_cselect_b32 s43, s31, s67
	s_cselect_b32 s42, s64, s65

; #define PG8_STAGE(bufoff, gbase, voff) do { _Pragma("unroll") for (int _i = 0; _i < 2; ++_i) \
;         __builtin_amdgcn_global_load_lds((const unsigned*)((const char*)(gbase) + (voff)[_i]), (PG8_LAS unsigned*)(lds + (bufoff) + ldsw + _i * 8192), 16, 0, 0); } while (0)
; #define PG8_LDA(dst, b, h) do { _Pragma("unroll") for (int m = 0; m < 4; ++m) _Pragma("unroll") for (int k = 0; k < 2; ++k) dst[m][k] = *(const PG8_LAS bf16x8*)(lds + PG8_SA(b, h) + aoff + m * 2048 + k * 1024); } while (0)
; #define PG8_LDB(dst, b, h) do { _Pragma("unroll") for (int n = 0; n < 2; ++n) _Pragma("unroll") for (int k = 0; k < 2; ++k) dst[n][k] = *(const PG8_LAS bf16x8*)(lds + PG8_SB(b, h) + boff + n * 2048 + k * 1024); } while (0)
; #define PG8_SCHED __builtin_amdgcn_sched_barrier(0)
; template <class Epi, class Sched, bool ALIGN_EPI = false, bool SP2 = false>
; __device__ __forceinline__ void gemm_phase(PG8_LAS unsigned char* lds, const Gemm g, const Sched& S, const Epi& E) {
;     ...
;             PG8_LDB(B0, 0, 0); PG8_LDB(B1, 0, 1); PG8_SCHED; PG8_LDA(At, 0, 0); PG8_STAGE(PG8_SA(1, 1), a1 + hstep, voffA);
	s_add_i32 m0, s29, 0xc000
	ds_read_b128 v[184:187], v151
	ds_read_b128 v[188:191], v151 offset:1024
	ds_read_b128 v[192:195], v151 offset:2048
	ds_read_b128 v[196:199], v151 offset:3072
	ds_read_b128 v[200:203], v151 offset:4096
	ds_read_b128 v[204:207], v151 offset:5120
	ds_read_b128 v[208:211], v151 offset:6144

; #define PG8_STAGE(bufoff, gbase, voff) do { _Pragma("unroll") for (int _i = 0; _i < 2; ++_i) \
;         __builtin_amdgcn_global_load_lds((const unsigned*)((const char*)(gbase) + (voff)[_i]), (PG8_LAS unsigned*)(lds + (bufoff) + ldsw + _i * 8192), 16, 0, 0); } while (0)
; #define PG8_LDA(dst, b, h) do { _Pragma("unroll") for (int m = 0; m < 4; ++m) _Pragma("unroll") for (int k = 0; k < 2; ++k) dst[m][k] = *(const PG8_LAS bf16x8*)(lds + PG8_SA(b, h) + aoff + m * 2048 + k * 1024); } while (0)
; #define PG8_LDB(dst, b, h) do { _Pragma("unroll") for (int n = 0; n < 2; ++n) _Pragma("unroll") for (int k = 0; k < 2; ++k) dst[n][k] = *(const PG8_LAS bf16x8*)(lds + PG8_SB(b, h) + boff + n * 2048 + k * 1024); } while (0)
; #define PG8_SCHED __builtin_amdgcn_sched_barrier(0)
; template <class Epi, class Sched, bool ALIGN_EPI = false, bool SP2 = false>
; __device__ __forceinline__ void gemm_phase(PG8_LAS unsigned char* lds, const Gemm g, const Sched& S, const Epi& E) {
;     ...
;             PG8_LDB(B0, 0, 0); PG8_LDB(B1, 0, 1); PG8_SCHED; PG8_LDA(At, 0, 0); PG8_STAGE(PG8_SA(1, 1), a1 + hstep, voffA);
	global_load_lds_dwordx4 v136, s[40:41]

; #define PG8_STAGE(bufoff, gbase, voff) do { _Pragma("unroll") for (int _i = 0; _i < 2; ++_i) \
;         __builtin_amdgcn_global_load_lds((const unsigned*)((const char*)(gbase) + (voff)[_i]), (PG8_LAS unsigned*)(lds + (bufoff) + ldsw + _i * 8192), 16, 0, 0); } while (0)
; #define PG8_LDA(dst, b, h) do { _Pragma("unroll") for (int m = 0; m < 4; ++m) _Pragma("unroll") for (int k = 0; k < 2; ++k) dst[m][k] = *(const PG8_LAS bf16x8*)(lds + PG8_SA(b, h) + aoff + m * 2048 + k * 1024); } while (0)
; #define PG8_LDB(dst, b, h) do { _Pragma("unroll") for (int n = 0; n < 2; ++n) _Pragma("unroll") for (int k = 0; k < 2; ++k) dst[n][k] = *(const PG8_LAS bf16x8*)(lds + PG8_SB(b, h) + boff + n * 2048 + k * 1024); } while (0)
; #define PG8_MMA(ai, bj, At, Bt) do { __builtin_amdgcn_s_setprio(1); _Pragma("unroll") for (int m = 0; m < 4; ++m) _Pragma("unroll") for (int n = 0; n < 2; ++n) _Pragma("unroll") for (int k = 0; k < 2; ++k) \
;         acc[ai][bj][m][n] = __builtin_amdgcn_mfma_f32_16x16x32_bf16(Bt[n][k], At[m][k], acc[ai][bj][m][n], 0, 0, 0); __builtin_amdgcn_s_setprio(0); } while (0)
; #define PG8_WAIT_V(n) asm volatile("s_waitcnt vmcnt(" #n ")" ::: "memory")
; #define PG8_WAIT_L(n) asm volatile("s_waitcnt lgkmcnt(" #n ")" ::: "memory")
; #define PG8_BAR __builtin_amdgcn_s_barrier()
; #define PG8_SCHED __builtin_amdgcn_sched_barrier(0)
; template <class Epi, class Sched, bool ALIGN_EPI = false, bool SP2 = false>
; __device__ __forceinline__ void gemm_phase(PG8_LAS unsigned char* lds, const Gemm g, const Sched& S, const Epi& E) {
;     ...
;             PG8_LDB(B0, 0, 0); PG8_LDB(B1, 0, 1); PG8_SCHED; PG8_LDA(At, 0, 0); PG8_STAGE(PG8_SA(1, 1), a1 + hstep, voffA);
;             PG8_WAIT_V(8); PG8_WAIT_L(0); PG8_BAR; PG8_MMA(0, 0, At, B0); PG8_MMA(0, 1, At, B1); PG8_BAR; PG8_SCHED;
	s_add_i32 m0, s29, 0xe000
	ds_read_b128 v[212:215], v151 offset:7168
	global_load_lds_dwordx4 v138, s[40:41]
	s_waitcnt vmcnt(8)
	s_waitcnt lgkmcnt(0)
	s_barrier
	s_setprio 1
	s_waitcnt lgkmcnt(0)
	v_mfma_f32_16x16x32_bf16 v[124:127], v[152:155], v[184:187], v[124:127]
	v_mfma_f32_16x16x32_bf16 v[120:123], v[160:163], v[184:187], v[120:123]
	v_mfma_f32_16x16x32_bf16 v[116:119], v[152:155], v[192:195], v[116:119]
	v_mfma_f32_16x16x32_bf16 v[112:115], v[160:163], v[192:195], v[112:115]
	v_mfma_f32_16x16x32_bf16 v[100:103], v[152:155], v[200:203], v[100:103]
	v_mfma_f32_16x16x32_bf16 v[96:99], v[160:163], v[200:203], v[96:99]
	v_mfma_f32_16x16x32_bf16 v[84:87], v[152:155], v[208:211], v[84:87]
	v_mfma_f32_16x16x32_bf16 v[80:83], v[160:163], v[208:211], v[80:83]
	v_mfma_f32_16x16x32_bf16 v[124:127], v[156:159], v[188:191], v[124:127]
	v_mfma_f32_16x16x32_bf16 v[120:123], v[164:167], v[188:191], v[120:123]
	v_mfma_f32_16x16x32_bf16 v[116:119], v[156:159], v[196:199], v[116:119]
	v_mfma_f32_16x16x32_bf16 v[112:115], v[164:167], v[196:199], v[112:115]
	v_mfma_f32_16x16x32_bf16 v[100:103], v[156:159], v[204:207], v[100:103]
	v_mfma_f32_16x16x32_bf16 v[96:99], v[164:167], v[204:207], v[96:99]
	v_mfma_f32_16x16x32_bf16 v[84:87], v[156:159], v[212:215], v[84:87]
	v_mfma_f32_16x16x32_bf16 v[80:83], v[164:167], v[212:215], v[80:83]


; #define PG8_STAGE(bufoff, gbase, voff) do { _Pragma("unroll") for (int _i = 0; _i < 2; ++_i) \
;         __builtin_amdgcn_global_load_lds((const unsigned*)((const char*)(gbase) + (voff)[_i]), (PG8_LAS unsigned*)(lds + (bufoff) + ldsw + _i * 8192), 16, 0, 0); } while (0)
; #define PG8_LDA(dst, b, h) do { _Pragma("unroll") for (int m = 0; m < 4; ++m) _Pragma("unroll") for (int k = 0; k < 2; ++k) dst[m][k] = *(const PG8_LAS bf16x8*)(lds + PG8_SA(b, h) + aoff + m * 2048 + k * 1024); } while (0)
; #define PG8_MMA(ai, bj, At, Bt) do { __builtin_amdgcn_s_setprio(1); _Pragma("unroll") for (int m = 0; m < 4; ++m) _Pragma("unroll") for (int n = 0; n < 2; ++n) _Pragma("unroll") for (int k = 0; k < 2; ++k) \
;         acc[ai][bj][m][n] = __builtin_amdgcn_mfma_f32_16x16x32_bf16(Bt[n][k], At[m][k], acc[ai][bj][m][n], 0, 0, 0); __builtin_amdgcn_s_setprio(0); } while (0)
; #define PG8_WAIT_V(n) asm volatile("s_waitcnt vmcnt(" #n ")" ::: "memory")
; #define PG8_WAIT_L(n) asm volatile("s_waitcnt lgkmcnt(" #n ")" ::: "memory")
; #define PG8_BAR __builtin_amdgcn_s_barrier()
; #define PG8_SCHED __builtin_amdgcn_sched_barrier(0)
; template <class Epi, class Sched, bool ALIGN_EPI = false, bool SP2 = false>
; __device__ __forceinline__ void gemm_phase(PG8_LAS unsigned char* lds, const Gemm g, const Sched& S, const Epi& E) {
;     ...
;             PG8_WAIT_V(8); PG8_WAIT_L(0); PG8_BAR; PG8_MMA(0, 0, At, B0); PG8_MMA(0, 1, At, B1); PG8_BAR; PG8_SCHED;
;             PG8_LDA(At, 0, 1); PG8_STAGE(PG8_SB(0, 0), b2, voffB); PG8_STAGE(PG8_SB(0, 1), b2 + hstep, voffB); PG8_STAGE(PG8_SA(0, 0), a2, voffA);
	v_mfma_f32_16x16x32_bf16 v[108:111], v[168:171], v[184:187], v[108:111]
	v_mfma_f32_16x16x32_bf16 v[104:107], v[176:179], v[184:187], v[104:107]
	v_mfma_f32_16x16x32_bf16 v[92:95], v[168:171], v[192:195], v[92:95]
	v_mfma_f32_16x16x32_bf16 v[88:91], v[176:179], v[192:195], v[88:91]
	v_mfma_f32_16x16x32_bf16 v[76:79], v[168:171], v[200:203], v[76:79]
	v_mfma_f32_16x16x32_bf16 v[72:75], v[176:179], v[200:203], v[72:75]
	v_mfma_f32_16x16x32_bf16 v[68:71], v[168:171], v[208:211], v[68:71]
	v_mfma_f32_16x16x32_bf16 v[64:67], v[176:179], v[208:211], v[64:67]
	v_mfma_f32_16x16x32_bf16 v[108:111], v[172:175], v[188:191], v[108:111]
	v_mfma_f32_16x16x32_bf16 v[104:107], v[180:183], v[188:191], v[104:107]
	v_mfma_f32_16x16x32_bf16 v[92:95], v[172:175], v[196:199], v[92:95]
	v_mfma_f32_16x16x32_bf16 v[88:91], v[180:183], v[196:199], v[88:91]
	v_mfma_f32_16x16x32_bf16 v[76:79], v[172:175], v[204:207], v[76:79]
	v_mfma_f32_16x16x32_bf16 v[72:75], v[180:183], v[204:207], v[72:75]
	v_mfma_f32_16x16x32_bf16 v[68:71], v[172:175], v[212:215], v[68:71]
	v_mfma_f32_16x16x32_bf16 v[64:67], v[180:183], v[212:215], v[64:67]
	s_setprio 0
	s_barrier
	s_add_i32 s69, s59, s48
	s_mov_b64 s[96:97], s[42:43]

; #define PG8_STAGE(bufoff, gbase, voff) do { _Pragma("unroll") for (int _i = 0; _i < 2; ++_i) \
;         __builtin_amdgcn_global_load_lds((const unsigned*)((const char*)(gbase) + (voff)[_i]), (PG8_LAS unsigned*)(lds + (bufoff) + ldsw + _i * 8192), 16, 0, 0); } while (0)
; #define PG8_LDA(dst, b, h) do { _Pragma("unroll") for (int m = 0; m < 4; ++m) _Pragma("unroll") for (int k = 0; k < 2; ++k) dst[m][k] = *(const PG8_LAS bf16x8*)(lds + PG8_SA(b, h) + aoff + m * 2048 + k * 1024); } while (0)
; template <class Epi, class Sched, bool ALIGN_EPI = false, bool SP2 = false>
; __device__ __forceinline__ void gemm_phase(PG8_LAS unsigned char* lds, const Gemm g, const Sched& S, const Epi& E) {
;     ...
;             PG8_LDA(At, 0, 1); PG8_STAGE(PG8_SB(0, 0), b2, voffB); PG8_STAGE(PG8_SB(0, 1), b2 + hstep, voffB); PG8_STAGE(PG8_SA(0, 0), a2, voffA);
	s_mov_b32 m0, s69
	ds_read_b128 v[184:187], v151 offset:16384
	ds_read_b128 v[188:191], v151 offset:17408
	ds_read_b128 v[192:195], v151 offset:18432
	ds_read_b128 v[196:199], v151 offset:19456


; #define PG8_STAGE(bufoff, gbase, voff) do { _Pragma("unroll") for (int _i = 0; _i < 2; ++_i) \
;         __builtin_amdgcn_global_load_lds((const unsigned*)((const char*)(gbase) + (voff)[_i]), (PG8_LAS unsigned*)(lds + (bufoff) + ldsw + _i * 8192), 16, 0, 0); } while (0)
; #define PG8_LDA(dst, b, h) do { _Pragma("unroll") for (int m = 0; m < 4; ++m) _Pragma("unroll") for (int k = 0; k < 2; ++k) dst[m][k] = *(const PG8_LAS bf16x8*)(lds + PG8_SA(b, h) + aoff + m * 2048 + k * 1024); } while (0)
; template <class Epi, class Sched, bool ALIGN_EPI = false, bool SP2 = false>
; __device__ __forceinline__ void gemm_phase(PG8_LAS unsigned char* lds, const Gemm g, const Sched& S, const Epi& E) {
;     ...
;             PG8_LDA(At, 0, 1); PG8_STAGE(PG8_SB(0, 0), b2, voffB); PG8_STAGE(PG8_SB(0, 1), b2 + hstep, voffB); PG8_STAGE(PG8_SA(0, 0), a2, voffA);
	global_load_lds_dwordx4 v132, s[42:43]
	s_add_i32 m0, s69, 0x2000
	s_add_u32 s70, s42, 0x80000

; #define PG8_STAGE(bufoff, gbase, voff) do { _Pragma("unroll") for (int _i = 0; _i < 2; ++_i) \
;         __builtin_amdgcn_global_load_lds((const unsigned*)((const char*)(gbase) + (voff)[_i]), (PG8_LAS unsigned*)(lds + (bufoff) + ldsw + _i * 8192), 16, 0, 0); } while (0)
; #define PG8_LDA(dst, b, h) do { _Pragma("unroll") for (int m = 0; m < 4; ++m) _Pragma("unroll") for (int k = 0; k < 2; ++k) dst[m][k] = *(const PG8_LAS bf16x8*)(lds + PG8_SA(b, h) + aoff + m * 2048 + k * 1024); } while (0)
; template <class Epi, class Sched, bool ALIGN_EPI = false, bool SP2 = false>
; __device__ __forceinline__ void gemm_phase(PG8_LAS unsigned char* lds, const Gemm g, const Sched& S, const Epi& E) {
;     ...
;             PG8_LDA(At, 0, 1); PG8_STAGE(PG8_SB(0, 0), b2, voffB); PG8_STAGE(PG8_SB(0, 1), b2 + hstep, voffB); PG8_STAGE(PG8_SA(0, 0), a2, voffA);
	s_addc_u32 s71, s43, 0
	s_add_i32 s69, s60, s48
	global_load_lds_dwordx4 v128, s[42:43]

; #define PG8_STAGE(bufoff, gbase, voff) do { _Pragma("unroll") for (int _i = 0; _i < 2; ++_i) \
;         __builtin_amdgcn_global_load_lds((const unsigned*)((const char*)(gbase) + (voff)[_i]), (PG8_LAS unsigned*)(lds + (bufoff) + ldsw + _i * 8192), 16, 0, 0); } while (0)
; #define PG8_LDA(dst, b, h) do { _Pragma("unroll") for (int m = 0; m < 4; ++m) _Pragma("unroll") for (int k = 0; k < 2; ++k) dst[m][k] = *(const PG8_LAS bf16x8*)(lds + PG8_SA(b, h) + aoff + m * 2048 + k * 1024); } while (0)
; template <class Epi, class Sched, bool ALIGN_EPI = false, bool SP2 = false>
; __device__ __forceinline__ void gemm_phase(PG8_LAS unsigned char* lds, const Gemm g, const Sched& S, const Epi& E) {
;     ...
;             PG8_LDA(At, 0, 1); PG8_STAGE(PG8_SB(0, 0), b2, voffB); PG8_STAGE(PG8_SB(0, 1), b2 + hstep, voffB); PG8_STAGE(PG8_SA(0, 0), a2, voffA);
	s_mov_b32 m0, s69
	ds_read_b128 v[200:203], v151 offset:20480
	global_load_lds_dwordx4 v132, s[70:71]

; #define PG8_STAGE(bufoff, gbase, voff) do { _Pragma("unroll") for (int _i = 0; _i < 2; ++_i) \
;         __builtin_amdgcn_global_load_lds((const unsigned*)((const char*)(gbase) + (voff)[_i]), (PG8_LAS unsigned*)(lds + (bufoff) + ldsw + _i * 8192), 16, 0, 0); } while (0)
; #define PG8_LDA(dst, b, h) do { _Pragma("unroll") for (int m = 0; m < 4; ++m) _Pragma("unroll") for (int k = 0; k < 2; ++k) dst[m][k] = *(const PG8_LAS bf16x8*)(lds + PG8_SA(b, h) + aoff + m * 2048 + k * 1024); } while (0)
; template <class Epi, class Sched, bool ALIGN_EPI = false, bool SP2 = false>
; __device__ __forceinline__ void gemm_phase(PG8_LAS unsigned char* lds, const Gemm g, const Sched& S, const Epi& E) {
;     ...
;             PG8_LDA(At, 0, 1); PG8_STAGE(PG8_SB(0, 0), b2, voffB); PG8_STAGE(PG8_SB(0, 1), b2 + hstep, voffB); PG8_STAGE(PG8_SA(0, 0), a2, voffA);
	s_add_i32 m0, s69, 0x2000
	ds_read_b128 v[204:207], v151 offset:21504
	global_load_lds_dwordx4 v128, s[70:71]
	s_mov_b64 s[98:99], s[44:45]

; #define PG8_STAGE(bufoff, gbase, voff) do { _Pragma("unroll") for (int _i = 0; _i < 2; ++_i) \
;         __builtin_amdgcn_global_load_lds((const unsigned*)((const char*)(gbase) + (voff)[_i]), (PG8_LAS unsigned*)(lds + (bufoff) + ldsw + _i * 8192), 16, 0, 0); } while (0)
; #define PG8_LDA(dst, b, h) do { _Pragma("unroll") for (int m = 0; m < 4; ++m) _Pragma("unroll") for (int k = 0; k < 2; ++k) dst[m][k] = *(const PG8_LAS bf16x8*)(lds + PG8_SA(b, h) + aoff + m * 2048 + k * 1024); } while (0)
; #define PG8_MMA(ai, bj, At, Bt) do { __builtin_amdgcn_s_setprio(1); _Pragma("unroll") for (int m = 0; m < 4; ++m) _Pragma("unroll") for (int n = 0; n < 2; ++n) _Pragma("unroll") for (int k = 0; k < 2; ++k) \
;         acc[ai][bj][m][n] = __builtin_amdgcn_mfma_f32_16x16x32_bf16(Bt[n][k], At[m][k], acc[ai][bj][m][n], 0, 0, 0); __builtin_amdgcn_s_setprio(0); } while (0)
; #define PG8_WAIT_V(n) asm volatile("s_waitcnt vmcnt(" #n ")" ::: "memory")
; #define PG8_WAIT_L(n) asm volatile("s_waitcnt lgkmcnt(" #n ")" ::: "memory")
; #define PG8_BAR __builtin_amdgcn_s_barrier()
; #define PG8_SCHED __builtin_amdgcn_sched_barrier(0)
; template <class Epi, class Sched, bool ALIGN_EPI = false, bool SP2 = false>
; __device__ __forceinline__ void gemm_phase(PG8_LAS unsigned char* lds, const Gemm g, const Sched& S, const Epi& E) {
;     ...
;             PG8_LDA(At, 0, 1); PG8_STAGE(PG8_SB(0, 0), b2, voffB); PG8_STAGE(PG8_SB(0, 1), b2 + hstep, voffB); PG8_STAGE(PG8_SA(0, 0), a2, voffA);
;             PG8_WAIT_V(8); PG8_WAIT_L(0); PG8_BAR; PG8_MMA(1, 0, At, B0); PG8_MMA(1, 1, At, B1); PG8_BAR; PG8_SCHED;
	s_mov_b32 m0, s29
	ds_read_b128 v[208:211], v151 offset:22528
	global_load_lds_dwordx4 v134, s[44:45]
	s_mov_b32 m0, s51
	ds_read_b128 v[212:215], v151 offset:23552
	global_load_lds_dwordx4 v130, s[44:45]
	s_waitcnt vmcnt(8)
	s_waitcnt lgkmcnt(0)
	s_barrier
	s_setprio 1
	s_waitcnt lgkmcnt(0)
	v_mfma_f32_16x16x32_bf16 v[60:63], v[152:155], v[184:187], v[60:63]
	v_mfma_f32_16x16x32_bf16 v[56:59], v[160:163], v[184:187], v[56:59]
	v_mfma_f32_16x16x32_bf16 v[52:55], v[152:155], v[192:195], v[52:55]
	v_mfma_f32_16x16x32_bf16 v[48:51], v[160:163], v[192:195], v[48:51]
	v_mfma_f32_16x16x32_bf16 v[36:39], v[152:155], v[200:203], v[36:39]
	v_mfma_f32_16x16x32_bf16 v[32:35], v[160:163], v[200:203], v[32:35]
	v_mfma_f32_16x16x32_bf16 v[20:23], v[152:155], v[208:211], v[20:23]
	v_mfma_f32_16x16x32_bf16 v[16:19], v[160:163], v[208:211], v[16:19]
	v_mfma_f32_16x16x32_bf16 v[60:63], v[156:159], v[188:191], v[60:63]
	v_mfma_f32_16x16x32_bf16 v[56:59], v[164:167], v[188:191], v[56:59]
	v_mfma_f32_16x16x32_bf16 v[52:55], v[156:159], v[196:199], v[52:55]
	v_mfma_f32_16x16x32_bf16 v[48:51], v[164:167], v[196:199], v[48:51]
	v_mfma_f32_16x16x32_bf16 v[36:39], v[156:159], v[204:207], v[36:39]
	v_mfma_f32_16x16x32_bf16 v[32:35], v[164:167], v[204:207], v[32:35]
	v_mfma_f32_16x16x32_bf16 v[20:23], v[156:159], v[212:215], v[20:23]
	v_mfma_f32_16x16x32_bf16 v[16:19], v[164:167], v[212:215], v[16:19]


; #define PG8_STAGE(bufoff, gbase, voff) do { _Pragma("unroll") for (int _i = 0; _i < 2; ++_i) \
;         __builtin_amdgcn_global_load_lds((const unsigned*)((const char*)(gbase) + (voff)[_i]), (PG8_LAS unsigned*)(lds + (bufoff) + ldsw + _i * 8192), 16, 0, 0); } while (0)
; #define PG8_LDA(dst, b, h) do { _Pragma("unroll") for (int m = 0; m < 4; ++m) _Pragma("unroll") for (int k = 0; k < 2; ++k) dst[m][k] = *(const PG8_LAS bf16x8*)(lds + PG8_SA(b, h) + aoff + m * 2048 + k * 1024); } while (0)
; #define PG8_LDB(dst, b, h) do { _Pragma("unroll") for (int n = 0; n < 2; ++n) _Pragma("unroll") for (int k = 0; k < 2; ++k) dst[n][k] = *(const PG8_LAS bf16x8*)(lds + PG8_SB(b, h) + boff + n * 2048 + k * 1024); } while (0)
; #define PG8_MMA(ai, bj, At, Bt) do { __builtin_amdgcn_s_setprio(1); _Pragma("unroll") for (int m = 0; m < 4; ++m) _Pragma("unroll") for (int n = 0; n < 2; ++n) _Pragma("unroll") for (int k = 0; k < 2; ++k) \
;         acc[ai][bj][m][n] = __builtin_amdgcn_mfma_f32_16x16x32_bf16(Bt[n][k], At[m][k], acc[ai][bj][m][n], 0, 0, 0); __builtin_amdgcn_s_setprio(0); } while (0)
; #define PG8_WAIT_V(n) asm volatile("s_waitcnt vmcnt(" #n ")" ::: "memory")
; #define PG8_WAIT_L(n) asm volatile("s_waitcnt lgkmcnt(" #n ")" ::: "memory")
; #define PG8_BAR __builtin_amdgcn_s_barrier()
; #define PG8_SCHED __builtin_amdgcn_sched_barrier(0)
; template <class Epi, class Sched, bool ALIGN_EPI = false, bool SP2 = false>
; __device__ __forceinline__ void gemm_phase(PG8_LAS unsigned char* lds, const Gemm g, const Sched& S, const Epi& E) {
;     ...
;             PG8_WAIT_V(8); PG8_WAIT_L(0); PG8_BAR; PG8_MMA(1, 0, At, B0); PG8_MMA(1, 1, At, B1); PG8_BAR; PG8_SCHED;
;             PG8_LDB(B0, 1, 0); PG8_LDB(B1, 1, 1); PG8_SCHED; PG8_LDA(At, 1, 0); PG8_STAGE(PG8_SA(0, 1), a2 + hstep, voffA);
	v_mfma_f32_16x16x32_bf16 v[44:47], v[168:171], v[184:187], v[44:47]
	v_mfma_f32_16x16x32_bf16 v[40:43], v[176:179], v[184:187], v[40:43]
	v_mfma_f32_16x16x32_bf16 v[28:31], v[168:171], v[192:195], v[28:31]
	v_mfma_f32_16x16x32_bf16 v[24:27], v[176:179], v[192:195], v[24:27]
	v_mfma_f32_16x16x32_bf16 v[12:15], v[168:171], v[200:203], v[12:15]
	v_mfma_f32_16x16x32_bf16 v[8:11], v[176:179], v[200:203], v[8:11]
	v_mfma_f32_16x16x32_bf16 v[4:7], v[168:171], v[208:211], v[4:7]
	v_mfma_f32_16x16x32_bf16 v[0:3], v[176:179], v[208:211], v[0:3]
	v_mfma_f32_16x16x32_bf16 v[44:47], v[172:175], v[188:191], v[44:47]
	v_mfma_f32_16x16x32_bf16 v[40:43], v[180:183], v[188:191], v[40:43]
	v_mfma_f32_16x16x32_bf16 v[28:31], v[172:175], v[196:199], v[28:31]
	v_mfma_f32_16x16x32_bf16 v[24:27], v[180:183], v[196:199], v[24:27]
	v_mfma_f32_16x16x32_bf16 v[12:15], v[172:175], v[204:207], v[12:15]
	v_mfma_f32_16x16x32_bf16 v[8:11], v[180:183], v[204:207], v[8:11]
	v_mfma_f32_16x16x32_bf16 v[4:7], v[172:175], v[212:215], v[4:7]
	v_mfma_f32_16x16x32_bf16 v[0:3], v[180:183], v[212:215], v[0:3]
	s_setprio 0
	s_barrier
	s_add_i32 s69, 0, 0x18000
	s_add_i32 s70, 0, 0x1c000
	v_add_u32_e32 v164, s69, v147
	v_add_u32_e32 v180, s70, v147
	ds_read_b128 v[152:155], v164
	ds_read_b128 v[156:159], v164 offset:1024
	ds_read_b128 v[160:163], v164 offset:2048
	ds_read_b128 v[164:167], v164 offset:3072
	ds_read_b128 v[168:171], v180
	ds_read_b128 v[172:175], v180 offset:1024
	ds_read_b128 v[176:179], v180 offset:2048
	ds_read_b128 v[180:183], v180 offset:3072
	s_add_u32 s44, s44, 0x80000
	s_addc_u32 s45, s45, 0
	s_mov_b32 m0, s52

; #define PG8_STAGE(bufoff, gbase, voff) do { _Pragma("unroll") for (int _i = 0; _i < 2; ++_i) \
;         __builtin_amdgcn_global_load_lds((const unsigned*)((const char*)(gbase) + (voff)[_i]), (PG8_LAS unsigned*)(lds + (bufoff) + ldsw + _i * 8192), 16, 0, 0); } while (0)
; #define PG8_LDA(dst, b, h) do { _Pragma("unroll") for (int m = 0; m < 4; ++m) _Pragma("unroll") for (int k = 0; k < 2; ++k) dst[m][k] = *(const PG8_LAS bf16x8*)(lds + PG8_SA(b, h) + aoff + m * 2048 + k * 1024); } while (0)
; #define PG8_LDB(dst, b, h) do { _Pragma("unroll") for (int n = 0; n < 2; ++n) _Pragma("unroll") for (int k = 0; k < 2; ++k) dst[n][k] = *(const PG8_LAS bf16x8*)(lds + PG8_SB(b, h) + boff + n * 2048 + k * 1024); } while (0)
; #define PG8_SCHED __builtin_amdgcn_sched_barrier(0)
; template <class Epi, class Sched, bool ALIGN_EPI = false, bool SP2 = false>
; __device__ __forceinline__ void gemm_phase(PG8_LAS unsigned char* lds, const Gemm g, const Sched& S, const Epi& E) {
;     ...
;             PG8_LDB(B0, 1, 0); PG8_LDB(B1, 1, 1); PG8_SCHED; PG8_LDA(At, 1, 0); PG8_STAGE(PG8_SA(0, 1), a2 + hstep, voffA);
	ds_read_b128 v[184:187], v151 offset:32768
	ds_read_b128 v[188:191], v151 offset:33792
	ds_read_b128 v[192:195], v151 offset:34816
	ds_read_b128 v[196:199], v151 offset:35840
	ds_read_b128 v[200:203], v151 offset:36864
	ds_read_b128 v[204:207], v151 offset:37888
	ds_read_b128 v[208:211], v151 offset:38912

; #define PG8_STAGE(bufoff, gbase, voff) do { _Pragma("unroll") for (int _i = 0; _i < 2; ++_i) \
;         __builtin_amdgcn_global_load_lds((const unsigned*)((const char*)(gbase) + (voff)[_i]), (PG8_LAS unsigned*)(lds + (bufoff) + ldsw + _i * 8192), 16, 0, 0); } while (0)
; #define PG8_LDA(dst, b, h) do { _Pragma("unroll") for (int m = 0; m < 4; ++m) _Pragma("unroll") for (int k = 0; k < 2; ++k) dst[m][k] = *(const PG8_LAS bf16x8*)(lds + PG8_SA(b, h) + aoff + m * 2048 + k * 1024); } while (0)
; #define PG8_LDB(dst, b, h) do { _Pragma("unroll") for (int n = 0; n < 2; ++n) _Pragma("unroll") for (int k = 0; k < 2; ++k) dst[n][k] = *(const PG8_LAS bf16x8*)(lds + PG8_SB(b, h) + boff + n * 2048 + k * 1024); } while (0)
; #define PG8_SCHED __builtin_amdgcn_sched_barrier(0)
; template <class Epi, class Sched, bool ALIGN_EPI = false, bool SP2 = false>
; __device__ __forceinline__ void gemm_phase(PG8_LAS unsigned char* lds, const Gemm g, const Sched& S, const Epi& E) {
;     ...
;             PG8_LDB(B0, 1, 0); PG8_LDB(B1, 1, 1); PG8_SCHED; PG8_LDA(At, 1, 0); PG8_STAGE(PG8_SA(0, 1), a2 + hstep, voffA);
	global_load_lds_dwordx4 v134, s[44:45]

; #define PG8_STAGE(bufoff, gbase, voff) do { _Pragma("unroll") for (int _i = 0; _i < 2; ++_i) \
;         __builtin_amdgcn_global_load_lds((const unsigned*)((const char*)(gbase) + (voff)[_i]), (PG8_LAS unsigned*)(lds + (bufoff) + ldsw + _i * 8192), 16, 0, 0); } while (0)
; #define PG8_LDA(dst, b, h) do { _Pragma("unroll") for (int m = 0; m < 4; ++m) _Pragma("unroll") for (int k = 0; k < 2; ++k) dst[m][k] = *(const PG8_LAS bf16x8*)(lds + PG8_SA(b, h) + aoff + m * 2048 + k * 1024); } while (0)
; #define PG8_LDB(dst, b, h) do { _Pragma("unroll") for (int n = 0; n < 2; ++n) _Pragma("unroll") for (int k = 0; k < 2; ++k) dst[n][k] = *(const PG8_LAS bf16x8*)(lds + PG8_SB(b, h) + boff + n * 2048 + k * 1024); } while (0)
; #define PG8_MMA(ai, bj, At, Bt) do { __builtin_amdgcn_s_setprio(1); _Pragma("unroll") for (int m = 0; m < 4; ++m) _Pragma("unroll") for (int n = 0; n < 2; ++n) _Pragma("unroll") for (int k = 0; k < 2; ++k) \
;         acc[ai][bj][m][n] = __builtin_amdgcn_mfma_f32_16x16x32_bf16(Bt[n][k], At[m][k], acc[ai][bj][m][n], 0, 0, 0); __builtin_amdgcn_s_setprio(0); } while (0)
; #define PG8_WAIT_V(n) asm volatile("s_waitcnt vmcnt(" #n ")" ::: "memory")
; #define PG8_WAIT_L(n) asm volatile("s_waitcnt lgkmcnt(" #n ")" ::: "memory")
; #define PG8_BAR __builtin_amdgcn_s_barrier()
; #define PG8_SCHED __builtin_amdgcn_sched_barrier(0)
; template <class Epi, class Sched, bool ALIGN_EPI = false, bool SP2 = false>
; __device__ __forceinline__ void gemm_phase(PG8_LAS unsigned char* lds, const Gemm g, const Sched& S, const Epi& E) {
;     ...
;             PG8_LDB(B0, 1, 0); PG8_LDB(B1, 1, 1); PG8_SCHED; PG8_LDA(At, 1, 0); PG8_STAGE(PG8_SA(0, 1), a2 + hstep, voffA);
;             PG8_WAIT_V(8); PG8_WAIT_L(0); PG8_BAR; PG8_MMA(0, 0, At, B0); PG8_MMA(0, 1, At, B1); PG8_BAR; PG8_SCHED;
	s_mov_b32 m0, s53
	ds_read_b128 v[212:215], v151 offset:39936
	global_load_lds_dwordx4 v130, s[44:45]
	s_waitcnt vmcnt(8)
	s_waitcnt lgkmcnt(0)
	s_barrier
	s_setprio 1
	s_waitcnt lgkmcnt(0)
	v_mfma_f32_16x16x32_bf16 v[124:127], v[152:155], v[184:187], v[124:127]
	v_mfma_f32_16x16x32_bf16 v[120:123], v[160:163], v[184:187], v[120:123]
	v_mfma_f32_16x16x32_bf16 v[116:119], v[152:155], v[192:195], v[116:119]
	v_mfma_f32_16x16x32_bf16 v[112:115], v[160:163], v[192:195], v[112:115]
	v_mfma_f32_16x16x32_bf16 v[100:103], v[152:155], v[200:203], v[100:103]
	v_mfma_f32_16x16x32_bf16 v[96:99], v[160:163], v[200:203], v[96:99]
	v_mfma_f32_16x16x32_bf16 v[84:87], v[152:155], v[208:211], v[84:87]
	v_mfma_f32_16x16x32_bf16 v[80:83], v[160:163], v[208:211], v[80:83]
	v_mfma_f32_16x16x32_bf16 v[124:127], v[156:159], v[188:191], v[124:127]
	v_mfma_f32_16x16x32_bf16 v[120:123], v[164:167], v[188:191], v[120:123]
	v_mfma_f32_16x16x32_bf16 v[116:119], v[156:159], v[196:199], v[116:119]
	v_mfma_f32_16x16x32_bf16 v[112:115], v[164:167], v[196:199], v[112:115]
	v_mfma_f32_16x16x32_bf16 v[100:103], v[156:159], v[204:207], v[100:103]
	v_mfma_f32_16x16x32_bf16 v[96:99], v[164:167], v[204:207], v[96:99]
	v_mfma_f32_16x16x32_bf16 v[84:87], v[156:159], v[212:215], v[84:87]
	v_mfma_f32_16x16x32_bf16 v[80:83], v[164:167], v[212:215], v[80:83]


; #define PG8_STAGE(bufoff, gbase, voff) do { _Pragma("unroll") for (int _i = 0; _i < 2; ++_i) \
;         __builtin_amdgcn_global_load_lds((const unsigned*)((const char*)(gbase) + (voff)[_i]), (PG8_LAS unsigned*)(lds + (bufoff) + ldsw + _i * 8192), 16, 0, 0); } while (0)
; #define PG8_LDA(dst, b, h) do { _Pragma("unroll") for (int m = 0; m < 4; ++m) _Pragma("unroll") for (int k = 0; k < 2; ++k) dst[m][k] = *(const PG8_LAS bf16x8*)(lds + PG8_SA(b, h) + aoff + m * 2048 + k * 1024); } while (0)
; #define PG8_MMA(ai, bj, At, Bt) do { __builtin_amdgcn_s_setprio(1); _Pragma("unroll") for (int m = 0; m < 4; ++m) _Pragma("unroll") for (int n = 0; n < 2; ++n) _Pragma("unroll") for (int k = 0; k < 2; ++k) \
;         acc[ai][bj][m][n] = __builtin_amdgcn_mfma_f32_16x16x32_bf16(Bt[n][k], At[m][k], acc[ai][bj][m][n], 0, 0, 0); __builtin_amdgcn_s_setprio(0); } while (0)
; #define PG8_WAIT_V(n) asm volatile("s_waitcnt vmcnt(" #n ")" ::: "memory")
; #define PG8_WAIT_L(n) asm volatile("s_waitcnt lgkmcnt(" #n ")" ::: "memory")
; #define PG8_BAR __builtin_amdgcn_s_barrier()
; #define PG8_SCHED __builtin_amdgcn_sched_barrier(0)
; template <class Epi, class Sched, bool ALIGN_EPI = false, bool SP2 = false>
; __device__ __forceinline__ void gemm_phase(PG8_LAS unsigned char* lds, const Gemm g, const Sched& S, const Epi& E) {
;     ...
;             PG8_WAIT_V(8); PG8_WAIT_L(0); PG8_BAR; PG8_MMA(0, 0, At, B0); PG8_MMA(0, 1, At, B1); PG8_BAR; PG8_SCHED;
;             PG8_LDA(At, 1, 1); PG8_STAGE(PG8_SB(1, 0), b3, voffB); PG8_STAGE(PG8_SB(1, 1), b3 + hstep, voffB); PG8_STAGE(PG8_SA(1, 0), a3, voffA);
	v_mfma_f32_16x16x32_bf16 v[108:111], v[168:171], v[184:187], v[108:111]
	v_mfma_f32_16x16x32_bf16 v[104:107], v[176:179], v[184:187], v[104:107]
	v_mfma_f32_16x16x32_bf16 v[92:95], v[168:171], v[192:195], v[92:95]
	v_mfma_f32_16x16x32_bf16 v[88:91], v[176:179], v[192:195], v[88:91]
	v_mfma_f32_16x16x32_bf16 v[76:79], v[168:171], v[200:203], v[76:79]
	v_mfma_f32_16x16x32_bf16 v[72:75], v[176:179], v[200:203], v[72:75]
	v_mfma_f32_16x16x32_bf16 v[68:71], v[168:171], v[208:211], v[68:71]
	v_mfma_f32_16x16x32_bf16 v[64:67], v[176:179], v[208:211], v[64:67]
	v_mfma_f32_16x16x32_bf16 v[108:111], v[172:175], v[188:191], v[108:111]
	v_mfma_f32_16x16x32_bf16 v[104:107], v[180:183], v[188:191], v[104:107]
	v_mfma_f32_16x16x32_bf16 v[92:95], v[172:175], v[196:199], v[92:95]
	v_mfma_f32_16x16x32_bf16 v[88:91], v[180:183], v[196:199], v[88:91]
	v_mfma_f32_16x16x32_bf16 v[76:79], v[172:175], v[204:207], v[76:79]
	v_mfma_f32_16x16x32_bf16 v[72:75], v[180:183], v[204:207], v[72:75]
	v_mfma_f32_16x16x32_bf16 v[68:71], v[172:175], v[212:215], v[68:71]
	v_mfma_f32_16x16x32_bf16 v[64:67], v[180:183], v[212:215], v[64:67]
	s_setprio 0
	s_barrier
	s_add_i32 s44, s69, s48

; #define PG8_STAGE(bufoff, gbase, voff) do { _Pragma("unroll") for (int _i = 0; _i < 2; ++_i) \
;         __builtin_amdgcn_global_load_lds((const unsigned*)((const char*)(gbase) + (voff)[_i]), (PG8_LAS unsigned*)(lds + (bufoff) + ldsw + _i * 8192), 16, 0, 0); } while (0)
; #define PG8_LDA(dst, b, h) do { _Pragma("unroll") for (int m = 0; m < 4; ++m) _Pragma("unroll") for (int k = 0; k < 2; ++k) dst[m][k] = *(const PG8_LAS bf16x8*)(lds + PG8_SA(b, h) + aoff + m * 2048 + k * 1024); } while (0)
; template <class Epi, class Sched, bool ALIGN_EPI = false, bool SP2 = false>
; __device__ __forceinline__ void gemm_phase(PG8_LAS unsigned char* lds, const Gemm g, const Sched& S, const Epi& E) {
;     ...
;             PG8_LDA(At, 1, 1); PG8_STAGE(PG8_SB(1, 0), b3, voffB); PG8_STAGE(PG8_SB(1, 1), b3 + hstep, voffB); PG8_STAGE(PG8_SA(1, 0), a3, voffA);
	s_mov_b32 m0, s44
	ds_read_b128 v[184:187], v151 offset:49152
	ds_read_b128 v[188:191], v151 offset:50176
	ds_read_b128 v[192:195], v151 offset:51200
	ds_read_b128 v[196:199], v151 offset:52224


; #define PG8_STAGE(bufoff, gbase, voff) do { _Pragma("unroll") for (int _i = 0; _i < 2; ++_i) \
;         __builtin_amdgcn_global_load_lds((const unsigned*)((const char*)(gbase) + (voff)[_i]), (PG8_LAS unsigned*)(lds + (bufoff) + ldsw + _i * 8192), 16, 0, 0); } while (0)
; #define PG8_LDA(dst, b, h) do { _Pragma("unroll") for (int m = 0; m < 4; ++m) _Pragma("unroll") for (int k = 0; k < 2; ++k) dst[m][k] = *(const PG8_LAS bf16x8*)(lds + PG8_SA(b, h) + aoff + m * 2048 + k * 1024); } while (0)
; template <class Epi, class Sched, bool ALIGN_EPI = false, bool SP2 = false>
; __device__ __forceinline__ void gemm_phase(PG8_LAS unsigned char* lds, const Gemm g, const Sched& S, const Epi& E) {
;     ...
;             PG8_LDA(At, 1, 1); PG8_STAGE(PG8_SB(1, 0), b3, voffB); PG8_STAGE(PG8_SB(1, 1), b3 + hstep, voffB); PG8_STAGE(PG8_SA(1, 0), a3, voffA);
	global_load_lds_dwordx4 v250, s[96:97]
	s_add_i32 m0, s44, 0x2000
	s_add_u32 s42, s42, 0x80080

; #define PG8_STAGE(bufoff, gbase, voff) do { _Pragma("unroll") for (int _i = 0; _i < 2; ++_i) \
;         __builtin_amdgcn_global_load_lds((const unsigned*)((const char*)(gbase) + (voff)[_i]), (PG8_LAS unsigned*)(lds + (bufoff) + ldsw + _i * 8192), 16, 0, 0); } while (0)
; #define PG8_LDA(dst, b, h) do { _Pragma("unroll") for (int m = 0; m < 4; ++m) _Pragma("unroll") for (int k = 0; k < 2; ++k) dst[m][k] = *(const PG8_LAS bf16x8*)(lds + PG8_SA(b, h) + aoff + m * 2048 + k * 1024); } while (0)
; template <class Epi, class Sched, bool ALIGN_EPI = false, bool SP2 = false>
; __device__ __forceinline__ void gemm_phase(PG8_LAS unsigned char* lds, const Gemm g, const Sched& S, const Epi& E) {
;     ...
;             PG8_LDA(At, 1, 1); PG8_STAGE(PG8_SB(1, 0), b3, voffB); PG8_STAGE(PG8_SB(1, 1), b3 + hstep, voffB); PG8_STAGE(PG8_SA(1, 0), a3, voffA);
	s_addc_u32 s43, s43, 0
	s_add_i32 s44, s70, s48
	global_load_lds_dwordx4 v251, s[96:97]

; #define PG8_STAGE(bufoff, gbase, voff) do { _Pragma("unroll") for (int _i = 0; _i < 2; ++_i) \
;         __builtin_amdgcn_global_load_lds((const unsigned*)((const char*)(gbase) + (voff)[_i]), (PG8_LAS unsigned*)(lds + (bufoff) + ldsw + _i * 8192), 16, 0, 0); } while (0)
; #define PG8_LDA(dst, b, h) do { _Pragma("unroll") for (int m = 0; m < 4; ++m) _Pragma("unroll") for (int k = 0; k < 2; ++k) dst[m][k] = *(const PG8_LAS bf16x8*)(lds + PG8_SA(b, h) + aoff + m * 2048 + k * 1024); } while (0)
; template <class Epi, class Sched, bool ALIGN_EPI = false, bool SP2 = false>
; __device__ __forceinline__ void gemm_phase(PG8_LAS unsigned char* lds, const Gemm g, const Sched& S, const Epi& E) {
;     ...
;             PG8_LDA(At, 1, 1); PG8_STAGE(PG8_SB(1, 0), b3, voffB); PG8_STAGE(PG8_SB(1, 1), b3 + hstep, voffB); PG8_STAGE(PG8_SA(1, 0), a3, voffA);
	s_mov_b32 m0, s44
	ds_read_b128 v[200:203], v151 offset:53248
	global_load_lds_dwordx4 v132, s[42:43]

; #define PG8_STAGE(bufoff, gbase, voff) do { _Pragma("unroll") for (int _i = 0; _i < 2; ++_i) \
;         __builtin_amdgcn_global_load_lds((const unsigned*)((const char*)(gbase) + (voff)[_i]), (PG8_LAS unsigned*)(lds + (bufoff) + ldsw + _i * 8192), 16, 0, 0); } while (0)
; #define PG8_LDA(dst, b, h) do { _Pragma("unroll") for (int m = 0; m < 4; ++m) _Pragma("unroll") for (int k = 0; k < 2; ++k) dst[m][k] = *(const PG8_LAS bf16x8*)(lds + PG8_SA(b, h) + aoff + m * 2048 + k * 1024); } while (0)
; template <class Epi, class Sched, bool ALIGN_EPI = false, bool SP2 = false>
; __device__ __forceinline__ void gemm_phase(PG8_LAS unsigned char* lds, const Gemm g, const Sched& S, const Epi& E) {
;     ...
;             PG8_LDA(At, 1, 1); PG8_STAGE(PG8_SB(1, 0), b3, voffB); PG8_STAGE(PG8_SB(1, 1), b3 + hstep, voffB); PG8_STAGE(PG8_SA(1, 0), a3, voffA);
	s_add_i32 m0, s44, 0x2000
	ds_read_b128 v[204:207], v151 offset:54272
	global_load_lds_dwordx4 v128, s[42:43]

; #define PG8_STAGE(bufoff, gbase, voff) do { _Pragma("unroll") for (int _i = 0; _i < 2; ++_i) \
;         __builtin_amdgcn_global_load_lds((const unsigned*)((const char*)(gbase) + (voff)[_i]), (PG8_LAS unsigned*)(lds + (bufoff) + ldsw + _i * 8192), 16, 0, 0); } while (0)
; #define PG8_LDA(dst, b, h) do { _Pragma("unroll") for (int m = 0; m < 4; ++m) _Pragma("unroll") for (int k = 0; k < 2; ++k) dst[m][k] = *(const PG8_LAS bf16x8*)(lds + PG8_SA(b, h) + aoff + m * 2048 + k * 1024); } while (0)
; template <class Epi, class Sched, bool ALIGN_EPI = false, bool SP2 = false>
; __device__ __forceinline__ void gemm_phase(PG8_LAS unsigned char* lds, const Gemm g, const Sched& S, const Epi& E) {
;     ...
;             PG8_LDA(At, 1, 1); PG8_STAGE(PG8_SB(1, 0), b3, voffB); PG8_STAGE(PG8_SB(1, 1), b3 + hstep, voffB); PG8_STAGE(PG8_SA(1, 0), a3, voffA);
	s_mov_b32 m0, s55
	ds_read_b128 v[208:211], v151 offset:55296
	global_load_lds_dwordx4 v252, s[98:99]

; #define PG8_STAGE(bufoff, gbase, voff) do { _Pragma("unroll") for (int _i = 0; _i < 2; ++_i) \
;         __builtin_amdgcn_global_load_lds((const unsigned*)((const char*)(gbase) + (voff)[_i]), (PG8_LAS unsigned*)(lds + (bufoff) + ldsw + _i * 8192), 16, 0, 0); } while (0)
; #define PG8_LDA(dst, b, h) do { _Pragma("unroll") for (int m = 0; m < 4; ++m) _Pragma("unroll") for (int k = 0; k < 2; ++k) dst[m][k] = *(const PG8_LAS bf16x8*)(lds + PG8_SA(b, h) + aoff + m * 2048 + k * 1024); } while (0)
; #define PG8_MMA(ai, bj, At, Bt) do { __builtin_amdgcn_s_setprio(1); _Pragma("unroll") for (int m = 0; m < 4; ++m) _Pragma("unroll") for (int n = 0; n < 2; ++n) _Pragma("unroll") for (int k = 0; k < 2; ++k) \
;         acc[ai][bj][m][n] = __builtin_amdgcn_mfma_f32_16x16x32_bf16(Bt[n][k], At[m][k], acc[ai][bj][m][n], 0, 0, 0); __builtin_amdgcn_s_setprio(0); } while (0)
; #define PG8_WAIT_V(n) asm volatile("s_waitcnt vmcnt(" #n ")" ::: "memory")
; #define PG8_WAIT_L(n) asm volatile("s_waitcnt lgkmcnt(" #n ")" ::: "memory")
; #define PG8_BAR __builtin_amdgcn_s_barrier()
; #define PG8_SCHED __builtin_amdgcn_sched_barrier(0)
; template <class Epi, class Sched, bool ALIGN_EPI = false, bool SP2 = false>
; __device__ __forceinline__ void gemm_phase(PG8_LAS unsigned char* lds, const Gemm g, const Sched& S, const Epi& E) {
;     ...
;             PG8_LDA(At, 1, 1); PG8_STAGE(PG8_SB(1, 0), b3, voffB); PG8_STAGE(PG8_SB(1, 1), b3 + hstep, voffB); PG8_STAGE(PG8_SA(1, 0), a3, voffA);
;             PG8_WAIT_V(8); PG8_WAIT_L(0); PG8_BAR; PG8_MMA(1, 0, At, B0); PG8_MMA(1, 1, At, B1); PG8_BAR; PG8_SCHED;
	s_mov_b32 m0, s56
	ds_read_b128 v[212:215], v151 offset:56320
	global_load_lds_dwordx4 v253, s[98:99]
	s_waitcnt vmcnt(8)
	s_waitcnt lgkmcnt(0)
	s_barrier
	s_setprio 1
	s_waitcnt lgkmcnt(0)
	v_mfma_f32_16x16x32_bf16 v[60:63], v[152:155], v[184:187], v[60:63]
	v_mfma_f32_16x16x32_bf16 v[56:59], v[160:163], v[184:187], v[56:59]
	v_mfma_f32_16x16x32_bf16 v[52:55], v[152:155], v[192:195], v[52:55]
	v_mfma_f32_16x16x32_bf16 v[48:51], v[160:163], v[192:195], v[48:51]
	v_mfma_f32_16x16x32_bf16 v[36:39], v[152:155], v[200:203], v[36:39]
	v_mfma_f32_16x16x32_bf16 v[32:35], v[160:163], v[200:203], v[32:35]
	v_mfma_f32_16x16x32_bf16 v[20:23], v[152:155], v[208:211], v[20:23]
	v_mfma_f32_16x16x32_bf16 v[16:19], v[160:163], v[208:211], v[16:19]
	v_mfma_f32_16x16x32_bf16 v[60:63], v[156:159], v[188:191], v[60:63]
	v_mfma_f32_16x16x32_bf16 v[56:59], v[164:167], v[188:191], v[56:59]
	v_mfma_f32_16x16x32_bf16 v[52:55], v[156:159], v[196:199], v[52:55]
	v_mfma_f32_16x16x32_bf16 v[48:51], v[164:167], v[196:199], v[48:51]
	v_mfma_f32_16x16x32_bf16 v[36:39], v[156:159], v[204:207], v[36:39]
	v_mfma_f32_16x16x32_bf16 v[32:35], v[164:167], v[204:207], v[32:35]
	v_mfma_f32_16x16x32_bf16 v[20:23], v[156:159], v[212:215], v[20:23]
	v_mfma_f32_16x16x32_bf16 v[16:19], v[164:167], v[212:215], v[16:19]


; #define PG8_STAGE(bufoff, gbase, voff) do { _Pragma("unroll") for (int _i = 0; _i < 2; ++_i) \
;         __builtin_amdgcn_global_load_lds((const unsigned*)((const char*)(gbase) + (voff)[_i]), (PG8_LAS unsigned*)(lds + (bufoff) + ldsw + _i * 8192), 16, 0, 0); } while (0)
; #define PG8_LDA(dst, b, h) do { _Pragma("unroll") for (int m = 0; m < 4; ++m) _Pragma("unroll") for (int k = 0; k < 2; ++k) dst[m][k] = *(const PG8_LAS bf16x8*)(lds + PG8_SA(b, h) + aoff + m * 2048 + k * 1024); } while (0)
; #define PG8_LDB(dst, b, h) do { _Pragma("unroll") for (int n = 0; n < 2; ++n) _Pragma("unroll") for (int k = 0; k < 2; ++k) dst[n][k] = *(const PG8_LAS bf16x8*)(lds + PG8_SB(b, h) + boff + n * 2048 + k * 1024); } while (0)
; template <class Epi, class Sched, bool ALIGN_EPI = false, bool SP2 = false>
; __device__ __forceinline__ void gemm_phase(PG8_LAS unsigned char* lds, const Gemm g, const Sched& S, const Epi& E) {
;     ...
;             PG8_WAIT_V(8); PG8_WAIT_L(0); PG8_BAR; PG8_MMA(1, 0, At, B0); PG8_MMA(1, 1, At, B1); PG8_BAR; PG8_SCHED;
;             } else {
;             PG8_LDB(B0, 0, 0); PG8_SCHED; PG8_LDA(At, 0, 0); PG8_STAGE(PG8_SA(1, 1), a1 + hstep, voffA);
;             PG8_WAIT_L(8); PG8_BAR; PG8_WAIT_L(0); PG8_MMA(0, 0, At, B0); PG8_BAR; PG8_SCHED;
;             PG8_LDB(B1, 0, 1); PG8_STAGE(PG8_SB(0, 0), b2, voffB);
;             PG8_BAR; PG8_WAIT_L(0); PG8_MMA(0, 1, At, B1); PG8_BAR;
;             PG8_LDA(At, 0, 1); PG8_STAGE(PG8_SA(0, 0), a2, voffA);
;             PG8_BAR; PG8_WAIT_L(0); PG8_MMA(1, 0, At, B0); PG8_BAR; PG8_SCHED;
;             PG8_STAGE(PG8_SB(0, 1), b2 + hstep, voffB);
;             PG8_WAIT_V(6); PG8_BAR; PG8_MMA(1, 1, At, B1); PG8_BAR;
;             PG8_LDB(B0, 1, 0); PG8_SCHED; PG8_LDA(At, 1, 0); PG8_STAGE(PG8_SA(0, 1), a2 + hstep, voffA);
;             PG8_WAIT_L(8); PG8_BAR; PG8_WAIT_L(0); PG8_MMA(0, 0, At, B0); PG8_BAR; PG8_SCHED;
;             PG8_LDB(B1, 1, 1); PG8_STAGE(PG8_SB(1, 0), b3, voffB);
;             PG8_BAR; PG8_WAIT_L(0); PG8_MMA(0, 1, At, B1); PG8_BAR;
;             PG8_LDA(At, 1, 1); PG8_STAGE(PG8_SA(1, 0), a3, voffA);
;             PG8_BAR; PG8_WAIT_L(0); PG8_MMA(1, 0, At, B0); PG8_BAR; PG8_SCHED;
;             PG8_STAGE(PG8_SB(1, 1), b3 + hstep, voffB);
;             PG8_WAIT_V(6); PG8_BAR; PG8_MMA(1, 1, At, B1); PG8_BAR;
;             }
;         }
;         if constexpr (ALIGN_EPI) { if (wr == 0) PG8_BAR; }
	v_mfma_f32_16x16x32_bf16 v[44:47], v[168:171], v[184:187], v[44:47]
	v_mfma_f32_16x16x32_bf16 v[40:43], v[176:179], v[184:187], v[40:43]
	v_mfma_f32_16x16x32_bf16 v[28:31], v[168:171], v[192:195], v[28:31]
	v_mfma_f32_16x16x32_bf16 v[24:27], v[176:179], v[192:195], v[24:27]
	v_mfma_f32_16x16x32_bf16 v[12:15], v[168:171], v[200:203], v[12:15]
	v_mfma_f32_16x16x32_bf16 v[8:11], v[176:179], v[200:203], v[8:11]
	v_mfma_f32_16x16x32_bf16 v[4:7], v[168:171], v[208:211], v[4:7]
	v_mfma_f32_16x16x32_bf16 v[0:3], v[176:179], v[208:211], v[0:3]
	v_mfma_f32_16x16x32_bf16 v[44:47], v[172:175], v[188:191], v[44:47]
	v_mfma_f32_16x16x32_bf16 v[40:43], v[180:183], v[188:191], v[40:43]
	v_mfma_f32_16x16x32_bf16 v[28:31], v[172:175], v[196:199], v[28:31]
	v_mfma_f32_16x16x32_bf16 v[24:27], v[180:183], v[196:199], v[24:27]
	v_mfma_f32_16x16x32_bf16 v[12:15], v[172:175], v[204:207], v[12:15]
	v_mfma_f32_16x16x32_bf16 v[8:11], v[180:183], v[204:207], v[8:11]
	v_mfma_f32_16x16x32_bf16 v[4:7], v[172:175], v[212:215], v[4:7]
	v_mfma_f32_16x16x32_bf16 v[0:3], v[180:183], v[212:215], v[0:3]
	s_setprio 0
	s_barrier
	s_add_i32 s68, s68, 2
	s_add_u32 s40, s40, 0x100
	s_addc_u32 s41, s41, 0
	s_add_u32 s65, s65, 0x100
	s_addc_u32 s67, s67, 0
	s_cmp_gt_u32 s68, 29
	s_cbranch_scc0 .LBB0_66
	s_and_b64 vcc, exec, s[26:27]
	s_cbranch_vccz .LBB0_69
	s_barrier

; #define PG8_STAGE(bufoff, gbase, voff) do { _Pragma("unroll") for (int _i = 0; _i < 2; ++_i) \
;         __builtin_amdgcn_global_load_lds((const unsigned*)((const char*)(gbase) + (voff)[_i]), (PG8_LAS unsigned*)(lds + (bufoff) + ldsw + _i * 8192), 16, 0, 0); } while (0)
; #define PG8_LDA(dst, b, h) do { _Pragma("unroll") for (int m = 0; m < 4; ++m) _Pragma("unroll") for (int k = 0; k < 2; ++k) dst[m][k] = *(const PG8_LAS bf16x8*)(lds + PG8_SA(b, h) + aoff + m * 2048 + k * 1024); } while (0)
; #define PG8_LDB(dst, b, h) do { _Pragma("unroll") for (int n = 0; n < 2; ++n) _Pragma("unroll") for (int k = 0; k < 2; ++k) dst[n][k] = *(const PG8_LAS bf16x8*)(lds + PG8_SB(b, h) + boff + n * 2048 + k * 1024); } while (0)
; #define PG8_SCHED __builtin_amdgcn_sched_barrier(0)
; template <class Epi, class Sched, bool ALIGN_EPI = false, bool SP2 = false>
; __device__ __forceinline__ void gemm_phase(PG8_LAS unsigned char* lds, const Gemm g, const Sched& S, const Epi& E) {
;     ...
;         for (int t = 0; t < nt; t += 2) {
;             const bool last = (t == nt - 2);
;             const char* a1 = cA + (size_t)(t + 1) * kstep;
;             const char* a2 = last ? nA : cA + (size_t)(t + 2) * kstep; const char* b2 = last ? nB : cB + (size_t)(t + 2) * kstep;
;             const char* a3 = a2 + kstep; const char* b3 = b2 + kstep;
;             if (last && has_next) S.a_ready(nxt);
;             if constexpr (SP2) {
;             PG8_LDB(B0, 0, 0); PG8_LDB(B1, 0, 1); PG8_SCHED; PG8_LDA(At, 0, 0); PG8_STAGE(PG8_SA(1, 1), a1 + hstep, voffA);
.LBB0_333:
	ds_read_b128 v[64:67], v211
	ds_read_b128 v[68:71], v211 offset:1024
	ds_read_b128 v[72:75], v211 offset:2048
	ds_read_b128 v[76:79], v211 offset:3072
	ds_read_b128 v[144:147], v212
	ds_read_b128 v[148:151], v212 offset:1024
	ds_read_b128 v[152:155], v212 offset:2048
	ds_read_b128 v[156:159], v212 offset:3072
	s_add_u32 s60, s58, 0xfff80080
	s_addc_u32 s61, s59, -1
	s_cmp_eq_u32 s81, 28
	s_cselect_b32 s63, s11, s61
	s_cselect_b32 s62, s51, s60
	s_cselect_b32 s61, s49, s80
	s_cselect_b32 s60, s78, s79

; #define PG8_STAGE(bufoff, gbase, voff) do { _Pragma("unroll") for (int _i = 0; _i < 2; ++_i) \
;         __builtin_amdgcn_global_load_lds((const unsigned*)((const char*)(gbase) + (voff)[_i]), (PG8_LAS unsigned*)(lds + (bufoff) + ldsw + _i * 8192), 16, 0, 0); } while (0)
; #define PG8_LDA(dst, b, h) do { _Pragma("unroll") for (int m = 0; m < 4; ++m) _Pragma("unroll") for (int k = 0; k < 2; ++k) dst[m][k] = *(const PG8_LAS bf16x8*)(lds + PG8_SA(b, h) + aoff + m * 2048 + k * 1024); } while (0)
; #define PG8_LDB(dst, b, h) do { _Pragma("unroll") for (int n = 0; n < 2; ++n) _Pragma("unroll") for (int k = 0; k < 2; ++k) dst[n][k] = *(const PG8_LAS bf16x8*)(lds + PG8_SB(b, h) + boff + n * 2048 + k * 1024); } while (0)
; #define PG8_SCHED __builtin_amdgcn_sched_barrier(0)
; template <class Epi, class Sched, bool ALIGN_EPI = false, bool SP2 = false>
; __device__ __forceinline__ void gemm_phase(PG8_LAS unsigned char* lds, const Gemm g, const Sched& S, const Epi& E) {
;     ...
;             PG8_LDB(B0, 0, 0); PG8_LDB(B1, 0, 1); PG8_SCHED; PG8_LDA(At, 0, 0); PG8_STAGE(PG8_SA(1, 1), a1 + hstep, voffA);
	s_add_i32 m0, s57, 0xc000
	ds_read_b128 v[176:179], v213
	ds_read_b128 v[180:183], v213 offset:1024
	ds_read_b128 v[184:187], v213 offset:2048
	ds_read_b128 v[188:191], v213 offset:3072
	ds_read_b128 v[192:195], v213 offset:4096
	ds_read_b128 v[196:199], v213 offset:5120
	ds_read_b128 v[200:203], v213 offset:6144

; #define PG8_STAGE(bufoff, gbase, voff) do { _Pragma("unroll") for (int _i = 0; _i < 2; ++_i) \
;         __builtin_amdgcn_global_load_lds((const unsigned*)((const char*)(gbase) + (voff)[_i]), (PG8_LAS unsigned*)(lds + (bufoff) + ldsw + _i * 8192), 16, 0, 0); } while (0)
; #define PG8_LDA(dst, b, h) do { _Pragma("unroll") for (int m = 0; m < 4; ++m) _Pragma("unroll") for (int k = 0; k < 2; ++k) dst[m][k] = *(const PG8_LAS bf16x8*)(lds + PG8_SA(b, h) + aoff + m * 2048 + k * 1024); } while (0)
; #define PG8_LDB(dst, b, h) do { _Pragma("unroll") for (int n = 0; n < 2; ++n) _Pragma("unroll") for (int k = 0; k < 2; ++k) dst[n][k] = *(const PG8_LAS bf16x8*)(lds + PG8_SB(b, h) + boff + n * 2048 + k * 1024); } while (0)
; #define PG8_SCHED __builtin_amdgcn_sched_barrier(0)
; template <class Epi, class Sched, bool ALIGN_EPI = false, bool SP2 = false>
; __device__ __forceinline__ void gemm_phase(PG8_LAS unsigned char* lds, const Gemm g, const Sched& S, const Epi& E) {
;     ...
;             PG8_LDB(B0, 0, 0); PG8_LDB(B1, 0, 1); PG8_SCHED; PG8_LDA(At, 0, 0); PG8_STAGE(PG8_SA(1, 1), a1 + hstep, voffA);
	global_load_lds_dwordx4 v168, s[58:59]

; #define PG8_STAGE(bufoff, gbase, voff) do { _Pragma("unroll") for (int _i = 0; _i < 2; ++_i) \
;         __builtin_amdgcn_global_load_lds((const unsigned*)((const char*)(gbase) + (voff)[_i]), (PG8_LAS unsigned*)(lds + (bufoff) + ldsw + _i * 8192), 16, 0, 0); } while (0)
; #define PG8_LDA(dst, b, h) do { _Pragma("unroll") for (int m = 0; m < 4; ++m) _Pragma("unroll") for (int k = 0; k < 2; ++k) dst[m][k] = *(const PG8_LAS bf16x8*)(lds + PG8_SA(b, h) + aoff + m * 2048 + k * 1024); } while (0)
; #define PG8_LDB(dst, b, h) do { _Pragma("unroll") for (int n = 0; n < 2; ++n) _Pragma("unroll") for (int k = 0; k < 2; ++k) dst[n][k] = *(const PG8_LAS bf16x8*)(lds + PG8_SB(b, h) + boff + n * 2048 + k * 1024); } while (0)
; #define PG8_MMA(ai, bj, At, Bt) do { __builtin_amdgcn_s_setprio(1); _Pragma("unroll") for (int m = 0; m < 4; ++m) _Pragma("unroll") for (int n = 0; n < 2; ++n) _Pragma("unroll") for (int k = 0; k < 2; ++k) \
;         acc[ai][bj][m][n] = __builtin_amdgcn_mfma_f32_16x16x32_bf16(Bt[n][k], At[m][k], acc[ai][bj][m][n], 0, 0, 0); __builtin_amdgcn_s_setprio(0); } while (0)
; #define PG8_WAIT_V(n) asm volatile("s_waitcnt vmcnt(" #n ")" ::: "memory")
; #define PG8_WAIT_L(n) asm volatile("s_waitcnt lgkmcnt(" #n ")" ::: "memory")
; #define PG8_BAR __builtin_amdgcn_s_barrier()
; #define PG8_SCHED __builtin_amdgcn_sched_barrier(0)
; template <class Epi, class Sched, bool ALIGN_EPI = false, bool SP2 = false>
; __device__ __forceinline__ void gemm_phase(PG8_LAS unsigned char* lds, const Gemm g, const Sched& S, const Epi& E) {
;     ...
;             PG8_LDB(B0, 0, 0); PG8_LDB(B1, 0, 1); PG8_SCHED; PG8_LDA(At, 0, 0); PG8_STAGE(PG8_SA(1, 1), a1 + hstep, voffA);
;             PG8_WAIT_V(8); PG8_WAIT_L(0); PG8_BAR; PG8_MMA(0, 0, At, B0); PG8_MMA(0, 1, At, B1); PG8_BAR; PG8_SCHED;
	s_add_i32 m0, s57, 0xe000
	ds_read_b128 v[204:207], v213 offset:7168
	global_load_lds_dwordx4 v170, s[58:59]
	s_waitcnt vmcnt(8)
	s_waitcnt lgkmcnt(0)
	s_barrier
	s_setprio 1
	s_waitcnt lgkmcnt(0)
	v_mfma_f32_16x16x32_bf16 v[140:143], v[64:67], v[176:179], v[140:143]
	v_mfma_f32_16x16x32_bf16 v[136:139], v[72:75], v[176:179], v[136:139]
	v_mfma_f32_16x16x32_bf16 v[124:127], v[64:67], v[184:187], v[124:127]
	v_mfma_f32_16x16x32_bf16 v[120:123], v[72:75], v[184:187], v[120:123]
	v_mfma_f32_16x16x32_bf16 v[108:111], v[64:67], v[192:195], v[108:111]
	v_mfma_f32_16x16x32_bf16 v[104:107], v[72:75], v[192:195], v[104:107]
	v_mfma_f32_16x16x32_bf16 v[92:95], v[64:67], v[200:203], v[92:95]
	v_mfma_f32_16x16x32_bf16 v[88:91], v[72:75], v[200:203], v[88:91]
	v_mfma_f32_16x16x32_bf16 v[140:143], v[68:71], v[180:183], v[140:143]
	v_mfma_f32_16x16x32_bf16 v[136:139], v[76:79], v[180:183], v[136:139]
	v_mfma_f32_16x16x32_bf16 v[124:127], v[68:71], v[188:191], v[124:127]
	v_mfma_f32_16x16x32_bf16 v[120:123], v[76:79], v[188:191], v[120:123]
	v_mfma_f32_16x16x32_bf16 v[108:111], v[68:71], v[196:199], v[108:111]
	v_mfma_f32_16x16x32_bf16 v[104:107], v[76:79], v[196:199], v[104:107]
	v_mfma_f32_16x16x32_bf16 v[92:95], v[68:71], v[204:207], v[92:95]
	v_mfma_f32_16x16x32_bf16 v[88:91], v[76:79], v[204:207], v[88:91]


; #define PG8_STAGE(bufoff, gbase, voff) do { _Pragma("unroll") for (int _i = 0; _i < 2; ++_i) \
;         __builtin_amdgcn_global_load_lds((const unsigned*)((const char*)(gbase) + (voff)[_i]), (PG8_LAS unsigned*)(lds + (bufoff) + ldsw + _i * 8192), 16, 0, 0); } while (0)
; #define PG8_LDA(dst, b, h) do { _Pragma("unroll") for (int m = 0; m < 4; ++m) _Pragma("unroll") for (int k = 0; k < 2; ++k) dst[m][k] = *(const PG8_LAS bf16x8*)(lds + PG8_SA(b, h) + aoff + m * 2048 + k * 1024); } while (0)
; #define PG8_MMA(ai, bj, At, Bt) do { __builtin_amdgcn_s_setprio(1); _Pragma("unroll") for (int m = 0; m < 4; ++m) _Pragma("unroll") for (int n = 0; n < 2; ++n) _Pragma("unroll") for (int k = 0; k < 2; ++k) \
;         acc[ai][bj][m][n] = __builtin_amdgcn_mfma_f32_16x16x32_bf16(Bt[n][k], At[m][k], acc[ai][bj][m][n], 0, 0, 0); __builtin_amdgcn_s_setprio(0); } while (0)
; #define PG8_WAIT_V(n) asm volatile("s_waitcnt vmcnt(" #n ")" ::: "memory")
; #define PG8_WAIT_L(n) asm volatile("s_waitcnt lgkmcnt(" #n ")" ::: "memory")
; #define PG8_BAR __builtin_amdgcn_s_barrier()
; #define PG8_SCHED __builtin_amdgcn_sched_barrier(0)
; template <class Epi, class Sched, bool ALIGN_EPI = false, bool SP2 = false>
; __device__ __forceinline__ void gemm_phase(PG8_LAS unsigned char* lds, const Gemm g, const Sched& S, const Epi& E) {
;     ...
;             PG8_WAIT_V(8); PG8_WAIT_L(0); PG8_BAR; PG8_MMA(0, 0, At, B0); PG8_MMA(0, 1, At, B1); PG8_BAR; PG8_SCHED;
;             PG8_LDA(At, 0, 1); PG8_STAGE(PG8_SB(0, 0), b2, voffB); PG8_STAGE(PG8_SB(0, 1), b2 + hstep, voffB); PG8_STAGE(PG8_SA(0, 0), a2, voffA);
	v_mfma_f32_16x16x32_bf16 v[132:135], v[144:147], v[176:179], v[132:135]
	v_mfma_f32_16x16x32_bf16 v[128:131], v[152:155], v[176:179], v[128:131]
	v_mfma_f32_16x16x32_bf16 v[116:119], v[144:147], v[184:187], v[116:119]
	v_mfma_f32_16x16x32_bf16 v[112:115], v[152:155], v[184:187], v[112:115]
	v_mfma_f32_16x16x32_bf16 v[100:103], v[144:147], v[192:195], v[100:103]
	v_mfma_f32_16x16x32_bf16 v[96:99], v[152:155], v[192:195], v[96:99]
	v_mfma_f32_16x16x32_bf16 v[84:87], v[144:147], v[200:203], v[84:87]
	v_mfma_f32_16x16x32_bf16 v[80:83], v[152:155], v[200:203], v[80:83]
	v_mfma_f32_16x16x32_bf16 v[132:135], v[148:151], v[180:183], v[132:135]
	v_mfma_f32_16x16x32_bf16 v[128:131], v[156:159], v[180:183], v[128:131]
	v_mfma_f32_16x16x32_bf16 v[116:119], v[148:151], v[188:191], v[116:119]
	v_mfma_f32_16x16x32_bf16 v[112:115], v[156:159], v[188:191], v[112:115]
	v_mfma_f32_16x16x32_bf16 v[100:103], v[148:151], v[196:199], v[100:103]
	v_mfma_f32_16x16x32_bf16 v[96:99], v[156:159], v[196:199], v[96:99]
	v_mfma_f32_16x16x32_bf16 v[84:87], v[148:151], v[204:207], v[84:87]
	v_mfma_f32_16x16x32_bf16 v[80:83], v[156:159], v[204:207], v[80:83]
	s_setprio 0
	s_barrier
	s_add_i32 s82, s75, s64
	s_mov_b64 s[96:97], s[60:61]

; #define PG8_STAGE(bufoff, gbase, voff) do { _Pragma("unroll") for (int _i = 0; _i < 2; ++_i) \
;         __builtin_amdgcn_global_load_lds((const unsigned*)((const char*)(gbase) + (voff)[_i]), (PG8_LAS unsigned*)(lds + (bufoff) + ldsw + _i * 8192), 16, 0, 0); } while (0)
; #define PG8_LDA(dst, b, h) do { _Pragma("unroll") for (int m = 0; m < 4; ++m) _Pragma("unroll") for (int k = 0; k < 2; ++k) dst[m][k] = *(const PG8_LAS bf16x8*)(lds + PG8_SA(b, h) + aoff + m * 2048 + k * 1024); } while (0)
; template <class Epi, class Sched, bool ALIGN_EPI = false, bool SP2 = false>
; __device__ __forceinline__ void gemm_phase(PG8_LAS unsigned char* lds, const Gemm g, const Sched& S, const Epi& E) {
;     ...
;             PG8_LDA(At, 0, 1); PG8_STAGE(PG8_SB(0, 0), b2, voffB); PG8_STAGE(PG8_SB(0, 1), b2 + hstep, voffB); PG8_STAGE(PG8_SA(0, 0), a2, voffA);
	s_mov_b32 m0, s82
	ds_read_b128 v[176:179], v213 offset:16384
	ds_read_b128 v[180:183], v213 offset:17408
	ds_read_b128 v[184:187], v213 offset:18432
	ds_read_b128 v[188:191], v213 offset:19456


; #define PG8_STAGE(bufoff, gbase, voff) do { _Pragma("unroll") for (int _i = 0; _i < 2; ++_i) \
;         __builtin_amdgcn_global_load_lds((const unsigned*)((const char*)(gbase) + (voff)[_i]), (PG8_LAS unsigned*)(lds + (bufoff) + ldsw + _i * 8192), 16, 0, 0); } while (0)
; #define PG8_LDA(dst, b, h) do { _Pragma("unroll") for (int m = 0; m < 4; ++m) _Pragma("unroll") for (int k = 0; k < 2; ++k) dst[m][k] = *(const PG8_LAS bf16x8*)(lds + PG8_SA(b, h) + aoff + m * 2048 + k * 1024); } while (0)
; template <class Epi, class Sched, bool ALIGN_EPI = false, bool SP2 = false>
; __device__ __forceinline__ void gemm_phase(PG8_LAS unsigned char* lds, const Gemm g, const Sched& S, const Epi& E) {
;     ...
;             PG8_LDA(At, 0, 1); PG8_STAGE(PG8_SB(0, 0), b2, voffB); PG8_STAGE(PG8_SB(0, 1), b2 + hstep, voffB); PG8_STAGE(PG8_SA(0, 0), a2, voffA);
	global_load_lds_dwordx4 v162, s[60:61]
	s_add_i32 m0, s82, 0x2000
	s_add_u32 s82, s60, 0x80000

; #define PG8_STAGE(bufoff, gbase, voff) do { _Pragma("unroll") for (int _i = 0; _i < 2; ++_i) \
;         __builtin_amdgcn_global_load_lds((const unsigned*)((const char*)(gbase) + (voff)[_i]), (PG8_LAS unsigned*)(lds + (bufoff) + ldsw + _i * 8192), 16, 0, 0); } while (0)
; #define PG8_LDA(dst, b, h) do { _Pragma("unroll") for (int m = 0; m < 4; ++m) _Pragma("unroll") for (int k = 0; k < 2; ++k) dst[m][k] = *(const PG8_LAS bf16x8*)(lds + PG8_SA(b, h) + aoff + m * 2048 + k * 1024); } while (0)
; template <class Epi, class Sched, bool ALIGN_EPI = false, bool SP2 = false>
; __device__ __forceinline__ void gemm_phase(PG8_LAS unsigned char* lds, const Gemm g, const Sched& S, const Epi& E) {
;     ...
;             PG8_LDA(At, 0, 1); PG8_STAGE(PG8_SB(0, 0), b2, voffB); PG8_STAGE(PG8_SB(0, 1), b2 + hstep, voffB); PG8_STAGE(PG8_SA(0, 0), a2, voffA);
	s_addc_u32 s83, s61, 0
	s_add_i32 s84, s76, s64
	global_load_lds_dwordx4 v166, s[60:61]

; #define PG8_STAGE(bufoff, gbase, voff) do { _Pragma("unroll") for (int _i = 0; _i < 2; ++_i) \
;         __builtin_amdgcn_global_load_lds((const unsigned*)((const char*)(gbase) + (voff)[_i]), (PG8_LAS unsigned*)(lds + (bufoff) + ldsw + _i * 8192), 16, 0, 0); } while (0)
; #define PG8_LDA(dst, b, h) do { _Pragma("unroll") for (int m = 0; m < 4; ++m) _Pragma("unroll") for (int k = 0; k < 2; ++k) dst[m][k] = *(const PG8_LAS bf16x8*)(lds + PG8_SA(b, h) + aoff + m * 2048 + k * 1024); } while (0)
; template <class Epi, class Sched, bool ALIGN_EPI = false, bool SP2 = false>
; __device__ __forceinline__ void gemm_phase(PG8_LAS unsigned char* lds, const Gemm g, const Sched& S, const Epi& E) {
;     ...
;             PG8_LDA(At, 0, 1); PG8_STAGE(PG8_SB(0, 0), b2, voffB); PG8_STAGE(PG8_SB(0, 1), b2 + hstep, voffB); PG8_STAGE(PG8_SA(0, 0), a2, voffA);
	s_mov_b32 m0, s84
	ds_read_b128 v[192:195], v213 offset:20480
	global_load_lds_dwordx4 v162, s[82:83]

; #define PG8_STAGE(bufoff, gbase, voff) do { _Pragma("unroll") for (int _i = 0; _i < 2; ++_i) \
;         __builtin_amdgcn_global_load_lds((const unsigned*)((const char*)(gbase) + (voff)[_i]), (PG8_LAS unsigned*)(lds + (bufoff) + ldsw + _i * 8192), 16, 0, 0); } while (0)
; #define PG8_LDA(dst, b, h) do { _Pragma("unroll") for (int m = 0; m < 4; ++m) _Pragma("unroll") for (int k = 0; k < 2; ++k) dst[m][k] = *(const PG8_LAS bf16x8*)(lds + PG8_SA(b, h) + aoff + m * 2048 + k * 1024); } while (0)
; template <class Epi, class Sched, bool ALIGN_EPI = false, bool SP2 = false>
; __device__ __forceinline__ void gemm_phase(PG8_LAS unsigned char* lds, const Gemm g, const Sched& S, const Epi& E) {
;     ...
;             PG8_LDA(At, 0, 1); PG8_STAGE(PG8_SB(0, 0), b2, voffB); PG8_STAGE(PG8_SB(0, 1), b2 + hstep, voffB); PG8_STAGE(PG8_SA(0, 0), a2, voffA);
	s_add_i32 m0, s84, 0x2000
	ds_read_b128 v[196:199], v213 offset:21504
	global_load_lds_dwordx4 v166, s[82:83]
	s_mov_b64 s[98:99], s[62:63]

; #define PG8_STAGE(bufoff, gbase, voff) do { _Pragma("unroll") for (int _i = 0; _i < 2; ++_i) \
;         __builtin_amdgcn_global_load_lds((const unsigned*)((const char*)(gbase) + (voff)[_i]), (PG8_LAS unsigned*)(lds + (bufoff) + ldsw + _i * 8192), 16, 0, 0); } while (0)
; #define PG8_LDA(dst, b, h) do { _Pragma("unroll") for (int m = 0; m < 4; ++m) _Pragma("unroll") for (int k = 0; k < 2; ++k) dst[m][k] = *(const PG8_LAS bf16x8*)(lds + PG8_SA(b, h) + aoff + m * 2048 + k * 1024); } while (0)
; #define PG8_MMA(ai, bj, At, Bt) do { __builtin_amdgcn_s_setprio(1); _Pragma("unroll") for (int m = 0; m < 4; ++m) _Pragma("unroll") for (int n = 0; n < 2; ++n) _Pragma("unroll") for (int k = 0; k < 2; ++k) \
;         acc[ai][bj][m][n] = __builtin_amdgcn_mfma_f32_16x16x32_bf16(Bt[n][k], At[m][k], acc[ai][bj][m][n], 0, 0, 0); __builtin_amdgcn_s_setprio(0); } while (0)
; #define PG8_WAIT_V(n) asm volatile("s_waitcnt vmcnt(" #n ")" ::: "memory")
; #define PG8_WAIT_L(n) asm volatile("s_waitcnt lgkmcnt(" #n ")" ::: "memory")
; #define PG8_BAR __builtin_amdgcn_s_barrier()
; #define PG8_SCHED __builtin_amdgcn_sched_barrier(0)
; template <class Epi, class Sched, bool ALIGN_EPI = false, bool SP2 = false>
; __device__ __forceinline__ void gemm_phase(PG8_LAS unsigned char* lds, const Gemm g, const Sched& S, const Epi& E) {
;     ...
;             PG8_LDA(At, 0, 1); PG8_STAGE(PG8_SB(0, 0), b2, voffB); PG8_STAGE(PG8_SB(0, 1), b2 + hstep, voffB); PG8_STAGE(PG8_SA(0, 0), a2, voffA);
;             PG8_WAIT_V(8); PG8_WAIT_L(0); PG8_BAR; PG8_MMA(1, 0, At, B0); PG8_MMA(1, 1, At, B1); PG8_BAR; PG8_SCHED;
	s_mov_b32 m0, s57
	ds_read_b128 v[200:203], v213 offset:22528
	global_load_lds_dwordx4 v160, s[62:63]
	s_mov_b32 m0, s65
	ds_read_b128 v[204:207], v213 offset:23552
	global_load_lds_dwordx4 v164, s[62:63]
	s_waitcnt vmcnt(8)
	s_waitcnt lgkmcnt(0)
	s_barrier
	s_setprio 1
	s_waitcnt lgkmcnt(0)
	v_mfma_f32_16x16x32_bf16 v[60:63], v[64:67], v[176:179], v[60:63]
	v_mfma_f32_16x16x32_bf16 v[56:59], v[72:75], v[176:179], v[56:59]
	v_mfma_f32_16x16x32_bf16 v[44:47], v[64:67], v[184:187], v[44:47]
	v_mfma_f32_16x16x32_bf16 v[40:43], v[72:75], v[184:187], v[40:43]
	v_mfma_f32_16x16x32_bf16 v[28:31], v[64:67], v[192:195], v[28:31]
	v_mfma_f32_16x16x32_bf16 v[24:27], v[72:75], v[192:195], v[24:27]
	v_mfma_f32_16x16x32_bf16 v[12:15], v[64:67], v[200:203], v[12:15]
	v_mfma_f32_16x16x32_bf16 v[8:11], v[72:75], v[200:203], v[8:11]
	v_mfma_f32_16x16x32_bf16 v[60:63], v[68:71], v[180:183], v[60:63]
	v_mfma_f32_16x16x32_bf16 v[56:59], v[76:79], v[180:183], v[56:59]
	v_mfma_f32_16x16x32_bf16 v[44:47], v[68:71], v[188:191], v[44:47]
	v_mfma_f32_16x16x32_bf16 v[40:43], v[76:79], v[188:191], v[40:43]
	v_mfma_f32_16x16x32_bf16 v[28:31], v[68:71], v[196:199], v[28:31]
	v_mfma_f32_16x16x32_bf16 v[24:27], v[76:79], v[196:199], v[24:27]
	v_mfma_f32_16x16x32_bf16 v[12:15], v[68:71], v[204:207], v[12:15]
	v_mfma_f32_16x16x32_bf16 v[8:11], v[76:79], v[204:207], v[8:11]


; #define PG8_STAGE(bufoff, gbase, voff) do { _Pragma("unroll") for (int _i = 0; _i < 2; ++_i) \
;         __builtin_amdgcn_global_load_lds((const unsigned*)((const char*)(gbase) + (voff)[_i]), (PG8_LAS unsigned*)(lds + (bufoff) + ldsw + _i * 8192), 16, 0, 0); } while (0)
; #define PG8_LDA(dst, b, h) do { _Pragma("unroll") for (int m = 0; m < 4; ++m) _Pragma("unroll") for (int k = 0; k < 2; ++k) dst[m][k] = *(const PG8_LAS bf16x8*)(lds + PG8_SA(b, h) + aoff + m * 2048 + k * 1024); } while (0)
; #define PG8_LDB(dst, b, h) do { _Pragma("unroll") for (int n = 0; n < 2; ++n) _Pragma("unroll") for (int k = 0; k < 2; ++k) dst[n][k] = *(const PG8_LAS bf16x8*)(lds + PG8_SB(b, h) + boff + n * 2048 + k * 1024); } while (0)
; #define PG8_MMA(ai, bj, At, Bt) do { __builtin_amdgcn_s_setprio(1); _Pragma("unroll") for (int m = 0; m < 4; ++m) _Pragma("unroll") for (int n = 0; n < 2; ++n) _Pragma("unroll") for (int k = 0; k < 2; ++k) \
;         acc[ai][bj][m][n] = __builtin_amdgcn_mfma_f32_16x16x32_bf16(Bt[n][k], At[m][k], acc[ai][bj][m][n], 0, 0, 0); __builtin_amdgcn_s_setprio(0); } while (0)
; #define PG8_WAIT_V(n) asm volatile("s_waitcnt vmcnt(" #n ")" ::: "memory")
; #define PG8_WAIT_L(n) asm volatile("s_waitcnt lgkmcnt(" #n ")" ::: "memory")
; #define PG8_BAR __builtin_amdgcn_s_barrier()
; #define PG8_SCHED __builtin_amdgcn_sched_barrier(0)
; template <class Epi, class Sched, bool ALIGN_EPI = false, bool SP2 = false>
; __device__ __forceinline__ void gemm_phase(PG8_LAS unsigned char* lds, const Gemm g, const Sched& S, const Epi& E) {
;     ...
;             PG8_WAIT_V(8); PG8_WAIT_L(0); PG8_BAR; PG8_MMA(1, 0, At, B0); PG8_MMA(1, 1, At, B1); PG8_BAR; PG8_SCHED;
;             PG8_LDB(B0, 1, 0); PG8_LDB(B1, 1, 1); PG8_SCHED; PG8_LDA(At, 1, 0); PG8_STAGE(PG8_SA(0, 1), a2 + hstep, voffA);
	v_mfma_f32_16x16x32_bf16 v[52:55], v[144:147], v[176:179], v[52:55]
	v_mfma_f32_16x16x32_bf16 v[48:51], v[152:155], v[176:179], v[48:51]
	v_mfma_f32_16x16x32_bf16 v[36:39], v[144:147], v[184:187], v[36:39]
	v_mfma_f32_16x16x32_bf16 v[32:35], v[152:155], v[184:187], v[32:35]
	v_mfma_f32_16x16x32_bf16 v[20:23], v[144:147], v[192:195], v[20:23]
	v_mfma_f32_16x16x32_bf16 v[16:19], v[152:155], v[192:195], v[16:19]
	v_mfma_f32_16x16x32_bf16 v[4:7], v[144:147], v[200:203], v[4:7]
	v_mfma_f32_16x16x32_bf16 v[0:3], v[152:155], v[200:203], v[0:3]
	v_mfma_f32_16x16x32_bf16 v[52:55], v[148:151], v[180:183], v[52:55]
	v_mfma_f32_16x16x32_bf16 v[48:51], v[156:159], v[180:183], v[48:51]
	v_mfma_f32_16x16x32_bf16 v[36:39], v[148:151], v[188:191], v[36:39]
	v_mfma_f32_16x16x32_bf16 v[32:35], v[156:159], v[188:191], v[32:35]
	v_mfma_f32_16x16x32_bf16 v[20:23], v[148:151], v[196:199], v[20:23]
	v_mfma_f32_16x16x32_bf16 v[16:19], v[156:159], v[196:199], v[16:19]
	v_mfma_f32_16x16x32_bf16 v[4:7], v[148:151], v[204:207], v[4:7]
	v_mfma_f32_16x16x32_bf16 v[0:3], v[156:159], v[204:207], v[0:3]
	s_setprio 0
	s_barrier
	s_add_i32 s82, 0, 0x18000
	s_add_i32 s83, 0, 0x1c000
	v_add_u32_e32 v76, s82, v209
	v_add_u32_e32 v156, s83, v209
	ds_read_b128 v[64:67], v76
	ds_read_b128 v[68:71], v76 offset:1024
	ds_read_b128 v[72:75], v76 offset:2048
	ds_read_b128 v[76:79], v76 offset:3072
	ds_read_b128 v[144:147], v156
	ds_read_b128 v[148:151], v156 offset:1024
	ds_read_b128 v[152:155], v156 offset:2048
	ds_read_b128 v[156:159], v156 offset:3072
	s_add_u32 s62, s62, 0x80000
	s_addc_u32 s63, s63, 0
	s_mov_b32 m0, s67

; #define PG8_STAGE(bufoff, gbase, voff) do { _Pragma("unroll") for (int _i = 0; _i < 2; ++_i) \
;         __builtin_amdgcn_global_load_lds((const unsigned*)((const char*)(gbase) + (voff)[_i]), (PG8_LAS unsigned*)(lds + (bufoff) + ldsw + _i * 8192), 16, 0, 0); } while (0)
; #define PG8_LDA(dst, b, h) do { _Pragma("unroll") for (int m = 0; m < 4; ++m) _Pragma("unroll") for (int k = 0; k < 2; ++k) dst[m][k] = *(const PG8_LAS bf16x8*)(lds + PG8_SA(b, h) + aoff + m * 2048 + k * 1024); } while (0)
; #define PG8_LDB(dst, b, h) do { _Pragma("unroll") for (int n = 0; n < 2; ++n) _Pragma("unroll") for (int k = 0; k < 2; ++k) dst[n][k] = *(const PG8_LAS bf16x8*)(lds + PG8_SB(b, h) + boff + n * 2048 + k * 1024); } while (0)
; #define PG8_SCHED __builtin_amdgcn_sched_barrier(0)
; template <class Epi, class Sched, bool ALIGN_EPI = false, bool SP2 = false>
; __device__ __forceinline__ void gemm_phase(PG8_LAS unsigned char* lds, const Gemm g, const Sched& S, const Epi& E) {
;     ...
;             PG8_LDB(B0, 1, 0); PG8_LDB(B1, 1, 1); PG8_SCHED; PG8_LDA(At, 1, 0); PG8_STAGE(PG8_SA(0, 1), a2 + hstep, voffA);
	ds_read_b128 v[176:179], v213 offset:32768
	ds_read_b128 v[180:183], v213 offset:33792
	ds_read_b128 v[184:187], v213 offset:34816
	ds_read_b128 v[188:191], v213 offset:35840
	ds_read_b128 v[192:195], v213 offset:36864
	ds_read_b128 v[196:199], v213 offset:37888
	ds_read_b128 v[200:203], v213 offset:38912

; #define PG8_STAGE(bufoff, gbase, voff) do { _Pragma("unroll") for (int _i = 0; _i < 2; ++_i) \
;         __builtin_amdgcn_global_load_lds((const unsigned*)((const char*)(gbase) + (voff)[_i]), (PG8_LAS unsigned*)(lds + (bufoff) + ldsw + _i * 8192), 16, 0, 0); } while (0)
; #define PG8_LDA(dst, b, h) do { _Pragma("unroll") for (int m = 0; m < 4; ++m) _Pragma("unroll") for (int k = 0; k < 2; ++k) dst[m][k] = *(const PG8_LAS bf16x8*)(lds + PG8_SA(b, h) + aoff + m * 2048 + k * 1024); } while (0)
; #define PG8_LDB(dst, b, h) do { _Pragma("unroll") for (int n = 0; n < 2; ++n) _Pragma("unroll") for (int k = 0; k < 2; ++k) dst[n][k] = *(const PG8_LAS bf16x8*)(lds + PG8_SB(b, h) + boff + n * 2048 + k * 1024); } while (0)
; #define PG8_SCHED __builtin_amdgcn_sched_barrier(0)
; template <class Epi, class Sched, bool ALIGN_EPI = false, bool SP2 = false>
; __device__ __forceinline__ void gemm_phase(PG8_LAS unsigned char* lds, const Gemm g, const Sched& S, const Epi& E) {
;     ...
;             PG8_LDB(B0, 1, 0); PG8_LDB(B1, 1, 1); PG8_SCHED; PG8_LDA(At, 1, 0); PG8_STAGE(PG8_SA(0, 1), a2 + hstep, voffA);
	global_load_lds_dwordx4 v160, s[62:63]

; #define PG8_STAGE(bufoff, gbase, voff) do { _Pragma("unroll") for (int _i = 0; _i < 2; ++_i) \
;         __builtin_amdgcn_global_load_lds((const unsigned*)((const char*)(gbase) + (voff)[_i]), (PG8_LAS unsigned*)(lds + (bufoff) + ldsw + _i * 8192), 16, 0, 0); } while (0)
; #define PG8_LDA(dst, b, h) do { _Pragma("unroll") for (int m = 0; m < 4; ++m) _Pragma("unroll") for (int k = 0; k < 2; ++k) dst[m][k] = *(const PG8_LAS bf16x8*)(lds + PG8_SA(b, h) + aoff + m * 2048 + k * 1024); } while (0)
; #define PG8_LDB(dst, b, h) do { _Pragma("unroll") for (int n = 0; n < 2; ++n) _Pragma("unroll") for (int k = 0; k < 2; ++k) dst[n][k] = *(const PG8_LAS bf16x8*)(lds + PG8_SB(b, h) + boff + n * 2048 + k * 1024); } while (0)
; #define PG8_MMA(ai, bj, At, Bt) do { __builtin_amdgcn_s_setprio(1); _Pragma("unroll") for (int m = 0; m < 4; ++m) _Pragma("unroll") for (int n = 0; n < 2; ++n) _Pragma("unroll") for (int k = 0; k < 2; ++k) \
;         acc[ai][bj][m][n] = __builtin_amdgcn_mfma_f32_16x16x32_bf16(Bt[n][k], At[m][k], acc[ai][bj][m][n], 0, 0, 0); __builtin_amdgcn_s_setprio(0); } while (0)
; #define PG8_WAIT_V(n) asm volatile("s_waitcnt vmcnt(" #n ")" ::: "memory")
; #define PG8_WAIT_L(n) asm volatile("s_waitcnt lgkmcnt(" #n ")" ::: "memory")
; #define PG8_BAR __builtin_amdgcn_s_barrier()
; #define PG8_SCHED __builtin_amdgcn_sched_barrier(0)
; template <class Epi, class Sched, bool ALIGN_EPI = false, bool SP2 = false>
; __device__ __forceinline__ void gemm_phase(PG8_LAS unsigned char* lds, const Gemm g, const Sched& S, const Epi& E) {
;     ...
;             PG8_LDB(B0, 1, 0); PG8_LDB(B1, 1, 1); PG8_SCHED; PG8_LDA(At, 1, 0); PG8_STAGE(PG8_SA(0, 1), a2 + hstep, voffA);
;             PG8_WAIT_V(8); PG8_WAIT_L(0); PG8_BAR; PG8_MMA(0, 0, At, B0); PG8_MMA(0, 1, At, B1); PG8_BAR; PG8_SCHED;
	s_mov_b32 m0, s68
	ds_read_b128 v[204:207], v213 offset:39936
	global_load_lds_dwordx4 v164, s[62:63]
	s_waitcnt vmcnt(8)
	s_waitcnt lgkmcnt(0)
	s_barrier
	s_setprio 1
	s_waitcnt lgkmcnt(0)
	v_mfma_f32_16x16x32_bf16 v[140:143], v[64:67], v[176:179], v[140:143]
	v_mfma_f32_16x16x32_bf16 v[136:139], v[72:75], v[176:179], v[136:139]
	v_mfma_f32_16x16x32_bf16 v[124:127], v[64:67], v[184:187], v[124:127]
	v_mfma_f32_16x16x32_bf16 v[120:123], v[72:75], v[184:187], v[120:123]
	v_mfma_f32_16x16x32_bf16 v[108:111], v[64:67], v[192:195], v[108:111]
	v_mfma_f32_16x16x32_bf16 v[104:107], v[72:75], v[192:195], v[104:107]
	v_mfma_f32_16x16x32_bf16 v[92:95], v[64:67], v[200:203], v[92:95]
	v_mfma_f32_16x16x32_bf16 v[88:91], v[72:75], v[200:203], v[88:91]
	v_mfma_f32_16x16x32_bf16 v[140:143], v[68:71], v[180:183], v[140:143]
	v_mfma_f32_16x16x32_bf16 v[136:139], v[76:79], v[180:183], v[136:139]
	v_mfma_f32_16x16x32_bf16 v[124:127], v[68:71], v[188:191], v[124:127]
	v_mfma_f32_16x16x32_bf16 v[120:123], v[76:79], v[188:191], v[120:123]
	v_mfma_f32_16x16x32_bf16 v[108:111], v[68:71], v[196:199], v[108:111]
	v_mfma_f32_16x16x32_bf16 v[104:107], v[76:79], v[196:199], v[104:107]
	v_mfma_f32_16x16x32_bf16 v[92:95], v[68:71], v[204:207], v[92:95]
	v_mfma_f32_16x16x32_bf16 v[88:91], v[76:79], v[204:207], v[88:91]


; #define PG8_STAGE(bufoff, gbase, voff) do { _Pragma("unroll") for (int _i = 0; _i < 2; ++_i) \
;         __builtin_amdgcn_global_load_lds((const unsigned*)((const char*)(gbase) + (voff)[_i]), (PG8_LAS unsigned*)(lds + (bufoff) + ldsw + _i * 8192), 16, 0, 0); } while (0)
; #define PG8_LDA(dst, b, h) do { _Pragma("unroll") for (int m = 0; m < 4; ++m) _Pragma("unroll") for (int k = 0; k < 2; ++k) dst[m][k] = *(const PG8_LAS bf16x8*)(lds + PG8_SA(b, h) + aoff + m * 2048 + k * 1024); } while (0)
; #define PG8_MMA(ai, bj, At, Bt) do { __builtin_amdgcn_s_setprio(1); _Pragma("unroll") for (int m = 0; m < 4; ++m) _Pragma("unroll") for (int n = 0; n < 2; ++n) _Pragma("unroll") for (int k = 0; k < 2; ++k) \
;         acc[ai][bj][m][n] = __builtin_amdgcn_mfma_f32_16x16x32_bf16(Bt[n][k], At[m][k], acc[ai][bj][m][n], 0, 0, 0); __builtin_amdgcn_s_setprio(0); } while (0)
; #define PG8_WAIT_V(n) asm volatile("s_waitcnt vmcnt(" #n ")" ::: "memory")
; #define PG8_WAIT_L(n) asm volatile("s_waitcnt lgkmcnt(" #n ")" ::: "memory")
; #define PG8_BAR __builtin_amdgcn_s_barrier()
; #define PG8_SCHED __builtin_amdgcn_sched_barrier(0)
; template <class Epi, class Sched, bool ALIGN_EPI = false, bool SP2 = false>
; __device__ __forceinline__ void gemm_phase(PG8_LAS unsigned char* lds, const Gemm g, const Sched& S, const Epi& E) {
;     ...
;             PG8_WAIT_V(8); PG8_WAIT_L(0); PG8_BAR; PG8_MMA(0, 0, At, B0); PG8_MMA(0, 1, At, B1); PG8_BAR; PG8_SCHED;
;             PG8_LDA(At, 1, 1); PG8_STAGE(PG8_SB(1, 0), b3, voffB); PG8_STAGE(PG8_SB(1, 1), b3 + hstep, voffB); PG8_STAGE(PG8_SA(1, 0), a3, voffA);
	v_mfma_f32_16x16x32_bf16 v[132:135], v[144:147], v[176:179], v[132:135]
	v_mfma_f32_16x16x32_bf16 v[128:131], v[152:155], v[176:179], v[128:131]
	v_mfma_f32_16x16x32_bf16 v[116:119], v[144:147], v[184:187], v[116:119]
	v_mfma_f32_16x16x32_bf16 v[112:115], v[152:155], v[184:187], v[112:115]
	v_mfma_f32_16x16x32_bf16 v[100:103], v[144:147], v[192:195], v[100:103]
	v_mfma_f32_16x16x32_bf16 v[96:99], v[152:155], v[192:195], v[96:99]
	v_mfma_f32_16x16x32_bf16 v[84:87], v[144:147], v[200:203], v[84:87]
	v_mfma_f32_16x16x32_bf16 v[80:83], v[152:155], v[200:203], v[80:83]
	v_mfma_f32_16x16x32_bf16 v[132:135], v[148:151], v[180:183], v[132:135]
	v_mfma_f32_16x16x32_bf16 v[128:131], v[156:159], v[180:183], v[128:131]
	v_mfma_f32_16x16x32_bf16 v[116:119], v[148:151], v[188:191], v[116:119]
	v_mfma_f32_16x16x32_bf16 v[112:115], v[156:159], v[188:191], v[112:115]
	v_mfma_f32_16x16x32_bf16 v[100:103], v[148:151], v[196:199], v[100:103]
	v_mfma_f32_16x16x32_bf16 v[96:99], v[156:159], v[196:199], v[96:99]
	v_mfma_f32_16x16x32_bf16 v[84:87], v[148:151], v[204:207], v[84:87]
	v_mfma_f32_16x16x32_bf16 v[80:83], v[156:159], v[204:207], v[80:83]
	s_setprio 0
	s_barrier
	s_add_i32 s62, s82, s64

; #define PG8_STAGE(bufoff, gbase, voff) do { _Pragma("unroll") for (int _i = 0; _i < 2; ++_i) \
;         __builtin_amdgcn_global_load_lds((const unsigned*)((const char*)(gbase) + (voff)[_i]), (PG8_LAS unsigned*)(lds + (bufoff) + ldsw + _i * 8192), 16, 0, 0); } while (0)
; #define PG8_LDA(dst, b, h) do { _Pragma("unroll") for (int m = 0; m < 4; ++m) _Pragma("unroll") for (int k = 0; k < 2; ++k) dst[m][k] = *(const PG8_LAS bf16x8*)(lds + PG8_SA(b, h) + aoff + m * 2048 + k * 1024); } while (0)
; template <class Epi, class Sched, bool ALIGN_EPI = false, bool SP2 = false>
; __device__ __forceinline__ void gemm_phase(PG8_LAS unsigned char* lds, const Gemm g, const Sched& S, const Epi& E) {
;     ...
;             PG8_LDA(At, 1, 1); PG8_STAGE(PG8_SB(1, 0), b3, voffB); PG8_STAGE(PG8_SB(1, 1), b3 + hstep, voffB); PG8_STAGE(PG8_SA(1, 0), a3, voffA);
	s_mov_b32 m0, s62
	ds_read_b128 v[176:179], v213 offset:49152
	ds_read_b128 v[180:183], v213 offset:50176
	ds_read_b128 v[184:187], v213 offset:51200
	ds_read_b128 v[188:191], v213 offset:52224


; #define PG8_STAGE(bufoff, gbase, voff) do { _Pragma("unroll") for (int _i = 0; _i < 2; ++_i) \
;         __builtin_amdgcn_global_load_lds((const unsigned*)((const char*)(gbase) + (voff)[_i]), (PG8_LAS unsigned*)(lds + (bufoff) + ldsw + _i * 8192), 16, 0, 0); } while (0)
; #define PG8_LDA(dst, b, h) do { _Pragma("unroll") for (int m = 0; m < 4; ++m) _Pragma("unroll") for (int k = 0; k < 2; ++k) dst[m][k] = *(const PG8_LAS bf16x8*)(lds + PG8_SA(b, h) + aoff + m * 2048 + k * 1024); } while (0)
; template <class Epi, class Sched, bool ALIGN_EPI = false, bool SP2 = false>
; __device__ __forceinline__ void gemm_phase(PG8_LAS unsigned char* lds, const Gemm g, const Sched& S, const Epi& E) {
;     ...
;             PG8_LDA(At, 1, 1); PG8_STAGE(PG8_SB(1, 0), b3, voffB); PG8_STAGE(PG8_SB(1, 1), b3 + hstep, voffB); PG8_STAGE(PG8_SA(1, 0), a3, voffA);
	global_load_lds_dwordx4 v250, s[96:97]
	s_add_i32 m0, s62, 0x2000
	s_add_u32 s60, s60, 0x80080

; #define PG8_STAGE(bufoff, gbase, voff) do { _Pragma("unroll") for (int _i = 0; _i < 2; ++_i) \
;         __builtin_amdgcn_global_load_lds((const unsigned*)((const char*)(gbase) + (voff)[_i]), (PG8_LAS unsigned*)(lds + (bufoff) + ldsw + _i * 8192), 16, 0, 0); } while (0)
; #define PG8_LDA(dst, b, h) do { _Pragma("unroll") for (int m = 0; m < 4; ++m) _Pragma("unroll") for (int k = 0; k < 2; ++k) dst[m][k] = *(const PG8_LAS bf16x8*)(lds + PG8_SA(b, h) + aoff + m * 2048 + k * 1024); } while (0)
; template <class Epi, class Sched, bool ALIGN_EPI = false, bool SP2 = false>
; __device__ __forceinline__ void gemm_phase(PG8_LAS unsigned char* lds, const Gemm g, const Sched& S, const Epi& E) {
;     ...
;             PG8_LDA(At, 1, 1); PG8_STAGE(PG8_SB(1, 0), b3, voffB); PG8_STAGE(PG8_SB(1, 1), b3 + hstep, voffB); PG8_STAGE(PG8_SA(1, 0), a3, voffA);
	s_addc_u32 s61, s61, 0
	s_add_i32 s62, s83, s64
	global_load_lds_dwordx4 v251, s[96:97]

; #define PG8_STAGE(bufoff, gbase, voff) do { _Pragma("unroll") for (int _i = 0; _i < 2; ++_i) \
;         __builtin_amdgcn_global_load_lds((const unsigned*)((const char*)(gbase) + (voff)[_i]), (PG8_LAS unsigned*)(lds + (bufoff) + ldsw + _i * 8192), 16, 0, 0); } while (0)
; #define PG8_LDA(dst, b, h) do { _Pragma("unroll") for (int m = 0; m < 4; ++m) _Pragma("unroll") for (int k = 0; k < 2; ++k) dst[m][k] = *(const PG8_LAS bf16x8*)(lds + PG8_SA(b, h) + aoff + m * 2048 + k * 1024); } while (0)
; template <class Epi, class Sched, bool ALIGN_EPI = false, bool SP2 = false>
; __device__ __forceinline__ void gemm_phase(PG8_LAS unsigned char* lds, const Gemm g, const Sched& S, const Epi& E) {
;     ...
;             PG8_LDA(At, 1, 1); PG8_STAGE(PG8_SB(1, 0), b3, voffB); PG8_STAGE(PG8_SB(1, 1), b3 + hstep, voffB); PG8_STAGE(PG8_SA(1, 0), a3, voffA);
	s_mov_b32 m0, s62
	ds_read_b128 v[192:195], v213 offset:53248
	global_load_lds_dwordx4 v162, s[60:61]

; #define PG8_STAGE(bufoff, gbase, voff) do { _Pragma("unroll") for (int _i = 0; _i < 2; ++_i) \
;         __builtin_amdgcn_global_load_lds((const unsigned*)((const char*)(gbase) + (voff)[_i]), (PG8_LAS unsigned*)(lds + (bufoff) + ldsw + _i * 8192), 16, 0, 0); } while (0)
; #define PG8_LDA(dst, b, h) do { _Pragma("unroll") for (int m = 0; m < 4; ++m) _Pragma("unroll") for (int k = 0; k < 2; ++k) dst[m][k] = *(const PG8_LAS bf16x8*)(lds + PG8_SA(b, h) + aoff + m * 2048 + k * 1024); } while (0)
; template <class Epi, class Sched, bool ALIGN_EPI = false, bool SP2 = false>
; __device__ __forceinline__ void gemm_phase(PG8_LAS unsigned char* lds, const Gemm g, const Sched& S, const Epi& E) {
;     ...
;             PG8_LDA(At, 1, 1); PG8_STAGE(PG8_SB(1, 0), b3, voffB); PG8_STAGE(PG8_SB(1, 1), b3 + hstep, voffB); PG8_STAGE(PG8_SA(1, 0), a3, voffA);
	s_add_i32 m0, s62, 0x2000
	ds_read_b128 v[196:199], v213 offset:54272
	global_load_lds_dwordx4 v166, s[60:61]

; #define PG8_STAGE(bufoff, gbase, voff) do { _Pragma("unroll") for (int _i = 0; _i < 2; ++_i) \
;         __builtin_amdgcn_global_load_lds((const unsigned*)((const char*)(gbase) + (voff)[_i]), (PG8_LAS unsigned*)(lds + (bufoff) + ldsw + _i * 8192), 16, 0, 0); } while (0)
; #define PG8_LDA(dst, b, h) do { _Pragma("unroll") for (int m = 0; m < 4; ++m) _Pragma("unroll") for (int k = 0; k < 2; ++k) dst[m][k] = *(const PG8_LAS bf16x8*)(lds + PG8_SA(b, h) + aoff + m * 2048 + k * 1024); } while (0)
; template <class Epi, class Sched, bool ALIGN_EPI = false, bool SP2 = false>
; __device__ __forceinline__ void gemm_phase(PG8_LAS unsigned char* lds, const Gemm g, const Sched& S, const Epi& E) {
;     ...
;             PG8_LDA(At, 1, 1); PG8_STAGE(PG8_SB(1, 0), b3, voffB); PG8_STAGE(PG8_SB(1, 1), b3 + hstep, voffB); PG8_STAGE(PG8_SA(1, 0), a3, voffA);
	s_mov_b32 m0, s70
	ds_read_b128 v[200:203], v213 offset:55296
	global_load_lds_dwordx4 v252, s[98:99]

; #define PG8_STAGE(bufoff, gbase, voff) do { _Pragma("unroll") for (int _i = 0; _i < 2; ++_i) \
;         __builtin_amdgcn_global_load_lds((const unsigned*)((const char*)(gbase) + (voff)[_i]), (PG8_LAS unsigned*)(lds + (bufoff) + ldsw + _i * 8192), 16, 0, 0); } while (0)
; #define PG8_LDA(dst, b, h) do { _Pragma("unroll") for (int m = 0; m < 4; ++m) _Pragma("unroll") for (int k = 0; k < 2; ++k) dst[m][k] = *(const PG8_LAS bf16x8*)(lds + PG8_SA(b, h) + aoff + m * 2048 + k * 1024); } while (0)
; #define PG8_MMA(ai, bj, At, Bt) do { __builtin_amdgcn_s_setprio(1); _Pragma("unroll") for (int m = 0; m < 4; ++m) _Pragma("unroll") for (int n = 0; n < 2; ++n) _Pragma("unroll") for (int k = 0; k < 2; ++k) \
;         acc[ai][bj][m][n] = __builtin_amdgcn_mfma_f32_16x16x32_bf16(Bt[n][k], At[m][k], acc[ai][bj][m][n], 0, 0, 0); __builtin_amdgcn_s_setprio(0); } while (0)
; #define PG8_WAIT_V(n) asm volatile("s_waitcnt vmcnt(" #n ")" ::: "memory")
; #define PG8_WAIT_L(n) asm volatile("s_waitcnt lgkmcnt(" #n ")" ::: "memory")
; #define PG8_BAR __builtin_amdgcn_s_barrier()
; #define PG8_SCHED __builtin_amdgcn_sched_barrier(0)
; template <class Epi, class Sched, bool ALIGN_EPI = false, bool SP2 = false>
; __device__ __forceinline__ void gemm_phase(PG8_LAS unsigned char* lds, const Gemm g, const Sched& S, const Epi& E) {
;     ...
;             PG8_LDA(At, 1, 1); PG8_STAGE(PG8_SB(1, 0), b3, voffB); PG8_STAGE(PG8_SB(1, 1), b3 + hstep, voffB); PG8_STAGE(PG8_SA(1, 0), a3, voffA);
;             PG8_WAIT_V(8); PG8_WAIT_L(0); PG8_BAR; PG8_MMA(1, 0, At, B0); PG8_MMA(1, 1, At, B1); PG8_BAR; PG8_SCHED;
	s_mov_b32 m0, s71
	ds_read_b128 v[204:207], v213 offset:56320
	global_load_lds_dwordx4 v253, s[98:99]
	s_waitcnt vmcnt(8)
	s_waitcnt lgkmcnt(0)
	s_barrier
	s_setprio 1
	s_waitcnt lgkmcnt(0)
	v_mfma_f32_16x16x32_bf16 v[60:63], v[64:67], v[176:179], v[60:63]
	v_mfma_f32_16x16x32_bf16 v[56:59], v[72:75], v[176:179], v[56:59]
	v_mfma_f32_16x16x32_bf16 v[44:47], v[64:67], v[184:187], v[44:47]
	v_mfma_f32_16x16x32_bf16 v[40:43], v[72:75], v[184:187], v[40:43]
	v_mfma_f32_16x16x32_bf16 v[28:31], v[64:67], v[192:195], v[28:31]
	v_mfma_f32_16x16x32_bf16 v[24:27], v[72:75], v[192:195], v[24:27]
	v_mfma_f32_16x16x32_bf16 v[12:15], v[64:67], v[200:203], v[12:15]
	v_mfma_f32_16x16x32_bf16 v[8:11], v[72:75], v[200:203], v[8:11]
	v_mfma_f32_16x16x32_bf16 v[60:63], v[68:71], v[180:183], v[60:63]
	v_mfma_f32_16x16x32_bf16 v[56:59], v[76:79], v[180:183], v[56:59]
	v_mfma_f32_16x16x32_bf16 v[44:47], v[68:71], v[188:191], v[44:47]
	v_mfma_f32_16x16x32_bf16 v[40:43], v[76:79], v[188:191], v[40:43]
	v_mfma_f32_16x16x32_bf16 v[28:31], v[68:71], v[196:199], v[28:31]
	v_mfma_f32_16x16x32_bf16 v[24:27], v[76:79], v[196:199], v[24:27]
	v_mfma_f32_16x16x32_bf16 v[12:15], v[68:71], v[204:207], v[12:15]
	v_mfma_f32_16x16x32_bf16 v[8:11], v[76:79], v[204:207], v[8:11]


; #define PG8_STAGE(bufoff, gbase, voff) do { _Pragma("unroll") for (int _i = 0; _i < 2; ++_i) \
;         __builtin_amdgcn_global_load_lds((const unsigned*)((const char*)(gbase) + (voff)[_i]), (PG8_LAS unsigned*)(lds + (bufoff) + ldsw + _i * 8192), 16, 0, 0); } while (0)
; #define PG8_LDA(dst, b, h) do { _Pragma("unroll") for (int m = 0; m < 4; ++m) _Pragma("unroll") for (int k = 0; k < 2; ++k) dst[m][k] = *(const PG8_LAS bf16x8*)(lds + PG8_SA(b, h) + aoff + m * 2048 + k * 1024); } while (0)
; #define PG8_LDB(dst, b, h) do { _Pragma("unroll") for (int n = 0; n < 2; ++n) _Pragma("unroll") for (int k = 0; k < 2; ++k) dst[n][k] = *(const PG8_LAS bf16x8*)(lds + PG8_SB(b, h) + boff + n * 2048 + k * 1024); } while (0)
; template <class Epi, class Sched, bool ALIGN_EPI = false, bool SP2 = false>
; __device__ __forceinline__ void gemm_phase(PG8_LAS unsigned char* lds, const Gemm g, const Sched& S, const Epi& E) {
;     ...
;             PG8_WAIT_V(8); PG8_WAIT_L(0); PG8_BAR; PG8_MMA(1, 0, At, B0); PG8_MMA(1, 1, At, B1); PG8_BAR; PG8_SCHED;
;             } else {
;             PG8_LDB(B0, 0, 0); PG8_SCHED; PG8_LDA(At, 0, 0); PG8_STAGE(PG8_SA(1, 1), a1 + hstep, voffA);
;             PG8_WAIT_L(8); PG8_BAR; PG8_WAIT_L(0); PG8_MMA(0, 0, At, B0); PG8_BAR; PG8_SCHED;
;             PG8_LDB(B1, 0, 1); PG8_STAGE(PG8_SB(0, 0), b2, voffB);
;             PG8_BAR; PG8_WAIT_L(0); PG8_MMA(0, 1, At, B1); PG8_BAR;
;             PG8_LDA(At, 0, 1); PG8_STAGE(PG8_SA(0, 0), a2, voffA);
;             PG8_BAR; PG8_WAIT_L(0); PG8_MMA(1, 0, At, B0); PG8_BAR; PG8_SCHED;
;             PG8_STAGE(PG8_SB(0, 1), b2 + hstep, voffB);
;             PG8_WAIT_V(6); PG8_BAR; PG8_MMA(1, 1, At, B1); PG8_BAR;
;             PG8_LDB(B0, 1, 0); PG8_SCHED; PG8_LDA(At, 1, 0); PG8_STAGE(PG8_SA(0, 1), a2 + hstep, voffA);
;             PG8_WAIT_L(8); PG8_BAR; PG8_WAIT_L(0); PG8_MMA(0, 0, At, B0); PG8_BAR; PG8_SCHED;
;             PG8_LDB(B1, 1, 1); PG8_STAGE(PG8_SB(1, 0), b3, voffB);
;             PG8_BAR; PG8_WAIT_L(0); PG8_MMA(0, 1, At, B1); PG8_BAR;
;             PG8_LDA(At, 1, 1); PG8_STAGE(PG8_SA(1, 0), a3, voffA);
;             PG8_BAR; PG8_WAIT_L(0); PG8_MMA(1, 0, At, B0); PG8_BAR; PG8_SCHED;
;             PG8_STAGE(PG8_SB(1, 1), b3 + hstep, voffB);
;             PG8_WAIT_V(6); PG8_BAR; PG8_MMA(1, 1, At, B1); PG8_BAR;
;             }
;         }
;         if constexpr (ALIGN_EPI) { if (wr == 0) PG8_BAR; }
	v_mfma_f32_16x16x32_bf16 v[52:55], v[144:147], v[176:179], v[52:55]
	v_mfma_f32_16x16x32_bf16 v[48:51], v[152:155], v[176:179], v[48:51]
	v_mfma_f32_16x16x32_bf16 v[36:39], v[144:147], v[184:187], v[36:39]
	v_mfma_f32_16x16x32_bf16 v[32:35], v[152:155], v[184:187], v[32:35]
	v_mfma_f32_16x16x32_bf16 v[20:23], v[144:147], v[192:195], v[20:23]
	v_mfma_f32_16x16x32_bf16 v[16:19], v[152:155], v[192:195], v[16:19]
	v_mfma_f32_16x16x32_bf16 v[4:7], v[144:147], v[200:203], v[4:7]
	v_mfma_f32_16x16x32_bf16 v[0:3], v[152:155], v[200:203], v[0:3]
	v_mfma_f32_16x16x32_bf16 v[52:55], v[148:151], v[180:183], v[52:55]
	v_mfma_f32_16x16x32_bf16 v[48:51], v[156:159], v[180:183], v[48:51]
	v_mfma_f32_16x16x32_bf16 v[36:39], v[148:151], v[188:191], v[36:39]
	v_mfma_f32_16x16x32_bf16 v[32:35], v[156:159], v[188:191], v[32:35]
	v_mfma_f32_16x16x32_bf16 v[20:23], v[148:151], v[196:199], v[20:23]
	v_mfma_f32_16x16x32_bf16 v[16:19], v[156:159], v[196:199], v[16:19]
	v_mfma_f32_16x16x32_bf16 v[4:7], v[148:151], v[204:207], v[4:7]
	v_mfma_f32_16x16x32_bf16 v[0:3], v[156:159], v[204:207], v[0:3]
	s_setprio 0
	s_barrier
	s_add_i32 s81, s81, 2
	s_add_u32 s58, s58, 0x100
	s_addc_u32 s59, s59, 0
	s_add_u32 s79, s79, 0x100
	s_addc_u32 s80, s80, 0
	s_cmp_gt_u32 s81, 29
	s_cbranch_scc0 .LBB0_333
	s_and_b64 vcc, exec, s[42:43]
	s_cbranch_vccz .LBB0_336
	s_barrier

; #define PG8_STAGE(bufoff, gbase, voff) do { _Pragma("unroll") for (int _i = 0; _i < 2; ++_i) \
;         __builtin_amdgcn_global_load_lds((const unsigned*)((const char*)(gbase) + (voff)[_i]), (PG8_LAS unsigned*)(lds + (bufoff) + ldsw + _i * 8192), 16, 0, 0); } while (0)
; #define PG8_LDA(dst, b, h) do { _Pragma("unroll") for (int m = 0; m < 4; ++m) _Pragma("unroll") for (int k = 0; k < 2; ++k) dst[m][k] = *(const PG8_LAS bf16x8*)(lds + PG8_SA(b, h) + aoff + m * 2048 + k * 1024); } while (0)
; #define PG8_LDB(dst, b, h) do { _Pragma("unroll") for (int n = 0; n < 2; ++n) _Pragma("unroll") for (int k = 0; k < 2; ++k) dst[n][k] = *(const PG8_LAS bf16x8*)(lds + PG8_SB(b, h) + boff + n * 2048 + k * 1024); } while (0)
; #define PG8_SCHED __builtin_amdgcn_sched_barrier(0)
; template <class Epi, class Sched, bool ALIGN_EPI = false, bool SP2 = false>
; __device__ __forceinline__ void gemm_phase(PG8_LAS unsigned char* lds, const Gemm g, const Sched& S, const Epi& E) {
;     ...
;         for (int t = 0; t < nt; t += 2) {
;             const bool last = (t == nt - 2);
;             const char* a1 = cA + (size_t)(t + 1) * kstep;
;             const char* a2 = last ? nA : cA + (size_t)(t + 2) * kstep; const char* b2 = last ? nB : cB + (size_t)(t + 2) * kstep;
;             const char* a3 = a2 + kstep; const char* b3 = b2 + kstep;
;             if (last && has_next) S.a_ready(nxt);
;             if constexpr (SP2) {
;             PG8_LDB(B0, 0, 0); PG8_LDB(B1, 0, 1); PG8_SCHED; PG8_LDA(At, 0, 0); PG8_STAGE(PG8_SA(1, 1), a1 + hstep, voffA);
.LBB0_428:
	ds_read_b128 v[128:131], v201
	ds_read_b128 v[132:135], v201 offset:1024
	ds_read_b128 v[136:139], v201 offset:2048
	ds_read_b128 v[140:143], v201 offset:3072
	ds_read_b128 v[144:147], v205
	ds_read_b128 v[148:151], v205 offset:1024
	ds_read_b128 v[152:155], v205 offset:2048
	ds_read_b128 v[156:159], v205 offset:3072
	s_add_u32 s12, s10, 0xfff80080
	s_addc_u32 s13, s11, -1
	s_cmp_eq_u32 s85, 28
	s_cselect_b32 s61, s55, s13
	s_cselect_b32 s60, s81, s12
	s_cselect_b32 s13, s53, s84
	s_cselect_b32 s12, s82, s83

; #define PG8_STAGE(bufoff, gbase, voff) do { _Pragma("unroll") for (int _i = 0; _i < 2; ++_i) \
;         __builtin_amdgcn_global_load_lds((const unsigned*)((const char*)(gbase) + (voff)[_i]), (PG8_LAS unsigned*)(lds + (bufoff) + ldsw + _i * 8192), 16, 0, 0); } while (0)
; #define PG8_LDA(dst, b, h) do { _Pragma("unroll") for (int m = 0; m < 4; ++m) _Pragma("unroll") for (int k = 0; k < 2; ++k) dst[m][k] = *(const PG8_LAS bf16x8*)(lds + PG8_SA(b, h) + aoff + m * 2048 + k * 1024); } while (0)
; #define PG8_LDB(dst, b, h) do { _Pragma("unroll") for (int n = 0; n < 2; ++n) _Pragma("unroll") for (int k = 0; k < 2; ++k) dst[n][k] = *(const PG8_LAS bf16x8*)(lds + PG8_SB(b, h) + boff + n * 2048 + k * 1024); } while (0)
; #define PG8_SCHED __builtin_amdgcn_sched_barrier(0)
; template <class Epi, class Sched, bool ALIGN_EPI = false, bool SP2 = false>
; __device__ __forceinline__ void gemm_phase(PG8_LAS unsigned char* lds, const Gemm g, const Sched& S, const Epi& E) {
;     ...
;             PG8_LDB(B0, 0, 0); PG8_LDB(B1, 0, 1); PG8_SCHED; PG8_LDA(At, 0, 0); PG8_STAGE(PG8_SA(1, 1), a1 + hstep, voffA);
	s_add_i32 m0, s65, 0xc000
	ds_read_b128 v[176:179], v207
	ds_read_b128 v[184:187], v207 offset:1024
	ds_read_b128 v[190:193], v207 offset:2048
	ds_read_b128 v[210:213], v207 offset:3072
	ds_read_b128 v[214:217], v207 offset:4096
	ds_read_b128 v[218:221], v207 offset:5120
	ds_read_b128 v[222:225], v207 offset:6144

; #define PG8_STAGE(bufoff, gbase, voff) do { _Pragma("unroll") for (int _i = 0; _i < 2; ++_i) \
;         __builtin_amdgcn_global_load_lds((const unsigned*)((const char*)(gbase) + (voff)[_i]), (PG8_LAS unsigned*)(lds + (bufoff) + ldsw + _i * 8192), 16, 0, 0); } while (0)
; #define PG8_LDA(dst, b, h) do { _Pragma("unroll") for (int m = 0; m < 4; ++m) _Pragma("unroll") for (int k = 0; k < 2; ++k) dst[m][k] = *(const PG8_LAS bf16x8*)(lds + PG8_SA(b, h) + aoff + m * 2048 + k * 1024); } while (0)
; #define PG8_LDB(dst, b, h) do { _Pragma("unroll") for (int n = 0; n < 2; ++n) _Pragma("unroll") for (int k = 0; k < 2; ++k) dst[n][k] = *(const PG8_LAS bf16x8*)(lds + PG8_SB(b, h) + boff + n * 2048 + k * 1024); } while (0)
; #define PG8_SCHED __builtin_amdgcn_sched_barrier(0)
; template <class Epi, class Sched, bool ALIGN_EPI = false, bool SP2 = false>
; __device__ __forceinline__ void gemm_phase(PG8_LAS unsigned char* lds, const Gemm g, const Sched& S, const Epi& E) {
;     ...
;             PG8_LDB(B0, 0, 0); PG8_LDB(B1, 0, 1); PG8_SCHED; PG8_LDA(At, 0, 0); PG8_STAGE(PG8_SA(1, 1), a1 + hstep, voffA);
	global_load_lds_dwordx4 v168, s[10:11]

; #define PG8_STAGE(bufoff, gbase, voff) do { _Pragma("unroll") for (int _i = 0; _i < 2; ++_i) \
;         __builtin_amdgcn_global_load_lds((const unsigned*)((const char*)(gbase) + (voff)[_i]), (PG8_LAS unsigned*)(lds + (bufoff) + ldsw + _i * 8192), 16, 0, 0); } while (0)
; #define PG8_LDA(dst, b, h) do { _Pragma("unroll") for (int m = 0; m < 4; ++m) _Pragma("unroll") for (int k = 0; k < 2; ++k) dst[m][k] = *(const PG8_LAS bf16x8*)(lds + PG8_SA(b, h) + aoff + m * 2048 + k * 1024); } while (0)
; #define PG8_LDB(dst, b, h) do { _Pragma("unroll") for (int n = 0; n < 2; ++n) _Pragma("unroll") for (int k = 0; k < 2; ++k) dst[n][k] = *(const PG8_LAS bf16x8*)(lds + PG8_SB(b, h) + boff + n * 2048 + k * 1024); } while (0)
; #define PG8_MMA(ai, bj, At, Bt) do { __builtin_amdgcn_s_setprio(1); _Pragma("unroll") for (int m = 0; m < 4; ++m) _Pragma("unroll") for (int n = 0; n < 2; ++n) _Pragma("unroll") for (int k = 0; k < 2; ++k) \
;         acc[ai][bj][m][n] = __builtin_amdgcn_mfma_f32_16x16x32_bf16(Bt[n][k], At[m][k], acc[ai][bj][m][n], 0, 0, 0); __builtin_amdgcn_s_setprio(0); } while (0)
; #define PG8_WAIT_V(n) asm volatile("s_waitcnt vmcnt(" #n ")" ::: "memory")
; #define PG8_WAIT_L(n) asm volatile("s_waitcnt lgkmcnt(" #n ")" ::: "memory")
; #define PG8_BAR __builtin_amdgcn_s_barrier()
; #define PG8_SCHED __builtin_amdgcn_sched_barrier(0)
; template <class Epi, class Sched, bool ALIGN_EPI = false, bool SP2 = false>
; __device__ __forceinline__ void gemm_phase(PG8_LAS unsigned char* lds, const Gemm g, const Sched& S, const Epi& E) {
;     ...
;             PG8_LDB(B0, 0, 0); PG8_LDB(B1, 0, 1); PG8_SCHED; PG8_LDA(At, 0, 0); PG8_STAGE(PG8_SA(1, 1), a1 + hstep, voffA);
;             PG8_WAIT_V(8); PG8_WAIT_L(0); PG8_BAR; PG8_MMA(0, 0, At, B0); PG8_MMA(0, 1, At, B1); PG8_BAR; PG8_SCHED;
	s_add_i32 m0, s65, 0xe000
	ds_read_b128 v[226:229], v207 offset:7168
	global_load_lds_dwordx4 v170, s[10:11]
	s_waitcnt vmcnt(8)
	s_waitcnt lgkmcnt(0)
	s_barrier
	s_setprio 1
	s_waitcnt lgkmcnt(0)
	v_mfma_f32_16x16x32_bf16 v[124:127], v[128:131], v[176:179], v[124:127]
	v_mfma_f32_16x16x32_bf16 v[120:123], v[136:139], v[176:179], v[120:123]
	v_mfma_f32_16x16x32_bf16 v[108:111], v[128:131], v[190:193], v[108:111]
	v_mfma_f32_16x16x32_bf16 v[104:107], v[136:139], v[190:193], v[104:107]
	v_mfma_f32_16x16x32_bf16 v[92:95], v[128:131], v[214:217], v[92:95]
	v_mfma_f32_16x16x32_bf16 v[88:91], v[136:139], v[214:217], v[88:91]
	v_mfma_f32_16x16x32_bf16 v[76:79], v[128:131], v[222:225], v[76:79]
	v_mfma_f32_16x16x32_bf16 v[72:75], v[136:139], v[222:225], v[72:75]
	v_mfma_f32_16x16x32_bf16 v[124:127], v[132:135], v[184:187], v[124:127]
	v_mfma_f32_16x16x32_bf16 v[120:123], v[140:143], v[184:187], v[120:123]
	v_mfma_f32_16x16x32_bf16 v[108:111], v[132:135], v[210:213], v[108:111]
	v_mfma_f32_16x16x32_bf16 v[104:107], v[140:143], v[210:213], v[104:107]
	v_mfma_f32_16x16x32_bf16 v[92:95], v[132:135], v[218:221], v[92:95]
	v_mfma_f32_16x16x32_bf16 v[88:91], v[140:143], v[218:221], v[88:91]
	v_mfma_f32_16x16x32_bf16 v[76:79], v[132:135], v[226:229], v[76:79]
	v_mfma_f32_16x16x32_bf16 v[72:75], v[140:143], v[226:229], v[72:75]


; #define PG8_STAGE(bufoff, gbase, voff) do { _Pragma("unroll") for (int _i = 0; _i < 2; ++_i) \
;         __builtin_amdgcn_global_load_lds((const unsigned*)((const char*)(gbase) + (voff)[_i]), (PG8_LAS unsigned*)(lds + (bufoff) + ldsw + _i * 8192), 16, 0, 0); } while (0)
; #define PG8_LDA(dst, b, h) do { _Pragma("unroll") for (int m = 0; m < 4; ++m) _Pragma("unroll") for (int k = 0; k < 2; ++k) dst[m][k] = *(const PG8_LAS bf16x8*)(lds + PG8_SA(b, h) + aoff + m * 2048 + k * 1024); } while (0)
; #define PG8_MMA(ai, bj, At, Bt) do { __builtin_amdgcn_s_setprio(1); _Pragma("unroll") for (int m = 0; m < 4; ++m) _Pragma("unroll") for (int n = 0; n < 2; ++n) _Pragma("unroll") for (int k = 0; k < 2; ++k) \
;         acc[ai][bj][m][n] = __builtin_amdgcn_mfma_f32_16x16x32_bf16(Bt[n][k], At[m][k], acc[ai][bj][m][n], 0, 0, 0); __builtin_amdgcn_s_setprio(0); } while (0)
; #define PG8_WAIT_V(n) asm volatile("s_waitcnt vmcnt(" #n ")" ::: "memory")
; #define PG8_WAIT_L(n) asm volatile("s_waitcnt lgkmcnt(" #n ")" ::: "memory")
; #define PG8_BAR __builtin_amdgcn_s_barrier()
; #define PG8_SCHED __builtin_amdgcn_sched_barrier(0)
; template <class Epi, class Sched, bool ALIGN_EPI = false, bool SP2 = false>
; __device__ __forceinline__ void gemm_phase(PG8_LAS unsigned char* lds, const Gemm g, const Sched& S, const Epi& E) {
;     ...
;             PG8_WAIT_V(8); PG8_WAIT_L(0); PG8_BAR; PG8_MMA(0, 0, At, B0); PG8_MMA(0, 1, At, B1); PG8_BAR; PG8_SCHED;
;             PG8_LDA(At, 0, 1); PG8_STAGE(PG8_SB(0, 0), b2, voffB); PG8_STAGE(PG8_SB(0, 1), b2 + hstep, voffB); PG8_STAGE(PG8_SA(0, 0), a2, voffA);
	v_mfma_f32_16x16x32_bf16 v[116:119], v[144:147], v[176:179], v[116:119]
	v_mfma_f32_16x16x32_bf16 v[112:115], v[152:155], v[176:179], v[112:115]
	v_mfma_f32_16x16x32_bf16 v[100:103], v[144:147], v[190:193], v[100:103]
	v_mfma_f32_16x16x32_bf16 v[96:99], v[152:155], v[190:193], v[96:99]
	v_mfma_f32_16x16x32_bf16 v[84:87], v[144:147], v[214:217], v[84:87]
	v_mfma_f32_16x16x32_bf16 v[80:83], v[152:155], v[214:217], v[80:83]
	v_mfma_f32_16x16x32_bf16 v[68:71], v[144:147], v[222:225], v[68:71]
	v_mfma_f32_16x16x32_bf16 v[64:67], v[152:155], v[222:225], v[64:67]
	v_mfma_f32_16x16x32_bf16 v[116:119], v[148:151], v[184:187], v[116:119]
	v_mfma_f32_16x16x32_bf16 v[112:115], v[156:159], v[184:187], v[112:115]
	v_mfma_f32_16x16x32_bf16 v[100:103], v[148:151], v[210:213], v[100:103]
	v_mfma_f32_16x16x32_bf16 v[96:99], v[156:159], v[210:213], v[96:99]
	v_mfma_f32_16x16x32_bf16 v[84:87], v[148:151], v[218:221], v[84:87]
	v_mfma_f32_16x16x32_bf16 v[80:83], v[156:159], v[218:221], v[80:83]
	v_mfma_f32_16x16x32_bf16 v[68:71], v[148:151], v[226:229], v[68:71]
	v_mfma_f32_16x16x32_bf16 v[64:67], v[156:159], v[226:229], v[64:67]
	s_setprio 0
	s_barrier
	s_add_i32 s86, s75, s64
	s_mov_b64 s[96:97], s[12:13]

; #define PG8_STAGE(bufoff, gbase, voff) do { _Pragma("unroll") for (int _i = 0; _i < 2; ++_i) \
;         __builtin_amdgcn_global_load_lds((const unsigned*)((const char*)(gbase) + (voff)[_i]), (PG8_LAS unsigned*)(lds + (bufoff) + ldsw + _i * 8192), 16, 0, 0); } while (0)
; #define PG8_LDA(dst, b, h) do { _Pragma("unroll") for (int m = 0; m < 4; ++m) _Pragma("unroll") for (int k = 0; k < 2; ++k) dst[m][k] = *(const PG8_LAS bf16x8*)(lds + PG8_SA(b, h) + aoff + m * 2048 + k * 1024); } while (0)
; template <class Epi, class Sched, bool ALIGN_EPI = false, bool SP2 = false>
; __device__ __forceinline__ void gemm_phase(PG8_LAS unsigned char* lds, const Gemm g, const Sched& S, const Epi& E) {
;     ...
;             PG8_LDA(At, 0, 1); PG8_STAGE(PG8_SB(0, 0), b2, voffB); PG8_STAGE(PG8_SB(0, 1), b2 + hstep, voffB); PG8_STAGE(PG8_SA(0, 0), a2, voffA);
	s_mov_b32 m0, s86
	ds_read_b128 v[176:179], v207 offset:16384
	ds_read_b128 v[184:187], v207 offset:17408
	ds_read_b128 v[190:193], v207 offset:18432
	ds_read_b128 v[210:213], v207 offset:19456


; #define PG8_STAGE(bufoff, gbase, voff) do { _Pragma("unroll") for (int _i = 0; _i < 2; ++_i) \
;         __builtin_amdgcn_global_load_lds((const unsigned*)((const char*)(gbase) + (voff)[_i]), (PG8_LAS unsigned*)(lds + (bufoff) + ldsw + _i * 8192), 16, 0, 0); } while (0)
; #define PG8_LDA(dst, b, h) do { _Pragma("unroll") for (int m = 0; m < 4; ++m) _Pragma("unroll") for (int k = 0; k < 2; ++k) dst[m][k] = *(const PG8_LAS bf16x8*)(lds + PG8_SA(b, h) + aoff + m * 2048 + k * 1024); } while (0)
; template <class Epi, class Sched, bool ALIGN_EPI = false, bool SP2 = false>
; __device__ __forceinline__ void gemm_phase(PG8_LAS unsigned char* lds, const Gemm g, const Sched& S, const Epi& E) {
;     ...
;             PG8_LDA(At, 0, 1); PG8_STAGE(PG8_SB(0, 0), b2, voffB); PG8_STAGE(PG8_SB(0, 1), b2 + hstep, voffB); PG8_STAGE(PG8_SA(0, 0), a2, voffA);
	global_load_lds_dwordx4 v162, s[12:13]
	s_add_i32 m0, s86, 0x2000
	s_add_u32 s86, s12, 0x80000

; #define PG8_STAGE(bufoff, gbase, voff) do { _Pragma("unroll") for (int _i = 0; _i < 2; ++_i) \
;         __builtin_amdgcn_global_load_lds((const unsigned*)((const char*)(gbase) + (voff)[_i]), (PG8_LAS unsigned*)(lds + (bufoff) + ldsw + _i * 8192), 16, 0, 0); } while (0)
; #define PG8_LDA(dst, b, h) do { _Pragma("unroll") for (int m = 0; m < 4; ++m) _Pragma("unroll") for (int k = 0; k < 2; ++k) dst[m][k] = *(const PG8_LAS bf16x8*)(lds + PG8_SA(b, h) + aoff + m * 2048 + k * 1024); } while (0)
; template <class Epi, class Sched, bool ALIGN_EPI = false, bool SP2 = false>
; __device__ __forceinline__ void gemm_phase(PG8_LAS unsigned char* lds, const Gemm g, const Sched& S, const Epi& E) {
;     ...
;             PG8_LDA(At, 0, 1); PG8_STAGE(PG8_SB(0, 0), b2, voffB); PG8_STAGE(PG8_SB(0, 1), b2 + hstep, voffB); PG8_STAGE(PG8_SA(0, 0), a2, voffA);
	s_addc_u32 s87, s13, 0
	s_add_i32 s88, s76, s64
	global_load_lds_dwordx4 v166, s[12:13]

; #define PG8_STAGE(bufoff, gbase, voff) do { _Pragma("unroll") for (int _i = 0; _i < 2; ++_i) \
;         __builtin_amdgcn_global_load_lds((const unsigned*)((const char*)(gbase) + (voff)[_i]), (PG8_LAS unsigned*)(lds + (bufoff) + ldsw + _i * 8192), 16, 0, 0); } while (0)
; #define PG8_LDA(dst, b, h) do { _Pragma("unroll") for (int m = 0; m < 4; ++m) _Pragma("unroll") for (int k = 0; k < 2; ++k) dst[m][k] = *(const PG8_LAS bf16x8*)(lds + PG8_SA(b, h) + aoff + m * 2048 + k * 1024); } while (0)
; template <class Epi, class Sched, bool ALIGN_EPI = false, bool SP2 = false>
; __device__ __forceinline__ void gemm_phase(PG8_LAS unsigned char* lds, const Gemm g, const Sched& S, const Epi& E) {
;     ...
;             PG8_LDA(At, 0, 1); PG8_STAGE(PG8_SB(0, 0), b2, voffB); PG8_STAGE(PG8_SB(0, 1), b2 + hstep, voffB); PG8_STAGE(PG8_SA(0, 0), a2, voffA);
	s_mov_b32 m0, s88
	ds_read_b128 v[214:217], v207 offset:20480
	global_load_lds_dwordx4 v162, s[86:87]

; #define PG8_STAGE(bufoff, gbase, voff) do { _Pragma("unroll") for (int _i = 0; _i < 2; ++_i) \
;         __builtin_amdgcn_global_load_lds((const unsigned*)((const char*)(gbase) + (voff)[_i]), (PG8_LAS unsigned*)(lds + (bufoff) + ldsw + _i * 8192), 16, 0, 0); } while (0)
; #define PG8_LDA(dst, b, h) do { _Pragma("unroll") for (int m = 0; m < 4; ++m) _Pragma("unroll") for (int k = 0; k < 2; ++k) dst[m][k] = *(const PG8_LAS bf16x8*)(lds + PG8_SA(b, h) + aoff + m * 2048 + k * 1024); } while (0)
; template <class Epi, class Sched, bool ALIGN_EPI = false, bool SP2 = false>
; __device__ __forceinline__ void gemm_phase(PG8_LAS unsigned char* lds, const Gemm g, const Sched& S, const Epi& E) {
;     ...
;             PG8_LDA(At, 0, 1); PG8_STAGE(PG8_SB(0, 0), b2, voffB); PG8_STAGE(PG8_SB(0, 1), b2 + hstep, voffB); PG8_STAGE(PG8_SA(0, 0), a2, voffA);
	s_add_i32 m0, s88, 0x2000
	ds_read_b128 v[218:221], v207 offset:21504
	global_load_lds_dwordx4 v166, s[86:87]
	s_mov_b64 s[98:99], s[60:61]

; #define PG8_STAGE(bufoff, gbase, voff) do { _Pragma("unroll") for (int _i = 0; _i < 2; ++_i) \
;         __builtin_amdgcn_global_load_lds((const unsigned*)((const char*)(gbase) + (voff)[_i]), (PG8_LAS unsigned*)(lds + (bufoff) + ldsw + _i * 8192), 16, 0, 0); } while (0)
; #define PG8_LDA(dst, b, h) do { _Pragma("unroll") for (int m = 0; m < 4; ++m) _Pragma("unroll") for (int k = 0; k < 2; ++k) dst[m][k] = *(const PG8_LAS bf16x8*)(lds + PG8_SA(b, h) + aoff + m * 2048 + k * 1024); } while (0)
; #define PG8_MMA(ai, bj, At, Bt) do { __builtin_amdgcn_s_setprio(1); _Pragma("unroll") for (int m = 0; m < 4; ++m) _Pragma("unroll") for (int n = 0; n < 2; ++n) _Pragma("unroll") for (int k = 0; k < 2; ++k) \
;         acc[ai][bj][m][n] = __builtin_amdgcn_mfma_f32_16x16x32_bf16(Bt[n][k], At[m][k], acc[ai][bj][m][n], 0, 0, 0); __builtin_amdgcn_s_setprio(0); } while (0)
; #define PG8_WAIT_V(n) asm volatile("s_waitcnt vmcnt(" #n ")" ::: "memory")
; #define PG8_WAIT_L(n) asm volatile("s_waitcnt lgkmcnt(" #n ")" ::: "memory")
; #define PG8_BAR __builtin_amdgcn_s_barrier()
; #define PG8_SCHED __builtin_amdgcn_sched_barrier(0)
; template <class Epi, class Sched, bool ALIGN_EPI = false, bool SP2 = false>
; __device__ __forceinline__ void gemm_phase(PG8_LAS unsigned char* lds, const Gemm g, const Sched& S, const Epi& E) {
;     ...
;             PG8_LDA(At, 0, 1); PG8_STAGE(PG8_SB(0, 0), b2, voffB); PG8_STAGE(PG8_SB(0, 1), b2 + hstep, voffB); PG8_STAGE(PG8_SA(0, 0), a2, voffA);
;             PG8_WAIT_V(8); PG8_WAIT_L(0); PG8_BAR; PG8_MMA(1, 0, At, B0); PG8_MMA(1, 1, At, B1); PG8_BAR; PG8_SCHED;
	s_mov_b32 m0, s65
	ds_read_b128 v[222:225], v207 offset:22528
	global_load_lds_dwordx4 v160, s[60:61]
	s_mov_b32 m0, s67
	ds_read_b128 v[226:229], v207 offset:23552
	global_load_lds_dwordx4 v164, s[60:61]
	s_waitcnt vmcnt(8)
	s_waitcnt lgkmcnt(0)
	s_barrier
	s_setprio 1
	s_waitcnt lgkmcnt(0)
	v_mfma_f32_16x16x32_bf16 v[60:63], v[128:131], v[176:179], v[60:63]
	v_mfma_f32_16x16x32_bf16 v[56:59], v[136:139], v[176:179], v[56:59]
	v_mfma_f32_16x16x32_bf16 v[44:47], v[128:131], v[190:193], v[44:47]
	v_mfma_f32_16x16x32_bf16 v[40:43], v[136:139], v[190:193], v[40:43]
	v_mfma_f32_16x16x32_bf16 v[28:31], v[128:131], v[214:217], v[28:31]
	v_mfma_f32_16x16x32_bf16 v[24:27], v[136:139], v[214:217], v[24:27]
	v_mfma_f32_16x16x32_bf16 v[12:15], v[128:131], v[222:225], v[12:15]
	v_mfma_f32_16x16x32_bf16 v[8:11], v[136:139], v[222:225], v[8:11]
	v_mfma_f32_16x16x32_bf16 v[60:63], v[132:135], v[184:187], v[60:63]
	v_mfma_f32_16x16x32_bf16 v[56:59], v[140:143], v[184:187], v[56:59]
	v_mfma_f32_16x16x32_bf16 v[44:47], v[132:135], v[210:213], v[44:47]
	v_mfma_f32_16x16x32_bf16 v[40:43], v[140:143], v[210:213], v[40:43]
	v_mfma_f32_16x16x32_bf16 v[28:31], v[132:135], v[218:221], v[28:31]
	v_mfma_f32_16x16x32_bf16 v[24:27], v[140:143], v[218:221], v[24:27]
	v_mfma_f32_16x16x32_bf16 v[12:15], v[132:135], v[226:229], v[12:15]
	v_mfma_f32_16x16x32_bf16 v[8:11], v[140:143], v[226:229], v[8:11]


; #define PG8_STAGE(bufoff, gbase, voff) do { _Pragma("unroll") for (int _i = 0; _i < 2; ++_i) \
;         __builtin_amdgcn_global_load_lds((const unsigned*)((const char*)(gbase) + (voff)[_i]), (PG8_LAS unsigned*)(lds + (bufoff) + ldsw + _i * 8192), 16, 0, 0); } while (0)
; #define PG8_LDA(dst, b, h) do { _Pragma("unroll") for (int m = 0; m < 4; ++m) _Pragma("unroll") for (int k = 0; k < 2; ++k) dst[m][k] = *(const PG8_LAS bf16x8*)(lds + PG8_SA(b, h) + aoff + m * 2048 + k * 1024); } while (0)
; #define PG8_LDB(dst, b, h) do { _Pragma("unroll") for (int n = 0; n < 2; ++n) _Pragma("unroll") for (int k = 0; k < 2; ++k) dst[n][k] = *(const PG8_LAS bf16x8*)(lds + PG8_SB(b, h) + boff + n * 2048 + k * 1024); } while (0)
; #define PG8_MMA(ai, bj, At, Bt) do { __builtin_amdgcn_s_setprio(1); _Pragma("unroll") for (int m = 0; m < 4; ++m) _Pragma("unroll") for (int n = 0; n < 2; ++n) _Pragma("unroll") for (int k = 0; k < 2; ++k) \
;         acc[ai][bj][m][n] = __builtin_amdgcn_mfma_f32_16x16x32_bf16(Bt[n][k], At[m][k], acc[ai][bj][m][n], 0, 0, 0); __builtin_amdgcn_s_setprio(0); } while (0)
; #define PG8_WAIT_V(n) asm volatile("s_waitcnt vmcnt(" #n ")" ::: "memory")
; #define PG8_WAIT_L(n) asm volatile("s_waitcnt lgkmcnt(" #n ")" ::: "memory")
; #define PG8_BAR __builtin_amdgcn_s_barrier()
; #define PG8_SCHED __builtin_amdgcn_sched_barrier(0)
; template <class Epi, class Sched, bool ALIGN_EPI = false, bool SP2 = false>
; __device__ __forceinline__ void gemm_phase(PG8_LAS unsigned char* lds, const Gemm g, const Sched& S, const Epi& E) {
;     ...
;             PG8_WAIT_V(8); PG8_WAIT_L(0); PG8_BAR; PG8_MMA(1, 0, At, B0); PG8_MMA(1, 1, At, B1); PG8_BAR; PG8_SCHED;
;             PG8_LDB(B0, 1, 0); PG8_LDB(B1, 1, 1); PG8_SCHED; PG8_LDA(At, 1, 0); PG8_STAGE(PG8_SA(0, 1), a2 + hstep, voffA);
	v_mfma_f32_16x16x32_bf16 v[52:55], v[144:147], v[176:179], v[52:55]
	v_mfma_f32_16x16x32_bf16 v[48:51], v[152:155], v[176:179], v[48:51]
	v_mfma_f32_16x16x32_bf16 v[36:39], v[144:147], v[190:193], v[36:39]
	v_mfma_f32_16x16x32_bf16 v[32:35], v[152:155], v[190:193], v[32:35]
	v_mfma_f32_16x16x32_bf16 v[20:23], v[144:147], v[214:217], v[20:23]
	v_mfma_f32_16x16x32_bf16 v[16:19], v[152:155], v[214:217], v[16:19]
	v_mfma_f32_16x16x32_bf16 v[4:7], v[144:147], v[222:225], v[4:7]
	v_mfma_f32_16x16x32_bf16 v[0:3], v[152:155], v[222:225], v[0:3]
	v_mfma_f32_16x16x32_bf16 v[52:55], v[148:151], v[184:187], v[52:55]
	v_mfma_f32_16x16x32_bf16 v[48:51], v[156:159], v[184:187], v[48:51]
	v_mfma_f32_16x16x32_bf16 v[36:39], v[148:151], v[210:213], v[36:39]
	v_mfma_f32_16x16x32_bf16 v[32:35], v[156:159], v[210:213], v[32:35]
	v_mfma_f32_16x16x32_bf16 v[20:23], v[148:151], v[218:221], v[20:23]
	v_mfma_f32_16x16x32_bf16 v[16:19], v[156:159], v[218:221], v[16:19]
	v_mfma_f32_16x16x32_bf16 v[4:7], v[148:151], v[226:229], v[4:7]
	v_mfma_f32_16x16x32_bf16 v[0:3], v[156:159], v[226:229], v[0:3]
	s_setprio 0
	s_barrier
	s_add_i32 s86, 0, 0x18000
	s_add_i32 s87, 0, 0x1c000
	v_add_u32_e32 v140, s86, v189
	v_add_u32_e32 v156, s87, v189
	ds_read_b128 v[128:131], v140
	ds_read_b128 v[132:135], v140 offset:1024
	ds_read_b128 v[136:139], v140 offset:2048
	ds_read_b128 v[140:143], v140 offset:3072
	ds_read_b128 v[144:147], v156
	ds_read_b128 v[148:151], v156 offset:1024
	ds_read_b128 v[152:155], v156 offset:2048
	ds_read_b128 v[156:159], v156 offset:3072
	s_add_u32 s60, s60, 0x80000
	s_addc_u32 s61, s61, 0
	s_mov_b32 m0, s68

; #define PG8_STAGE(bufoff, gbase, voff) do { _Pragma("unroll") for (int _i = 0; _i < 2; ++_i) \
;         __builtin_amdgcn_global_load_lds((const unsigned*)((const char*)(gbase) + (voff)[_i]), (PG8_LAS unsigned*)(lds + (bufoff) + ldsw + _i * 8192), 16, 0, 0); } while (0)
; #define PG8_LDA(dst, b, h) do { _Pragma("unroll") for (int m = 0; m < 4; ++m) _Pragma("unroll") for (int k = 0; k < 2; ++k) dst[m][k] = *(const PG8_LAS bf16x8*)(lds + PG8_SA(b, h) + aoff + m * 2048 + k * 1024); } while (0)
; #define PG8_LDB(dst, b, h) do { _Pragma("unroll") for (int n = 0; n < 2; ++n) _Pragma("unroll") for (int k = 0; k < 2; ++k) dst[n][k] = *(const PG8_LAS bf16x8*)(lds + PG8_SB(b, h) + boff + n * 2048 + k * 1024); } while (0)
; #define PG8_SCHED __builtin_amdgcn_sched_barrier(0)
; template <class Epi, class Sched, bool ALIGN_EPI = false, bool SP2 = false>
; __device__ __forceinline__ void gemm_phase(PG8_LAS unsigned char* lds, const Gemm g, const Sched& S, const Epi& E) {
;     ...
;             PG8_LDB(B0, 1, 0); PG8_LDB(B1, 1, 1); PG8_SCHED; PG8_LDA(At, 1, 0); PG8_STAGE(PG8_SA(0, 1), a2 + hstep, voffA);
	ds_read_b128 v[176:179], v207 offset:32768
	ds_read_b128 v[184:187], v207 offset:33792
	ds_read_b128 v[190:193], v207 offset:34816
	ds_read_b128 v[210:213], v207 offset:35840
	ds_read_b128 v[214:217], v207 offset:36864
	ds_read_b128 v[218:221], v207 offset:37888
	ds_read_b128 v[222:225], v207 offset:38912

; #define PG8_STAGE(bufoff, gbase, voff) do { _Pragma("unroll") for (int _i = 0; _i < 2; ++_i) \
;         __builtin_amdgcn_global_load_lds((const unsigned*)((const char*)(gbase) + (voff)[_i]), (PG8_LAS unsigned*)(lds + (bufoff) + ldsw + _i * 8192), 16, 0, 0); } while (0)
; #define PG8_LDA(dst, b, h) do { _Pragma("unroll") for (int m = 0; m < 4; ++m) _Pragma("unroll") for (int k = 0; k < 2; ++k) dst[m][k] = *(const PG8_LAS bf16x8*)(lds + PG8_SA(b, h) + aoff + m * 2048 + k * 1024); } while (0)
; #define PG8_LDB(dst, b, h) do { _Pragma("unroll") for (int n = 0; n < 2; ++n) _Pragma("unroll") for (int k = 0; k < 2; ++k) dst[n][k] = *(const PG8_LAS bf16x8*)(lds + PG8_SB(b, h) + boff + n * 2048 + k * 1024); } while (0)
; #define PG8_SCHED __builtin_amdgcn_sched_barrier(0)
; template <class Epi, class Sched, bool ALIGN_EPI = false, bool SP2 = false>
; __device__ __forceinline__ void gemm_phase(PG8_LAS unsigned char* lds, const Gemm g, const Sched& S, const Epi& E) {
;     ...
;             PG8_LDB(B0, 1, 0); PG8_LDB(B1, 1, 1); PG8_SCHED; PG8_LDA(At, 1, 0); PG8_STAGE(PG8_SA(0, 1), a2 + hstep, voffA);
	global_load_lds_dwordx4 v160, s[60:61]

; #define PG8_STAGE(bufoff, gbase, voff) do { _Pragma("unroll") for (int _i = 0; _i < 2; ++_i) \
;         __builtin_amdgcn_global_load_lds((const unsigned*)((const char*)(gbase) + (voff)[_i]), (PG8_LAS unsigned*)(lds + (bufoff) + ldsw + _i * 8192), 16, 0, 0); } while (0)
; #define PG8_LDA(dst, b, h) do { _Pragma("unroll") for (int m = 0; m < 4; ++m) _Pragma("unroll") for (int k = 0; k < 2; ++k) dst[m][k] = *(const PG8_LAS bf16x8*)(lds + PG8_SA(b, h) + aoff + m * 2048 + k * 1024); } while (0)
; #define PG8_LDB(dst, b, h) do { _Pragma("unroll") for (int n = 0; n < 2; ++n) _Pragma("unroll") for (int k = 0; k < 2; ++k) dst[n][k] = *(const PG8_LAS bf16x8*)(lds + PG8_SB(b, h) + boff + n * 2048 + k * 1024); } while (0)
; #define PG8_MMA(ai, bj, At, Bt) do { __builtin_amdgcn_s_setprio(1); _Pragma("unroll") for (int m = 0; m < 4; ++m) _Pragma("unroll") for (int n = 0; n < 2; ++n) _Pragma("unroll") for (int k = 0; k < 2; ++k) \
;         acc[ai][bj][m][n] = __builtin_amdgcn_mfma_f32_16x16x32_bf16(Bt[n][k], At[m][k], acc[ai][bj][m][n], 0, 0, 0); __builtin_amdgcn_s_setprio(0); } while (0)
; #define PG8_WAIT_V(n) asm volatile("s_waitcnt vmcnt(" #n ")" ::: "memory")
; #define PG8_WAIT_L(n) asm volatile("s_waitcnt lgkmcnt(" #n ")" ::: "memory")
; #define PG8_BAR __builtin_amdgcn_s_barrier()
; #define PG8_SCHED __builtin_amdgcn_sched_barrier(0)
; template <class Epi, class Sched, bool ALIGN_EPI = false, bool SP2 = false>
; __device__ __forceinline__ void gemm_phase(PG8_LAS unsigned char* lds, const Gemm g, const Sched& S, const Epi& E) {
;     ...
;             PG8_LDB(B0, 1, 0); PG8_LDB(B1, 1, 1); PG8_SCHED; PG8_LDA(At, 1, 0); PG8_STAGE(PG8_SA(0, 1), a2 + hstep, voffA);
;             PG8_WAIT_V(8); PG8_WAIT_L(0); PG8_BAR; PG8_MMA(0, 0, At, B0); PG8_MMA(0, 1, At, B1); PG8_BAR; PG8_SCHED;
	s_mov_b32 m0, s69
	ds_read_b128 v[226:229], v207 offset:39936
	global_load_lds_dwordx4 v164, s[60:61]
	s_waitcnt vmcnt(8)
	s_waitcnt lgkmcnt(0)
	s_barrier
	s_setprio 1
	s_waitcnt lgkmcnt(0)
	v_mfma_f32_16x16x32_bf16 v[124:127], v[128:131], v[176:179], v[124:127]
	v_mfma_f32_16x16x32_bf16 v[120:123], v[136:139], v[176:179], v[120:123]
	v_mfma_f32_16x16x32_bf16 v[108:111], v[128:131], v[190:193], v[108:111]
	v_mfma_f32_16x16x32_bf16 v[104:107], v[136:139], v[190:193], v[104:107]
	v_mfma_f32_16x16x32_bf16 v[92:95], v[128:131], v[214:217], v[92:95]
	v_mfma_f32_16x16x32_bf16 v[88:91], v[136:139], v[214:217], v[88:91]
	v_mfma_f32_16x16x32_bf16 v[76:79], v[128:131], v[222:225], v[76:79]
	v_mfma_f32_16x16x32_bf16 v[72:75], v[136:139], v[222:225], v[72:75]
	v_mfma_f32_16x16x32_bf16 v[124:127], v[132:135], v[184:187], v[124:127]
	v_mfma_f32_16x16x32_bf16 v[120:123], v[140:143], v[184:187], v[120:123]
	v_mfma_f32_16x16x32_bf16 v[108:111], v[132:135], v[210:213], v[108:111]
	v_mfma_f32_16x16x32_bf16 v[104:107], v[140:143], v[210:213], v[104:107]
	v_mfma_f32_16x16x32_bf16 v[92:95], v[132:135], v[218:221], v[92:95]
	v_mfma_f32_16x16x32_bf16 v[88:91], v[140:143], v[218:221], v[88:91]
	v_mfma_f32_16x16x32_bf16 v[76:79], v[132:135], v[226:229], v[76:79]
	v_mfma_f32_16x16x32_bf16 v[72:75], v[140:143], v[226:229], v[72:75]


; #define PG8_STAGE(bufoff, gbase, voff) do { _Pragma("unroll") for (int _i = 0; _i < 2; ++_i) \
;         __builtin_amdgcn_global_load_lds((const unsigned*)((const char*)(gbase) + (voff)[_i]), (PG8_LAS unsigned*)(lds + (bufoff) + ldsw + _i * 8192), 16, 0, 0); } while (0)
; #define PG8_LDA(dst, b, h) do { _Pragma("unroll") for (int m = 0; m < 4; ++m) _Pragma("unroll") for (int k = 0; k < 2; ++k) dst[m][k] = *(const PG8_LAS bf16x8*)(lds + PG8_SA(b, h) + aoff + m * 2048 + k * 1024); } while (0)
; #define PG8_MMA(ai, bj, At, Bt) do { __builtin_amdgcn_s_setprio(1); _Pragma("unroll") for (int m = 0; m < 4; ++m) _Pragma("unroll") for (int n = 0; n < 2; ++n) _Pragma("unroll") for (int k = 0; k < 2; ++k) \
;         acc[ai][bj][m][n] = __builtin_amdgcn_mfma_f32_16x16x32_bf16(Bt[n][k], At[m][k], acc[ai][bj][m][n], 0, 0, 0); __builtin_amdgcn_s_setprio(0); } while (0)
; #define PG8_WAIT_V(n) asm volatile("s_waitcnt vmcnt(" #n ")" ::: "memory")
; #define PG8_WAIT_L(n) asm volatile("s_waitcnt lgkmcnt(" #n ")" ::: "memory")
; #define PG8_BAR __builtin_amdgcn_s_barrier()
; #define PG8_SCHED __builtin_amdgcn_sched_barrier(0)
; template <class Epi, class Sched, bool ALIGN_EPI = false, bool SP2 = false>
; __device__ __forceinline__ void gemm_phase(PG8_LAS unsigned char* lds, const Gemm g, const Sched& S, const Epi& E) {
;     ...
;             PG8_WAIT_V(8); PG8_WAIT_L(0); PG8_BAR; PG8_MMA(0, 0, At, B0); PG8_MMA(0, 1, At, B1); PG8_BAR; PG8_SCHED;
;             PG8_LDA(At, 1, 1); PG8_STAGE(PG8_SB(1, 0), b3, voffB); PG8_STAGE(PG8_SB(1, 1), b3 + hstep, voffB); PG8_STAGE(PG8_SA(1, 0), a3, voffA);
	v_mfma_f32_16x16x32_bf16 v[116:119], v[144:147], v[176:179], v[116:119]
	v_mfma_f32_16x16x32_bf16 v[112:115], v[152:155], v[176:179], v[112:115]
	v_mfma_f32_16x16x32_bf16 v[100:103], v[144:147], v[190:193], v[100:103]
	v_mfma_f32_16x16x32_bf16 v[96:99], v[152:155], v[190:193], v[96:99]
	v_mfma_f32_16x16x32_bf16 v[84:87], v[144:147], v[214:217], v[84:87]
	v_mfma_f32_16x16x32_bf16 v[80:83], v[152:155], v[214:217], v[80:83]
	v_mfma_f32_16x16x32_bf16 v[68:71], v[144:147], v[222:225], v[68:71]
	v_mfma_f32_16x16x32_bf16 v[64:67], v[152:155], v[222:225], v[64:67]
	v_mfma_f32_16x16x32_bf16 v[116:119], v[148:151], v[184:187], v[116:119]
	v_mfma_f32_16x16x32_bf16 v[112:115], v[156:159], v[184:187], v[112:115]
	v_mfma_f32_16x16x32_bf16 v[100:103], v[148:151], v[210:213], v[100:103]
	v_mfma_f32_16x16x32_bf16 v[96:99], v[156:159], v[210:213], v[96:99]
	v_mfma_f32_16x16x32_bf16 v[84:87], v[148:151], v[218:221], v[84:87]
	v_mfma_f32_16x16x32_bf16 v[80:83], v[156:159], v[218:221], v[80:83]
	v_mfma_f32_16x16x32_bf16 v[68:71], v[148:151], v[226:229], v[68:71]
	v_mfma_f32_16x16x32_bf16 v[64:67], v[156:159], v[226:229], v[64:67]
	s_setprio 0
	s_barrier
	s_add_i32 s60, s86, s64

; #define PG8_STAGE(bufoff, gbase, voff) do { _Pragma("unroll") for (int _i = 0; _i < 2; ++_i) \
;         __builtin_amdgcn_global_load_lds((const unsigned*)((const char*)(gbase) + (voff)[_i]), (PG8_LAS unsigned*)(lds + (bufoff) + ldsw + _i * 8192), 16, 0, 0); } while (0)
; #define PG8_LDA(dst, b, h) do { _Pragma("unroll") for (int m = 0; m < 4; ++m) _Pragma("unroll") for (int k = 0; k < 2; ++k) dst[m][k] = *(const PG8_LAS bf16x8*)(lds + PG8_SA(b, h) + aoff + m * 2048 + k * 1024); } while (0)
; template <class Epi, class Sched, bool ALIGN_EPI = false, bool SP2 = false>
; __device__ __forceinline__ void gemm_phase(PG8_LAS unsigned char* lds, const Gemm g, const Sched& S, const Epi& E) {
;     ...
;             PG8_LDA(At, 1, 1); PG8_STAGE(PG8_SB(1, 0), b3, voffB); PG8_STAGE(PG8_SB(1, 1), b3 + hstep, voffB); PG8_STAGE(PG8_SA(1, 0), a3, voffA);
	s_mov_b32 m0, s60
	ds_read_b128 v[176:179], v207 offset:49152
	ds_read_b128 v[184:187], v207 offset:50176
	ds_read_b128 v[190:193], v207 offset:51200
	ds_read_b128 v[210:213], v207 offset:52224


; #define PG8_STAGE(bufoff, gbase, voff) do { _Pragma("unroll") for (int _i = 0; _i < 2; ++_i) \
;         __builtin_amdgcn_global_load_lds((const unsigned*)((const char*)(gbase) + (voff)[_i]), (PG8_LAS unsigned*)(lds + (bufoff) + ldsw + _i * 8192), 16, 0, 0); } while (0)
; #define PG8_LDA(dst, b, h) do { _Pragma("unroll") for (int m = 0; m < 4; ++m) _Pragma("unroll") for (int k = 0; k < 2; ++k) dst[m][k] = *(const PG8_LAS bf16x8*)(lds + PG8_SA(b, h) + aoff + m * 2048 + k * 1024); } while (0)
; template <class Epi, class Sched, bool ALIGN_EPI = false, bool SP2 = false>
; __device__ __forceinline__ void gemm_phase(PG8_LAS unsigned char* lds, const Gemm g, const Sched& S, const Epi& E) {
;     ...
;             PG8_LDA(At, 1, 1); PG8_STAGE(PG8_SB(1, 0), b3, voffB); PG8_STAGE(PG8_SB(1, 1), b3 + hstep, voffB); PG8_STAGE(PG8_SA(1, 0), a3, voffA);
	global_load_lds_dwordx4 v250, s[96:97]
	s_add_i32 m0, s60, 0x2000
	s_add_u32 s12, s12, 0x80080

; #define PG8_STAGE(bufoff, gbase, voff) do { _Pragma("unroll") for (int _i = 0; _i < 2; ++_i) \
;         __builtin_amdgcn_global_load_lds((const unsigned*)((const char*)(gbase) + (voff)[_i]), (PG8_LAS unsigned*)(lds + (bufoff) + ldsw + _i * 8192), 16, 0, 0); } while (0)
; #define PG8_LDA(dst, b, h) do { _Pragma("unroll") for (int m = 0; m < 4; ++m) _Pragma("unroll") for (int k = 0; k < 2; ++k) dst[m][k] = *(const PG8_LAS bf16x8*)(lds + PG8_SA(b, h) + aoff + m * 2048 + k * 1024); } while (0)
; template <class Epi, class Sched, bool ALIGN_EPI = false, bool SP2 = false>
; __device__ __forceinline__ void gemm_phase(PG8_LAS unsigned char* lds, const Gemm g, const Sched& S, const Epi& E) {
;     ...
;             PG8_LDA(At, 1, 1); PG8_STAGE(PG8_SB(1, 0), b3, voffB); PG8_STAGE(PG8_SB(1, 1), b3 + hstep, voffB); PG8_STAGE(PG8_SA(1, 0), a3, voffA);
	s_addc_u32 s13, s13, 0
	s_add_i32 s60, s87, s64
	global_load_lds_dwordx4 v251, s[96:97]

; #define PG8_STAGE(bufoff, gbase, voff) do { _Pragma("unroll") for (int _i = 0; _i < 2; ++_i) \
;         __builtin_amdgcn_global_load_lds((const unsigned*)((const char*)(gbase) + (voff)[_i]), (PG8_LAS unsigned*)(lds + (bufoff) + ldsw + _i * 8192), 16, 0, 0); } while (0)
; #define PG8_LDA(dst, b, h) do { _Pragma("unroll") for (int m = 0; m < 4; ++m) _Pragma("unroll") for (int k = 0; k < 2; ++k) dst[m][k] = *(const PG8_LAS bf16x8*)(lds + PG8_SA(b, h) + aoff + m * 2048 + k * 1024); } while (0)
; template <class Epi, class Sched, bool ALIGN_EPI = false, bool SP2 = false>
; __device__ __forceinline__ void gemm_phase(PG8_LAS unsigned char* lds, const Gemm g, const Sched& S, const Epi& E) {
;     ...
;             PG8_LDA(At, 1, 1); PG8_STAGE(PG8_SB(1, 0), b3, voffB); PG8_STAGE(PG8_SB(1, 1), b3 + hstep, voffB); PG8_STAGE(PG8_SA(1, 0), a3, voffA);
	s_mov_b32 m0, s60
	ds_read_b128 v[214:217], v207 offset:53248
	global_load_lds_dwordx4 v162, s[12:13]

; #define PG8_STAGE(bufoff, gbase, voff) do { _Pragma("unroll") for (int _i = 0; _i < 2; ++_i) \
;         __builtin_amdgcn_global_load_lds((const unsigned*)((const char*)(gbase) + (voff)[_i]), (PG8_LAS unsigned*)(lds + (bufoff) + ldsw + _i * 8192), 16, 0, 0); } while (0)
; #define PG8_LDA(dst, b, h) do { _Pragma("unroll") for (int m = 0; m < 4; ++m) _Pragma("unroll") for (int k = 0; k < 2; ++k) dst[m][k] = *(const PG8_LAS bf16x8*)(lds + PG8_SA(b, h) + aoff + m * 2048 + k * 1024); } while (0)
; template <class Epi, class Sched, bool ALIGN_EPI = false, bool SP2 = false>
; __device__ __forceinline__ void gemm_phase(PG8_LAS unsigned char* lds, const Gemm g, const Sched& S, const Epi& E) {
;     ...
;             PG8_LDA(At, 1, 1); PG8_STAGE(PG8_SB(1, 0), b3, voffB); PG8_STAGE(PG8_SB(1, 1), b3 + hstep, voffB); PG8_STAGE(PG8_SA(1, 0), a3, voffA);
	s_add_i32 m0, s60, 0x2000
	ds_read_b128 v[218:221], v207 offset:54272
	global_load_lds_dwordx4 v166, s[12:13]

; #define PG8_STAGE(bufoff, gbase, voff) do { _Pragma("unroll") for (int _i = 0; _i < 2; ++_i) \
;         __builtin_amdgcn_global_load_lds((const unsigned*)((const char*)(gbase) + (voff)[_i]), (PG8_LAS unsigned*)(lds + (bufoff) + ldsw + _i * 8192), 16, 0, 0); } while (0)
; #define PG8_LDA(dst, b, h) do { _Pragma("unroll") for (int m = 0; m < 4; ++m) _Pragma("unroll") for (int k = 0; k < 2; ++k) dst[m][k] = *(const PG8_LAS bf16x8*)(lds + PG8_SA(b, h) + aoff + m * 2048 + k * 1024); } while (0)
; template <class Epi, class Sched, bool ALIGN_EPI = false, bool SP2 = false>
; __device__ __forceinline__ void gemm_phase(PG8_LAS unsigned char* lds, const Gemm g, const Sched& S, const Epi& E) {
;     ...
;             PG8_LDA(At, 1, 1); PG8_STAGE(PG8_SB(1, 0), b3, voffB); PG8_STAGE(PG8_SB(1, 1), b3 + hstep, voffB); PG8_STAGE(PG8_SA(1, 0), a3, voffA);
	s_mov_b32 m0, s71
	ds_read_b128 v[222:225], v207 offset:55296
	global_load_lds_dwordx4 v252, s[98:99]

; #define PG8_STAGE(bufoff, gbase, voff) do { _Pragma("unroll") for (int _i = 0; _i < 2; ++_i) \
;         __builtin_amdgcn_global_load_lds((const unsigned*)((const char*)(gbase) + (voff)[_i]), (PG8_LAS unsigned*)(lds + (bufoff) + ldsw + _i * 8192), 16, 0, 0); } while (0)
; #define PG8_LDA(dst, b, h) do { _Pragma("unroll") for (int m = 0; m < 4; ++m) _Pragma("unroll") for (int k = 0; k < 2; ++k) dst[m][k] = *(const PG8_LAS bf16x8*)(lds + PG8_SA(b, h) + aoff + m * 2048 + k * 1024); } while (0)
; #define PG8_MMA(ai, bj, At, Bt) do { __builtin_amdgcn_s_setprio(1); _Pragma("unroll") for (int m = 0; m < 4; ++m) _Pragma("unroll") for (int n = 0; n < 2; ++n) _Pragma("unroll") for (int k = 0; k < 2; ++k) \
;         acc[ai][bj][m][n] = __builtin_amdgcn_mfma_f32_16x16x32_bf16(Bt[n][k], At[m][k], acc[ai][bj][m][n], 0, 0, 0); __builtin_amdgcn_s_setprio(0); } while (0)
; #define PG8_WAIT_V(n) asm volatile("s_waitcnt vmcnt(" #n ")" ::: "memory")
; #define PG8_WAIT_L(n) asm volatile("s_waitcnt lgkmcnt(" #n ")" ::: "memory")
; #define PG8_BAR __builtin_amdgcn_s_barrier()
; #define PG8_SCHED __builtin_amdgcn_sched_barrier(0)
; template <class Epi, class Sched, bool ALIGN_EPI = false, bool SP2 = false>
; __device__ __forceinline__ void gemm_phase(PG8_LAS unsigned char* lds, const Gemm g, const Sched& S, const Epi& E) {
;     ...
;             PG8_LDA(At, 1, 1); PG8_STAGE(PG8_SB(1, 0), b3, voffB); PG8_STAGE(PG8_SB(1, 1), b3 + hstep, voffB); PG8_STAGE(PG8_SA(1, 0), a3, voffA);
;             PG8_WAIT_V(8); PG8_WAIT_L(0); PG8_BAR; PG8_MMA(1, 0, At, B0); PG8_MMA(1, 1, At, B1); PG8_BAR; PG8_SCHED;
	s_mov_b32 m0, s72
	ds_read_b128 v[226:229], v207 offset:56320
	global_load_lds_dwordx4 v253, s[98:99]
	s_waitcnt vmcnt(8)
	s_waitcnt lgkmcnt(0)
	s_barrier
	s_setprio 1
	s_waitcnt lgkmcnt(0)
	v_mfma_f32_16x16x32_bf16 v[60:63], v[128:131], v[176:179], v[60:63]
	v_mfma_f32_16x16x32_bf16 v[56:59], v[136:139], v[176:179], v[56:59]
	v_mfma_f32_16x16x32_bf16 v[44:47], v[128:131], v[190:193], v[44:47]
	v_mfma_f32_16x16x32_bf16 v[40:43], v[136:139], v[190:193], v[40:43]
	v_mfma_f32_16x16x32_bf16 v[28:31], v[128:131], v[214:217], v[28:31]
	v_mfma_f32_16x16x32_bf16 v[24:27], v[136:139], v[214:217], v[24:27]
	v_mfma_f32_16x16x32_bf16 v[12:15], v[128:131], v[222:225], v[12:15]
	v_mfma_f32_16x16x32_bf16 v[8:11], v[136:139], v[222:225], v[8:11]
	v_mfma_f32_16x16x32_bf16 v[60:63], v[132:135], v[184:187], v[60:63]
	v_mfma_f32_16x16x32_bf16 v[56:59], v[140:143], v[184:187], v[56:59]
	v_mfma_f32_16x16x32_bf16 v[44:47], v[132:135], v[210:213], v[44:47]
	v_mfma_f32_16x16x32_bf16 v[40:43], v[140:143], v[210:213], v[40:43]
	v_mfma_f32_16x16x32_bf16 v[28:31], v[132:135], v[218:221], v[28:31]
	v_mfma_f32_16x16x32_bf16 v[24:27], v[140:143], v[218:221], v[24:27]
	v_mfma_f32_16x16x32_bf16 v[12:15], v[132:135], v[226:229], v[12:15]
	v_mfma_f32_16x16x32_bf16 v[8:11], v[140:143], v[226:229], v[8:11]


; #define PG8_STAGE(bufoff, gbase, voff) do { _Pragma("unroll") for (int _i = 0; _i < 2; ++_i) \
;         __builtin_amdgcn_global_load_lds((const unsigned*)((const char*)(gbase) + (voff)[_i]), (PG8_LAS unsigned*)(lds + (bufoff) + ldsw + _i * 8192), 16, 0, 0); } while (0)
; #define PG8_LDA(dst, b, h) do { _Pragma("unroll") for (int m = 0; m < 4; ++m) _Pragma("unroll") for (int k = 0; k < 2; ++k) dst[m][k] = *(const PG8_LAS bf16x8*)(lds + PG8_SA(b, h) + aoff + m * 2048 + k * 1024); } while (0)
; #define PG8_LDB(dst, b, h) do { _Pragma("unroll") for (int n = 0; n < 2; ++n) _Pragma("unroll") for (int k = 0; k < 2; ++k) dst[n][k] = *(const PG8_LAS bf16x8*)(lds + PG8_SB(b, h) + boff + n * 2048 + k * 1024); } while (0)
; template <class Epi, class Sched, bool ALIGN_EPI = false, bool SP2 = false>
; __device__ __forceinline__ void gemm_phase(PG8_LAS unsigned char* lds, const Gemm g, const Sched& S, const Epi& E) {
;     ...
;             PG8_WAIT_V(8); PG8_WAIT_L(0); PG8_BAR; PG8_MMA(1, 0, At, B0); PG8_MMA(1, 1, At, B1); PG8_BAR; PG8_SCHED;
;             } else {
;             PG8_LDB(B0, 0, 0); PG8_SCHED; PG8_LDA(At, 0, 0); PG8_STAGE(PG8_SA(1, 1), a1 + hstep, voffA);
;             PG8_WAIT_L(8); PG8_BAR; PG8_WAIT_L(0); PG8_MMA(0, 0, At, B0); PG8_BAR; PG8_SCHED;
;             PG8_LDB(B1, 0, 1); PG8_STAGE(PG8_SB(0, 0), b2, voffB);
;             PG8_BAR; PG8_WAIT_L(0); PG8_MMA(0, 1, At, B1); PG8_BAR;
;             PG8_LDA(At, 0, 1); PG8_STAGE(PG8_SA(0, 0), a2, voffA);
;             PG8_BAR; PG8_WAIT_L(0); PG8_MMA(1, 0, At, B0); PG8_BAR; PG8_SCHED;
;             PG8_STAGE(PG8_SB(0, 1), b2 + hstep, voffB);
;             PG8_WAIT_V(6); PG8_BAR; PG8_MMA(1, 1, At, B1); PG8_BAR;
;             PG8_LDB(B0, 1, 0); PG8_SCHED; PG8_LDA(At, 1, 0); PG8_STAGE(PG8_SA(0, 1), a2 + hstep, voffA);
;             PG8_WAIT_L(8); PG8_BAR; PG8_WAIT_L(0); PG8_MMA(0, 0, At, B0); PG8_BAR; PG8_SCHED;
;             PG8_LDB(B1, 1, 1); PG8_STAGE(PG8_SB(1, 0), b3, voffB);
;             PG8_BAR; PG8_WAIT_L(0); PG8_MMA(0, 1, At, B1); PG8_BAR;
;             PG8_LDA(At, 1, 1); PG8_STAGE(PG8_SA(1, 0), a3, voffA);
;             PG8_BAR; PG8_WAIT_L(0); PG8_MMA(1, 0, At, B0); PG8_BAR; PG8_SCHED;
;             PG8_STAGE(PG8_SB(1, 1), b3 + hstep, voffB);
;             PG8_WAIT_V(6); PG8_BAR; PG8_MMA(1, 1, At, B1); PG8_BAR;
;             }
;         }
;         if constexpr (ALIGN_EPI) { if (wr == 0) PG8_BAR; }
	v_mfma_f32_16x16x32_bf16 v[52:55], v[144:147], v[176:179], v[52:55]
	v_mfma_f32_16x16x32_bf16 v[48:51], v[152:155], v[176:179], v[48:51]
	v_mfma_f32_16x16x32_bf16 v[36:39], v[144:147], v[190:193], v[36:39]
	v_mfma_f32_16x16x32_bf16 v[32:35], v[152:155], v[190:193], v[32:35]
	v_mfma_f32_16x16x32_bf16 v[20:23], v[144:147], v[214:217], v[20:23]
	v_mfma_f32_16x16x32_bf16 v[16:19], v[152:155], v[214:217], v[16:19]
	v_mfma_f32_16x16x32_bf16 v[4:7], v[144:147], v[222:225], v[4:7]
	v_mfma_f32_16x16x32_bf16 v[0:3], v[152:155], v[222:225], v[0:3]
	v_mfma_f32_16x16x32_bf16 v[52:55], v[148:151], v[184:187], v[52:55]
	v_mfma_f32_16x16x32_bf16 v[48:51], v[156:159], v[184:187], v[48:51]
	v_mfma_f32_16x16x32_bf16 v[36:39], v[148:151], v[210:213], v[36:39]
	v_mfma_f32_16x16x32_bf16 v[32:35], v[156:159], v[210:213], v[32:35]
	v_mfma_f32_16x16x32_bf16 v[20:23], v[148:151], v[218:221], v[20:23]
	v_mfma_f32_16x16x32_bf16 v[16:19], v[156:159], v[218:221], v[16:19]
	v_mfma_f32_16x16x32_bf16 v[4:7], v[148:151], v[226:229], v[4:7]
	v_mfma_f32_16x16x32_bf16 v[0:3], v[156:159], v[226:229], v[0:3]
	s_setprio 0
	s_barrier
	s_add_i32 s85, s85, 2
	s_add_u32 s10, s10, 0x100
	s_addc_u32 s11, s11, 0
	s_add_u32 s83, s83, 0x100
	s_addc_u32 s84, s84, 0
	s_cmp_gt_u32 s85, 29
	s_cbranch_scc0 .LBB0_428
	s_and_b64 vcc, exec, s[42:43]
	s_cbranch_vccz .LBB0_431
	s_barrier

; #define PG8_STAGE(bufoff, gbase, voff) do { _Pragma("unroll") for (int _i = 0; _i < 2; ++_i) \
;         __builtin_amdgcn_global_load_lds((const unsigned*)((const char*)(gbase) + (voff)[_i]), (PG8_LAS unsigned*)(lds + (bufoff) + ldsw + _i * 8192), 16, 0, 0); } while (0)
; #define PG8_LDA(dst, b, h) do { _Pragma("unroll") for (int m = 0; m < 4; ++m) _Pragma("unroll") for (int k = 0; k < 2; ++k) dst[m][k] = *(const PG8_LAS bf16x8*)(lds + PG8_SA(b, h) + aoff + m * 2048 + k * 1024); } while (0)
; #define PG8_LDB(dst, b, h) do { _Pragma("unroll") for (int n = 0; n < 2; ++n) _Pragma("unroll") for (int k = 0; k < 2; ++k) dst[n][k] = *(const PG8_LAS bf16x8*)(lds + PG8_SB(b, h) + boff + n * 2048 + k * 1024); } while (0)
; #define PG8_SCHED __builtin_amdgcn_sched_barrier(0)
; template <class Epi, class Sched, bool ALIGN_EPI = false, bool SP2 = false>
; __device__ __forceinline__ void gemm_phase(PG8_LAS unsigned char* lds, const Gemm g, const Sched& S, const Epi& E) {
;     ...
;         for (int t = 0; t < nt; t += 2) {
;             const bool last = (t == nt - 2);
;             const char* a1 = cA + (size_t)(t + 1) * kstep;
;             const char* a2 = last ? nA : cA + (size_t)(t + 2) * kstep; const char* b2 = last ? nB : cB + (size_t)(t + 2) * kstep;
;             const char* a3 = a2 + kstep; const char* b3 = b2 + kstep;
;             if (last && has_next) S.a_ready(nxt);
;             if constexpr (SP2) {
;             PG8_LDB(B0, 0, 0); PG8_LDB(B1, 0, 1); PG8_SCHED; PG8_LDA(At, 0, 0); PG8_STAGE(PG8_SA(1, 1), a1 + hstep, voffA);
.LBB0_509:
	ds_read_b128 v[64:67], v213
	ds_read_b128 v[68:71], v213 offset:1024
	ds_read_b128 v[72:75], v213 offset:2048
	ds_read_b128 v[76:79], v213 offset:3072
	ds_read_b128 v[144:147], v214
	ds_read_b128 v[148:151], v214 offset:1024
	ds_read_b128 v[152:155], v214 offset:2048
	ds_read_b128 v[156:159], v214 offset:3072
	s_add_u32 s60, s58, 0xffe00080
	s_addc_u32 s61, s59, -1
	s_cmpk_eq_i32 s81, 0x7c
	s_cselect_b32 s63, s11, s61
	s_cselect_b32 s62, s51, s60
	s_cselect_b32 s61, s49, s80
	s_cselect_b32 s60, s78, s79

; #define PG8_STAGE(bufoff, gbase, voff) do { _Pragma("unroll") for (int _i = 0; _i < 2; ++_i) \
;         __builtin_amdgcn_global_load_lds((const unsigned*)((const char*)(gbase) + (voff)[_i]), (PG8_LAS unsigned*)(lds + (bufoff) + ldsw + _i * 8192), 16, 0, 0); } while (0)
; #define PG8_LDA(dst, b, h) do { _Pragma("unroll") for (int m = 0; m < 4; ++m) _Pragma("unroll") for (int k = 0; k < 2; ++k) dst[m][k] = *(const PG8_LAS bf16x8*)(lds + PG8_SA(b, h) + aoff + m * 2048 + k * 1024); } while (0)
; #define PG8_LDB(dst, b, h) do { _Pragma("unroll") for (int n = 0; n < 2; ++n) _Pragma("unroll") for (int k = 0; k < 2; ++k) dst[n][k] = *(const PG8_LAS bf16x8*)(lds + PG8_SB(b, h) + boff + n * 2048 + k * 1024); } while (0)
; #define PG8_SCHED __builtin_amdgcn_sched_barrier(0)
; template <class Epi, class Sched, bool ALIGN_EPI = false, bool SP2 = false>
; __device__ __forceinline__ void gemm_phase(PG8_LAS unsigned char* lds, const Gemm g, const Sched& S, const Epi& E) {
;     ...
;             PG8_LDB(B0, 0, 0); PG8_LDB(B1, 0, 1); PG8_SCHED; PG8_LDA(At, 0, 0); PG8_STAGE(PG8_SA(1, 1), a1 + hstep, voffA);
	s_add_i32 m0, s57, 0xc000
	ds_read_b128 v[176:179], v215
	ds_read_b128 v[180:183], v215 offset:1024
	ds_read_b128 v[184:187], v215 offset:2048
	ds_read_b128 v[188:191], v215 offset:3072
	ds_read_b128 v[192:195], v215 offset:4096
	ds_read_b128 v[196:199], v215 offset:5120
	ds_read_b128 v[200:203], v215 offset:6144

; #define PG8_STAGE(bufoff, gbase, voff) do { _Pragma("unroll") for (int _i = 0; _i < 2; ++_i) \
;         __builtin_amdgcn_global_load_lds((const unsigned*)((const char*)(gbase) + (voff)[_i]), (PG8_LAS unsigned*)(lds + (bufoff) + ldsw + _i * 8192), 16, 0, 0); } while (0)
; #define PG8_LDA(dst, b, h) do { _Pragma("unroll") for (int m = 0; m < 4; ++m) _Pragma("unroll") for (int k = 0; k < 2; ++k) dst[m][k] = *(const PG8_LAS bf16x8*)(lds + PG8_SA(b, h) + aoff + m * 2048 + k * 1024); } while (0)
; #define PG8_LDB(dst, b, h) do { _Pragma("unroll") for (int n = 0; n < 2; ++n) _Pragma("unroll") for (int k = 0; k < 2; ++k) dst[n][k] = *(const PG8_LAS bf16x8*)(lds + PG8_SB(b, h) + boff + n * 2048 + k * 1024); } while (0)
; #define PG8_SCHED __builtin_amdgcn_sched_barrier(0)
; template <class Epi, class Sched, bool ALIGN_EPI = false, bool SP2 = false>
; __device__ __forceinline__ void gemm_phase(PG8_LAS unsigned char* lds, const Gemm g, const Sched& S, const Epi& E) {
;     ...
;             PG8_LDB(B0, 0, 0); PG8_LDB(B1, 0, 1); PG8_SCHED; PG8_LDA(At, 0, 0); PG8_STAGE(PG8_SA(1, 1), a1 + hstep, voffA);
	global_load_lds_dwordx4 v168, s[58:59]

; #define PG8_STAGE(bufoff, gbase, voff) do { _Pragma("unroll") for (int _i = 0; _i < 2; ++_i) \
;         __builtin_amdgcn_global_load_lds((const unsigned*)((const char*)(gbase) + (voff)[_i]), (PG8_LAS unsigned*)(lds + (bufoff) + ldsw + _i * 8192), 16, 0, 0); } while (0)
; #define PG8_LDA(dst, b, h) do { _Pragma("unroll") for (int m = 0; m < 4; ++m) _Pragma("unroll") for (int k = 0; k < 2; ++k) dst[m][k] = *(const PG8_LAS bf16x8*)(lds + PG8_SA(b, h) + aoff + m * 2048 + k * 1024); } while (0)
; #define PG8_LDB(dst, b, h) do { _Pragma("unroll") for (int n = 0; n < 2; ++n) _Pragma("unroll") for (int k = 0; k < 2; ++k) dst[n][k] = *(const PG8_LAS bf16x8*)(lds + PG8_SB(b, h) + boff + n * 2048 + k * 1024); } while (0)
; #define PG8_MMA(ai, bj, At, Bt) do { __builtin_amdgcn_s_setprio(1); _Pragma("unroll") for (int m = 0; m < 4; ++m) _Pragma("unroll") for (int n = 0; n < 2; ++n) _Pragma("unroll") for (int k = 0; k < 2; ++k) \
;         acc[ai][bj][m][n] = __builtin_amdgcn_mfma_f32_16x16x32_bf16(Bt[n][k], At[m][k], acc[ai][bj][m][n], 0, 0, 0); __builtin_amdgcn_s_setprio(0); } while (0)
; #define PG8_WAIT_V(n) asm volatile("s_waitcnt vmcnt(" #n ")" ::: "memory")
; #define PG8_WAIT_L(n) asm volatile("s_waitcnt lgkmcnt(" #n ")" ::: "memory")
; #define PG8_BAR __builtin_amdgcn_s_barrier()
; #define PG8_SCHED __builtin_amdgcn_sched_barrier(0)
; template <class Epi, class Sched, bool ALIGN_EPI = false, bool SP2 = false>
; __device__ __forceinline__ void gemm_phase(PG8_LAS unsigned char* lds, const Gemm g, const Sched& S, const Epi& E) {
;     ...
;             PG8_LDB(B0, 0, 0); PG8_LDB(B1, 0, 1); PG8_SCHED; PG8_LDA(At, 0, 0); PG8_STAGE(PG8_SA(1, 1), a1 + hstep, voffA);
;             PG8_WAIT_V(8); PG8_WAIT_L(0); PG8_BAR; PG8_MMA(0, 0, At, B0); PG8_MMA(0, 1, At, B1); PG8_BAR; PG8_SCHED;
	s_add_i32 m0, s57, 0xe000
	ds_read_b128 v[204:207], v215 offset:7168
	global_load_lds_dwordx4 v170, s[58:59]
	s_waitcnt vmcnt(8)
	s_waitcnt lgkmcnt(0)
	s_barrier
	s_setprio 1
	s_waitcnt lgkmcnt(0)
	v_mfma_f32_16x16x32_bf16 v[140:143], v[64:67], v[176:179], v[140:143]
	v_mfma_f32_16x16x32_bf16 v[136:139], v[72:75], v[176:179], v[136:139]
	v_mfma_f32_16x16x32_bf16 v[124:127], v[64:67], v[184:187], v[124:127]
	v_mfma_f32_16x16x32_bf16 v[120:123], v[72:75], v[184:187], v[120:123]
	v_mfma_f32_16x16x32_bf16 v[108:111], v[64:67], v[192:195], v[108:111]
	v_mfma_f32_16x16x32_bf16 v[104:107], v[72:75], v[192:195], v[104:107]
	v_mfma_f32_16x16x32_bf16 v[92:95], v[64:67], v[200:203], v[92:95]
	v_mfma_f32_16x16x32_bf16 v[88:91], v[72:75], v[200:203], v[88:91]
	v_mfma_f32_16x16x32_bf16 v[140:143], v[68:71], v[180:183], v[140:143]
	v_mfma_f32_16x16x32_bf16 v[136:139], v[76:79], v[180:183], v[136:139]
	v_mfma_f32_16x16x32_bf16 v[124:127], v[68:71], v[188:191], v[124:127]
	v_mfma_f32_16x16x32_bf16 v[120:123], v[76:79], v[188:191], v[120:123]
	v_mfma_f32_16x16x32_bf16 v[108:111], v[68:71], v[196:199], v[108:111]
	v_mfma_f32_16x16x32_bf16 v[104:107], v[76:79], v[196:199], v[104:107]
	v_mfma_f32_16x16x32_bf16 v[92:95], v[68:71], v[204:207], v[92:95]
	v_mfma_f32_16x16x32_bf16 v[88:91], v[76:79], v[204:207], v[88:91]


; #define PG8_MMA(ai, bj, At, Bt) do { __builtin_amdgcn_s_setprio(1); _Pragma("unroll") for (int m = 0; m < 4; ++m) _Pragma("unroll") for (int n = 0; n < 2; ++n) _Pragma("unroll") for (int k = 0; k < 2; ++k) \
;         acc[ai][bj][m][n] = __builtin_amdgcn_mfma_f32_16x16x32_bf16(Bt[n][k], At[m][k], acc[ai][bj][m][n], 0, 0, 0); __builtin_amdgcn_s_setprio(0); } while (0)
; #define PG8_WAIT_V(n) asm volatile("s_waitcnt vmcnt(" #n ")" ::: "memory")
; #define PG8_WAIT_L(n) asm volatile("s_waitcnt lgkmcnt(" #n ")" ::: "memory")
; #define PG8_BAR __builtin_amdgcn_s_barrier()
; #define PG8_SCHED __builtin_amdgcn_sched_barrier(0)
; template <class Epi, class Sched, bool ALIGN_EPI = false, bool SP2 = false>
; __device__ __forceinline__ void gemm_phase(PG8_LAS unsigned char* lds, const Gemm g, const Sched& S, const Epi& E) {
;     ...
;             PG8_WAIT_V(8); PG8_WAIT_L(0); PG8_BAR; PG8_MMA(0, 0, At, B0); PG8_MMA(0, 1, At, B1); PG8_BAR; PG8_SCHED;
	v_mfma_f32_16x16x32_bf16 v[132:135], v[144:147], v[176:179], v[132:135]
	v_mfma_f32_16x16x32_bf16 v[128:131], v[152:155], v[176:179], v[128:131]
	v_mfma_f32_16x16x32_bf16 v[116:119], v[144:147], v[184:187], v[116:119]
	v_mfma_f32_16x16x32_bf16 v[112:115], v[152:155], v[184:187], v[112:115]
	v_mfma_f32_16x16x32_bf16 v[100:103], v[144:147], v[192:195], v[100:103]
	v_mfma_f32_16x16x32_bf16 v[96:99], v[152:155], v[192:195], v[96:99]
	v_mfma_f32_16x16x32_bf16 v[84:87], v[144:147], v[200:203], v[84:87]
	v_mfma_f32_16x16x32_bf16 v[80:83], v[152:155], v[200:203], v[80:83]
	v_mfma_f32_16x16x32_bf16 v[132:135], v[148:151], v[180:183], v[132:135]
	v_mfma_f32_16x16x32_bf16 v[128:131], v[156:159], v[180:183], v[128:131]
	v_mfma_f32_16x16x32_bf16 v[116:119], v[148:151], v[188:191], v[116:119]
	v_mfma_f32_16x16x32_bf16 v[112:115], v[156:159], v[188:191], v[112:115]
	v_mfma_f32_16x16x32_bf16 v[100:103], v[148:151], v[196:199], v[100:103]
	v_mfma_f32_16x16x32_bf16 v[96:99], v[156:159], v[196:199], v[96:99]
	v_mfma_f32_16x16x32_bf16 v[84:87], v[148:151], v[204:207], v[84:87]
	v_mfma_f32_16x16x32_bf16 v[80:83], v[156:159], v[204:207], v[80:83]
	s_setprio 0
	s_barrier
	s_add_i32 s82, s75, s64
	s_mov_b64 s[96:97], s[60:61]

; #define PG8_STAGE(bufoff, gbase, voff) do { _Pragma("unroll") for (int _i = 0; _i < 2; ++_i) \
;         __builtin_amdgcn_global_load_lds((const unsigned*)((const char*)(gbase) + (voff)[_i]), (PG8_LAS unsigned*)(lds + (bufoff) + ldsw + _i * 8192), 16, 0, 0); } while (0)
; #define PG8_LDA(dst, b, h) do { _Pragma("unroll") for (int m = 0; m < 4; ++m) _Pragma("unroll") for (int k = 0; k < 2; ++k) dst[m][k] = *(const PG8_LAS bf16x8*)(lds + PG8_SA(b, h) + aoff + m * 2048 + k * 1024); } while (0)
; template <class Epi, class Sched, bool ALIGN_EPI = false, bool SP2 = false>
; __device__ __forceinline__ void gemm_phase(PG8_LAS unsigned char* lds, const Gemm g, const Sched& S, const Epi& E) {
;     ...
;             PG8_LDA(At, 0, 1); PG8_STAGE(PG8_SB(0, 0), b2, voffB); PG8_STAGE(PG8_SB(0, 1), b2 + hstep, voffB); PG8_STAGE(PG8_SA(0, 0), a2, voffA);
	s_mov_b32 m0, s82
	ds_read_b128 v[176:179], v215 offset:16384
	ds_read_b128 v[180:183], v215 offset:17408
	ds_read_b128 v[184:187], v215 offset:18432
	ds_read_b128 v[188:191], v215 offset:19456


; #define PG8_STAGE(bufoff, gbase, voff) do { _Pragma("unroll") for (int _i = 0; _i < 2; ++_i) \
;         __builtin_amdgcn_global_load_lds((const unsigned*)((const char*)(gbase) + (voff)[_i]), (PG8_LAS unsigned*)(lds + (bufoff) + ldsw + _i * 8192), 16, 0, 0); } while (0)
; #define PG8_LDA(dst, b, h) do { _Pragma("unroll") for (int m = 0; m < 4; ++m) _Pragma("unroll") for (int k = 0; k < 2; ++k) dst[m][k] = *(const PG8_LAS bf16x8*)(lds + PG8_SA(b, h) + aoff + m * 2048 + k * 1024); } while (0)
; template <class Epi, class Sched, bool ALIGN_EPI = false, bool SP2 = false>
; __device__ __forceinline__ void gemm_phase(PG8_LAS unsigned char* lds, const Gemm g, const Sched& S, const Epi& E) {
;     ...
;             PG8_LDA(At, 0, 1); PG8_STAGE(PG8_SB(0, 0), b2, voffB); PG8_STAGE(PG8_SB(0, 1), b2 + hstep, voffB); PG8_STAGE(PG8_SA(0, 0), a2, voffA);
	global_load_lds_dwordx4 v162, s[60:61]
	s_add_i32 m0, s82, 0x2000
	s_add_u32 s82, s60, 0x200000

; #define PG8_STAGE(bufoff, gbase, voff) do { _Pragma("unroll") for (int _i = 0; _i < 2; ++_i) \
;         __builtin_amdgcn_global_load_lds((const unsigned*)((const char*)(gbase) + (voff)[_i]), (PG8_LAS unsigned*)(lds + (bufoff) + ldsw + _i * 8192), 16, 0, 0); } while (0)
; #define PG8_LDA(dst, b, h) do { _Pragma("unroll") for (int m = 0; m < 4; ++m) _Pragma("unroll") for (int k = 0; k < 2; ++k) dst[m][k] = *(const PG8_LAS bf16x8*)(lds + PG8_SA(b, h) + aoff + m * 2048 + k * 1024); } while (0)
; template <class Epi, class Sched, bool ALIGN_EPI = false, bool SP2 = false>
; __device__ __forceinline__ void gemm_phase(PG8_LAS unsigned char* lds, const Gemm g, const Sched& S, const Epi& E) {
;     ...
;             PG8_LDA(At, 0, 1); PG8_STAGE(PG8_SB(0, 0), b2, voffB); PG8_STAGE(PG8_SB(0, 1), b2 + hstep, voffB); PG8_STAGE(PG8_SA(0, 0), a2, voffA);
	s_addc_u32 s83, s61, 0
	s_add_i32 s84, s76, s64
	global_load_lds_dwordx4 v166, s[60:61]

; #define PG8_STAGE(bufoff, gbase, voff) do { _Pragma("unroll") for (int _i = 0; _i < 2; ++_i) \
;         __builtin_amdgcn_global_load_lds((const unsigned*)((const char*)(gbase) + (voff)[_i]), (PG8_LAS unsigned*)(lds + (bufoff) + ldsw + _i * 8192), 16, 0, 0); } while (0)
; #define PG8_LDA(dst, b, h) do { _Pragma("unroll") for (int m = 0; m < 4; ++m) _Pragma("unroll") for (int k = 0; k < 2; ++k) dst[m][k] = *(const PG8_LAS bf16x8*)(lds + PG8_SA(b, h) + aoff + m * 2048 + k * 1024); } while (0)
; template <class Epi, class Sched, bool ALIGN_EPI = false, bool SP2 = false>
; __device__ __forceinline__ void gemm_phase(PG8_LAS unsigned char* lds, const Gemm g, const Sched& S, const Epi& E) {
;     ...
;             PG8_LDA(At, 0, 1); PG8_STAGE(PG8_SB(0, 0), b2, voffB); PG8_STAGE(PG8_SB(0, 1), b2 + hstep, voffB); PG8_STAGE(PG8_SA(0, 0), a2, voffA);
	s_mov_b32 m0, s84
	ds_read_b128 v[192:195], v215 offset:20480
	global_load_lds_dwordx4 v162, s[82:83]

; #define PG8_STAGE(bufoff, gbase, voff) do { _Pragma("unroll") for (int _i = 0; _i < 2; ++_i) \
;         __builtin_amdgcn_global_load_lds((const unsigned*)((const char*)(gbase) + (voff)[_i]), (PG8_LAS unsigned*)(lds + (bufoff) + ldsw + _i * 8192), 16, 0, 0); } while (0)
; #define PG8_LDA(dst, b, h) do { _Pragma("unroll") for (int m = 0; m < 4; ++m) _Pragma("unroll") for (int k = 0; k < 2; ++k) dst[m][k] = *(const PG8_LAS bf16x8*)(lds + PG8_SA(b, h) + aoff + m * 2048 + k * 1024); } while (0)
; template <class Epi, class Sched, bool ALIGN_EPI = false, bool SP2 = false>
; __device__ __forceinline__ void gemm_phase(PG8_LAS unsigned char* lds, const Gemm g, const Sched& S, const Epi& E) {
;     ...
;             PG8_LDA(At, 0, 1); PG8_STAGE(PG8_SB(0, 0), b2, voffB); PG8_STAGE(PG8_SB(0, 1), b2 + hstep, voffB); PG8_STAGE(PG8_SA(0, 0), a2, voffA);
	s_add_i32 m0, s84, 0x2000
	ds_read_b128 v[196:199], v215 offset:21504
	global_load_lds_dwordx4 v166, s[82:83]
	s_mov_b64 s[98:99], s[62:63]

; #define PG8_STAGE(bufoff, gbase, voff) do { _Pragma("unroll") for (int _i = 0; _i < 2; ++_i) \
;         __builtin_amdgcn_global_load_lds((const unsigned*)((const char*)(gbase) + (voff)[_i]), (PG8_LAS unsigned*)(lds + (bufoff) + ldsw + _i * 8192), 16, 0, 0); } while (0)
; #define PG8_LDA(dst, b, h) do { _Pragma("unroll") for (int m = 0; m < 4; ++m) _Pragma("unroll") for (int k = 0; k < 2; ++k) dst[m][k] = *(const PG8_LAS bf16x8*)(lds + PG8_SA(b, h) + aoff + m * 2048 + k * 1024); } while (0)
; #define PG8_MMA(ai, bj, At, Bt) do { __builtin_amdgcn_s_setprio(1); _Pragma("unroll") for (int m = 0; m < 4; ++m) _Pragma("unroll") for (int n = 0; n < 2; ++n) _Pragma("unroll") for (int k = 0; k < 2; ++k) \
;         acc[ai][bj][m][n] = __builtin_amdgcn_mfma_f32_16x16x32_bf16(Bt[n][k], At[m][k], acc[ai][bj][m][n], 0, 0, 0); __builtin_amdgcn_s_setprio(0); } while (0)
; #define PG8_WAIT_V(n) asm volatile("s_waitcnt vmcnt(" #n ")" ::: "memory")
; #define PG8_WAIT_L(n) asm volatile("s_waitcnt lgkmcnt(" #n ")" ::: "memory")
; #define PG8_BAR __builtin_amdgcn_s_barrier()
; #define PG8_SCHED __builtin_amdgcn_sched_barrier(0)
; template <class Epi, class Sched, bool ALIGN_EPI = false, bool SP2 = false>
; __device__ __forceinline__ void gemm_phase(PG8_LAS unsigned char* lds, const Gemm g, const Sched& S, const Epi& E) {
;     ...
;             PG8_LDA(At, 0, 1); PG8_STAGE(PG8_SB(0, 0), b2, voffB); PG8_STAGE(PG8_SB(0, 1), b2 + hstep, voffB); PG8_STAGE(PG8_SA(0, 0), a2, voffA);
;             PG8_WAIT_V(8); PG8_WAIT_L(0); PG8_BAR; PG8_MMA(1, 0, At, B0); PG8_MMA(1, 1, At, B1); PG8_BAR; PG8_SCHED;
	s_mov_b32 m0, s57
	ds_read_b128 v[200:203], v215 offset:22528
	global_load_lds_dwordx4 v160, s[62:63]
	s_mov_b32 m0, s65
	ds_read_b128 v[204:207], v215 offset:23552
	global_load_lds_dwordx4 v164, s[62:63]
	s_waitcnt vmcnt(8)
	s_waitcnt lgkmcnt(0)
	s_barrier
	s_setprio 1
	s_waitcnt lgkmcnt(0)
	v_mfma_f32_16x16x32_bf16 v[60:63], v[64:67], v[176:179], v[60:63]
	v_mfma_f32_16x16x32_bf16 v[56:59], v[72:75], v[176:179], v[56:59]
	v_mfma_f32_16x16x32_bf16 v[44:47], v[64:67], v[184:187], v[44:47]
	v_mfma_f32_16x16x32_bf16 v[40:43], v[72:75], v[184:187], v[40:43]
	v_mfma_f32_16x16x32_bf16 v[28:31], v[64:67], v[192:195], v[28:31]
	v_mfma_f32_16x16x32_bf16 v[24:27], v[72:75], v[192:195], v[24:27]
	v_mfma_f32_16x16x32_bf16 v[12:15], v[64:67], v[200:203], v[12:15]
	v_mfma_f32_16x16x32_bf16 v[8:11], v[72:75], v[200:203], v[8:11]
	v_mfma_f32_16x16x32_bf16 v[60:63], v[68:71], v[180:183], v[60:63]
	v_mfma_f32_16x16x32_bf16 v[56:59], v[76:79], v[180:183], v[56:59]
	v_mfma_f32_16x16x32_bf16 v[44:47], v[68:71], v[188:191], v[44:47]
	v_mfma_f32_16x16x32_bf16 v[40:43], v[76:79], v[188:191], v[40:43]
	v_mfma_f32_16x16x32_bf16 v[28:31], v[68:71], v[196:199], v[28:31]
	v_mfma_f32_16x16x32_bf16 v[24:27], v[76:79], v[196:199], v[24:27]
	v_mfma_f32_16x16x32_bf16 v[12:15], v[68:71], v[204:207], v[12:15]
	v_mfma_f32_16x16x32_bf16 v[8:11], v[76:79], v[204:207], v[8:11]


; #define PG8_STAGE(bufoff, gbase, voff) do { _Pragma("unroll") for (int _i = 0; _i < 2; ++_i) \
;         __builtin_amdgcn_global_load_lds((const unsigned*)((const char*)(gbase) + (voff)[_i]), (PG8_LAS unsigned*)(lds + (bufoff) + ldsw + _i * 8192), 16, 0, 0); } while (0)
; #define PG8_LDA(dst, b, h) do { _Pragma("unroll") for (int m = 0; m < 4; ++m) _Pragma("unroll") for (int k = 0; k < 2; ++k) dst[m][k] = *(const PG8_LAS bf16x8*)(lds + PG8_SA(b, h) + aoff + m * 2048 + k * 1024); } while (0)
; #define PG8_LDB(dst, b, h) do { _Pragma("unroll") for (int n = 0; n < 2; ++n) _Pragma("unroll") for (int k = 0; k < 2; ++k) dst[n][k] = *(const PG8_LAS bf16x8*)(lds + PG8_SB(b, h) + boff + n * 2048 + k * 1024); } while (0)
; #define PG8_MMA(ai, bj, At, Bt) do { __builtin_amdgcn_s_setprio(1); _Pragma("unroll") for (int m = 0; m < 4; ++m) _Pragma("unroll") for (int n = 0; n < 2; ++n) _Pragma("unroll") for (int k = 0; k < 2; ++k) \
;         acc[ai][bj][m][n] = __builtin_amdgcn_mfma_f32_16x16x32_bf16(Bt[n][k], At[m][k], acc[ai][bj][m][n], 0, 0, 0); __builtin_amdgcn_s_setprio(0); } while (0)
; #define PG8_WAIT_V(n) asm volatile("s_waitcnt vmcnt(" #n ")" ::: "memory")
; #define PG8_WAIT_L(n) asm volatile("s_waitcnt lgkmcnt(" #n ")" ::: "memory")
; #define PG8_BAR __builtin_amdgcn_s_barrier()
; #define PG8_SCHED __builtin_amdgcn_sched_barrier(0)
; template <class Epi, class Sched, bool ALIGN_EPI = false, bool SP2 = false>
; __device__ __forceinline__ void gemm_phase(PG8_LAS unsigned char* lds, const Gemm g, const Sched& S, const Epi& E) {
;     ...
;             PG8_WAIT_V(8); PG8_WAIT_L(0); PG8_BAR; PG8_MMA(1, 0, At, B0); PG8_MMA(1, 1, At, B1); PG8_BAR; PG8_SCHED;
;             PG8_LDB(B0, 1, 0); PG8_LDB(B1, 1, 1); PG8_SCHED; PG8_LDA(At, 1, 0); PG8_STAGE(PG8_SA(0, 1), a2 + hstep, voffA);
	v_mfma_f32_16x16x32_bf16 v[52:55], v[144:147], v[176:179], v[52:55]
	v_mfma_f32_16x16x32_bf16 v[48:51], v[152:155], v[176:179], v[48:51]
	v_mfma_f32_16x16x32_bf16 v[36:39], v[144:147], v[184:187], v[36:39]
	v_mfma_f32_16x16x32_bf16 v[32:35], v[152:155], v[184:187], v[32:35]
	v_mfma_f32_16x16x32_bf16 v[20:23], v[144:147], v[192:195], v[20:23]
	v_mfma_f32_16x16x32_bf16 v[16:19], v[152:155], v[192:195], v[16:19]
	v_mfma_f32_16x16x32_bf16 v[4:7], v[144:147], v[200:203], v[4:7]
	v_mfma_f32_16x16x32_bf16 v[0:3], v[152:155], v[200:203], v[0:3]
	v_mfma_f32_16x16x32_bf16 v[52:55], v[148:151], v[180:183], v[52:55]
	v_mfma_f32_16x16x32_bf16 v[48:51], v[156:159], v[180:183], v[48:51]
	v_mfma_f32_16x16x32_bf16 v[36:39], v[148:151], v[188:191], v[36:39]
	v_mfma_f32_16x16x32_bf16 v[32:35], v[156:159], v[188:191], v[32:35]
	v_mfma_f32_16x16x32_bf16 v[20:23], v[148:151], v[196:199], v[20:23]
	v_mfma_f32_16x16x32_bf16 v[16:19], v[156:159], v[196:199], v[16:19]
	v_mfma_f32_16x16x32_bf16 v[4:7], v[148:151], v[204:207], v[4:7]
	v_mfma_f32_16x16x32_bf16 v[0:3], v[156:159], v[204:207], v[0:3]
	s_setprio 0
	s_barrier
	s_add_i32 s82, 0, 0x18000
	s_add_i32 s83, 0, 0x1c000
	v_add_u32_e32 v76, s82, v211
	v_add_u32_e32 v156, s83, v211
	ds_read_b128 v[64:67], v76
	ds_read_b128 v[68:71], v76 offset:1024
	ds_read_b128 v[72:75], v76 offset:2048
	ds_read_b128 v[76:79], v76 offset:3072
	ds_read_b128 v[144:147], v156
	ds_read_b128 v[148:151], v156 offset:1024
	ds_read_b128 v[152:155], v156 offset:2048
	ds_read_b128 v[156:159], v156 offset:3072
	s_add_u32 s62, s62, 0x200000
	s_addc_u32 s63, s63, 0
	s_mov_b32 m0, s67

; #define PG8_STAGE(bufoff, gbase, voff) do { _Pragma("unroll") for (int _i = 0; _i < 2; ++_i) \
;         __builtin_amdgcn_global_load_lds((const unsigned*)((const char*)(gbase) + (voff)[_i]), (PG8_LAS unsigned*)(lds + (bufoff) + ldsw + _i * 8192), 16, 0, 0); } while (0)
; #define PG8_LDA(dst, b, h) do { _Pragma("unroll") for (int m = 0; m < 4; ++m) _Pragma("unroll") for (int k = 0; k < 2; ++k) dst[m][k] = *(const PG8_LAS bf16x8*)(lds + PG8_SA(b, h) + aoff + m * 2048 + k * 1024); } while (0)
; #define PG8_LDB(dst, b, h) do { _Pragma("unroll") for (int n = 0; n < 2; ++n) _Pragma("unroll") for (int k = 0; k < 2; ++k) dst[n][k] = *(const PG8_LAS bf16x8*)(lds + PG8_SB(b, h) + boff + n * 2048 + k * 1024); } while (0)
; #define PG8_SCHED __builtin_amdgcn_sched_barrier(0)
; template <class Epi, class Sched, bool ALIGN_EPI = false, bool SP2 = false>
; __device__ __forceinline__ void gemm_phase(PG8_LAS unsigned char* lds, const Gemm g, const Sched& S, const Epi& E) {
;     ...
;             PG8_LDB(B0, 1, 0); PG8_LDB(B1, 1, 1); PG8_SCHED; PG8_LDA(At, 1, 0); PG8_STAGE(PG8_SA(0, 1), a2 + hstep, voffA);
	ds_read_b128 v[176:179], v215 offset:32768
	ds_read_b128 v[180:183], v215 offset:33792
	ds_read_b128 v[184:187], v215 offset:34816
	ds_read_b128 v[188:191], v215 offset:35840
	ds_read_b128 v[192:195], v215 offset:36864
	ds_read_b128 v[196:199], v215 offset:37888
	ds_read_b128 v[200:203], v215 offset:38912

; #define PG8_STAGE(bufoff, gbase, voff) do { _Pragma("unroll") for (int _i = 0; _i < 2; ++_i) \
;         __builtin_amdgcn_global_load_lds((const unsigned*)((const char*)(gbase) + (voff)[_i]), (PG8_LAS unsigned*)(lds + (bufoff) + ldsw + _i * 8192), 16, 0, 0); } while (0)
; #define PG8_LDA(dst, b, h) do { _Pragma("unroll") for (int m = 0; m < 4; ++m) _Pragma("unroll") for (int k = 0; k < 2; ++k) dst[m][k] = *(const PG8_LAS bf16x8*)(lds + PG8_SA(b, h) + aoff + m * 2048 + k * 1024); } while (0)
; #define PG8_LDB(dst, b, h) do { _Pragma("unroll") for (int n = 0; n < 2; ++n) _Pragma("unroll") for (int k = 0; k < 2; ++k) dst[n][k] = *(const PG8_LAS bf16x8*)(lds + PG8_SB(b, h) + boff + n * 2048 + k * 1024); } while (0)
; #define PG8_SCHED __builtin_amdgcn_sched_barrier(0)
; template <class Epi, class Sched, bool ALIGN_EPI = false, bool SP2 = false>
; __device__ __forceinline__ void gemm_phase(PG8_LAS unsigned char* lds, const Gemm g, const Sched& S, const Epi& E) {
;     ...
;             PG8_LDB(B0, 1, 0); PG8_LDB(B1, 1, 1); PG8_SCHED; PG8_LDA(At, 1, 0); PG8_STAGE(PG8_SA(0, 1), a2 + hstep, voffA);
	global_load_lds_dwordx4 v160, s[62:63]

; #define PG8_STAGE(bufoff, gbase, voff) do { _Pragma("unroll") for (int _i = 0; _i < 2; ++_i) \
;         __builtin_amdgcn_global_load_lds((const unsigned*)((const char*)(gbase) + (voff)[_i]), (PG8_LAS unsigned*)(lds + (bufoff) + ldsw + _i * 8192), 16, 0, 0); } while (0)
; #define PG8_LDA(dst, b, h) do { _Pragma("unroll") for (int m = 0; m < 4; ++m) _Pragma("unroll") for (int k = 0; k < 2; ++k) dst[m][k] = *(const PG8_LAS bf16x8*)(lds + PG8_SA(b, h) + aoff + m * 2048 + k * 1024); } while (0)
; #define PG8_LDB(dst, b, h) do { _Pragma("unroll") for (int n = 0; n < 2; ++n) _Pragma("unroll") for (int k = 0; k < 2; ++k) dst[n][k] = *(const PG8_LAS bf16x8*)(lds + PG8_SB(b, h) + boff + n * 2048 + k * 1024); } while (0)
; #define PG8_MMA(ai, bj, At, Bt) do { __builtin_amdgcn_s_setprio(1); _Pragma("unroll") for (int m = 0; m < 4; ++m) _Pragma("unroll") for (int n = 0; n < 2; ++n) _Pragma("unroll") for (int k = 0; k < 2; ++k) \
;         acc[ai][bj][m][n] = __builtin_amdgcn_mfma_f32_16x16x32_bf16(Bt[n][k], At[m][k], acc[ai][bj][m][n], 0, 0, 0); __builtin_amdgcn_s_setprio(0); } while (0)
; #define PG8_WAIT_V(n) asm volatile("s_waitcnt vmcnt(" #n ")" ::: "memory")
; #define PG8_WAIT_L(n) asm volatile("s_waitcnt lgkmcnt(" #n ")" ::: "memory")
; #define PG8_BAR __builtin_amdgcn_s_barrier()
; #define PG8_SCHED __builtin_amdgcn_sched_barrier(0)
; template <class Epi, class Sched, bool ALIGN_EPI = false, bool SP2 = false>
; __device__ __forceinline__ void gemm_phase(PG8_LAS unsigned char* lds, const Gemm g, const Sched& S, const Epi& E) {
;     ...
;             PG8_LDB(B0, 1, 0); PG8_LDB(B1, 1, 1); PG8_SCHED; PG8_LDA(At, 1, 0); PG8_STAGE(PG8_SA(0, 1), a2 + hstep, voffA);
;             PG8_WAIT_V(8); PG8_WAIT_L(0); PG8_BAR; PG8_MMA(0, 0, At, B0); PG8_MMA(0, 1, At, B1); PG8_BAR; PG8_SCHED;
	s_mov_b32 m0, s68
	ds_read_b128 v[204:207], v215 offset:39936
	global_load_lds_dwordx4 v164, s[62:63]
	s_waitcnt vmcnt(8)
	s_waitcnt lgkmcnt(0)
	s_barrier
	s_setprio 1
	s_waitcnt lgkmcnt(0)
	v_mfma_f32_16x16x32_bf16 v[140:143], v[64:67], v[176:179], v[140:143]
	v_mfma_f32_16x16x32_bf16 v[136:139], v[72:75], v[176:179], v[136:139]
	v_mfma_f32_16x16x32_bf16 v[124:127], v[64:67], v[184:187], v[124:127]
	v_mfma_f32_16x16x32_bf16 v[120:123], v[72:75], v[184:187], v[120:123]
	v_mfma_f32_16x16x32_bf16 v[108:111], v[64:67], v[192:195], v[108:111]
	v_mfma_f32_16x16x32_bf16 v[104:107], v[72:75], v[192:195], v[104:107]
	v_mfma_f32_16x16x32_bf16 v[92:95], v[64:67], v[200:203], v[92:95]
	v_mfma_f32_16x16x32_bf16 v[88:91], v[72:75], v[200:203], v[88:91]
	v_mfma_f32_16x16x32_bf16 v[140:143], v[68:71], v[180:183], v[140:143]
	v_mfma_f32_16x16x32_bf16 v[136:139], v[76:79], v[180:183], v[136:139]
	v_mfma_f32_16x16x32_bf16 v[124:127], v[68:71], v[188:191], v[124:127]
	v_mfma_f32_16x16x32_bf16 v[120:123], v[76:79], v[188:191], v[120:123]
	v_mfma_f32_16x16x32_bf16 v[108:111], v[68:71], v[196:199], v[108:111]
	v_mfma_f32_16x16x32_bf16 v[104:107], v[76:79], v[196:199], v[104:107]
	v_mfma_f32_16x16x32_bf16 v[92:95], v[68:71], v[204:207], v[92:95]
	v_mfma_f32_16x16x32_bf16 v[88:91], v[76:79], v[204:207], v[88:91]


; #define PG8_MMA(ai, bj, At, Bt) do { __builtin_amdgcn_s_setprio(1); _Pragma("unroll") for (int m = 0; m < 4; ++m) _Pragma("unroll") for (int n = 0; n < 2; ++n) _Pragma("unroll") for (int k = 0; k < 2; ++k) \
;         acc[ai][bj][m][n] = __builtin_amdgcn_mfma_f32_16x16x32_bf16(Bt[n][k], At[m][k], acc[ai][bj][m][n], 0, 0, 0); __builtin_amdgcn_s_setprio(0); } while (0)
; #define PG8_WAIT_V(n) asm volatile("s_waitcnt vmcnt(" #n ")" ::: "memory")
; #define PG8_WAIT_L(n) asm volatile("s_waitcnt lgkmcnt(" #n ")" ::: "memory")
; #define PG8_BAR __builtin_amdgcn_s_barrier()
; #define PG8_SCHED __builtin_amdgcn_sched_barrier(0)
; template <class Epi, class Sched, bool ALIGN_EPI = false, bool SP2 = false>
; __device__ __forceinline__ void gemm_phase(PG8_LAS unsigned char* lds, const Gemm g, const Sched& S, const Epi& E) {
;     ...
;             PG8_WAIT_V(8); PG8_WAIT_L(0); PG8_BAR; PG8_MMA(0, 0, At, B0); PG8_MMA(0, 1, At, B1); PG8_BAR; PG8_SCHED;
	v_mfma_f32_16x16x32_bf16 v[132:135], v[144:147], v[176:179], v[132:135]
	v_mfma_f32_16x16x32_bf16 v[128:131], v[152:155], v[176:179], v[128:131]
	v_mfma_f32_16x16x32_bf16 v[116:119], v[144:147], v[184:187], v[116:119]
	v_mfma_f32_16x16x32_bf16 v[112:115], v[152:155], v[184:187], v[112:115]
	v_mfma_f32_16x16x32_bf16 v[100:103], v[144:147], v[192:195], v[100:103]
	v_mfma_f32_16x16x32_bf16 v[96:99], v[152:155], v[192:195], v[96:99]
	v_mfma_f32_16x16x32_bf16 v[84:87], v[144:147], v[200:203], v[84:87]
	v_mfma_f32_16x16x32_bf16 v[80:83], v[152:155], v[200:203], v[80:83]
	v_mfma_f32_16x16x32_bf16 v[132:135], v[148:151], v[180:183], v[132:135]
	v_mfma_f32_16x16x32_bf16 v[128:131], v[156:159], v[180:183], v[128:131]
	v_mfma_f32_16x16x32_bf16 v[116:119], v[148:151], v[188:191], v[116:119]
	v_mfma_f32_16x16x32_bf16 v[112:115], v[156:159], v[188:191], v[112:115]
	v_mfma_f32_16x16x32_bf16 v[100:103], v[148:151], v[196:199], v[100:103]
	v_mfma_f32_16x16x32_bf16 v[96:99], v[156:159], v[196:199], v[96:99]
	v_mfma_f32_16x16x32_bf16 v[84:87], v[148:151], v[204:207], v[84:87]
	v_mfma_f32_16x16x32_bf16 v[80:83], v[156:159], v[204:207], v[80:83]
	s_setprio 0
	s_barrier
	s_add_i32 s62, s82, s64

; #define PG8_STAGE(bufoff, gbase, voff) do { _Pragma("unroll") for (int _i = 0; _i < 2; ++_i) \
;         __builtin_amdgcn_global_load_lds((const unsigned*)((const char*)(gbase) + (voff)[_i]), (PG8_LAS unsigned*)(lds + (bufoff) + ldsw + _i * 8192), 16, 0, 0); } while (0)
; #define PG8_LDA(dst, b, h) do { _Pragma("unroll") for (int m = 0; m < 4; ++m) _Pragma("unroll") for (int k = 0; k < 2; ++k) dst[m][k] = *(const PG8_LAS bf16x8*)(lds + PG8_SA(b, h) + aoff + m * 2048 + k * 1024); } while (0)
; template <class Epi, class Sched, bool ALIGN_EPI = false, bool SP2 = false>
; __device__ __forceinline__ void gemm_phase(PG8_LAS unsigned char* lds, const Gemm g, const Sched& S, const Epi& E) {
;     ...
;             PG8_LDA(At, 1, 1); PG8_STAGE(PG8_SB(1, 0), b3, voffB); PG8_STAGE(PG8_SB(1, 1), b3 + hstep, voffB); PG8_STAGE(PG8_SA(1, 0), a3, voffA);
	s_mov_b32 m0, s62
	ds_read_b128 v[176:179], v215 offset:49152
	ds_read_b128 v[180:183], v215 offset:50176
	ds_read_b128 v[184:187], v215 offset:51200
	ds_read_b128 v[188:191], v215 offset:52224


; #define PG8_STAGE(bufoff, gbase, voff) do { _Pragma("unroll") for (int _i = 0; _i < 2; ++_i) \
;         __builtin_amdgcn_global_load_lds((const unsigned*)((const char*)(gbase) + (voff)[_i]), (PG8_LAS unsigned*)(lds + (bufoff) + ldsw + _i * 8192), 16, 0, 0); } while (0)
; #define PG8_LDA(dst, b, h) do { _Pragma("unroll") for (int m = 0; m < 4; ++m) _Pragma("unroll") for (int k = 0; k < 2; ++k) dst[m][k] = *(const PG8_LAS bf16x8*)(lds + PG8_SA(b, h) + aoff + m * 2048 + k * 1024); } while (0)
; template <class Epi, class Sched, bool ALIGN_EPI = false, bool SP2 = false>
; __device__ __forceinline__ void gemm_phase(PG8_LAS unsigned char* lds, const Gemm g, const Sched& S, const Epi& E) {
;     ...
;             PG8_LDA(At, 1, 1); PG8_STAGE(PG8_SB(1, 0), b3, voffB); PG8_STAGE(PG8_SB(1, 1), b3 + hstep, voffB); PG8_STAGE(PG8_SA(1, 0), a3, voffA);
	global_load_lds_dwordx4 v250, s[96:97]
	s_add_i32 m0, s62, 0x2000
	s_add_u32 s60, s60, 0x200080

; #define PG8_STAGE(bufoff, gbase, voff) do { _Pragma("unroll") for (int _i = 0; _i < 2; ++_i) \
;         __builtin_amdgcn_global_load_lds((const unsigned*)((const char*)(gbase) + (voff)[_i]), (PG8_LAS unsigned*)(lds + (bufoff) + ldsw + _i * 8192), 16, 0, 0); } while (0)
; #define PG8_LDA(dst, b, h) do { _Pragma("unroll") for (int m = 0; m < 4; ++m) _Pragma("unroll") for (int k = 0; k < 2; ++k) dst[m][k] = *(const PG8_LAS bf16x8*)(lds + PG8_SA(b, h) + aoff + m * 2048 + k * 1024); } while (0)
; template <class Epi, class Sched, bool ALIGN_EPI = false, bool SP2 = false>
; __device__ __forceinline__ void gemm_phase(PG8_LAS unsigned char* lds, const Gemm g, const Sched& S, const Epi& E) {
;     ...
;             PG8_LDA(At, 1, 1); PG8_STAGE(PG8_SB(1, 0), b3, voffB); PG8_STAGE(PG8_SB(1, 1), b3 + hstep, voffB); PG8_STAGE(PG8_SA(1, 0), a3, voffA);
	s_addc_u32 s61, s61, 0
	s_add_i32 s62, s83, s64
	global_load_lds_dwordx4 v251, s[96:97]

; #define PG8_STAGE(bufoff, gbase, voff) do { _Pragma("unroll") for (int _i = 0; _i < 2; ++_i) \
;         __builtin_amdgcn_global_load_lds((const unsigned*)((const char*)(gbase) + (voff)[_i]), (PG8_LAS unsigned*)(lds + (bufoff) + ldsw + _i * 8192), 16, 0, 0); } while (0)
; #define PG8_LDA(dst, b, h) do { _Pragma("unroll") for (int m = 0; m < 4; ++m) _Pragma("unroll") for (int k = 0; k < 2; ++k) dst[m][k] = *(const PG8_LAS bf16x8*)(lds + PG8_SA(b, h) + aoff + m * 2048 + k * 1024); } while (0)
; template <class Epi, class Sched, bool ALIGN_EPI = false, bool SP2 = false>
; __device__ __forceinline__ void gemm_phase(PG8_LAS unsigned char* lds, const Gemm g, const Sched& S, const Epi& E) {
;     ...
;             PG8_LDA(At, 1, 1); PG8_STAGE(PG8_SB(1, 0), b3, voffB); PG8_STAGE(PG8_SB(1, 1), b3 + hstep, voffB); PG8_STAGE(PG8_SA(1, 0), a3, voffA);
	s_mov_b32 m0, s62
	ds_read_b128 v[192:195], v215 offset:53248
	global_load_lds_dwordx4 v162, s[60:61]

; #define PG8_STAGE(bufoff, gbase, voff) do { _Pragma("unroll") for (int _i = 0; _i < 2; ++_i) \
;         __builtin_amdgcn_global_load_lds((const unsigned*)((const char*)(gbase) + (voff)[_i]), (PG8_LAS unsigned*)(lds + (bufoff) + ldsw + _i * 8192), 16, 0, 0); } while (0)
; #define PG8_LDA(dst, b, h) do { _Pragma("unroll") for (int m = 0; m < 4; ++m) _Pragma("unroll") for (int k = 0; k < 2; ++k) dst[m][k] = *(const PG8_LAS bf16x8*)(lds + PG8_SA(b, h) + aoff + m * 2048 + k * 1024); } while (0)
; template <class Epi, class Sched, bool ALIGN_EPI = false, bool SP2 = false>
; __device__ __forceinline__ void gemm_phase(PG8_LAS unsigned char* lds, const Gemm g, const Sched& S, const Epi& E) {
;     ...
;             PG8_LDA(At, 1, 1); PG8_STAGE(PG8_SB(1, 0), b3, voffB); PG8_STAGE(PG8_SB(1, 1), b3 + hstep, voffB); PG8_STAGE(PG8_SA(1, 0), a3, voffA);
	s_add_i32 m0, s62, 0x2000
	ds_read_b128 v[196:199], v215 offset:54272
	global_load_lds_dwordx4 v166, s[60:61]

; #define PG8_STAGE(bufoff, gbase, voff) do { _Pragma("unroll") for (int _i = 0; _i < 2; ++_i) \
;         __builtin_amdgcn_global_load_lds((const unsigned*)((const char*)(gbase) + (voff)[_i]), (PG8_LAS unsigned*)(lds + (bufoff) + ldsw + _i * 8192), 16, 0, 0); } while (0)
; #define PG8_LDA(dst, b, h) do { _Pragma("unroll") for (int m = 0; m < 4; ++m) _Pragma("unroll") for (int k = 0; k < 2; ++k) dst[m][k] = *(const PG8_LAS bf16x8*)(lds + PG8_SA(b, h) + aoff + m * 2048 + k * 1024); } while (0)
; template <class Epi, class Sched, bool ALIGN_EPI = false, bool SP2 = false>
; __device__ __forceinline__ void gemm_phase(PG8_LAS unsigned char* lds, const Gemm g, const Sched& S, const Epi& E) {
;     ...
;             PG8_LDA(At, 1, 1); PG8_STAGE(PG8_SB(1, 0), b3, voffB); PG8_STAGE(PG8_SB(1, 1), b3 + hstep, voffB); PG8_STAGE(PG8_SA(1, 0), a3, voffA);
	s_mov_b32 m0, s70
	ds_read_b128 v[200:203], v215 offset:55296
	global_load_lds_dwordx4 v252, s[98:99]

; #define PG8_STAGE(bufoff, gbase, voff) do { _Pragma("unroll") for (int _i = 0; _i < 2; ++_i) \
;         __builtin_amdgcn_global_load_lds((const unsigned*)((const char*)(gbase) + (voff)[_i]), (PG8_LAS unsigned*)(lds + (bufoff) + ldsw + _i * 8192), 16, 0, 0); } while (0)
; #define PG8_LDA(dst, b, h) do { _Pragma("unroll") for (int m = 0; m < 4; ++m) _Pragma("unroll") for (int k = 0; k < 2; ++k) dst[m][k] = *(const PG8_LAS bf16x8*)(lds + PG8_SA(b, h) + aoff + m * 2048 + k * 1024); } while (0)
; #define PG8_MMA(ai, bj, At, Bt) do { __builtin_amdgcn_s_setprio(1); _Pragma("unroll") for (int m = 0; m < 4; ++m) _Pragma("unroll") for (int n = 0; n < 2; ++n) _Pragma("unroll") for (int k = 0; k < 2; ++k) \
;         acc[ai][bj][m][n] = __builtin_amdgcn_mfma_f32_16x16x32_bf16(Bt[n][k], At[m][k], acc[ai][bj][m][n], 0, 0, 0); __builtin_amdgcn_s_setprio(0); } while (0)
; #define PG8_WAIT_V(n) asm volatile("s_waitcnt vmcnt(" #n ")" ::: "memory")
; #define PG8_WAIT_L(n) asm volatile("s_waitcnt lgkmcnt(" #n ")" ::: "memory")
; #define PG8_BAR __builtin_amdgcn_s_barrier()
; #define PG8_SCHED __builtin_amdgcn_sched_barrier(0)
; template <class Epi, class Sched, bool ALIGN_EPI = false, bool SP2 = false>
; __device__ __forceinline__ void gemm_phase(PG8_LAS unsigned char* lds, const Gemm g, const Sched& S, const Epi& E) {
;     ...
;             PG8_LDA(At, 1, 1); PG8_STAGE(PG8_SB(1, 0), b3, voffB); PG8_STAGE(PG8_SB(1, 1), b3 + hstep, voffB); PG8_STAGE(PG8_SA(1, 0), a3, voffA);
;             PG8_WAIT_V(8); PG8_WAIT_L(0); PG8_BAR; PG8_MMA(1, 0, At, B0); PG8_MMA(1, 1, At, B1); PG8_BAR; PG8_SCHED;
	s_mov_b32 m0, s71
	ds_read_b128 v[204:207], v215 offset:56320
	global_load_lds_dwordx4 v253, s[98:99]
	s_waitcnt vmcnt(8)
	s_waitcnt lgkmcnt(0)
	s_barrier
	s_setprio 1
	s_waitcnt lgkmcnt(0)
	v_mfma_f32_16x16x32_bf16 v[60:63], v[64:67], v[176:179], v[60:63]
	v_mfma_f32_16x16x32_bf16 v[56:59], v[72:75], v[176:179], v[56:59]
	v_mfma_f32_16x16x32_bf16 v[44:47], v[64:67], v[184:187], v[44:47]
	v_mfma_f32_16x16x32_bf16 v[40:43], v[72:75], v[184:187], v[40:43]
	v_mfma_f32_16x16x32_bf16 v[28:31], v[64:67], v[192:195], v[28:31]
	v_mfma_f32_16x16x32_bf16 v[24:27], v[72:75], v[192:195], v[24:27]
	v_mfma_f32_16x16x32_bf16 v[12:15], v[64:67], v[200:203], v[12:15]
	v_mfma_f32_16x16x32_bf16 v[8:11], v[72:75], v[200:203], v[8:11]
	v_mfma_f32_16x16x32_bf16 v[60:63], v[68:71], v[180:183], v[60:63]
	v_mfma_f32_16x16x32_bf16 v[56:59], v[76:79], v[180:183], v[56:59]
	v_mfma_f32_16x16x32_bf16 v[44:47], v[68:71], v[188:191], v[44:47]
	v_mfma_f32_16x16x32_bf16 v[40:43], v[76:79], v[188:191], v[40:43]
	v_mfma_f32_16x16x32_bf16 v[28:31], v[68:71], v[196:199], v[28:31]
	v_mfma_f32_16x16x32_bf16 v[24:27], v[76:79], v[196:199], v[24:27]
	v_mfma_f32_16x16x32_bf16 v[12:15], v[68:71], v[204:207], v[12:15]
	v_mfma_f32_16x16x32_bf16 v[8:11], v[76:79], v[204:207], v[8:11]


; #define PG8_STAGE(bufoff, gbase, voff) do { _Pragma("unroll") for (int _i = 0; _i < 2; ++_i) \
;         __builtin_amdgcn_global_load_lds((const unsigned*)((const char*)(gbase) + (voff)[_i]), (PG8_LAS unsigned*)(lds + (bufoff) + ldsw + _i * 8192), 16, 0, 0); } while (0)
; #define PG8_LDA(dst, b, h) do { _Pragma("unroll") for (int m = 0; m < 4; ++m) _Pragma("unroll") for (int k = 0; k < 2; ++k) dst[m][k] = *(const PG8_LAS bf16x8*)(lds + PG8_SA(b, h) + aoff + m * 2048 + k * 1024); } while (0)
; #define PG8_LDB(dst, b, h) do { _Pragma("unroll") for (int n = 0; n < 2; ++n) _Pragma("unroll") for (int k = 0; k < 2; ++k) dst[n][k] = *(const PG8_LAS bf16x8*)(lds + PG8_SB(b, h) + boff + n * 2048 + k * 1024); } while (0)
; template <class Epi, class Sched, bool ALIGN_EPI = false, bool SP2 = false>
; __device__ __forceinline__ void gemm_phase(PG8_LAS unsigned char* lds, const Gemm g, const Sched& S, const Epi& E) {
;     ...
;             PG8_WAIT_V(8); PG8_WAIT_L(0); PG8_BAR; PG8_MMA(1, 0, At, B0); PG8_MMA(1, 1, At, B1); PG8_BAR; PG8_SCHED;
;             } else {
;             PG8_LDB(B0, 0, 0); PG8_SCHED; PG8_LDA(At, 0, 0); PG8_STAGE(PG8_SA(1, 1), a1 + hstep, voffA);
;             PG8_WAIT_L(8); PG8_BAR; PG8_WAIT_L(0); PG8_MMA(0, 0, At, B0); PG8_BAR; PG8_SCHED;
;             PG8_LDB(B1, 0, 1); PG8_STAGE(PG8_SB(0, 0), b2, voffB);
;             PG8_BAR; PG8_WAIT_L(0); PG8_MMA(0, 1, At, B1); PG8_BAR;
;             PG8_LDA(At, 0, 1); PG8_STAGE(PG8_SA(0, 0), a2, voffA);
;             PG8_BAR; PG8_WAIT_L(0); PG8_MMA(1, 0, At, B0); PG8_BAR; PG8_SCHED;
;             PG8_STAGE(PG8_SB(0, 1), b2 + hstep, voffB);
;             PG8_WAIT_V(6); PG8_BAR; PG8_MMA(1, 1, At, B1); PG8_BAR;
;             PG8_LDB(B0, 1, 0); PG8_SCHED; PG8_LDA(At, 1, 0); PG8_STAGE(PG8_SA(0, 1), a2 + hstep, voffA);
;             PG8_WAIT_L(8); PG8_BAR; PG8_WAIT_L(0); PG8_MMA(0, 0, At, B0); PG8_BAR; PG8_SCHED;
;             PG8_LDB(B1, 1, 1); PG8_STAGE(PG8_SB(1, 0), b3, voffB);
;             PG8_BAR; PG8_WAIT_L(0); PG8_MMA(0, 1, At, B1); PG8_BAR;
;             PG8_LDA(At, 1, 1); PG8_STAGE(PG8_SA(1, 0), a3, voffA);
;             PG8_BAR; PG8_WAIT_L(0); PG8_MMA(1, 0, At, B0); PG8_BAR; PG8_SCHED;
;             PG8_STAGE(PG8_SB(1, 1), b3 + hstep, voffB);
;             PG8_WAIT_V(6); PG8_BAR; PG8_MMA(1, 1, At, B1); PG8_BAR;
;             }
;         }
;         if constexpr (ALIGN_EPI) { if (wr == 0) PG8_BAR; }
	v_mfma_f32_16x16x32_bf16 v[52:55], v[144:147], v[176:179], v[52:55]
	v_mfma_f32_16x16x32_bf16 v[48:51], v[152:155], v[176:179], v[48:51]
	v_mfma_f32_16x16x32_bf16 v[36:39], v[144:147], v[184:187], v[36:39]
	v_mfma_f32_16x16x32_bf16 v[32:35], v[152:155], v[184:187], v[32:35]
	v_mfma_f32_16x16x32_bf16 v[20:23], v[144:147], v[192:195], v[20:23]
	v_mfma_f32_16x16x32_bf16 v[16:19], v[152:155], v[192:195], v[16:19]
	v_mfma_f32_16x16x32_bf16 v[4:7], v[144:147], v[200:203], v[4:7]
	v_mfma_f32_16x16x32_bf16 v[0:3], v[152:155], v[200:203], v[0:3]
	v_mfma_f32_16x16x32_bf16 v[52:55], v[148:151], v[180:183], v[52:55]
	v_mfma_f32_16x16x32_bf16 v[48:51], v[156:159], v[180:183], v[48:51]
	v_mfma_f32_16x16x32_bf16 v[36:39], v[148:151], v[188:191], v[36:39]
	v_mfma_f32_16x16x32_bf16 v[32:35], v[156:159], v[188:191], v[32:35]
	v_mfma_f32_16x16x32_bf16 v[20:23], v[148:151], v[196:199], v[20:23]
	v_mfma_f32_16x16x32_bf16 v[16:19], v[156:159], v[196:199], v[16:19]
	v_mfma_f32_16x16x32_bf16 v[4:7], v[148:151], v[204:207], v[4:7]
	v_mfma_f32_16x16x32_bf16 v[0:3], v[156:159], v[204:207], v[0:3]
	s_setprio 0
	s_barrier
	s_add_i32 s81, s81, 2
	s_add_u32 s58, s58, 0x100
	s_addc_u32 s59, s59, 0
	s_add_u32 s79, s79, 0x100
	s_addc_u32 s80, s80, 0
	s_cmpk_gt_u32 s81, 0x7d
	s_cbranch_scc0 .LBB0_509
	s_and_b64 vcc, exec, s[42:43]
	s_cbranch_vccz .LBB0_512
	s_barrier

; #define PG8_STAGE(bufoff, gbase, voff) do { _Pragma("unroll") for (int _i = 0; _i < 2; ++_i) \
;         __builtin_amdgcn_global_load_lds((const unsigned*)((const char*)(gbase) + (voff)[_i]), (PG8_LAS unsigned*)(lds + (bufoff) + ldsw + _i * 8192), 16, 0, 0); } while (0)
; #define PG8_LDA(dst, b, h) do { _Pragma("unroll") for (int m = 0; m < 4; ++m) _Pragma("unroll") for (int k = 0; k < 2; ++k) dst[m][k] = *(const PG8_LAS bf16x8*)(lds + PG8_SA(b, h) + aoff + m * 2048 + k * 1024); } while (0)
; #define PG8_LDB(dst, b, h) do { _Pragma("unroll") for (int n = 0; n < 2; ++n) _Pragma("unroll") for (int k = 0; k < 2; ++k) dst[n][k] = *(const PG8_LAS bf16x8*)(lds + PG8_SB(b, h) + boff + n * 2048 + k * 1024); } while (0)
; #define PG8_SCHED __builtin_amdgcn_sched_barrier(0)
; template <class Epi, class Sched, bool ALIGN_EPI = false, bool SP2 = false>
; __device__ __forceinline__ void gemm_phase(PG8_LAS unsigned char* lds, const Gemm g, const Sched& S, const Epi& E) {
;     ...
;         for (int t = 0; t < nt; t += 2) {
;             const bool last = (t == nt - 2);
;             const char* a1 = cA + (size_t)(t + 1) * kstep;
;             const char* a2 = last ? nA : cA + (size_t)(t + 2) * kstep; const char* b2 = last ? nB : cB + (size_t)(t + 2) * kstep;
;             const char* a3 = a2 + kstep; const char* b3 = b2 + kstep;
;             if (last && has_next) S.a_ready(nxt);
;             if constexpr (SP2) {
;             PG8_LDB(B0, 0, 0); PG8_LDB(B1, 0, 1); PG8_SCHED; PG8_LDA(At, 0, 0); PG8_STAGE(PG8_SA(1, 1), a1 + hstep, voffA);
.LBB0_679:
	ds_read_b128 v[128:131], v203
	ds_read_b128 v[132:135], v203 offset:1024
	ds_read_b128 v[136:139], v203 offset:2048
	ds_read_b128 v[140:143], v203 offset:3072
	ds_read_b128 v[144:147], v205
	ds_read_b128 v[148:151], v205 offset:1024
	ds_read_b128 v[152:155], v205 offset:2048
	ds_read_b128 v[156:159], v205 offset:3072
	s_add_u32 s12, s10, 0xfff80080
	s_addc_u32 s13, s11, -1
	s_cmp_eq_u32 s78, 28
	s_cselect_b32 s55, s49, s13
	s_cselect_b32 s54, s74, s12
	s_cselect_b32 s13, s47, s77
	s_cselect_b32 s12, s75, s76

; #define PG8_STAGE(bufoff, gbase, voff) do { _Pragma("unroll") for (int _i = 0; _i < 2; ++_i) \
;         __builtin_amdgcn_global_load_lds((const unsigned*)((const char*)(gbase) + (voff)[_i]), (PG8_LAS unsigned*)(lds + (bufoff) + ldsw + _i * 8192), 16, 0, 0); } while (0)
; #define PG8_LDA(dst, b, h) do { _Pragma("unroll") for (int m = 0; m < 4; ++m) _Pragma("unroll") for (int k = 0; k < 2; ++k) dst[m][k] = *(const PG8_LAS bf16x8*)(lds + PG8_SA(b, h) + aoff + m * 2048 + k * 1024); } while (0)
; #define PG8_LDB(dst, b, h) do { _Pragma("unroll") for (int n = 0; n < 2; ++n) _Pragma("unroll") for (int k = 0; k < 2; ++k) dst[n][k] = *(const PG8_LAS bf16x8*)(lds + PG8_SB(b, h) + boff + n * 2048 + k * 1024); } while (0)
; #define PG8_SCHED __builtin_amdgcn_sched_barrier(0)
; template <class Epi, class Sched, bool ALIGN_EPI = false, bool SP2 = false>
; __device__ __forceinline__ void gemm_phase(PG8_LAS unsigned char* lds, const Gemm g, const Sched& S, const Epi& E) {
;     ...
;             PG8_LDB(B0, 0, 0); PG8_LDB(B1, 0, 1); PG8_SCHED; PG8_LDA(At, 0, 0); PG8_STAGE(PG8_SA(1, 1), a1 + hstep, voffA);
	s_add_i32 m0, s60, 0xc000
	ds_read_b128 v[176:179], v207
	ds_read_b128 v[180:183], v207 offset:1024
	ds_read_b128 v[184:187], v207 offset:2048
	ds_read_b128 v[192:195], v207 offset:3072
	ds_read_b128 v[210:213], v207 offset:4096
	ds_read_b128 v[214:217], v207 offset:5120
	ds_read_b128 v[218:221], v207 offset:6144

; #define PG8_STAGE(bufoff, gbase, voff) do { _Pragma("unroll") for (int _i = 0; _i < 2; ++_i) \
;         __builtin_amdgcn_global_load_lds((const unsigned*)((const char*)(gbase) + (voff)[_i]), (PG8_LAS unsigned*)(lds + (bufoff) + ldsw + _i * 8192), 16, 0, 0); } while (0)
; #define PG8_LDA(dst, b, h) do { _Pragma("unroll") for (int m = 0; m < 4; ++m) _Pragma("unroll") for (int k = 0; k < 2; ++k) dst[m][k] = *(const PG8_LAS bf16x8*)(lds + PG8_SA(b, h) + aoff + m * 2048 + k * 1024); } while (0)
; #define PG8_LDB(dst, b, h) do { _Pragma("unroll") for (int n = 0; n < 2; ++n) _Pragma("unroll") for (int k = 0; k < 2; ++k) dst[n][k] = *(const PG8_LAS bf16x8*)(lds + PG8_SB(b, h) + boff + n * 2048 + k * 1024); } while (0)
; #define PG8_SCHED __builtin_amdgcn_sched_barrier(0)
; template <class Epi, class Sched, bool ALIGN_EPI = false, bool SP2 = false>
; __device__ __forceinline__ void gemm_phase(PG8_LAS unsigned char* lds, const Gemm g, const Sched& S, const Epi& E) {
;     ...
;             PG8_LDB(B0, 0, 0); PG8_LDB(B1, 0, 1); PG8_SCHED; PG8_LDA(At, 0, 0); PG8_STAGE(PG8_SA(1, 1), a1 + hstep, voffA);
	global_load_lds_dwordx4 v168, s[10:11]

; #define PG8_STAGE(bufoff, gbase, voff) do { _Pragma("unroll") for (int _i = 0; _i < 2; ++_i) \
;         __builtin_amdgcn_global_load_lds((const unsigned*)((const char*)(gbase) + (voff)[_i]), (PG8_LAS unsigned*)(lds + (bufoff) + ldsw + _i * 8192), 16, 0, 0); } while (0)
; #define PG8_LDA(dst, b, h) do { _Pragma("unroll") for (int m = 0; m < 4; ++m) _Pragma("unroll") for (int k = 0; k < 2; ++k) dst[m][k] = *(const PG8_LAS bf16x8*)(lds + PG8_SA(b, h) + aoff + m * 2048 + k * 1024); } while (0)
; #define PG8_LDB(dst, b, h) do { _Pragma("unroll") for (int n = 0; n < 2; ++n) _Pragma("unroll") for (int k = 0; k < 2; ++k) dst[n][k] = *(const PG8_LAS bf16x8*)(lds + PG8_SB(b, h) + boff + n * 2048 + k * 1024); } while (0)
; #define PG8_MMA(ai, bj, At, Bt) do { __builtin_amdgcn_s_setprio(1); _Pragma("unroll") for (int m = 0; m < 4; ++m) _Pragma("unroll") for (int n = 0; n < 2; ++n) _Pragma("unroll") for (int k = 0; k < 2; ++k) \
;         acc[ai][bj][m][n] = __builtin_amdgcn_mfma_f32_16x16x32_bf16(Bt[n][k], At[m][k], acc[ai][bj][m][n], 0, 0, 0); __builtin_amdgcn_s_setprio(0); } while (0)
; #define PG8_WAIT_V(n) asm volatile("s_waitcnt vmcnt(" #n ")" ::: "memory")
; #define PG8_WAIT_L(n) asm volatile("s_waitcnt lgkmcnt(" #n ")" ::: "memory")
; #define PG8_BAR __builtin_amdgcn_s_barrier()
; #define PG8_SCHED __builtin_amdgcn_sched_barrier(0)
; template <class Epi, class Sched, bool ALIGN_EPI = false, bool SP2 = false>
; __device__ __forceinline__ void gemm_phase(PG8_LAS unsigned char* lds, const Gemm g, const Sched& S, const Epi& E) {
;     ...
;             PG8_LDB(B0, 0, 0); PG8_LDB(B1, 0, 1); PG8_SCHED; PG8_LDA(At, 0, 0); PG8_STAGE(PG8_SA(1, 1), a1 + hstep, voffA);
;             PG8_WAIT_V(8); PG8_WAIT_L(0); PG8_BAR; PG8_MMA(0, 0, At, B0); PG8_MMA(0, 1, At, B1); PG8_BAR; PG8_SCHED;
	s_add_i32 m0, s60, 0xe000
	ds_read_b128 v[222:225], v207 offset:7168
	global_load_lds_dwordx4 v170, s[10:11]
	s_waitcnt vmcnt(8)
	s_waitcnt lgkmcnt(0)
	s_barrier
	s_setprio 1
	s_waitcnt lgkmcnt(0)
	v_mfma_f32_16x16x32_bf16 v[124:127], v[128:131], v[176:179], v[124:127]
	v_mfma_f32_16x16x32_bf16 v[120:123], v[136:139], v[176:179], v[120:123]
	v_mfma_f32_16x16x32_bf16 v[112:115], v[128:131], v[184:187], v[112:115]
	v_mfma_f32_16x16x32_bf16 v[104:107], v[136:139], v[184:187], v[104:107]
	v_mfma_f32_16x16x32_bf16 v[100:103], v[128:131], v[210:213], v[100:103]
	v_mfma_f32_16x16x32_bf16 v[88:91], v[136:139], v[210:213], v[88:91]
	v_mfma_f32_16x16x32_bf16 v[84:87], v[128:131], v[218:221], v[84:87]
	v_mfma_f32_16x16x32_bf16 v[72:75], v[136:139], v[218:221], v[72:75]
	v_mfma_f32_16x16x32_bf16 v[124:127], v[132:135], v[180:183], v[124:127]
	v_mfma_f32_16x16x32_bf16 v[120:123], v[140:143], v[180:183], v[120:123]
	v_mfma_f32_16x16x32_bf16 v[112:115], v[132:135], v[192:195], v[112:115]
	v_mfma_f32_16x16x32_bf16 v[104:107], v[140:143], v[192:195], v[104:107]
	v_mfma_f32_16x16x32_bf16 v[100:103], v[132:135], v[214:217], v[100:103]
	v_mfma_f32_16x16x32_bf16 v[88:91], v[140:143], v[214:217], v[88:91]
	v_mfma_f32_16x16x32_bf16 v[84:87], v[132:135], v[222:225], v[84:87]
	v_mfma_f32_16x16x32_bf16 v[72:75], v[140:143], v[222:225], v[72:75]


; #define PG8_MMA(ai, bj, At, Bt) do { __builtin_amdgcn_s_setprio(1); _Pragma("unroll") for (int m = 0; m < 4; ++m) _Pragma("unroll") for (int n = 0; n < 2; ++n) _Pragma("unroll") for (int k = 0; k < 2; ++k) \
;         acc[ai][bj][m][n] = __builtin_amdgcn_mfma_f32_16x16x32_bf16(Bt[n][k], At[m][k], acc[ai][bj][m][n], 0, 0, 0); __builtin_amdgcn_s_setprio(0); } while (0)
; #define PG8_WAIT_V(n) asm volatile("s_waitcnt vmcnt(" #n ")" ::: "memory")
; #define PG8_WAIT_L(n) asm volatile("s_waitcnt lgkmcnt(" #n ")" ::: "memory")
; #define PG8_BAR __builtin_amdgcn_s_barrier()
; #define PG8_SCHED __builtin_amdgcn_sched_barrier(0)
; template <class Epi, class Sched, bool ALIGN_EPI = false, bool SP2 = false>
; __device__ __forceinline__ void gemm_phase(PG8_LAS unsigned char* lds, const Gemm g, const Sched& S, const Epi& E) {
;     ...
;             PG8_WAIT_V(8); PG8_WAIT_L(0); PG8_BAR; PG8_MMA(0, 0, At, B0); PG8_MMA(0, 1, At, B1); PG8_BAR; PG8_SCHED;
	v_mfma_f32_16x16x32_bf16 v[116:119], v[144:147], v[176:179], v[116:119]
	v_mfma_f32_16x16x32_bf16 v[108:111], v[152:155], v[176:179], v[108:111]
	v_mfma_f32_16x16x32_bf16 v[96:99], v[144:147], v[184:187], v[96:99]
	v_mfma_f32_16x16x32_bf16 v[92:95], v[152:155], v[184:187], v[92:95]
	v_mfma_f32_16x16x32_bf16 v[80:83], v[144:147], v[210:213], v[80:83]
	v_mfma_f32_16x16x32_bf16 v[76:79], v[152:155], v[210:213], v[76:79]
	v_mfma_f32_16x16x32_bf16 v[68:71], v[144:147], v[218:221], v[68:71]
	v_mfma_f32_16x16x32_bf16 v[64:67], v[152:155], v[218:221], v[64:67]
	v_mfma_f32_16x16x32_bf16 v[116:119], v[148:151], v[180:183], v[116:119]
	v_mfma_f32_16x16x32_bf16 v[108:111], v[156:159], v[180:183], v[108:111]
	v_mfma_f32_16x16x32_bf16 v[96:99], v[148:151], v[192:195], v[96:99]
	v_mfma_f32_16x16x32_bf16 v[92:95], v[156:159], v[192:195], v[92:95]
	v_mfma_f32_16x16x32_bf16 v[80:83], v[148:151], v[214:217], v[80:83]
	v_mfma_f32_16x16x32_bf16 v[76:79], v[156:159], v[214:217], v[76:79]
	v_mfma_f32_16x16x32_bf16 v[68:71], v[148:151], v[222:225], v[68:71]
	v_mfma_f32_16x16x32_bf16 v[64:67], v[156:159], v[222:225], v[64:67]
	s_setprio 0
	s_barrier
	s_add_i32 s79, s70, s57
	s_mov_b64 s[96:97], s[12:13]

; #define PG8_STAGE(bufoff, gbase, voff) do { _Pragma("unroll") for (int _i = 0; _i < 2; ++_i) \
;         __builtin_amdgcn_global_load_lds((const unsigned*)((const char*)(gbase) + (voff)[_i]), (PG8_LAS unsigned*)(lds + (bufoff) + ldsw + _i * 8192), 16, 0, 0); } while (0)
; #define PG8_LDA(dst, b, h) do { _Pragma("unroll") for (int m = 0; m < 4; ++m) _Pragma("unroll") for (int k = 0; k < 2; ++k) dst[m][k] = *(const PG8_LAS bf16x8*)(lds + PG8_SA(b, h) + aoff + m * 2048 + k * 1024); } while (0)
; template <class Epi, class Sched, bool ALIGN_EPI = false, bool SP2 = false>
; __device__ __forceinline__ void gemm_phase(PG8_LAS unsigned char* lds, const Gemm g, const Sched& S, const Epi& E) {
;     ...
;             PG8_LDA(At, 0, 1); PG8_STAGE(PG8_SB(0, 0), b2, voffB); PG8_STAGE(PG8_SB(0, 1), b2 + hstep, voffB); PG8_STAGE(PG8_SA(0, 0), a2, voffA);
	s_mov_b32 m0, s79
	ds_read_b128 v[176:179], v207 offset:16384
	ds_read_b128 v[180:183], v207 offset:17408
	ds_read_b128 v[184:187], v207 offset:18432
	ds_read_b128 v[192:195], v207 offset:19456


; #define PG8_STAGE(bufoff, gbase, voff) do { _Pragma("unroll") for (int _i = 0; _i < 2; ++_i) \
;         __builtin_amdgcn_global_load_lds((const unsigned*)((const char*)(gbase) + (voff)[_i]), (PG8_LAS unsigned*)(lds + (bufoff) + ldsw + _i * 8192), 16, 0, 0); } while (0)
; #define PG8_LDA(dst, b, h) do { _Pragma("unroll") for (int m = 0; m < 4; ++m) _Pragma("unroll") for (int k = 0; k < 2; ++k) dst[m][k] = *(const PG8_LAS bf16x8*)(lds + PG8_SA(b, h) + aoff + m * 2048 + k * 1024); } while (0)
; template <class Epi, class Sched, bool ALIGN_EPI = false, bool SP2 = false>
; __device__ __forceinline__ void gemm_phase(PG8_LAS unsigned char* lds, const Gemm g, const Sched& S, const Epi& E) {
;     ...
;             PG8_LDA(At, 0, 1); PG8_STAGE(PG8_SB(0, 0), b2, voffB); PG8_STAGE(PG8_SB(0, 1), b2 + hstep, voffB); PG8_STAGE(PG8_SA(0, 0), a2, voffA);
	global_load_lds_dwordx4 v164, s[12:13]
	s_add_i32 m0, s79, 0x2000
	s_add_u32 s80, s12, 0x80000

; #define PG8_STAGE(bufoff, gbase, voff) do { _Pragma("unroll") for (int _i = 0; _i < 2; ++_i) \
;         __builtin_amdgcn_global_load_lds((const unsigned*)((const char*)(gbase) + (voff)[_i]), (PG8_LAS unsigned*)(lds + (bufoff) + ldsw + _i * 8192), 16, 0, 0); } while (0)
; #define PG8_LDA(dst, b, h) do { _Pragma("unroll") for (int m = 0; m < 4; ++m) _Pragma("unroll") for (int k = 0; k < 2; ++k) dst[m][k] = *(const PG8_LAS bf16x8*)(lds + PG8_SA(b, h) + aoff + m * 2048 + k * 1024); } while (0)
; template <class Epi, class Sched, bool ALIGN_EPI = false, bool SP2 = false>
; __device__ __forceinline__ void gemm_phase(PG8_LAS unsigned char* lds, const Gemm g, const Sched& S, const Epi& E) {
;     ...
;             PG8_LDA(At, 0, 1); PG8_STAGE(PG8_SB(0, 0), b2, voffB); PG8_STAGE(PG8_SB(0, 1), b2 + hstep, voffB); PG8_STAGE(PG8_SA(0, 0), a2, voffA);
	s_addc_u32 s81, s13, 0
	s_add_i32 s79, s71, s57
	global_load_lds_dwordx4 v160, s[12:13]

; #define PG8_STAGE(bufoff, gbase, voff) do { _Pragma("unroll") for (int _i = 0; _i < 2; ++_i) \
;         __builtin_amdgcn_global_load_lds((const unsigned*)((const char*)(gbase) + (voff)[_i]), (PG8_LAS unsigned*)(lds + (bufoff) + ldsw + _i * 8192), 16, 0, 0); } while (0)
; #define PG8_LDA(dst, b, h) do { _Pragma("unroll") for (int m = 0; m < 4; ++m) _Pragma("unroll") for (int k = 0; k < 2; ++k) dst[m][k] = *(const PG8_LAS bf16x8*)(lds + PG8_SA(b, h) + aoff + m * 2048 + k * 1024); } while (0)
; template <class Epi, class Sched, bool ALIGN_EPI = false, bool SP2 = false>
; __device__ __forceinline__ void gemm_phase(PG8_LAS unsigned char* lds, const Gemm g, const Sched& S, const Epi& E) {
;     ...
;             PG8_LDA(At, 0, 1); PG8_STAGE(PG8_SB(0, 0), b2, voffB); PG8_STAGE(PG8_SB(0, 1), b2 + hstep, voffB); PG8_STAGE(PG8_SA(0, 0), a2, voffA);
	s_mov_b32 m0, s79
	ds_read_b128 v[210:213], v207 offset:20480
	global_load_lds_dwordx4 v164, s[80:81]

; #define PG8_STAGE(bufoff, gbase, voff) do { _Pragma("unroll") for (int _i = 0; _i < 2; ++_i) \
;         __builtin_amdgcn_global_load_lds((const unsigned*)((const char*)(gbase) + (voff)[_i]), (PG8_LAS unsigned*)(lds + (bufoff) + ldsw + _i * 8192), 16, 0, 0); } while (0)
; #define PG8_LDA(dst, b, h) do { _Pragma("unroll") for (int m = 0; m < 4; ++m) _Pragma("unroll") for (int k = 0; k < 2; ++k) dst[m][k] = *(const PG8_LAS bf16x8*)(lds + PG8_SA(b, h) + aoff + m * 2048 + k * 1024); } while (0)
; template <class Epi, class Sched, bool ALIGN_EPI = false, bool SP2 = false>
; __device__ __forceinline__ void gemm_phase(PG8_LAS unsigned char* lds, const Gemm g, const Sched& S, const Epi& E) {
;     ...
;             PG8_LDA(At, 0, 1); PG8_STAGE(PG8_SB(0, 0), b2, voffB); PG8_STAGE(PG8_SB(0, 1), b2 + hstep, voffB); PG8_STAGE(PG8_SA(0, 0), a2, voffA);
	s_add_i32 m0, s79, 0x2000
	ds_read_b128 v[214:217], v207 offset:21504
	global_load_lds_dwordx4 v160, s[80:81]
	s_mov_b64 s[98:99], s[54:55]

; #define PG8_STAGE(bufoff, gbase, voff) do { _Pragma("unroll") for (int _i = 0; _i < 2; ++_i) \
;         __builtin_amdgcn_global_load_lds((const unsigned*)((const char*)(gbase) + (voff)[_i]), (PG8_LAS unsigned*)(lds + (bufoff) + ldsw + _i * 8192), 16, 0, 0); } while (0)
; #define PG8_LDA(dst, b, h) do { _Pragma("unroll") for (int m = 0; m < 4; ++m) _Pragma("unroll") for (int k = 0; k < 2; ++k) dst[m][k] = *(const PG8_LAS bf16x8*)(lds + PG8_SA(b, h) + aoff + m * 2048 + k * 1024); } while (0)
; #define PG8_MMA(ai, bj, At, Bt) do { __builtin_amdgcn_s_setprio(1); _Pragma("unroll") for (int m = 0; m < 4; ++m) _Pragma("unroll") for (int n = 0; n < 2; ++n) _Pragma("unroll") for (int k = 0; k < 2; ++k) \
;         acc[ai][bj][m][n] = __builtin_amdgcn_mfma_f32_16x16x32_bf16(Bt[n][k], At[m][k], acc[ai][bj][m][n], 0, 0, 0); __builtin_amdgcn_s_setprio(0); } while (0)
; #define PG8_WAIT_V(n) asm volatile("s_waitcnt vmcnt(" #n ")" ::: "memory")
; #define PG8_WAIT_L(n) asm volatile("s_waitcnt lgkmcnt(" #n ")" ::: "memory")
; #define PG8_BAR __builtin_amdgcn_s_barrier()
; #define PG8_SCHED __builtin_amdgcn_sched_barrier(0)
; template <class Epi, class Sched, bool ALIGN_EPI = false, bool SP2 = false>
; __device__ __forceinline__ void gemm_phase(PG8_LAS unsigned char* lds, const Gemm g, const Sched& S, const Epi& E) {
;     ...
;             PG8_LDA(At, 0, 1); PG8_STAGE(PG8_SB(0, 0), b2, voffB); PG8_STAGE(PG8_SB(0, 1), b2 + hstep, voffB); PG8_STAGE(PG8_SA(0, 0), a2, voffA);
;             PG8_WAIT_V(8); PG8_WAIT_L(0); PG8_BAR; PG8_MMA(1, 0, At, B0); PG8_MMA(1, 1, At, B1); PG8_BAR; PG8_SCHED;
	s_mov_b32 m0, s60
	ds_read_b128 v[218:221], v207 offset:22528
	global_load_lds_dwordx4 v166, s[54:55]
	s_mov_b32 m0, s61
	ds_read_b128 v[222:225], v207 offset:23552
	global_load_lds_dwordx4 v162, s[54:55]
	s_waitcnt vmcnt(8)
	s_waitcnt lgkmcnt(0)
	s_barrier
	s_setprio 1
	s_waitcnt lgkmcnt(0)
	v_mfma_f32_16x16x32_bf16 v[60:63], v[128:131], v[176:179], v[60:63]
	v_mfma_f32_16x16x32_bf16 v[56:59], v[136:139], v[176:179], v[56:59]
	v_mfma_f32_16x16x32_bf16 v[52:55], v[128:131], v[184:187], v[52:55]
	v_mfma_f32_16x16x32_bf16 v[40:43], v[136:139], v[184:187], v[40:43]
	v_mfma_f32_16x16x32_bf16 v[36:39], v[128:131], v[210:213], v[36:39]
	v_mfma_f32_16x16x32_bf16 v[24:27], v[136:139], v[210:213], v[24:27]
	v_mfma_f32_16x16x32_bf16 v[20:23], v[128:131], v[218:221], v[20:23]
	v_mfma_f32_16x16x32_bf16 v[8:11], v[136:139], v[218:221], v[8:11]
	v_mfma_f32_16x16x32_bf16 v[60:63], v[132:135], v[180:183], v[60:63]
	v_mfma_f32_16x16x32_bf16 v[56:59], v[140:143], v[180:183], v[56:59]
	v_mfma_f32_16x16x32_bf16 v[52:55], v[132:135], v[192:195], v[52:55]
	v_mfma_f32_16x16x32_bf16 v[40:43], v[140:143], v[192:195], v[40:43]
	v_mfma_f32_16x16x32_bf16 v[36:39], v[132:135], v[214:217], v[36:39]
	v_mfma_f32_16x16x32_bf16 v[24:27], v[140:143], v[214:217], v[24:27]
	v_mfma_f32_16x16x32_bf16 v[20:23], v[132:135], v[222:225], v[20:23]
	v_mfma_f32_16x16x32_bf16 v[8:11], v[140:143], v[222:225], v[8:11]


; #define PG8_STAGE(bufoff, gbase, voff) do { _Pragma("unroll") for (int _i = 0; _i < 2; ++_i) \
;         __builtin_amdgcn_global_load_lds((const unsigned*)((const char*)(gbase) + (voff)[_i]), (PG8_LAS unsigned*)(lds + (bufoff) + ldsw + _i * 8192), 16, 0, 0); } while (0)
; #define PG8_LDA(dst, b, h) do { _Pragma("unroll") for (int m = 0; m < 4; ++m) _Pragma("unroll") for (int k = 0; k < 2; ++k) dst[m][k] = *(const PG8_LAS bf16x8*)(lds + PG8_SA(b, h) + aoff + m * 2048 + k * 1024); } while (0)
; #define PG8_LDB(dst, b, h) do { _Pragma("unroll") for (int n = 0; n < 2; ++n) _Pragma("unroll") for (int k = 0; k < 2; ++k) dst[n][k] = *(const PG8_LAS bf16x8*)(lds + PG8_SB(b, h) + boff + n * 2048 + k * 1024); } while (0)
; #define PG8_MMA(ai, bj, At, Bt) do { __builtin_amdgcn_s_setprio(1); _Pragma("unroll") for (int m = 0; m < 4; ++m) _Pragma("unroll") for (int n = 0; n < 2; ++n) _Pragma("unroll") for (int k = 0; k < 2; ++k) \
;         acc[ai][bj][m][n] = __builtin_amdgcn_mfma_f32_16x16x32_bf16(Bt[n][k], At[m][k], acc[ai][bj][m][n], 0, 0, 0); __builtin_amdgcn_s_setprio(0); } while (0)
; #define PG8_WAIT_V(n) asm volatile("s_waitcnt vmcnt(" #n ")" ::: "memory")
; #define PG8_WAIT_L(n) asm volatile("s_waitcnt lgkmcnt(" #n ")" ::: "memory")
; #define PG8_BAR __builtin_amdgcn_s_barrier()
; #define PG8_SCHED __builtin_amdgcn_sched_barrier(0)
; template <class Epi, class Sched, bool ALIGN_EPI = false, bool SP2 = false>
; __device__ __forceinline__ void gemm_phase(PG8_LAS unsigned char* lds, const Gemm g, const Sched& S, const Epi& E) {
;     ...
;             PG8_WAIT_V(8); PG8_WAIT_L(0); PG8_BAR; PG8_MMA(1, 0, At, B0); PG8_MMA(1, 1, At, B1); PG8_BAR; PG8_SCHED;
;             PG8_LDB(B0, 1, 0); PG8_LDB(B1, 1, 1); PG8_SCHED; PG8_LDA(At, 1, 0); PG8_STAGE(PG8_SA(0, 1), a2 + hstep, voffA);
	v_mfma_f32_16x16x32_bf16 v[48:51], v[144:147], v[176:179], v[48:51]
	v_mfma_f32_16x16x32_bf16 v[44:47], v[152:155], v[176:179], v[44:47]
	v_mfma_f32_16x16x32_bf16 v[32:35], v[144:147], v[184:187], v[32:35]
	v_mfma_f32_16x16x32_bf16 v[28:31], v[152:155], v[184:187], v[28:31]
	v_mfma_f32_16x16x32_bf16 v[16:19], v[144:147], v[210:213], v[16:19]
	v_mfma_f32_16x16x32_bf16 v[12:15], v[152:155], v[210:213], v[12:15]
	v_mfma_f32_16x16x32_bf16 v[4:7], v[144:147], v[218:221], v[4:7]
	v_mfma_f32_16x16x32_bf16 v[0:3], v[152:155], v[218:221], v[0:3]
	v_mfma_f32_16x16x32_bf16 v[48:51], v[148:151], v[180:183], v[48:51]
	v_mfma_f32_16x16x32_bf16 v[44:47], v[156:159], v[180:183], v[44:47]
	v_mfma_f32_16x16x32_bf16 v[32:35], v[148:151], v[192:195], v[32:35]
	v_mfma_f32_16x16x32_bf16 v[28:31], v[156:159], v[192:195], v[28:31]
	v_mfma_f32_16x16x32_bf16 v[16:19], v[148:151], v[214:217], v[16:19]
	v_mfma_f32_16x16x32_bf16 v[12:15], v[156:159], v[214:217], v[12:15]
	v_mfma_f32_16x16x32_bf16 v[4:7], v[148:151], v[222:225], v[4:7]
	v_mfma_f32_16x16x32_bf16 v[0:3], v[156:159], v[222:225], v[0:3]
	s_setprio 0
	s_barrier
	s_add_i32 s79, 0, 0x18000
	s_add_i32 s80, 0, 0x1c000
	v_add_u32_e32 v140, s79, v197
	v_add_u32_e32 v156, s80, v197
	ds_read_b128 v[128:131], v140
	ds_read_b128 v[132:135], v140 offset:1024
	ds_read_b128 v[136:139], v140 offset:2048
	ds_read_b128 v[140:143], v140 offset:3072
	ds_read_b128 v[144:147], v156
	ds_read_b128 v[148:151], v156 offset:1024
	ds_read_b128 v[152:155], v156 offset:2048
	ds_read_b128 v[156:159], v156 offset:3072
	s_add_u32 s54, s54, 0x80000
	s_addc_u32 s55, s55, 0
	s_mov_b32 m0, s62

; #define PG8_STAGE(bufoff, gbase, voff) do { _Pragma("unroll") for (int _i = 0; _i < 2; ++_i) \
;         __builtin_amdgcn_global_load_lds((const unsigned*)((const char*)(gbase) + (voff)[_i]), (PG8_LAS unsigned*)(lds + (bufoff) + ldsw + _i * 8192), 16, 0, 0); } while (0)
; #define PG8_LDA(dst, b, h) do { _Pragma("unroll") for (int m = 0; m < 4; ++m) _Pragma("unroll") for (int k = 0; k < 2; ++k) dst[m][k] = *(const PG8_LAS bf16x8*)(lds + PG8_SA(b, h) + aoff + m * 2048 + k * 1024); } while (0)
; #define PG8_LDB(dst, b, h) do { _Pragma("unroll") for (int n = 0; n < 2; ++n) _Pragma("unroll") for (int k = 0; k < 2; ++k) dst[n][k] = *(const PG8_LAS bf16x8*)(lds + PG8_SB(b, h) + boff + n * 2048 + k * 1024); } while (0)
; #define PG8_SCHED __builtin_amdgcn_sched_barrier(0)
; template <class Epi, class Sched, bool ALIGN_EPI = false, bool SP2 = false>
; __device__ __forceinline__ void gemm_phase(PG8_LAS unsigned char* lds, const Gemm g, const Sched& S, const Epi& E) {
;     ...
;             PG8_LDB(B0, 1, 0); PG8_LDB(B1, 1, 1); PG8_SCHED; PG8_LDA(At, 1, 0); PG8_STAGE(PG8_SA(0, 1), a2 + hstep, voffA);
	ds_read_b128 v[176:179], v207 offset:32768
	ds_read_b128 v[180:183], v207 offset:33792
	ds_read_b128 v[184:187], v207 offset:34816
	ds_read_b128 v[192:195], v207 offset:35840
	ds_read_b128 v[210:213], v207 offset:36864
	ds_read_b128 v[214:217], v207 offset:37888
	ds_read_b128 v[218:221], v207 offset:38912

; #define PG8_STAGE(bufoff, gbase, voff) do { _Pragma("unroll") for (int _i = 0; _i < 2; ++_i) \
;         __builtin_amdgcn_global_load_lds((const unsigned*)((const char*)(gbase) + (voff)[_i]), (PG8_LAS unsigned*)(lds + (bufoff) + ldsw + _i * 8192), 16, 0, 0); } while (0)
; #define PG8_LDA(dst, b, h) do { _Pragma("unroll") for (int m = 0; m < 4; ++m) _Pragma("unroll") for (int k = 0; k < 2; ++k) dst[m][k] = *(const PG8_LAS bf16x8*)(lds + PG8_SA(b, h) + aoff + m * 2048 + k * 1024); } while (0)
; #define PG8_LDB(dst, b, h) do { _Pragma("unroll") for (int n = 0; n < 2; ++n) _Pragma("unroll") for (int k = 0; k < 2; ++k) dst[n][k] = *(const PG8_LAS bf16x8*)(lds + PG8_SB(b, h) + boff + n * 2048 + k * 1024); } while (0)
; #define PG8_SCHED __builtin_amdgcn_sched_barrier(0)
; template <class Epi, class Sched, bool ALIGN_EPI = false, bool SP2 = false>
; __device__ __forceinline__ void gemm_phase(PG8_LAS unsigned char* lds, const Gemm g, const Sched& S, const Epi& E) {
;     ...
;             PG8_LDB(B0, 1, 0); PG8_LDB(B1, 1, 1); PG8_SCHED; PG8_LDA(At, 1, 0); PG8_STAGE(PG8_SA(0, 1), a2 + hstep, voffA);
	global_load_lds_dwordx4 v166, s[54:55]

; #define PG8_STAGE(bufoff, gbase, voff) do { _Pragma("unroll") for (int _i = 0; _i < 2; ++_i) \
;         __builtin_amdgcn_global_load_lds((const unsigned*)((const char*)(gbase) + (voff)[_i]), (PG8_LAS unsigned*)(lds + (bufoff) + ldsw + _i * 8192), 16, 0, 0); } while (0)
; #define PG8_LDA(dst, b, h) do { _Pragma("unroll") for (int m = 0; m < 4; ++m) _Pragma("unroll") for (int k = 0; k < 2; ++k) dst[m][k] = *(const PG8_LAS bf16x8*)(lds + PG8_SA(b, h) + aoff + m * 2048 + k * 1024); } while (0)
; #define PG8_LDB(dst, b, h) do { _Pragma("unroll") for (int n = 0; n < 2; ++n) _Pragma("unroll") for (int k = 0; k < 2; ++k) dst[n][k] = *(const PG8_LAS bf16x8*)(lds + PG8_SB(b, h) + boff + n * 2048 + k * 1024); } while (0)
; #define PG8_MMA(ai, bj, At, Bt) do { __builtin_amdgcn_s_setprio(1); _Pragma("unroll") for (int m = 0; m < 4; ++m) _Pragma("unroll") for (int n = 0; n < 2; ++n) _Pragma("unroll") for (int k = 0; k < 2; ++k) \
;         acc[ai][bj][m][n] = __builtin_amdgcn_mfma_f32_16x16x32_bf16(Bt[n][k], At[m][k], acc[ai][bj][m][n], 0, 0, 0); __builtin_amdgcn_s_setprio(0); } while (0)
; #define PG8_WAIT_V(n) asm volatile("s_waitcnt vmcnt(" #n ")" ::: "memory")
; #define PG8_WAIT_L(n) asm volatile("s_waitcnt lgkmcnt(" #n ")" ::: "memory")
; #define PG8_BAR __builtin_amdgcn_s_barrier()
; #define PG8_SCHED __builtin_amdgcn_sched_barrier(0)
; template <class Epi, class Sched, bool ALIGN_EPI = false, bool SP2 = false>
; __device__ __forceinline__ void gemm_phase(PG8_LAS unsigned char* lds, const Gemm g, const Sched& S, const Epi& E) {
;     ...
;             PG8_LDB(B0, 1, 0); PG8_LDB(B1, 1, 1); PG8_SCHED; PG8_LDA(At, 1, 0); PG8_STAGE(PG8_SA(0, 1), a2 + hstep, voffA);
;             PG8_WAIT_V(8); PG8_WAIT_L(0); PG8_BAR; PG8_MMA(0, 0, At, B0); PG8_MMA(0, 1, At, B1); PG8_BAR; PG8_SCHED;
	s_mov_b32 m0, s63
	ds_read_b128 v[222:225], v207 offset:39936
	global_load_lds_dwordx4 v162, s[54:55]
	s_waitcnt vmcnt(8)
	s_waitcnt lgkmcnt(0)
	s_barrier
	s_setprio 1
	s_waitcnt lgkmcnt(0)
	v_mfma_f32_16x16x32_bf16 v[124:127], v[128:131], v[176:179], v[124:127]
	v_mfma_f32_16x16x32_bf16 v[120:123], v[136:139], v[176:179], v[120:123]
	v_mfma_f32_16x16x32_bf16 v[112:115], v[128:131], v[184:187], v[112:115]
	v_mfma_f32_16x16x32_bf16 v[104:107], v[136:139], v[184:187], v[104:107]
	v_mfma_f32_16x16x32_bf16 v[100:103], v[128:131], v[210:213], v[100:103]
	v_mfma_f32_16x16x32_bf16 v[88:91], v[136:139], v[210:213], v[88:91]
	v_mfma_f32_16x16x32_bf16 v[84:87], v[128:131], v[218:221], v[84:87]
	v_mfma_f32_16x16x32_bf16 v[72:75], v[136:139], v[218:221], v[72:75]
	v_mfma_f32_16x16x32_bf16 v[124:127], v[132:135], v[180:183], v[124:127]
	v_mfma_f32_16x16x32_bf16 v[120:123], v[140:143], v[180:183], v[120:123]
	v_mfma_f32_16x16x32_bf16 v[112:115], v[132:135], v[192:195], v[112:115]
	v_mfma_f32_16x16x32_bf16 v[104:107], v[140:143], v[192:195], v[104:107]
	v_mfma_f32_16x16x32_bf16 v[100:103], v[132:135], v[214:217], v[100:103]
	v_mfma_f32_16x16x32_bf16 v[88:91], v[140:143], v[214:217], v[88:91]
	v_mfma_f32_16x16x32_bf16 v[84:87], v[132:135], v[222:225], v[84:87]
	v_mfma_f32_16x16x32_bf16 v[72:75], v[140:143], v[222:225], v[72:75]


; #define PG8_MMA(ai, bj, At, Bt) do { __builtin_amdgcn_s_setprio(1); _Pragma("unroll") for (int m = 0; m < 4; ++m) _Pragma("unroll") for (int n = 0; n < 2; ++n) _Pragma("unroll") for (int k = 0; k < 2; ++k) \
;         acc[ai][bj][m][n] = __builtin_amdgcn_mfma_f32_16x16x32_bf16(Bt[n][k], At[m][k], acc[ai][bj][m][n], 0, 0, 0); __builtin_amdgcn_s_setprio(0); } while (0)
; #define PG8_WAIT_V(n) asm volatile("s_waitcnt vmcnt(" #n ")" ::: "memory")
; #define PG8_WAIT_L(n) asm volatile("s_waitcnt lgkmcnt(" #n ")" ::: "memory")
; #define PG8_BAR __builtin_amdgcn_s_barrier()
; #define PG8_SCHED __builtin_amdgcn_sched_barrier(0)
; template <class Epi, class Sched, bool ALIGN_EPI = false, bool SP2 = false>
; __device__ __forceinline__ void gemm_phase(PG8_LAS unsigned char* lds, const Gemm g, const Sched& S, const Epi& E) {
;     ...
;             PG8_WAIT_V(8); PG8_WAIT_L(0); PG8_BAR; PG8_MMA(0, 0, At, B0); PG8_MMA(0, 1, At, B1); PG8_BAR; PG8_SCHED;
	v_mfma_f32_16x16x32_bf16 v[116:119], v[144:147], v[176:179], v[116:119]
	v_mfma_f32_16x16x32_bf16 v[108:111], v[152:155], v[176:179], v[108:111]
	v_mfma_f32_16x16x32_bf16 v[96:99], v[144:147], v[184:187], v[96:99]
	v_mfma_f32_16x16x32_bf16 v[92:95], v[152:155], v[184:187], v[92:95]
	v_mfma_f32_16x16x32_bf16 v[80:83], v[144:147], v[210:213], v[80:83]
	v_mfma_f32_16x16x32_bf16 v[76:79], v[152:155], v[210:213], v[76:79]
	v_mfma_f32_16x16x32_bf16 v[68:71], v[144:147], v[218:221], v[68:71]
	v_mfma_f32_16x16x32_bf16 v[64:67], v[152:155], v[218:221], v[64:67]
	v_mfma_f32_16x16x32_bf16 v[116:119], v[148:151], v[180:183], v[116:119]
	v_mfma_f32_16x16x32_bf16 v[108:111], v[156:159], v[180:183], v[108:111]
	v_mfma_f32_16x16x32_bf16 v[96:99], v[148:151], v[192:195], v[96:99]
	v_mfma_f32_16x16x32_bf16 v[92:95], v[156:159], v[192:195], v[92:95]
	v_mfma_f32_16x16x32_bf16 v[80:83], v[148:151], v[214:217], v[80:83]
	v_mfma_f32_16x16x32_bf16 v[76:79], v[156:159], v[214:217], v[76:79]
	v_mfma_f32_16x16x32_bf16 v[68:71], v[148:151], v[222:225], v[68:71]
	v_mfma_f32_16x16x32_bf16 v[64:67], v[156:159], v[222:225], v[64:67]
	s_setprio 0
	s_barrier
	s_add_i32 s54, s79, s57

; #define PG8_STAGE(bufoff, gbase, voff) do { _Pragma("unroll") for (int _i = 0; _i < 2; ++_i) \
;         __builtin_amdgcn_global_load_lds((const unsigned*)((const char*)(gbase) + (voff)[_i]), (PG8_LAS unsigned*)(lds + (bufoff) + ldsw + _i * 8192), 16, 0, 0); } while (0)
; #define PG8_LDA(dst, b, h) do { _Pragma("unroll") for (int m = 0; m < 4; ++m) _Pragma("unroll") for (int k = 0; k < 2; ++k) dst[m][k] = *(const PG8_LAS bf16x8*)(lds + PG8_SA(b, h) + aoff + m * 2048 + k * 1024); } while (0)
; template <class Epi, class Sched, bool ALIGN_EPI = false, bool SP2 = false>
; __device__ __forceinline__ void gemm_phase(PG8_LAS unsigned char* lds, const Gemm g, const Sched& S, const Epi& E) {
;     ...
;             PG8_LDA(At, 1, 1); PG8_STAGE(PG8_SB(1, 0), b3, voffB); PG8_STAGE(PG8_SB(1, 1), b3 + hstep, voffB); PG8_STAGE(PG8_SA(1, 0), a3, voffA);
	s_mov_b32 m0, s54
	ds_read_b128 v[176:179], v207 offset:49152
	ds_read_b128 v[180:183], v207 offset:50176
	ds_read_b128 v[184:187], v207 offset:51200
	ds_read_b128 v[192:195], v207 offset:52224


; #define PG8_STAGE(bufoff, gbase, voff) do { _Pragma("unroll") for (int _i = 0; _i < 2; ++_i) \
;         __builtin_amdgcn_global_load_lds((const unsigned*)((const char*)(gbase) + (voff)[_i]), (PG8_LAS unsigned*)(lds + (bufoff) + ldsw + _i * 8192), 16, 0, 0); } while (0)
; #define PG8_LDA(dst, b, h) do { _Pragma("unroll") for (int m = 0; m < 4; ++m) _Pragma("unroll") for (int k = 0; k < 2; ++k) dst[m][k] = *(const PG8_LAS bf16x8*)(lds + PG8_SA(b, h) + aoff + m * 2048 + k * 1024); } while (0)
; template <class Epi, class Sched, bool ALIGN_EPI = false, bool SP2 = false>
; __device__ __forceinline__ void gemm_phase(PG8_LAS unsigned char* lds, const Gemm g, const Sched& S, const Epi& E) {
;     ...
;             PG8_LDA(At, 1, 1); PG8_STAGE(PG8_SB(1, 0), b3, voffB); PG8_STAGE(PG8_SB(1, 1), b3 + hstep, voffB); PG8_STAGE(PG8_SA(1, 0), a3, voffA);
	global_load_lds_dwordx4 v250, s[96:97]
	s_add_i32 m0, s54, 0x2000
	s_add_u32 s12, s12, 0x80080

; #define PG8_STAGE(bufoff, gbase, voff) do { _Pragma("unroll") for (int _i = 0; _i < 2; ++_i) \
;         __builtin_amdgcn_global_load_lds((const unsigned*)((const char*)(gbase) + (voff)[_i]), (PG8_LAS unsigned*)(lds + (bufoff) + ldsw + _i * 8192), 16, 0, 0); } while (0)
; #define PG8_LDA(dst, b, h) do { _Pragma("unroll") for (int m = 0; m < 4; ++m) _Pragma("unroll") for (int k = 0; k < 2; ++k) dst[m][k] = *(const PG8_LAS bf16x8*)(lds + PG8_SA(b, h) + aoff + m * 2048 + k * 1024); } while (0)
; template <class Epi, class Sched, bool ALIGN_EPI = false, bool SP2 = false>
; __device__ __forceinline__ void gemm_phase(PG8_LAS unsigned char* lds, const Gemm g, const Sched& S, const Epi& E) {
;     ...
;             PG8_LDA(At, 1, 1); PG8_STAGE(PG8_SB(1, 0), b3, voffB); PG8_STAGE(PG8_SB(1, 1), b3 + hstep, voffB); PG8_STAGE(PG8_SA(1, 0), a3, voffA);
	s_addc_u32 s13, s13, 0
	s_add_i32 s54, s80, s57
	global_load_lds_dwordx4 v251, s[96:97]

; #define PG8_STAGE(bufoff, gbase, voff) do { _Pragma("unroll") for (int _i = 0; _i < 2; ++_i) \
;         __builtin_amdgcn_global_load_lds((const unsigned*)((const char*)(gbase) + (voff)[_i]), (PG8_LAS unsigned*)(lds + (bufoff) + ldsw + _i * 8192), 16, 0, 0); } while (0)
; #define PG8_LDA(dst, b, h) do { _Pragma("unroll") for (int m = 0; m < 4; ++m) _Pragma("unroll") for (int k = 0; k < 2; ++k) dst[m][k] = *(const PG8_LAS bf16x8*)(lds + PG8_SA(b, h) + aoff + m * 2048 + k * 1024); } while (0)
; template <class Epi, class Sched, bool ALIGN_EPI = false, bool SP2 = false>
; __device__ __forceinline__ void gemm_phase(PG8_LAS unsigned char* lds, const Gemm g, const Sched& S, const Epi& E) {
;     ...
;             PG8_LDA(At, 1, 1); PG8_STAGE(PG8_SB(1, 0), b3, voffB); PG8_STAGE(PG8_SB(1, 1), b3 + hstep, voffB); PG8_STAGE(PG8_SA(1, 0), a3, voffA);
	s_mov_b32 m0, s54
	ds_read_b128 v[210:213], v207 offset:53248
	global_load_lds_dwordx4 v164, s[12:13]

; #define PG8_STAGE(bufoff, gbase, voff) do { _Pragma("unroll") for (int _i = 0; _i < 2; ++_i) \
;         __builtin_amdgcn_global_load_lds((const unsigned*)((const char*)(gbase) + (voff)[_i]), (PG8_LAS unsigned*)(lds + (bufoff) + ldsw + _i * 8192), 16, 0, 0); } while (0)
; #define PG8_LDA(dst, b, h) do { _Pragma("unroll") for (int m = 0; m < 4; ++m) _Pragma("unroll") for (int k = 0; k < 2; ++k) dst[m][k] = *(const PG8_LAS bf16x8*)(lds + PG8_SA(b, h) + aoff + m * 2048 + k * 1024); } while (0)
; template <class Epi, class Sched, bool ALIGN_EPI = false, bool SP2 = false>
; __device__ __forceinline__ void gemm_phase(PG8_LAS unsigned char* lds, const Gemm g, const Sched& S, const Epi& E) {
;     ...
;             PG8_LDA(At, 1, 1); PG8_STAGE(PG8_SB(1, 0), b3, voffB); PG8_STAGE(PG8_SB(1, 1), b3 + hstep, voffB); PG8_STAGE(PG8_SA(1, 0), a3, voffA);
	s_add_i32 m0, s54, 0x2000
	ds_read_b128 v[214:217], v207 offset:54272
	global_load_lds_dwordx4 v160, s[12:13]

; #define PG8_STAGE(bufoff, gbase, voff) do { _Pragma("unroll") for (int _i = 0; _i < 2; ++_i) \
;         __builtin_amdgcn_global_load_lds((const unsigned*)((const char*)(gbase) + (voff)[_i]), (PG8_LAS unsigned*)(lds + (bufoff) + ldsw + _i * 8192), 16, 0, 0); } while (0)
; #define PG8_LDA(dst, b, h) do { _Pragma("unroll") for (int m = 0; m < 4; ++m) _Pragma("unroll") for (int k = 0; k < 2; ++k) dst[m][k] = *(const PG8_LAS bf16x8*)(lds + PG8_SA(b, h) + aoff + m * 2048 + k * 1024); } while (0)
; template <class Epi, class Sched, bool ALIGN_EPI = false, bool SP2 = false>
; __device__ __forceinline__ void gemm_phase(PG8_LAS unsigned char* lds, const Gemm g, const Sched& S, const Epi& E) {
;     ...
;             PG8_LDA(At, 1, 1); PG8_STAGE(PG8_SB(1, 0), b3, voffB); PG8_STAGE(PG8_SB(1, 1), b3 + hstep, voffB); PG8_STAGE(PG8_SA(1, 0), a3, voffA);
	s_mov_b32 m0, s65
	ds_read_b128 v[218:221], v207 offset:55296
	global_load_lds_dwordx4 v252, s[98:99]

; #define PG8_STAGE(bufoff, gbase, voff) do { _Pragma("unroll") for (int _i = 0; _i < 2; ++_i) \
;         __builtin_amdgcn_global_load_lds((const unsigned*)((const char*)(gbase) + (voff)[_i]), (PG8_LAS unsigned*)(lds + (bufoff) + ldsw + _i * 8192), 16, 0, 0); } while (0)
; #define PG8_LDA(dst, b, h) do { _Pragma("unroll") for (int m = 0; m < 4; ++m) _Pragma("unroll") for (int k = 0; k < 2; ++k) dst[m][k] = *(const PG8_LAS bf16x8*)(lds + PG8_SA(b, h) + aoff + m * 2048 + k * 1024); } while (0)
; #define PG8_MMA(ai, bj, At, Bt) do { __builtin_amdgcn_s_setprio(1); _Pragma("unroll") for (int m = 0; m < 4; ++m) _Pragma("unroll") for (int n = 0; n < 2; ++n) _Pragma("unroll") for (int k = 0; k < 2; ++k) \
;         acc[ai][bj][m][n] = __builtin_amdgcn_mfma_f32_16x16x32_bf16(Bt[n][k], At[m][k], acc[ai][bj][m][n], 0, 0, 0); __builtin_amdgcn_s_setprio(0); } while (0)
; #define PG8_WAIT_V(n) asm volatile("s_waitcnt vmcnt(" #n ")" ::: "memory")
; #define PG8_WAIT_L(n) asm volatile("s_waitcnt lgkmcnt(" #n ")" ::: "memory")
; #define PG8_BAR __builtin_amdgcn_s_barrier()
; #define PG8_SCHED __builtin_amdgcn_sched_barrier(0)
; template <class Epi, class Sched, bool ALIGN_EPI = false, bool SP2 = false>
; __device__ __forceinline__ void gemm_phase(PG8_LAS unsigned char* lds, const Gemm g, const Sched& S, const Epi& E) {
;     ...
;             PG8_LDA(At, 1, 1); PG8_STAGE(PG8_SB(1, 0), b3, voffB); PG8_STAGE(PG8_SB(1, 1), b3 + hstep, voffB); PG8_STAGE(PG8_SA(1, 0), a3, voffA);
;             PG8_WAIT_V(8); PG8_WAIT_L(0); PG8_BAR; PG8_MMA(1, 0, At, B0); PG8_MMA(1, 1, At, B1); PG8_BAR; PG8_SCHED;
	s_mov_b32 m0, s67
	ds_read_b128 v[222:225], v207 offset:56320
	global_load_lds_dwordx4 v253, s[98:99]
	s_waitcnt vmcnt(8)
	s_waitcnt lgkmcnt(0)
	s_barrier
	s_setprio 1
	s_waitcnt lgkmcnt(0)
	v_mfma_f32_16x16x32_bf16 v[60:63], v[128:131], v[176:179], v[60:63]
	v_mfma_f32_16x16x32_bf16 v[56:59], v[136:139], v[176:179], v[56:59]
	v_mfma_f32_16x16x32_bf16 v[52:55], v[128:131], v[184:187], v[52:55]
	v_mfma_f32_16x16x32_bf16 v[40:43], v[136:139], v[184:187], v[40:43]
	v_mfma_f32_16x16x32_bf16 v[36:39], v[128:131], v[210:213], v[36:39]
	v_mfma_f32_16x16x32_bf16 v[24:27], v[136:139], v[210:213], v[24:27]
	v_mfma_f32_16x16x32_bf16 v[20:23], v[128:131], v[218:221], v[20:23]
	v_mfma_f32_16x16x32_bf16 v[8:11], v[136:139], v[218:221], v[8:11]
	v_mfma_f32_16x16x32_bf16 v[60:63], v[132:135], v[180:183], v[60:63]
	v_mfma_f32_16x16x32_bf16 v[56:59], v[140:143], v[180:183], v[56:59]
	v_mfma_f32_16x16x32_bf16 v[52:55], v[132:135], v[192:195], v[52:55]
	v_mfma_f32_16x16x32_bf16 v[40:43], v[140:143], v[192:195], v[40:43]
	v_mfma_f32_16x16x32_bf16 v[36:39], v[132:135], v[214:217], v[36:39]
	v_mfma_f32_16x16x32_bf16 v[24:27], v[140:143], v[214:217], v[24:27]
	v_mfma_f32_16x16x32_bf16 v[20:23], v[132:135], v[222:225], v[20:23]
	v_mfma_f32_16x16x32_bf16 v[8:11], v[140:143], v[222:225], v[8:11]


; #define PG8_STAGE(bufoff, gbase, voff) do { _Pragma("unroll") for (int _i = 0; _i < 2; ++_i) \
;         __builtin_amdgcn_global_load_lds((const unsigned*)((const char*)(gbase) + (voff)[_i]), (PG8_LAS unsigned*)(lds + (bufoff) + ldsw + _i * 8192), 16, 0, 0); } while (0)
; #define PG8_LDA(dst, b, h) do { _Pragma("unroll") for (int m = 0; m < 4; ++m) _Pragma("unroll") for (int k = 0; k < 2; ++k) dst[m][k] = *(const PG8_LAS bf16x8*)(lds + PG8_SA(b, h) + aoff + m * 2048 + k * 1024); } while (0)
; #define PG8_LDB(dst, b, h) do { _Pragma("unroll") for (int n = 0; n < 2; ++n) _Pragma("unroll") for (int k = 0; k < 2; ++k) dst[n][k] = *(const PG8_LAS bf16x8*)(lds + PG8_SB(b, h) + boff + n * 2048 + k * 1024); } while (0)
; template <class Epi, class Sched, bool ALIGN_EPI = false, bool SP2 = false>
; __device__ __forceinline__ void gemm_phase(PG8_LAS unsigned char* lds, const Gemm g, const Sched& S, const Epi& E) {
;     ...
;             PG8_WAIT_V(8); PG8_WAIT_L(0); PG8_BAR; PG8_MMA(1, 0, At, B0); PG8_MMA(1, 1, At, B1); PG8_BAR; PG8_SCHED;
;             } else {
;             PG8_LDB(B0, 0, 0); PG8_SCHED; PG8_LDA(At, 0, 0); PG8_STAGE(PG8_SA(1, 1), a1 + hstep, voffA);
;             PG8_WAIT_L(8); PG8_BAR; PG8_WAIT_L(0); PG8_MMA(0, 0, At, B0); PG8_BAR; PG8_SCHED;
;             PG8_LDB(B1, 0, 1); PG8_STAGE(PG8_SB(0, 0), b2, voffB);
;             PG8_BAR; PG8_WAIT_L(0); PG8_MMA(0, 1, At, B1); PG8_BAR;
;             PG8_LDA(At, 0, 1); PG8_STAGE(PG8_SA(0, 0), a2, voffA);
;             PG8_BAR; PG8_WAIT_L(0); PG8_MMA(1, 0, At, B0); PG8_BAR; PG8_SCHED;
;             PG8_STAGE(PG8_SB(0, 1), b2 + hstep, voffB);
;             PG8_WAIT_V(6); PG8_BAR; PG8_MMA(1, 1, At, B1); PG8_BAR;
;             PG8_LDB(B0, 1, 0); PG8_SCHED; PG8_LDA(At, 1, 0); PG8_STAGE(PG8_SA(0, 1), a2 + hstep, voffA);
;             PG8_WAIT_L(8); PG8_BAR; PG8_WAIT_L(0); PG8_MMA(0, 0, At, B0); PG8_BAR; PG8_SCHED;
;             PG8_LDB(B1, 1, 1); PG8_STAGE(PG8_SB(1, 0), b3, voffB);
;             PG8_BAR; PG8_WAIT_L(0); PG8_MMA(0, 1, At, B1); PG8_BAR;
;             PG8_LDA(At, 1, 1); PG8_STAGE(PG8_SA(1, 0), a3, voffA);
;             PG8_BAR; PG8_WAIT_L(0); PG8_MMA(1, 0, At, B0); PG8_BAR; PG8_SCHED;
;             PG8_STAGE(PG8_SB(1, 1), b3 + hstep, voffB);
;             PG8_WAIT_V(6); PG8_BAR; PG8_MMA(1, 1, At, B1); PG8_BAR;
;             }
;         }
;         if constexpr (ALIGN_EPI) { if (wr == 0) PG8_BAR; }
	v_mfma_f32_16x16x32_bf16 v[48:51], v[144:147], v[176:179], v[48:51]
	v_mfma_f32_16x16x32_bf16 v[44:47], v[152:155], v[176:179], v[44:47]
	v_mfma_f32_16x16x32_bf16 v[32:35], v[144:147], v[184:187], v[32:35]
	v_mfma_f32_16x16x32_bf16 v[28:31], v[152:155], v[184:187], v[28:31]
	v_mfma_f32_16x16x32_bf16 v[16:19], v[144:147], v[210:213], v[16:19]
	v_mfma_f32_16x16x32_bf16 v[12:15], v[152:155], v[210:213], v[12:15]
	v_mfma_f32_16x16x32_bf16 v[4:7], v[144:147], v[218:221], v[4:7]
	v_mfma_f32_16x16x32_bf16 v[0:3], v[152:155], v[218:221], v[0:3]
	v_mfma_f32_16x16x32_bf16 v[48:51], v[148:151], v[180:183], v[48:51]
	v_mfma_f32_16x16x32_bf16 v[44:47], v[156:159], v[180:183], v[44:47]
	v_mfma_f32_16x16x32_bf16 v[32:35], v[148:151], v[192:195], v[32:35]
	v_mfma_f32_16x16x32_bf16 v[28:31], v[156:159], v[192:195], v[28:31]
	v_mfma_f32_16x16x32_bf16 v[16:19], v[148:151], v[214:217], v[16:19]
	v_mfma_f32_16x16x32_bf16 v[12:15], v[156:159], v[214:217], v[12:15]
	v_mfma_f32_16x16x32_bf16 v[4:7], v[148:151], v[222:225], v[4:7]
	v_mfma_f32_16x16x32_bf16 v[0:3], v[156:159], v[222:225], v[0:3]
	s_setprio 0
	s_barrier
	s_add_i32 s78, s78, 2
	s_add_u32 s10, s10, 0x100
	s_addc_u32 s11, s11, 0
	s_add_u32 s76, s76, 0x100
	s_addc_u32 s77, s77, 0
	s_cmp_gt_u32 s78, 29
	s_cbranch_scc0 .LBB0_679
	s_and_b64 vcc, exec, s[42:43]
	s_cbranch_vccz .LBB0_682
	s_barrier

; #define PG8_STAGE(bufoff, gbase, voff) do { _Pragma("unroll") for (int _i = 0; _i < 2; ++_i) \
;         __builtin_amdgcn_global_load_lds((const unsigned*)((const char*)(gbase) + (voff)[_i]), (PG8_LAS unsigned*)(lds + (bufoff) + ldsw + _i * 8192), 16, 0, 0); } while (0)
; #define PG8_LDA(dst, b, h) do { _Pragma("unroll") for (int m = 0; m < 4; ++m) _Pragma("unroll") for (int k = 0; k < 2; ++k) dst[m][k] = *(const PG8_LAS bf16x8*)(lds + PG8_SA(b, h) + aoff + m * 2048 + k * 1024); } while (0)
; #define PG8_LDB(dst, b, h) do { _Pragma("unroll") for (int n = 0; n < 2; ++n) _Pragma("unroll") for (int k = 0; k < 2; ++k) dst[n][k] = *(const PG8_LAS bf16x8*)(lds + PG8_SB(b, h) + boff + n * 2048 + k * 1024); } while (0)
; #define PG8_SCHED __builtin_amdgcn_sched_barrier(0)
; template <class Epi, class Sched, bool ALIGN_EPI = false, bool SP2 = false>
; __device__ __forceinline__ void gemm_phase(PG8_LAS unsigned char* lds, const Gemm g, const Sched& S, const Epi& E) {
;     ...
;         for (int t = 0; t < nt; t += 2) {
;             const bool last = (t == nt - 2);
;             const char* a1 = cA + (size_t)(t + 1) * kstep;
;             const char* a2 = last ? nA : cA + (size_t)(t + 2) * kstep; const char* b2 = last ? nB : cB + (size_t)(t + 2) * kstep;
;             const char* a3 = a2 + kstep; const char* b3 = b2 + kstep;
;             if (last && has_next) S.a_ready(nxt);
;             if constexpr (SP2) {
;             PG8_LDB(B0, 0, 0); PG8_LDB(B1, 0, 1); PG8_SCHED; PG8_LDA(At, 0, 0); PG8_STAGE(PG8_SA(1, 1), a1 + hstep, voffA);
.LBB0_939:
	ds_read_b128 v[64:67], v213
	ds_read_b128 v[68:71], v213 offset:1024
	ds_read_b128 v[72:75], v213 offset:2048
	ds_read_b128 v[76:79], v213 offset:3072
	ds_read_b128 v[144:147], v214
	ds_read_b128 v[148:151], v214 offset:1024
	ds_read_b128 v[152:155], v214 offset:2048
	ds_read_b128 v[156:159], v214 offset:3072
	s_add_u32 s60, s58, 0xfff80080
	s_addc_u32 s61, s59, -1
	s_cmp_eq_u32 s81, 28
	s_cselect_b32 s63, s11, s61
	s_cselect_b32 s62, s51, s60
	s_cselect_b32 s61, s49, s80
	s_cselect_b32 s60, s78, s79

; #define PG8_STAGE(bufoff, gbase, voff) do { _Pragma("unroll") for (int _i = 0; _i < 2; ++_i) \
;         __builtin_amdgcn_global_load_lds((const unsigned*)((const char*)(gbase) + (voff)[_i]), (PG8_LAS unsigned*)(lds + (bufoff) + ldsw + _i * 8192), 16, 0, 0); } while (0)
; #define PG8_LDA(dst, b, h) do { _Pragma("unroll") for (int m = 0; m < 4; ++m) _Pragma("unroll") for (int k = 0; k < 2; ++k) dst[m][k] = *(const PG8_LAS bf16x8*)(lds + PG8_SA(b, h) + aoff + m * 2048 + k * 1024); } while (0)
; #define PG8_LDB(dst, b, h) do { _Pragma("unroll") for (int n = 0; n < 2; ++n) _Pragma("unroll") for (int k = 0; k < 2; ++k) dst[n][k] = *(const PG8_LAS bf16x8*)(lds + PG8_SB(b, h) + boff + n * 2048 + k * 1024); } while (0)
; #define PG8_SCHED __builtin_amdgcn_sched_barrier(0)
; template <class Epi, class Sched, bool ALIGN_EPI = false, bool SP2 = false>
; __device__ __forceinline__ void gemm_phase(PG8_LAS unsigned char* lds, const Gemm g, const Sched& S, const Epi& E) {
;     ...
;             PG8_LDB(B0, 0, 0); PG8_LDB(B1, 0, 1); PG8_SCHED; PG8_LDA(At, 0, 0); PG8_STAGE(PG8_SA(1, 1), a1 + hstep, voffA);
	s_add_i32 m0, s57, 0xc000
	ds_read_b128 v[176:179], v215
	ds_read_b128 v[180:183], v215 offset:1024
	ds_read_b128 v[184:187], v215 offset:2048
	ds_read_b128 v[188:191], v215 offset:3072
	ds_read_b128 v[192:195], v215 offset:4096
	ds_read_b128 v[196:199], v215 offset:5120
	ds_read_b128 v[200:203], v215 offset:6144

; #define PG8_STAGE(bufoff, gbase, voff) do { _Pragma("unroll") for (int _i = 0; _i < 2; ++_i) \
;         __builtin_amdgcn_global_load_lds((const unsigned*)((const char*)(gbase) + (voff)[_i]), (PG8_LAS unsigned*)(lds + (bufoff) + ldsw + _i * 8192), 16, 0, 0); } while (0)
; #define PG8_LDA(dst, b, h) do { _Pragma("unroll") for (int m = 0; m < 4; ++m) _Pragma("unroll") for (int k = 0; k < 2; ++k) dst[m][k] = *(const PG8_LAS bf16x8*)(lds + PG8_SA(b, h) + aoff + m * 2048 + k * 1024); } while (0)
; #define PG8_LDB(dst, b, h) do { _Pragma("unroll") for (int n = 0; n < 2; ++n) _Pragma("unroll") for (int k = 0; k < 2; ++k) dst[n][k] = *(const PG8_LAS bf16x8*)(lds + PG8_SB(b, h) + boff + n * 2048 + k * 1024); } while (0)
; #define PG8_SCHED __builtin_amdgcn_sched_barrier(0)
; template <class Epi, class Sched, bool ALIGN_EPI = false, bool SP2 = false>
; __device__ __forceinline__ void gemm_phase(PG8_LAS unsigned char* lds, const Gemm g, const Sched& S, const Epi& E) {
;     ...
;             PG8_LDB(B0, 0, 0); PG8_LDB(B1, 0, 1); PG8_SCHED; PG8_LDA(At, 0, 0); PG8_STAGE(PG8_SA(1, 1), a1 + hstep, voffA);
	global_load_lds_dwordx4 v168, s[58:59]

; #define PG8_STAGE(bufoff, gbase, voff) do { _Pragma("unroll") for (int _i = 0; _i < 2; ++_i) \
;         __builtin_amdgcn_global_load_lds((const unsigned*)((const char*)(gbase) + (voff)[_i]), (PG8_LAS unsigned*)(lds + (bufoff) + ldsw + _i * 8192), 16, 0, 0); } while (0)
; #define PG8_LDA(dst, b, h) do { _Pragma("unroll") for (int m = 0; m < 4; ++m) _Pragma("unroll") for (int k = 0; k < 2; ++k) dst[m][k] = *(const PG8_LAS bf16x8*)(lds + PG8_SA(b, h) + aoff + m * 2048 + k * 1024); } while (0)
; #define PG8_LDB(dst, b, h) do { _Pragma("unroll") for (int n = 0; n < 2; ++n) _Pragma("unroll") for (int k = 0; k < 2; ++k) dst[n][k] = *(const PG8_LAS bf16x8*)(lds + PG8_SB(b, h) + boff + n * 2048 + k * 1024); } while (0)
; #define PG8_MMA(ai, bj, At, Bt) do { __builtin_amdgcn_s_setprio(1); _Pragma("unroll") for (int m = 0; m < 4; ++m) _Pragma("unroll") for (int n = 0; n < 2; ++n) _Pragma("unroll") for (int k = 0; k < 2; ++k) \
;         acc[ai][bj][m][n] = __builtin_amdgcn_mfma_f32_16x16x32_bf16(Bt[n][k], At[m][k], acc[ai][bj][m][n], 0, 0, 0); __builtin_amdgcn_s_setprio(0); } while (0)
; #define PG8_WAIT_V(n) asm volatile("s_waitcnt vmcnt(" #n ")" ::: "memory")
; #define PG8_WAIT_L(n) asm volatile("s_waitcnt lgkmcnt(" #n ")" ::: "memory")
; #define PG8_BAR __builtin_amdgcn_s_barrier()
; #define PG8_SCHED __builtin_amdgcn_sched_barrier(0)
; template <class Epi, class Sched, bool ALIGN_EPI = false, bool SP2 = false>
; __device__ __forceinline__ void gemm_phase(PG8_LAS unsigned char* lds, const Gemm g, const Sched& S, const Epi& E) {
;     ...
;             PG8_LDB(B0, 0, 0); PG8_LDB(B1, 0, 1); PG8_SCHED; PG8_LDA(At, 0, 0); PG8_STAGE(PG8_SA(1, 1), a1 + hstep, voffA);
;             PG8_WAIT_V(8); PG8_WAIT_L(0); PG8_BAR; PG8_MMA(0, 0, At, B0); PG8_MMA(0, 1, At, B1); PG8_BAR; PG8_SCHED;
	s_add_i32 m0, s57, 0xe000
	ds_read_b128 v[204:207], v215 offset:7168
	global_load_lds_dwordx4 v170, s[58:59]
	s_waitcnt vmcnt(8)
	s_waitcnt lgkmcnt(0)
	s_barrier
	s_setprio 1
	s_waitcnt lgkmcnt(0)
	v_mfma_f32_16x16x32_bf16 v[140:143], v[64:67], v[176:179], v[140:143]
	v_mfma_f32_16x16x32_bf16 v[136:139], v[72:75], v[176:179], v[136:139]
	v_mfma_f32_16x16x32_bf16 v[124:127], v[64:67], v[184:187], v[124:127]
	v_mfma_f32_16x16x32_bf16 v[120:123], v[72:75], v[184:187], v[120:123]
	v_mfma_f32_16x16x32_bf16 v[108:111], v[64:67], v[192:195], v[108:111]
	v_mfma_f32_16x16x32_bf16 v[104:107], v[72:75], v[192:195], v[104:107]
	v_mfma_f32_16x16x32_bf16 v[92:95], v[64:67], v[200:203], v[92:95]
	v_mfma_f32_16x16x32_bf16 v[88:91], v[72:75], v[200:203], v[88:91]
	v_mfma_f32_16x16x32_bf16 v[140:143], v[68:71], v[180:183], v[140:143]
	v_mfma_f32_16x16x32_bf16 v[136:139], v[76:79], v[180:183], v[136:139]
	v_mfma_f32_16x16x32_bf16 v[124:127], v[68:71], v[188:191], v[124:127]
	v_mfma_f32_16x16x32_bf16 v[120:123], v[76:79], v[188:191], v[120:123]
	v_mfma_f32_16x16x32_bf16 v[108:111], v[68:71], v[196:199], v[108:111]
	v_mfma_f32_16x16x32_bf16 v[104:107], v[76:79], v[196:199], v[104:107]
	v_mfma_f32_16x16x32_bf16 v[92:95], v[68:71], v[204:207], v[92:95]
	v_mfma_f32_16x16x32_bf16 v[88:91], v[76:79], v[204:207], v[88:91]


; #define PG8_STAGE(bufoff, gbase, voff) do { _Pragma("unroll") for (int _i = 0; _i < 2; ++_i) \
;         __builtin_amdgcn_global_load_lds((const unsigned*)((const char*)(gbase) + (voff)[_i]), (PG8_LAS unsigned*)(lds + (bufoff) + ldsw + _i * 8192), 16, 0, 0); } while (0)
; #define PG8_LDA(dst, b, h) do { _Pragma("unroll") for (int m = 0; m < 4; ++m) _Pragma("unroll") for (int k = 0; k < 2; ++k) dst[m][k] = *(const PG8_LAS bf16x8*)(lds + PG8_SA(b, h) + aoff + m * 2048 + k * 1024); } while (0)
; #define PG8_MMA(ai, bj, At, Bt) do { __builtin_amdgcn_s_setprio(1); _Pragma("unroll") for (int m = 0; m < 4; ++m) _Pragma("unroll") for (int n = 0; n < 2; ++n) _Pragma("unroll") for (int k = 0; k < 2; ++k) \
;         acc[ai][bj][m][n] = __builtin_amdgcn_mfma_f32_16x16x32_bf16(Bt[n][k], At[m][k], acc[ai][bj][m][n], 0, 0, 0); __builtin_amdgcn_s_setprio(0); } while (0)
; #define PG8_WAIT_V(n) asm volatile("s_waitcnt vmcnt(" #n ")" ::: "memory")
; #define PG8_WAIT_L(n) asm volatile("s_waitcnt lgkmcnt(" #n ")" ::: "memory")
; #define PG8_BAR __builtin_amdgcn_s_barrier()
; #define PG8_SCHED __builtin_amdgcn_sched_barrier(0)
; template <class Epi, class Sched, bool ALIGN_EPI = false, bool SP2 = false>
; __device__ __forceinline__ void gemm_phase(PG8_LAS unsigned char* lds, const Gemm g, const Sched& S, const Epi& E) {
;     ...
;             PG8_WAIT_V(8); PG8_WAIT_L(0); PG8_BAR; PG8_MMA(0, 0, At, B0); PG8_MMA(0, 1, At, B1); PG8_BAR; PG8_SCHED;
;             PG8_LDA(At, 0, 1); PG8_STAGE(PG8_SB(0, 0), b2, voffB); PG8_STAGE(PG8_SB(0, 1), b2 + hstep, voffB); PG8_STAGE(PG8_SA(0, 0), a2, voffA);
	v_mfma_f32_16x16x32_bf16 v[132:135], v[144:147], v[176:179], v[132:135]
	v_mfma_f32_16x16x32_bf16 v[128:131], v[152:155], v[176:179], v[128:131]
	v_mfma_f32_16x16x32_bf16 v[116:119], v[144:147], v[184:187], v[116:119]
	v_mfma_f32_16x16x32_bf16 v[112:115], v[152:155], v[184:187], v[112:115]
	v_mfma_f32_16x16x32_bf16 v[100:103], v[144:147], v[192:195], v[100:103]
	v_mfma_f32_16x16x32_bf16 v[96:99], v[152:155], v[192:195], v[96:99]
	v_mfma_f32_16x16x32_bf16 v[84:87], v[144:147], v[200:203], v[84:87]
	v_mfma_f32_16x16x32_bf16 v[80:83], v[152:155], v[200:203], v[80:83]
	v_mfma_f32_16x16x32_bf16 v[132:135], v[148:151], v[180:183], v[132:135]
	v_mfma_f32_16x16x32_bf16 v[128:131], v[156:159], v[180:183], v[128:131]
	v_mfma_f32_16x16x32_bf16 v[116:119], v[148:151], v[188:191], v[116:119]
	v_mfma_f32_16x16x32_bf16 v[112:115], v[156:159], v[188:191], v[112:115]
	v_mfma_f32_16x16x32_bf16 v[100:103], v[148:151], v[196:199], v[100:103]
	v_mfma_f32_16x16x32_bf16 v[96:99], v[156:159], v[196:199], v[96:99]
	v_mfma_f32_16x16x32_bf16 v[84:87], v[148:151], v[204:207], v[84:87]
	v_mfma_f32_16x16x32_bf16 v[80:83], v[156:159], v[204:207], v[80:83]
	s_setprio 0
	s_barrier
	s_add_i32 s82, s75, s64
	s_mov_b64 s[96:97], s[60:61]

; #define PG8_STAGE(bufoff, gbase, voff) do { _Pragma("unroll") for (int _i = 0; _i < 2; ++_i) \
;         __builtin_amdgcn_global_load_lds((const unsigned*)((const char*)(gbase) + (voff)[_i]), (PG8_LAS unsigned*)(lds + (bufoff) + ldsw + _i * 8192), 16, 0, 0); } while (0)
; #define PG8_LDA(dst, b, h) do { _Pragma("unroll") for (int m = 0; m < 4; ++m) _Pragma("unroll") for (int k = 0; k < 2; ++k) dst[m][k] = *(const PG8_LAS bf16x8*)(lds + PG8_SA(b, h) + aoff + m * 2048 + k * 1024); } while (0)
; template <class Epi, class Sched, bool ALIGN_EPI = false, bool SP2 = false>
; __device__ __forceinline__ void gemm_phase(PG8_LAS unsigned char* lds, const Gemm g, const Sched& S, const Epi& E) {
;     ...
;             PG8_LDA(At, 0, 1); PG8_STAGE(PG8_SB(0, 0), b2, voffB); PG8_STAGE(PG8_SB(0, 1), b2 + hstep, voffB); PG8_STAGE(PG8_SA(0, 0), a2, voffA);
	s_mov_b32 m0, s82
	ds_read_b128 v[176:179], v215 offset:16384
	ds_read_b128 v[180:183], v215 offset:17408
	ds_read_b128 v[184:187], v215 offset:18432
	ds_read_b128 v[188:191], v215 offset:19456


; #define PG8_STAGE(bufoff, gbase, voff) do { _Pragma("unroll") for (int _i = 0; _i < 2; ++_i) \
;         __builtin_amdgcn_global_load_lds((const unsigned*)((const char*)(gbase) + (voff)[_i]), (PG8_LAS unsigned*)(lds + (bufoff) + ldsw + _i * 8192), 16, 0, 0); } while (0)
; #define PG8_LDA(dst, b, h) do { _Pragma("unroll") for (int m = 0; m < 4; ++m) _Pragma("unroll") for (int k = 0; k < 2; ++k) dst[m][k] = *(const PG8_LAS bf16x8*)(lds + PG8_SA(b, h) + aoff + m * 2048 + k * 1024); } while (0)
; template <class Epi, class Sched, bool ALIGN_EPI = false, bool SP2 = false>
; __device__ __forceinline__ void gemm_phase(PG8_LAS unsigned char* lds, const Gemm g, const Sched& S, const Epi& E) {
;     ...
;             PG8_LDA(At, 0, 1); PG8_STAGE(PG8_SB(0, 0), b2, voffB); PG8_STAGE(PG8_SB(0, 1), b2 + hstep, voffB); PG8_STAGE(PG8_SA(0, 0), a2, voffA);
	global_load_lds_dwordx4 v162, s[60:61]
	s_add_i32 m0, s82, 0x2000
	s_add_u32 s82, s60, 0x80000

; #define PG8_STAGE(bufoff, gbase, voff) do { _Pragma("unroll") for (int _i = 0; _i < 2; ++_i) \
;         __builtin_amdgcn_global_load_lds((const unsigned*)((const char*)(gbase) + (voff)[_i]), (PG8_LAS unsigned*)(lds + (bufoff) + ldsw + _i * 8192), 16, 0, 0); } while (0)
; #define PG8_LDA(dst, b, h) do { _Pragma("unroll") for (int m = 0; m < 4; ++m) _Pragma("unroll") for (int k = 0; k < 2; ++k) dst[m][k] = *(const PG8_LAS bf16x8*)(lds + PG8_SA(b, h) + aoff + m * 2048 + k * 1024); } while (0)
; template <class Epi, class Sched, bool ALIGN_EPI = false, bool SP2 = false>
; __device__ __forceinline__ void gemm_phase(PG8_LAS unsigned char* lds, const Gemm g, const Sched& S, const Epi& E) {
;     ...
;             PG8_LDA(At, 0, 1); PG8_STAGE(PG8_SB(0, 0), b2, voffB); PG8_STAGE(PG8_SB(0, 1), b2 + hstep, voffB); PG8_STAGE(PG8_SA(0, 0), a2, voffA);
	s_addc_u32 s83, s61, 0
	s_add_i32 s84, s76, s64
	global_load_lds_dwordx4 v166, s[60:61]

; #define PG8_STAGE(bufoff, gbase, voff) do { _Pragma("unroll") for (int _i = 0; _i < 2; ++_i) \
;         __builtin_amdgcn_global_load_lds((const unsigned*)((const char*)(gbase) + (voff)[_i]), (PG8_LAS unsigned*)(lds + (bufoff) + ldsw + _i * 8192), 16, 0, 0); } while (0)
; #define PG8_LDA(dst, b, h) do { _Pragma("unroll") for (int m = 0; m < 4; ++m) _Pragma("unroll") for (int k = 0; k < 2; ++k) dst[m][k] = *(const PG8_LAS bf16x8*)(lds + PG8_SA(b, h) + aoff + m * 2048 + k * 1024); } while (0)
; template <class Epi, class Sched, bool ALIGN_EPI = false, bool SP2 = false>
; __device__ __forceinline__ void gemm_phase(PG8_LAS unsigned char* lds, const Gemm g, const Sched& S, const Epi& E) {
;     ...
;             PG8_LDA(At, 0, 1); PG8_STAGE(PG8_SB(0, 0), b2, voffB); PG8_STAGE(PG8_SB(0, 1), b2 + hstep, voffB); PG8_STAGE(PG8_SA(0, 0), a2, voffA);
	s_mov_b32 m0, s84
	ds_read_b128 v[192:195], v215 offset:20480
	global_load_lds_dwordx4 v162, s[82:83]

; #define PG8_STAGE(bufoff, gbase, voff) do { _Pragma("unroll") for (int _i = 0; _i < 2; ++_i) \
;         __builtin_amdgcn_global_load_lds((const unsigned*)((const char*)(gbase) + (voff)[_i]), (PG8_LAS unsigned*)(lds + (bufoff) + ldsw + _i * 8192), 16, 0, 0); } while (0)
; #define PG8_LDA(dst, b, h) do { _Pragma("unroll") for (int m = 0; m < 4; ++m) _Pragma("unroll") for (int k = 0; k < 2; ++k) dst[m][k] = *(const PG8_LAS bf16x8*)(lds + PG8_SA(b, h) + aoff + m * 2048 + k * 1024); } while (0)
; template <class Epi, class Sched, bool ALIGN_EPI = false, bool SP2 = false>
; __device__ __forceinline__ void gemm_phase(PG8_LAS unsigned char* lds, const Gemm g, const Sched& S, const Epi& E) {
;     ...
;             PG8_LDA(At, 0, 1); PG8_STAGE(PG8_SB(0, 0), b2, voffB); PG8_STAGE(PG8_SB(0, 1), b2 + hstep, voffB); PG8_STAGE(PG8_SA(0, 0), a2, voffA);
	s_add_i32 m0, s84, 0x2000
	ds_read_b128 v[196:199], v215 offset:21504
	global_load_lds_dwordx4 v166, s[82:83]
	s_mov_b64 s[98:99], s[62:63]

; #define PG8_STAGE(bufoff, gbase, voff) do { _Pragma("unroll") for (int _i = 0; _i < 2; ++_i) \
;         __builtin_amdgcn_global_load_lds((const unsigned*)((const char*)(gbase) + (voff)[_i]), (PG8_LAS unsigned*)(lds + (bufoff) + ldsw + _i * 8192), 16, 0, 0); } while (0)
; #define PG8_LDA(dst, b, h) do { _Pragma("unroll") for (int m = 0; m < 4; ++m) _Pragma("unroll") for (int k = 0; k < 2; ++k) dst[m][k] = *(const PG8_LAS bf16x8*)(lds + PG8_SA(b, h) + aoff + m * 2048 + k * 1024); } while (0)
; #define PG8_MMA(ai, bj, At, Bt) do { __builtin_amdgcn_s_setprio(1); _Pragma("unroll") for (int m = 0; m < 4; ++m) _Pragma("unroll") for (int n = 0; n < 2; ++n) _Pragma("unroll") for (int k = 0; k < 2; ++k) \
;         acc[ai][bj][m][n] = __builtin_amdgcn_mfma_f32_16x16x32_bf16(Bt[n][k], At[m][k], acc[ai][bj][m][n], 0, 0, 0); __builtin_amdgcn_s_setprio(0); } while (0)
; #define PG8_WAIT_V(n) asm volatile("s_waitcnt vmcnt(" #n ")" ::: "memory")
; #define PG8_WAIT_L(n) asm volatile("s_waitcnt lgkmcnt(" #n ")" ::: "memory")
; #define PG8_BAR __builtin_amdgcn_s_barrier()
; #define PG8_SCHED __builtin_amdgcn_sched_barrier(0)
; template <class Epi, class Sched, bool ALIGN_EPI = false, bool SP2 = false>
; __device__ __forceinline__ void gemm_phase(PG8_LAS unsigned char* lds, const Gemm g, const Sched& S, const Epi& E) {
;     ...
;             PG8_LDA(At, 0, 1); PG8_STAGE(PG8_SB(0, 0), b2, voffB); PG8_STAGE(PG8_SB(0, 1), b2 + hstep, voffB); PG8_STAGE(PG8_SA(0, 0), a2, voffA);
;             PG8_WAIT_V(8); PG8_WAIT_L(0); PG8_BAR; PG8_MMA(1, 0, At, B0); PG8_MMA(1, 1, At, B1); PG8_BAR; PG8_SCHED;
	s_mov_b32 m0, s57
	ds_read_b128 v[200:203], v215 offset:22528
	global_load_lds_dwordx4 v160, s[62:63]
	s_mov_b32 m0, s65
	ds_read_b128 v[204:207], v215 offset:23552
	global_load_lds_dwordx4 v164, s[62:63]
	s_waitcnt vmcnt(8)
	s_waitcnt lgkmcnt(0)
	s_barrier
	s_setprio 1
	s_waitcnt lgkmcnt(0)
	v_mfma_f32_16x16x32_bf16 v[60:63], v[64:67], v[176:179], v[60:63]
	v_mfma_f32_16x16x32_bf16 v[56:59], v[72:75], v[176:179], v[56:59]
	v_mfma_f32_16x16x32_bf16 v[44:47], v[64:67], v[184:187], v[44:47]
	v_mfma_f32_16x16x32_bf16 v[40:43], v[72:75], v[184:187], v[40:43]
	v_mfma_f32_16x16x32_bf16 v[28:31], v[64:67], v[192:195], v[28:31]
	v_mfma_f32_16x16x32_bf16 v[24:27], v[72:75], v[192:195], v[24:27]
	v_mfma_f32_16x16x32_bf16 v[12:15], v[64:67], v[200:203], v[12:15]
	v_mfma_f32_16x16x32_bf16 v[8:11], v[72:75], v[200:203], v[8:11]
	v_mfma_f32_16x16x32_bf16 v[60:63], v[68:71], v[180:183], v[60:63]
	v_mfma_f32_16x16x32_bf16 v[56:59], v[76:79], v[180:183], v[56:59]
	v_mfma_f32_16x16x32_bf16 v[44:47], v[68:71], v[188:191], v[44:47]
	v_mfma_f32_16x16x32_bf16 v[40:43], v[76:79], v[188:191], v[40:43]
	v_mfma_f32_16x16x32_bf16 v[28:31], v[68:71], v[196:199], v[28:31]
	v_mfma_f32_16x16x32_bf16 v[24:27], v[76:79], v[196:199], v[24:27]
	v_mfma_f32_16x16x32_bf16 v[12:15], v[68:71], v[204:207], v[12:15]
	v_mfma_f32_16x16x32_bf16 v[8:11], v[76:79], v[204:207], v[8:11]


; #define PG8_STAGE(bufoff, gbase, voff) do { _Pragma("unroll") for (int _i = 0; _i < 2; ++_i) \
;         __builtin_amdgcn_global_load_lds((const unsigned*)((const char*)(gbase) + (voff)[_i]), (PG8_LAS unsigned*)(lds + (bufoff) + ldsw + _i * 8192), 16, 0, 0); } while (0)
; #define PG8_LDA(dst, b, h) do { _Pragma("unroll") for (int m = 0; m < 4; ++m) _Pragma("unroll") for (int k = 0; k < 2; ++k) dst[m][k] = *(const PG8_LAS bf16x8*)(lds + PG8_SA(b, h) + aoff + m * 2048 + k * 1024); } while (0)
; #define PG8_LDB(dst, b, h) do { _Pragma("unroll") for (int n = 0; n < 2; ++n) _Pragma("unroll") for (int k = 0; k < 2; ++k) dst[n][k] = *(const PG8_LAS bf16x8*)(lds + PG8_SB(b, h) + boff + n * 2048 + k * 1024); } while (0)
; #define PG8_MMA(ai, bj, At, Bt) do { __builtin_amdgcn_s_setprio(1); _Pragma("unroll") for (int m = 0; m < 4; ++m) _Pragma("unroll") for (int n = 0; n < 2; ++n) _Pragma("unroll") for (int k = 0; k < 2; ++k) \
;         acc[ai][bj][m][n] = __builtin_amdgcn_mfma_f32_16x16x32_bf16(Bt[n][k], At[m][k], acc[ai][bj][m][n], 0, 0, 0); __builtin_amdgcn_s_setprio(0); } while (0)
; #define PG8_WAIT_V(n) asm volatile("s_waitcnt vmcnt(" #n ")" ::: "memory")
; #define PG8_WAIT_L(n) asm volatile("s_waitcnt lgkmcnt(" #n ")" ::: "memory")
; #define PG8_BAR __builtin_amdgcn_s_barrier()
; #define PG8_SCHED __builtin_amdgcn_sched_barrier(0)
; template <class Epi, class Sched, bool ALIGN_EPI = false, bool SP2 = false>
; __device__ __forceinline__ void gemm_phase(PG8_LAS unsigned char* lds, const Gemm g, const Sched& S, const Epi& E) {
;     ...
;             PG8_WAIT_V(8); PG8_WAIT_L(0); PG8_BAR; PG8_MMA(1, 0, At, B0); PG8_MMA(1, 1, At, B1); PG8_BAR; PG8_SCHED;
;             PG8_LDB(B0, 1, 0); PG8_LDB(B1, 1, 1); PG8_SCHED; PG8_LDA(At, 1, 0); PG8_STAGE(PG8_SA(0, 1), a2 + hstep, voffA);
	v_mfma_f32_16x16x32_bf16 v[52:55], v[144:147], v[176:179], v[52:55]
	v_mfma_f32_16x16x32_bf16 v[48:51], v[152:155], v[176:179], v[48:51]
	v_mfma_f32_16x16x32_bf16 v[36:39], v[144:147], v[184:187], v[36:39]
	v_mfma_f32_16x16x32_bf16 v[32:35], v[152:155], v[184:187], v[32:35]
	v_mfma_f32_16x16x32_bf16 v[20:23], v[144:147], v[192:195], v[20:23]
	v_mfma_f32_16x16x32_bf16 v[16:19], v[152:155], v[192:195], v[16:19]
	v_mfma_f32_16x16x32_bf16 v[4:7], v[144:147], v[200:203], v[4:7]
	v_mfma_f32_16x16x32_bf16 v[0:3], v[152:155], v[200:203], v[0:3]
	v_mfma_f32_16x16x32_bf16 v[52:55], v[148:151], v[180:183], v[52:55]
	v_mfma_f32_16x16x32_bf16 v[48:51], v[156:159], v[180:183], v[48:51]
	v_mfma_f32_16x16x32_bf16 v[36:39], v[148:151], v[188:191], v[36:39]
	v_mfma_f32_16x16x32_bf16 v[32:35], v[156:159], v[188:191], v[32:35]
	v_mfma_f32_16x16x32_bf16 v[20:23], v[148:151], v[196:199], v[20:23]
	v_mfma_f32_16x16x32_bf16 v[16:19], v[156:159], v[196:199], v[16:19]
	v_mfma_f32_16x16x32_bf16 v[4:7], v[148:151], v[204:207], v[4:7]
	v_mfma_f32_16x16x32_bf16 v[0:3], v[156:159], v[204:207], v[0:3]
	s_setprio 0
	s_barrier
	s_add_i32 s82, 0, 0x18000
	s_add_i32 s83, 0, 0x1c000
	v_add_u32_e32 v76, s82, v211
	v_add_u32_e32 v156, s83, v211
	ds_read_b128 v[64:67], v76
	ds_read_b128 v[68:71], v76 offset:1024
	ds_read_b128 v[72:75], v76 offset:2048
	ds_read_b128 v[76:79], v76 offset:3072
	ds_read_b128 v[144:147], v156
	ds_read_b128 v[148:151], v156 offset:1024
	ds_read_b128 v[152:155], v156 offset:2048
	ds_read_b128 v[156:159], v156 offset:3072
	s_add_u32 s62, s62, 0x80000
	s_addc_u32 s63, s63, 0
	s_mov_b32 m0, s67

; #define PG8_STAGE(bufoff, gbase, voff) do { _Pragma("unroll") for (int _i = 0; _i < 2; ++_i) \
;         __builtin_amdgcn_global_load_lds((const unsigned*)((const char*)(gbase) + (voff)[_i]), (PG8_LAS unsigned*)(lds + (bufoff) + ldsw + _i * 8192), 16, 0, 0); } while (0)
; #define PG8_LDA(dst, b, h) do { _Pragma("unroll") for (int m = 0; m < 4; ++m) _Pragma("unroll") for (int k = 0; k < 2; ++k) dst[m][k] = *(const PG8_LAS bf16x8*)(lds + PG8_SA(b, h) + aoff + m * 2048 + k * 1024); } while (0)
; #define PG8_LDB(dst, b, h) do { _Pragma("unroll") for (int n = 0; n < 2; ++n) _Pragma("unroll") for (int k = 0; k < 2; ++k) dst[n][k] = *(const PG8_LAS bf16x8*)(lds + PG8_SB(b, h) + boff + n * 2048 + k * 1024); } while (0)
; #define PG8_SCHED __builtin_amdgcn_sched_barrier(0)
; template <class Epi, class Sched, bool ALIGN_EPI = false, bool SP2 = false>
; __device__ __forceinline__ void gemm_phase(PG8_LAS unsigned char* lds, const Gemm g, const Sched& S, const Epi& E) {
;     ...
;             PG8_LDB(B0, 1, 0); PG8_LDB(B1, 1, 1); PG8_SCHED; PG8_LDA(At, 1, 0); PG8_STAGE(PG8_SA(0, 1), a2 + hstep, voffA);
	ds_read_b128 v[176:179], v215 offset:32768
	ds_read_b128 v[180:183], v215 offset:33792
	ds_read_b128 v[184:187], v215 offset:34816
	ds_read_b128 v[188:191], v215 offset:35840
	ds_read_b128 v[192:195], v215 offset:36864
	ds_read_b128 v[196:199], v215 offset:37888
	ds_read_b128 v[200:203], v215 offset:38912

; #define PG8_STAGE(bufoff, gbase, voff) do { _Pragma("unroll") for (int _i = 0; _i < 2; ++_i) \
;         __builtin_amdgcn_global_load_lds((const unsigned*)((const char*)(gbase) + (voff)[_i]), (PG8_LAS unsigned*)(lds + (bufoff) + ldsw + _i * 8192), 16, 0, 0); } while (0)
; #define PG8_LDA(dst, b, h) do { _Pragma("unroll") for (int m = 0; m < 4; ++m) _Pragma("unroll") for (int k = 0; k < 2; ++k) dst[m][k] = *(const PG8_LAS bf16x8*)(lds + PG8_SA(b, h) + aoff + m * 2048 + k * 1024); } while (0)
; #define PG8_LDB(dst, b, h) do { _Pragma("unroll") for (int n = 0; n < 2; ++n) _Pragma("unroll") for (int k = 0; k < 2; ++k) dst[n][k] = *(const PG8_LAS bf16x8*)(lds + PG8_SB(b, h) + boff + n * 2048 + k * 1024); } while (0)
; #define PG8_SCHED __builtin_amdgcn_sched_barrier(0)
; template <class Epi, class Sched, bool ALIGN_EPI = false, bool SP2 = false>
; __device__ __forceinline__ void gemm_phase(PG8_LAS unsigned char* lds, const Gemm g, const Sched& S, const Epi& E) {
;     ...
;             PG8_LDB(B0, 1, 0); PG8_LDB(B1, 1, 1); PG8_SCHED; PG8_LDA(At, 1, 0); PG8_STAGE(PG8_SA(0, 1), a2 + hstep, voffA);
	global_load_lds_dwordx4 v160, s[62:63]

; #define PG8_STAGE(bufoff, gbase, voff) do { _Pragma("unroll") for (int _i = 0; _i < 2; ++_i) \
;         __builtin_amdgcn_global_load_lds((const unsigned*)((const char*)(gbase) + (voff)[_i]), (PG8_LAS unsigned*)(lds + (bufoff) + ldsw + _i * 8192), 16, 0, 0); } while (0)
; #define PG8_LDA(dst, b, h) do { _Pragma("unroll") for (int m = 0; m < 4; ++m) _Pragma("unroll") for (int k = 0; k < 2; ++k) dst[m][k] = *(const PG8_LAS bf16x8*)(lds + PG8_SA(b, h) + aoff + m * 2048 + k * 1024); } while (0)
; #define PG8_LDB(dst, b, h) do { _Pragma("unroll") for (int n = 0; n < 2; ++n) _Pragma("unroll") for (int k = 0; k < 2; ++k) dst[n][k] = *(const PG8_LAS bf16x8*)(lds + PG8_SB(b, h) + boff + n * 2048 + k * 1024); } while (0)
; #define PG8_MMA(ai, bj, At, Bt) do { __builtin_amdgcn_s_setprio(1); _Pragma("unroll") for (int m = 0; m < 4; ++m) _Pragma("unroll") for (int n = 0; n < 2; ++n) _Pragma("unroll") for (int k = 0; k < 2; ++k) \
;         acc[ai][bj][m][n] = __builtin_amdgcn_mfma_f32_16x16x32_bf16(Bt[n][k], At[m][k], acc[ai][bj][m][n], 0, 0, 0); __builtin_amdgcn_s_setprio(0); } while (0)
; #define PG8_WAIT_V(n) asm volatile("s_waitcnt vmcnt(" #n ")" ::: "memory")
; #define PG8_WAIT_L(n) asm volatile("s_waitcnt lgkmcnt(" #n ")" ::: "memory")
; #define PG8_BAR __builtin_amdgcn_s_barrier()
; #define PG8_SCHED __builtin_amdgcn_sched_barrier(0)
; template <class Epi, class Sched, bool ALIGN_EPI = false, bool SP2 = false>
; __device__ __forceinline__ void gemm_phase(PG8_LAS unsigned char* lds, const Gemm g, const Sched& S, const Epi& E) {
;     ...
;             PG8_LDB(B0, 1, 0); PG8_LDB(B1, 1, 1); PG8_SCHED; PG8_LDA(At, 1, 0); PG8_STAGE(PG8_SA(0, 1), a2 + hstep, voffA);
;             PG8_WAIT_V(8); PG8_WAIT_L(0); PG8_BAR; PG8_MMA(0, 0, At, B0); PG8_MMA(0, 1, At, B1); PG8_BAR; PG8_SCHED;
	s_mov_b32 m0, s68
	ds_read_b128 v[204:207], v215 offset:39936
	global_load_lds_dwordx4 v164, s[62:63]
	s_waitcnt vmcnt(8)
	s_waitcnt lgkmcnt(0)
	s_barrier
	s_setprio 1
	s_waitcnt lgkmcnt(0)
	v_mfma_f32_16x16x32_bf16 v[140:143], v[64:67], v[176:179], v[140:143]
	v_mfma_f32_16x16x32_bf16 v[136:139], v[72:75], v[176:179], v[136:139]
	v_mfma_f32_16x16x32_bf16 v[124:127], v[64:67], v[184:187], v[124:127]
	v_mfma_f32_16x16x32_bf16 v[120:123], v[72:75], v[184:187], v[120:123]
	v_mfma_f32_16x16x32_bf16 v[108:111], v[64:67], v[192:195], v[108:111]
	v_mfma_f32_16x16x32_bf16 v[104:107], v[72:75], v[192:195], v[104:107]
	v_mfma_f32_16x16x32_bf16 v[92:95], v[64:67], v[200:203], v[92:95]
	v_mfma_f32_16x16x32_bf16 v[88:91], v[72:75], v[200:203], v[88:91]
	v_mfma_f32_16x16x32_bf16 v[140:143], v[68:71], v[180:183], v[140:143]
	v_mfma_f32_16x16x32_bf16 v[136:139], v[76:79], v[180:183], v[136:139]
	v_mfma_f32_16x16x32_bf16 v[124:127], v[68:71], v[188:191], v[124:127]
	v_mfma_f32_16x16x32_bf16 v[120:123], v[76:79], v[188:191], v[120:123]
	v_mfma_f32_16x16x32_bf16 v[108:111], v[68:71], v[196:199], v[108:111]
	v_mfma_f32_16x16x32_bf16 v[104:107], v[76:79], v[196:199], v[104:107]
	v_mfma_f32_16x16x32_bf16 v[92:95], v[68:71], v[204:207], v[92:95]
	v_mfma_f32_16x16x32_bf16 v[88:91], v[76:79], v[204:207], v[88:91]


; #define PG8_STAGE(bufoff, gbase, voff) do { _Pragma("unroll") for (int _i = 0; _i < 2; ++_i) \
;         __builtin_amdgcn_global_load_lds((const unsigned*)((const char*)(gbase) + (voff)[_i]), (PG8_LAS unsigned*)(lds + (bufoff) + ldsw + _i * 8192), 16, 0, 0); } while (0)
; #define PG8_LDA(dst, b, h) do { _Pragma("unroll") for (int m = 0; m < 4; ++m) _Pragma("unroll") for (int k = 0; k < 2; ++k) dst[m][k] = *(const PG8_LAS bf16x8*)(lds + PG8_SA(b, h) + aoff + m * 2048 + k * 1024); } while (0)
; #define PG8_MMA(ai, bj, At, Bt) do { __builtin_amdgcn_s_setprio(1); _Pragma("unroll") for (int m = 0; m < 4; ++m) _Pragma("unroll") for (int n = 0; n < 2; ++n) _Pragma("unroll") for (int k = 0; k < 2; ++k) \
;         acc[ai][bj][m][n] = __builtin_amdgcn_mfma_f32_16x16x32_bf16(Bt[n][k], At[m][k], acc[ai][bj][m][n], 0, 0, 0); __builtin_amdgcn_s_setprio(0); } while (0)
; #define PG8_WAIT_V(n) asm volatile("s_waitcnt vmcnt(" #n ")" ::: "memory")
; #define PG8_WAIT_L(n) asm volatile("s_waitcnt lgkmcnt(" #n ")" ::: "memory")
; #define PG8_BAR __builtin_amdgcn_s_barrier()
; #define PG8_SCHED __builtin_amdgcn_sched_barrier(0)
; template <class Epi, class Sched, bool ALIGN_EPI = false, bool SP2 = false>
; __device__ __forceinline__ void gemm_phase(PG8_LAS unsigned char* lds, const Gemm g, const Sched& S, const Epi& E) {
;     ...
;             PG8_WAIT_V(8); PG8_WAIT_L(0); PG8_BAR; PG8_MMA(0, 0, At, B0); PG8_MMA(0, 1, At, B1); PG8_BAR; PG8_SCHED;
;             PG8_LDA(At, 1, 1); PG8_STAGE(PG8_SB(1, 0), b3, voffB); PG8_STAGE(PG8_SB(1, 1), b3 + hstep, voffB); PG8_STAGE(PG8_SA(1, 0), a3, voffA);
	v_mfma_f32_16x16x32_bf16 v[132:135], v[144:147], v[176:179], v[132:135]
	v_mfma_f32_16x16x32_bf16 v[128:131], v[152:155], v[176:179], v[128:131]
	v_mfma_f32_16x16x32_bf16 v[116:119], v[144:147], v[184:187], v[116:119]
	v_mfma_f32_16x16x32_bf16 v[112:115], v[152:155], v[184:187], v[112:115]
	v_mfma_f32_16x16x32_bf16 v[100:103], v[144:147], v[192:195], v[100:103]
	v_mfma_f32_16x16x32_bf16 v[96:99], v[152:155], v[192:195], v[96:99]
	v_mfma_f32_16x16x32_bf16 v[84:87], v[144:147], v[200:203], v[84:87]
	v_mfma_f32_16x16x32_bf16 v[80:83], v[152:155], v[200:203], v[80:83]
	v_mfma_f32_16x16x32_bf16 v[132:135], v[148:151], v[180:183], v[132:135]
	v_mfma_f32_16x16x32_bf16 v[128:131], v[156:159], v[180:183], v[128:131]
	v_mfma_f32_16x16x32_bf16 v[116:119], v[148:151], v[188:191], v[116:119]
	v_mfma_f32_16x16x32_bf16 v[112:115], v[156:159], v[188:191], v[112:115]
	v_mfma_f32_16x16x32_bf16 v[100:103], v[148:151], v[196:199], v[100:103]
	v_mfma_f32_16x16x32_bf16 v[96:99], v[156:159], v[196:199], v[96:99]
	v_mfma_f32_16x16x32_bf16 v[84:87], v[148:151], v[204:207], v[84:87]
	v_mfma_f32_16x16x32_bf16 v[80:83], v[156:159], v[204:207], v[80:83]
	s_setprio 0
	s_barrier
	s_add_i32 s62, s82, s64

; #define PG8_STAGE(bufoff, gbase, voff) do { _Pragma("unroll") for (int _i = 0; _i < 2; ++_i) \
;         __builtin_amdgcn_global_load_lds((const unsigned*)((const char*)(gbase) + (voff)[_i]), (PG8_LAS unsigned*)(lds + (bufoff) + ldsw + _i * 8192), 16, 0, 0); } while (0)
; #define PG8_LDA(dst, b, h) do { _Pragma("unroll") for (int m = 0; m < 4; ++m) _Pragma("unroll") for (int k = 0; k < 2; ++k) dst[m][k] = *(const PG8_LAS bf16x8*)(lds + PG8_SA(b, h) + aoff + m * 2048 + k * 1024); } while (0)
; template <class Epi, class Sched, bool ALIGN_EPI = false, bool SP2 = false>
; __device__ __forceinline__ void gemm_phase(PG8_LAS unsigned char* lds, const Gemm g, const Sched& S, const Epi& E) {
;     ...
;             PG8_LDA(At, 1, 1); PG8_STAGE(PG8_SB(1, 0), b3, voffB); PG8_STAGE(PG8_SB(1, 1), b3 + hstep, voffB); PG8_STAGE(PG8_SA(1, 0), a3, voffA);
	s_mov_b32 m0, s62
	ds_read_b128 v[176:179], v215 offset:49152
	ds_read_b128 v[180:183], v215 offset:50176
	ds_read_b128 v[184:187], v215 offset:51200
	ds_read_b128 v[188:191], v215 offset:52224


; #define PG8_STAGE(bufoff, gbase, voff) do { _Pragma("unroll") for (int _i = 0; _i < 2; ++_i) \
;         __builtin_amdgcn_global_load_lds((const unsigned*)((const char*)(gbase) + (voff)[_i]), (PG8_LAS unsigned*)(lds + (bufoff) + ldsw + _i * 8192), 16, 0, 0); } while (0)
; #define PG8_LDA(dst, b, h) do { _Pragma("unroll") for (int m = 0; m < 4; ++m) _Pragma("unroll") for (int k = 0; k < 2; ++k) dst[m][k] = *(const PG8_LAS bf16x8*)(lds + PG8_SA(b, h) + aoff + m * 2048 + k * 1024); } while (0)
; template <class Epi, class Sched, bool ALIGN_EPI = false, bool SP2 = false>
; __device__ __forceinline__ void gemm_phase(PG8_LAS unsigned char* lds, const Gemm g, const Sched& S, const Epi& E) {
;     ...
;             PG8_LDA(At, 1, 1); PG8_STAGE(PG8_SB(1, 0), b3, voffB); PG8_STAGE(PG8_SB(1, 1), b3 + hstep, voffB); PG8_STAGE(PG8_SA(1, 0), a3, voffA);
	global_load_lds_dwordx4 v250, s[96:97]
	s_add_i32 m0, s62, 0x2000
	s_add_u32 s60, s60, 0x80080

; #define PG8_STAGE(bufoff, gbase, voff) do { _Pragma("unroll") for (int _i = 0; _i < 2; ++_i) \
;         __builtin_amdgcn_global_load_lds((const unsigned*)((const char*)(gbase) + (voff)[_i]), (PG8_LAS unsigned*)(lds + (bufoff) + ldsw + _i * 8192), 16, 0, 0); } while (0)
; #define PG8_LDA(dst, b, h) do { _Pragma("unroll") for (int m = 0; m < 4; ++m) _Pragma("unroll") for (int k = 0; k < 2; ++k) dst[m][k] = *(const PG8_LAS bf16x8*)(lds + PG8_SA(b, h) + aoff + m * 2048 + k * 1024); } while (0)
; template <class Epi, class Sched, bool ALIGN_EPI = false, bool SP2 = false>
; __device__ __forceinline__ void gemm_phase(PG8_LAS unsigned char* lds, const Gemm g, const Sched& S, const Epi& E) {
;     ...
;             PG8_LDA(At, 1, 1); PG8_STAGE(PG8_SB(1, 0), b3, voffB); PG8_STAGE(PG8_SB(1, 1), b3 + hstep, voffB); PG8_STAGE(PG8_SA(1, 0), a3, voffA);
	s_addc_u32 s61, s61, 0
	s_add_i32 s62, s83, s64
	global_load_lds_dwordx4 v251, s[96:97]

; #define PG8_STAGE(bufoff, gbase, voff) do { _Pragma("unroll") for (int _i = 0; _i < 2; ++_i) \
;         __builtin_amdgcn_global_load_lds((const unsigned*)((const char*)(gbase) + (voff)[_i]), (PG8_LAS unsigned*)(lds + (bufoff) + ldsw + _i * 8192), 16, 0, 0); } while (0)
; #define PG8_LDA(dst, b, h) do { _Pragma("unroll") for (int m = 0; m < 4; ++m) _Pragma("unroll") for (int k = 0; k < 2; ++k) dst[m][k] = *(const PG8_LAS bf16x8*)(lds + PG8_SA(b, h) + aoff + m * 2048 + k * 1024); } while (0)
; template <class Epi, class Sched, bool ALIGN_EPI = false, bool SP2 = false>
; __device__ __forceinline__ void gemm_phase(PG8_LAS unsigned char* lds, const Gemm g, const Sched& S, const Epi& E) {
;     ...
;             PG8_LDA(At, 1, 1); PG8_STAGE(PG8_SB(1, 0), b3, voffB); PG8_STAGE(PG8_SB(1, 1), b3 + hstep, voffB); PG8_STAGE(PG8_SA(1, 0), a3, voffA);
	s_mov_b32 m0, s62
	ds_read_b128 v[192:195], v215 offset:53248
	global_load_lds_dwordx4 v162, s[60:61]

; #define PG8_STAGE(bufoff, gbase, voff) do { _Pragma("unroll") for (int _i = 0; _i < 2; ++_i) \
;         __builtin_amdgcn_global_load_lds((const unsigned*)((const char*)(gbase) + (voff)[_i]), (PG8_LAS unsigned*)(lds + (bufoff) + ldsw + _i * 8192), 16, 0, 0); } while (0)
; #define PG8_LDA(dst, b, h) do { _Pragma("unroll") for (int m = 0; m < 4; ++m) _Pragma("unroll") for (int k = 0; k < 2; ++k) dst[m][k] = *(const PG8_LAS bf16x8*)(lds + PG8_SA(b, h) + aoff + m * 2048 + k * 1024); } while (0)
; template <class Epi, class Sched, bool ALIGN_EPI = false, bool SP2 = false>
; __device__ __forceinline__ void gemm_phase(PG8_LAS unsigned char* lds, const Gemm g, const Sched& S, const Epi& E) {
;     ...
;             PG8_LDA(At, 1, 1); PG8_STAGE(PG8_SB(1, 0), b3, voffB); PG8_STAGE(PG8_SB(1, 1), b3 + hstep, voffB); PG8_STAGE(PG8_SA(1, 0), a3, voffA);
	s_add_i32 m0, s62, 0x2000
	ds_read_b128 v[196:199], v215 offset:54272
	global_load_lds_dwordx4 v166, s[60:61]

; #define PG8_STAGE(bufoff, gbase, voff) do { _Pragma("unroll") for (int _i = 0; _i < 2; ++_i) \
;         __builtin_amdgcn_global_load_lds((const unsigned*)((const char*)(gbase) + (voff)[_i]), (PG8_LAS unsigned*)(lds + (bufoff) + ldsw + _i * 8192), 16, 0, 0); } while (0)
; #define PG8_LDA(dst, b, h) do { _Pragma("unroll") for (int m = 0; m < 4; ++m) _Pragma("unroll") for (int k = 0; k < 2; ++k) dst[m][k] = *(const PG8_LAS bf16x8*)(lds + PG8_SA(b, h) + aoff + m * 2048 + k * 1024); } while (0)
; template <class Epi, class Sched, bool ALIGN_EPI = false, bool SP2 = false>
; __device__ __forceinline__ void gemm_phase(PG8_LAS unsigned char* lds, const Gemm g, const Sched& S, const Epi& E) {
;     ...
;             PG8_LDA(At, 1, 1); PG8_STAGE(PG8_SB(1, 0), b3, voffB); PG8_STAGE(PG8_SB(1, 1), b3 + hstep, voffB); PG8_STAGE(PG8_SA(1, 0), a3, voffA);
	s_mov_b32 m0, s70
	ds_read_b128 v[200:203], v215 offset:55296
	global_load_lds_dwordx4 v252, s[98:99]

; #define PG8_STAGE(bufoff, gbase, voff) do { _Pragma("unroll") for (int _i = 0; _i < 2; ++_i) \
;         __builtin_amdgcn_global_load_lds((const unsigned*)((const char*)(gbase) + (voff)[_i]), (PG8_LAS unsigned*)(lds + (bufoff) + ldsw + _i * 8192), 16, 0, 0); } while (0)
; #define PG8_LDA(dst, b, h) do { _Pragma("unroll") for (int m = 0; m < 4; ++m) _Pragma("unroll") for (int k = 0; k < 2; ++k) dst[m][k] = *(const PG8_LAS bf16x8*)(lds + PG8_SA(b, h) + aoff + m * 2048 + k * 1024); } while (0)
; #define PG8_MMA(ai, bj, At, Bt) do { __builtin_amdgcn_s_setprio(1); _Pragma("unroll") for (int m = 0; m < 4; ++m) _Pragma("unroll") for (int n = 0; n < 2; ++n) _Pragma("unroll") for (int k = 0; k < 2; ++k) \
;         acc[ai][bj][m][n] = __builtin_amdgcn_mfma_f32_16x16x32_bf16(Bt[n][k], At[m][k], acc[ai][bj][m][n], 0, 0, 0); __builtin_amdgcn_s_setprio(0); } while (0)
; #define PG8_WAIT_V(n) asm volatile("s_waitcnt vmcnt(" #n ")" ::: "memory")
; #define PG8_WAIT_L(n) asm volatile("s_waitcnt lgkmcnt(" #n ")" ::: "memory")
; #define PG8_BAR __builtin_amdgcn_s_barrier()
; #define PG8_SCHED __builtin_amdgcn_sched_barrier(0)
; template <class Epi, class Sched, bool ALIGN_EPI = false, bool SP2 = false>
; __device__ __forceinline__ void gemm_phase(PG8_LAS unsigned char* lds, const Gemm g, const Sched& S, const Epi& E) {
;     ...
;             PG8_LDA(At, 1, 1); PG8_STAGE(PG8_SB(1, 0), b3, voffB); PG8_STAGE(PG8_SB(1, 1), b3 + hstep, voffB); PG8_STAGE(PG8_SA(1, 0), a3, voffA);
;             PG8_WAIT_V(8); PG8_WAIT_L(0); PG8_BAR; PG8_MMA(1, 0, At, B0); PG8_MMA(1, 1, At, B1); PG8_BAR; PG8_SCHED;
	s_mov_b32 m0, s71
	ds_read_b128 v[204:207], v215 offset:56320
	global_load_lds_dwordx4 v253, s[98:99]
	s_waitcnt vmcnt(8)
	s_waitcnt lgkmcnt(0)
	s_barrier
	s_setprio 1
	s_waitcnt lgkmcnt(0)
	v_mfma_f32_16x16x32_bf16 v[60:63], v[64:67], v[176:179], v[60:63]
	v_mfma_f32_16x16x32_bf16 v[56:59], v[72:75], v[176:179], v[56:59]
	v_mfma_f32_16x16x32_bf16 v[44:47], v[64:67], v[184:187], v[44:47]
	v_mfma_f32_16x16x32_bf16 v[40:43], v[72:75], v[184:187], v[40:43]
	v_mfma_f32_16x16x32_bf16 v[28:31], v[64:67], v[192:195], v[28:31]
	v_mfma_f32_16x16x32_bf16 v[24:27], v[72:75], v[192:195], v[24:27]
	v_mfma_f32_16x16x32_bf16 v[12:15], v[64:67], v[200:203], v[12:15]
	v_mfma_f32_16x16x32_bf16 v[8:11], v[72:75], v[200:203], v[8:11]
	v_mfma_f32_16x16x32_bf16 v[60:63], v[68:71], v[180:183], v[60:63]
	v_mfma_f32_16x16x32_bf16 v[56:59], v[76:79], v[180:183], v[56:59]
	v_mfma_f32_16x16x32_bf16 v[44:47], v[68:71], v[188:191], v[44:47]
	v_mfma_f32_16x16x32_bf16 v[40:43], v[76:79], v[188:191], v[40:43]
	v_mfma_f32_16x16x32_bf16 v[28:31], v[68:71], v[196:199], v[28:31]
	v_mfma_f32_16x16x32_bf16 v[24:27], v[76:79], v[196:199], v[24:27]
	v_mfma_f32_16x16x32_bf16 v[12:15], v[68:71], v[204:207], v[12:15]
	v_mfma_f32_16x16x32_bf16 v[8:11], v[76:79], v[204:207], v[8:11]


; #define PG8_MMA(ai, bj, At, Bt) do { __builtin_amdgcn_s_setprio(1); _Pragma("unroll") for (int m = 0; m < 4; ++m) _Pragma("unroll") for (int n = 0; n < 2; ++n) _Pragma("unroll") for (int k = 0; k < 2; ++k) \
;         acc[ai][bj][m][n] = __builtin_amdgcn_mfma_f32_16x16x32_bf16(Bt[n][k], At[m][k], acc[ai][bj][m][n], 0, 0, 0); __builtin_amdgcn_s_setprio(0); } while (0)
; #define PG8_WAIT_V(n) asm volatile("s_waitcnt vmcnt(" #n ")" ::: "memory")
; #define PG8_WAIT_L(n) asm volatile("s_waitcnt lgkmcnt(" #n ")" ::: "memory")
; #define PG8_BAR __builtin_amdgcn_s_barrier()
; #define PG8_SCHED __builtin_amdgcn_sched_barrier(0)
; template <class Epi, class Sched, bool ALIGN_EPI = false, bool SP2 = false>
; __device__ __forceinline__ void gemm_phase(PG8_LAS unsigned char* lds, const Gemm g, const Sched& S, const Epi& E) {
;     ...
;         for (int t = 0; t < nt; t += 2) {
;             const bool last = (t == nt - 2);
;     ...
;             PG8_WAIT_V(8); PG8_WAIT_L(0); PG8_BAR; PG8_MMA(1, 0, At, B0); PG8_MMA(1, 1, At, B1); PG8_BAR; PG8_SCHED;
;     ...
;         if constexpr (ALIGN_EPI) { if (wr == 0) PG8_BAR; }
	v_mfma_f32_16x16x32_bf16 v[52:55], v[144:147], v[176:179], v[52:55]
	v_mfma_f32_16x16x32_bf16 v[48:51], v[152:155], v[176:179], v[48:51]
	v_mfma_f32_16x16x32_bf16 v[36:39], v[144:147], v[184:187], v[36:39]
	v_mfma_f32_16x16x32_bf16 v[32:35], v[152:155], v[184:187], v[32:35]
	v_mfma_f32_16x16x32_bf16 v[20:23], v[144:147], v[192:195], v[20:23]
	v_mfma_f32_16x16x32_bf16 v[16:19], v[152:155], v[192:195], v[16:19]
	v_mfma_f32_16x16x32_bf16 v[4:7], v[144:147], v[200:203], v[4:7]
	v_mfma_f32_16x16x32_bf16 v[0:3], v[152:155], v[200:203], v[0:3]
	v_mfma_f32_16x16x32_bf16 v[52:55], v[148:151], v[180:183], v[52:55]
	v_mfma_f32_16x16x32_bf16 v[48:51], v[156:159], v[180:183], v[48:51]
	v_mfma_f32_16x16x32_bf16 v[36:39], v[148:151], v[188:191], v[36:39]
	v_mfma_f32_16x16x32_bf16 v[32:35], v[156:159], v[188:191], v[32:35]
	v_mfma_f32_16x16x32_bf16 v[20:23], v[148:151], v[196:199], v[20:23]
	v_mfma_f32_16x16x32_bf16 v[16:19], v[156:159], v[196:199], v[16:19]
	v_mfma_f32_16x16x32_bf16 v[4:7], v[148:151], v[204:207], v[4:7]
	v_mfma_f32_16x16x32_bf16 v[0:3], v[156:159], v[204:207], v[0:3]
	s_setprio 0
	s_barrier
	s_add_i32 s81, s81, 2
	s_add_u32 s58, s58, 0x100
	s_addc_u32 s59, s59, 0
	s_add_u32 s79, s79, 0x100
	s_addc_u32 s80, s80, 0
	s_cmp_gt_u32 s81, 29
	s_cbranch_scc0 .LBB0_939
	s_and_b64 vcc, exec, s[42:43]
	s_cbranch_vccz .LBB0_942
	s_barrier

; #define PG8_STAGE(bufoff, gbase, voff) do { _Pragma("unroll") for (int _i = 0; _i < 2; ++_i) \
;         __builtin_amdgcn_global_load_lds((const unsigned*)((const char*)(gbase) + (voff)[_i]), (PG8_LAS unsigned*)(lds + (bufoff) + ldsw + _i * 8192), 16, 0, 0); } while (0)
; #define PG8_LDA(dst, b, h) do { _Pragma("unroll") for (int m = 0; m < 4; ++m) _Pragma("unroll") for (int k = 0; k < 2; ++k) dst[m][k] = *(const PG8_LAS bf16x8*)(lds + PG8_SA(b, h) + aoff + m * 2048 + k * 1024); } while (0)
; #define PG8_LDB(dst, b, h) do { _Pragma("unroll") for (int n = 0; n < 2; ++n) _Pragma("unroll") for (int k = 0; k < 2; ++k) dst[n][k] = *(const PG8_LAS bf16x8*)(lds + PG8_SB(b, h) + boff + n * 2048 + k * 1024); } while (0)
; #define PG8_SCHED __builtin_amdgcn_sched_barrier(0)
; template <class Epi, class Sched, bool ALIGN_EPI = false, bool SP2 = false>
; __device__ __forceinline__ void gemm_phase(PG8_LAS unsigned char* lds, const Gemm g, const Sched& S, const Epi& E) {
;     ...
;         for (int t = 0; t < nt; t += 2) {
;             const bool last = (t == nt - 2);
;             const char* a1 = cA + (size_t)(t + 1) * kstep;
;             const char* a2 = last ? nA : cA + (size_t)(t + 2) * kstep; const char* b2 = last ? nB : cB + (size_t)(t + 2) * kstep;
;             const char* a3 = a2 + kstep; const char* b3 = b2 + kstep;
;             if (last && has_next) S.a_ready(nxt);
;             if constexpr (SP2) {
;             PG8_LDB(B0, 0, 0); PG8_LDB(B1, 0, 1); PG8_SCHED; PG8_LDA(At, 0, 0); PG8_STAGE(PG8_SA(1, 1), a1 + hstep, voffA);
.LBB0_1034:
	ds_read_b128 v[128:131], v201
	ds_read_b128 v[132:135], v201 offset:1024
	ds_read_b128 v[136:139], v201 offset:2048
	ds_read_b128 v[140:143], v201 offset:3072
	ds_read_b128 v[144:147], v205
	ds_read_b128 v[148:151], v205 offset:1024
	ds_read_b128 v[152:155], v205 offset:2048
	ds_read_b128 v[156:159], v205 offset:3072
	s_add_u32 s12, s10, 0xfff80080
	s_addc_u32 s13, s11, -1
	s_cmp_eq_u32 s83, 28
	s_cselect_b32 s59, s53, s13
	s_cselect_b32 s58, s79, s12
	s_cselect_b32 s13, s51, s82
	s_cselect_b32 s12, s80, s81

; #define PG8_STAGE(bufoff, gbase, voff) do { _Pragma("unroll") for (int _i = 0; _i < 2; ++_i) \
;         __builtin_amdgcn_global_load_lds((const unsigned*)((const char*)(gbase) + (voff)[_i]), (PG8_LAS unsigned*)(lds + (bufoff) + ldsw + _i * 8192), 16, 0, 0); } while (0)
; #define PG8_LDA(dst, b, h) do { _Pragma("unroll") for (int m = 0; m < 4; ++m) _Pragma("unroll") for (int k = 0; k < 2; ++k) dst[m][k] = *(const PG8_LAS bf16x8*)(lds + PG8_SA(b, h) + aoff + m * 2048 + k * 1024); } while (0)
; #define PG8_LDB(dst, b, h) do { _Pragma("unroll") for (int n = 0; n < 2; ++n) _Pragma("unroll") for (int k = 0; k < 2; ++k) dst[n][k] = *(const PG8_LAS bf16x8*)(lds + PG8_SB(b, h) + boff + n * 2048 + k * 1024); } while (0)
; #define PG8_SCHED __builtin_amdgcn_sched_barrier(0)
; template <class Epi, class Sched, bool ALIGN_EPI = false, bool SP2 = false>
; __device__ __forceinline__ void gemm_phase(PG8_LAS unsigned char* lds, const Gemm g, const Sched& S, const Epi& E) {
;     ...
;             PG8_LDB(B0, 0, 0); PG8_LDB(B1, 0, 1); PG8_SCHED; PG8_LDA(At, 0, 0); PG8_STAGE(PG8_SA(1, 1), a1 + hstep, voffA);
	s_add_i32 m0, s63, 0xc000
	ds_read_b128 v[176:179], v207
	ds_read_b128 v[184:187], v207 offset:1024
	ds_read_b128 v[190:193], v207 offset:2048
	ds_read_b128 v[210:213], v207 offset:3072
	ds_read_b128 v[214:217], v207 offset:4096
	ds_read_b128 v[218:221], v207 offset:5120
	ds_read_b128 v[222:225], v207 offset:6144

; #define PG8_STAGE(bufoff, gbase, voff) do { _Pragma("unroll") for (int _i = 0; _i < 2; ++_i) \
;         __builtin_amdgcn_global_load_lds((const unsigned*)((const char*)(gbase) + (voff)[_i]), (PG8_LAS unsigned*)(lds + (bufoff) + ldsw + _i * 8192), 16, 0, 0); } while (0)
; #define PG8_LDA(dst, b, h) do { _Pragma("unroll") for (int m = 0; m < 4; ++m) _Pragma("unroll") for (int k = 0; k < 2; ++k) dst[m][k] = *(const PG8_LAS bf16x8*)(lds + PG8_SA(b, h) + aoff + m * 2048 + k * 1024); } while (0)
; #define PG8_LDB(dst, b, h) do { _Pragma("unroll") for (int n = 0; n < 2; ++n) _Pragma("unroll") for (int k = 0; k < 2; ++k) dst[n][k] = *(const PG8_LAS bf16x8*)(lds + PG8_SB(b, h) + boff + n * 2048 + k * 1024); } while (0)
; #define PG8_SCHED __builtin_amdgcn_sched_barrier(0)
; template <class Epi, class Sched, bool ALIGN_EPI = false, bool SP2 = false>
; __device__ __forceinline__ void gemm_phase(PG8_LAS unsigned char* lds, const Gemm g, const Sched& S, const Epi& E) {
;     ...
;             PG8_LDB(B0, 0, 0); PG8_LDB(B1, 0, 1); PG8_SCHED; PG8_LDA(At, 0, 0); PG8_STAGE(PG8_SA(1, 1), a1 + hstep, voffA);
	global_load_lds_dwordx4 v168, s[10:11]

; #define PG8_STAGE(bufoff, gbase, voff) do { _Pragma("unroll") for (int _i = 0; _i < 2; ++_i) \
;         __builtin_amdgcn_global_load_lds((const unsigned*)((const char*)(gbase) + (voff)[_i]), (PG8_LAS unsigned*)(lds + (bufoff) + ldsw + _i * 8192), 16, 0, 0); } while (0)
; #define PG8_LDA(dst, b, h) do { _Pragma("unroll") for (int m = 0; m < 4; ++m) _Pragma("unroll") for (int k = 0; k < 2; ++k) dst[m][k] = *(const PG8_LAS bf16x8*)(lds + PG8_SA(b, h) + aoff + m * 2048 + k * 1024); } while (0)
; #define PG8_LDB(dst, b, h) do { _Pragma("unroll") for (int n = 0; n < 2; ++n) _Pragma("unroll") for (int k = 0; k < 2; ++k) dst[n][k] = *(const PG8_LAS bf16x8*)(lds + PG8_SB(b, h) + boff + n * 2048 + k * 1024); } while (0)
; #define PG8_MMA(ai, bj, At, Bt) do { __builtin_amdgcn_s_setprio(1); _Pragma("unroll") for (int m = 0; m < 4; ++m) _Pragma("unroll") for (int n = 0; n < 2; ++n) _Pragma("unroll") for (int k = 0; k < 2; ++k) \
;         acc[ai][bj][m][n] = __builtin_amdgcn_mfma_f32_16x16x32_bf16(Bt[n][k], At[m][k], acc[ai][bj][m][n], 0, 0, 0); __builtin_amdgcn_s_setprio(0); } while (0)
; #define PG8_WAIT_V(n) asm volatile("s_waitcnt vmcnt(" #n ")" ::: "memory")
; #define PG8_WAIT_L(n) asm volatile("s_waitcnt lgkmcnt(" #n ")" ::: "memory")
; #define PG8_BAR __builtin_amdgcn_s_barrier()
; #define PG8_SCHED __builtin_amdgcn_sched_barrier(0)
; template <class Epi, class Sched, bool ALIGN_EPI = false, bool SP2 = false>
; __device__ __forceinline__ void gemm_phase(PG8_LAS unsigned char* lds, const Gemm g, const Sched& S, const Epi& E) {
;     ...
;             PG8_LDB(B0, 0, 0); PG8_LDB(B1, 0, 1); PG8_SCHED; PG8_LDA(At, 0, 0); PG8_STAGE(PG8_SA(1, 1), a1 + hstep, voffA);
;             PG8_WAIT_V(8); PG8_WAIT_L(0); PG8_BAR; PG8_MMA(0, 0, At, B0); PG8_MMA(0, 1, At, B1); PG8_BAR; PG8_SCHED;
	s_add_i32 m0, s63, 0xe000
	ds_read_b128 v[226:229], v207 offset:7168
	global_load_lds_dwordx4 v170, s[10:11]
	s_waitcnt vmcnt(8)
	s_waitcnt lgkmcnt(0)
	s_barrier
	s_setprio 1
	s_waitcnt lgkmcnt(0)
	v_mfma_f32_16x16x32_bf16 v[124:127], v[128:131], v[176:179], v[124:127]
	v_mfma_f32_16x16x32_bf16 v[120:123], v[136:139], v[176:179], v[120:123]
	v_mfma_f32_16x16x32_bf16 v[108:111], v[128:131], v[190:193], v[108:111]
	v_mfma_f32_16x16x32_bf16 v[104:107], v[136:139], v[190:193], v[104:107]
	v_mfma_f32_16x16x32_bf16 v[92:95], v[128:131], v[214:217], v[92:95]
	v_mfma_f32_16x16x32_bf16 v[88:91], v[136:139], v[214:217], v[88:91]
	v_mfma_f32_16x16x32_bf16 v[76:79], v[128:131], v[222:225], v[76:79]
	v_mfma_f32_16x16x32_bf16 v[72:75], v[136:139], v[222:225], v[72:75]
	v_mfma_f32_16x16x32_bf16 v[124:127], v[132:135], v[184:187], v[124:127]
	v_mfma_f32_16x16x32_bf16 v[120:123], v[140:143], v[184:187], v[120:123]
	v_mfma_f32_16x16x32_bf16 v[108:111], v[132:135], v[210:213], v[108:111]
	v_mfma_f32_16x16x32_bf16 v[104:107], v[140:143], v[210:213], v[104:107]
	v_mfma_f32_16x16x32_bf16 v[92:95], v[132:135], v[218:221], v[92:95]
	v_mfma_f32_16x16x32_bf16 v[88:91], v[140:143], v[218:221], v[88:91]
	v_mfma_f32_16x16x32_bf16 v[76:79], v[132:135], v[226:229], v[76:79]
	v_mfma_f32_16x16x32_bf16 v[72:75], v[140:143], v[226:229], v[72:75]


; #define PG8_STAGE(bufoff, gbase, voff) do { _Pragma("unroll") for (int _i = 0; _i < 2; ++_i) \
;         __builtin_amdgcn_global_load_lds((const unsigned*)((const char*)(gbase) + (voff)[_i]), (PG8_LAS unsigned*)(lds + (bufoff) + ldsw + _i * 8192), 16, 0, 0); } while (0)
; #define PG8_LDA(dst, b, h) do { _Pragma("unroll") for (int m = 0; m < 4; ++m) _Pragma("unroll") for (int k = 0; k < 2; ++k) dst[m][k] = *(const PG8_LAS bf16x8*)(lds + PG8_SA(b, h) + aoff + m * 2048 + k * 1024); } while (0)
; #define PG8_MMA(ai, bj, At, Bt) do { __builtin_amdgcn_s_setprio(1); _Pragma("unroll") for (int m = 0; m < 4; ++m) _Pragma("unroll") for (int n = 0; n < 2; ++n) _Pragma("unroll") for (int k = 0; k < 2; ++k) \
;         acc[ai][bj][m][n] = __builtin_amdgcn_mfma_f32_16x16x32_bf16(Bt[n][k], At[m][k], acc[ai][bj][m][n], 0, 0, 0); __builtin_amdgcn_s_setprio(0); } while (0)
; #define PG8_WAIT_V(n) asm volatile("s_waitcnt vmcnt(" #n ")" ::: "memory")
; #define PG8_WAIT_L(n) asm volatile("s_waitcnt lgkmcnt(" #n ")" ::: "memory")
; #define PG8_BAR __builtin_amdgcn_s_barrier()
; #define PG8_SCHED __builtin_amdgcn_sched_barrier(0)
; template <class Epi, class Sched, bool ALIGN_EPI = false, bool SP2 = false>
; __device__ __forceinline__ void gemm_phase(PG8_LAS unsigned char* lds, const Gemm g, const Sched& S, const Epi& E) {
;     ...
;             PG8_WAIT_V(8); PG8_WAIT_L(0); PG8_BAR; PG8_MMA(0, 0, At, B0); PG8_MMA(0, 1, At, B1); PG8_BAR; PG8_SCHED;
;             PG8_LDA(At, 0, 1); PG8_STAGE(PG8_SB(0, 0), b2, voffB); PG8_STAGE(PG8_SB(0, 1), b2 + hstep, voffB); PG8_STAGE(PG8_SA(0, 0), a2, voffA);
	v_mfma_f32_16x16x32_bf16 v[116:119], v[144:147], v[176:179], v[116:119]
	v_mfma_f32_16x16x32_bf16 v[112:115], v[152:155], v[176:179], v[112:115]
	v_mfma_f32_16x16x32_bf16 v[100:103], v[144:147], v[190:193], v[100:103]
	v_mfma_f32_16x16x32_bf16 v[96:99], v[152:155], v[190:193], v[96:99]
	v_mfma_f32_16x16x32_bf16 v[84:87], v[144:147], v[214:217], v[84:87]
	v_mfma_f32_16x16x32_bf16 v[80:83], v[152:155], v[214:217], v[80:83]
	v_mfma_f32_16x16x32_bf16 v[68:71], v[144:147], v[222:225], v[68:71]
	v_mfma_f32_16x16x32_bf16 v[64:67], v[152:155], v[222:225], v[64:67]
	v_mfma_f32_16x16x32_bf16 v[116:119], v[148:151], v[184:187], v[116:119]
	v_mfma_f32_16x16x32_bf16 v[112:115], v[156:159], v[184:187], v[112:115]
	v_mfma_f32_16x16x32_bf16 v[100:103], v[148:151], v[210:213], v[100:103]
	v_mfma_f32_16x16x32_bf16 v[96:99], v[156:159], v[210:213], v[96:99]
	v_mfma_f32_16x16x32_bf16 v[84:87], v[148:151], v[218:221], v[84:87]
	v_mfma_f32_16x16x32_bf16 v[80:83], v[156:159], v[218:221], v[80:83]
	v_mfma_f32_16x16x32_bf16 v[68:71], v[148:151], v[226:229], v[68:71]
	v_mfma_f32_16x16x32_bf16 v[64:67], v[156:159], v[226:229], v[64:67]
	s_setprio 0
	s_barrier
	s_add_i32 s84, s73, s62
	s_mov_b64 s[96:97], s[12:13]

; #define PG8_STAGE(bufoff, gbase, voff) do { _Pragma("unroll") for (int _i = 0; _i < 2; ++_i) \
;         __builtin_amdgcn_global_load_lds((const unsigned*)((const char*)(gbase) + (voff)[_i]), (PG8_LAS unsigned*)(lds + (bufoff) + ldsw + _i * 8192), 16, 0, 0); } while (0)
; #define PG8_LDA(dst, b, h) do { _Pragma("unroll") for (int m = 0; m < 4; ++m) _Pragma("unroll") for (int k = 0; k < 2; ++k) dst[m][k] = *(const PG8_LAS bf16x8*)(lds + PG8_SA(b, h) + aoff + m * 2048 + k * 1024); } while (0)
; template <class Epi, class Sched, bool ALIGN_EPI = false, bool SP2 = false>
; __device__ __forceinline__ void gemm_phase(PG8_LAS unsigned char* lds, const Gemm g, const Sched& S, const Epi& E) {
;     ...
;             PG8_LDA(At, 0, 1); PG8_STAGE(PG8_SB(0, 0), b2, voffB); PG8_STAGE(PG8_SB(0, 1), b2 + hstep, voffB); PG8_STAGE(PG8_SA(0, 0), a2, voffA);
	s_mov_b32 m0, s84
	ds_read_b128 v[176:179], v207 offset:16384
	ds_read_b128 v[184:187], v207 offset:17408
	ds_read_b128 v[190:193], v207 offset:18432
	ds_read_b128 v[210:213], v207 offset:19456


; #define PG8_STAGE(bufoff, gbase, voff) do { _Pragma("unroll") for (int _i = 0; _i < 2; ++_i) \
;         __builtin_amdgcn_global_load_lds((const unsigned*)((const char*)(gbase) + (voff)[_i]), (PG8_LAS unsigned*)(lds + (bufoff) + ldsw + _i * 8192), 16, 0, 0); } while (0)
; #define PG8_LDA(dst, b, h) do { _Pragma("unroll") for (int m = 0; m < 4; ++m) _Pragma("unroll") for (int k = 0; k < 2; ++k) dst[m][k] = *(const PG8_LAS bf16x8*)(lds + PG8_SA(b, h) + aoff + m * 2048 + k * 1024); } while (0)
; template <class Epi, class Sched, bool ALIGN_EPI = false, bool SP2 = false>
; __device__ __forceinline__ void gemm_phase(PG8_LAS unsigned char* lds, const Gemm g, const Sched& S, const Epi& E) {
;     ...
;             PG8_LDA(At, 0, 1); PG8_STAGE(PG8_SB(0, 0), b2, voffB); PG8_STAGE(PG8_SB(0, 1), b2 + hstep, voffB); PG8_STAGE(PG8_SA(0, 0), a2, voffA);
	global_load_lds_dwordx4 v162, s[12:13]
	s_add_i32 m0, s84, 0x2000
	s_add_u32 s84, s12, 0x80000

; #define PG8_STAGE(bufoff, gbase, voff) do { _Pragma("unroll") for (int _i = 0; _i < 2; ++_i) \
;         __builtin_amdgcn_global_load_lds((const unsigned*)((const char*)(gbase) + (voff)[_i]), (PG8_LAS unsigned*)(lds + (bufoff) + ldsw + _i * 8192), 16, 0, 0); } while (0)
; #define PG8_LDA(dst, b, h) do { _Pragma("unroll") for (int m = 0; m < 4; ++m) _Pragma("unroll") for (int k = 0; k < 2; ++k) dst[m][k] = *(const PG8_LAS bf16x8*)(lds + PG8_SA(b, h) + aoff + m * 2048 + k * 1024); } while (0)
; template <class Epi, class Sched, bool ALIGN_EPI = false, bool SP2 = false>
; __device__ __forceinline__ void gemm_phase(PG8_LAS unsigned char* lds, const Gemm g, const Sched& S, const Epi& E) {
;     ...
;             PG8_LDA(At, 0, 1); PG8_STAGE(PG8_SB(0, 0), b2, voffB); PG8_STAGE(PG8_SB(0, 1), b2 + hstep, voffB); PG8_STAGE(PG8_SA(0, 0), a2, voffA);
	s_addc_u32 s85, s13, 0
	s_add_i32 s86, s74, s62
	global_load_lds_dwordx4 v166, s[12:13]

; #define PG8_STAGE(bufoff, gbase, voff) do { _Pragma("unroll") for (int _i = 0; _i < 2; ++_i) \
;         __builtin_amdgcn_global_load_lds((const unsigned*)((const char*)(gbase) + (voff)[_i]), (PG8_LAS unsigned*)(lds + (bufoff) + ldsw + _i * 8192), 16, 0, 0); } while (0)
; #define PG8_LDA(dst, b, h) do { _Pragma("unroll") for (int m = 0; m < 4; ++m) _Pragma("unroll") for (int k = 0; k < 2; ++k) dst[m][k] = *(const PG8_LAS bf16x8*)(lds + PG8_SA(b, h) + aoff + m * 2048 + k * 1024); } while (0)
; template <class Epi, class Sched, bool ALIGN_EPI = false, bool SP2 = false>
; __device__ __forceinline__ void gemm_phase(PG8_LAS unsigned char* lds, const Gemm g, const Sched& S, const Epi& E) {
;     ...
;             PG8_LDA(At, 0, 1); PG8_STAGE(PG8_SB(0, 0), b2, voffB); PG8_STAGE(PG8_SB(0, 1), b2 + hstep, voffB); PG8_STAGE(PG8_SA(0, 0), a2, voffA);
	s_mov_b32 m0, s86
	ds_read_b128 v[214:217], v207 offset:20480
	global_load_lds_dwordx4 v162, s[84:85]

; #define PG8_STAGE(bufoff, gbase, voff) do { _Pragma("unroll") for (int _i = 0; _i < 2; ++_i) \
;         __builtin_amdgcn_global_load_lds((const unsigned*)((const char*)(gbase) + (voff)[_i]), (PG8_LAS unsigned*)(lds + (bufoff) + ldsw + _i * 8192), 16, 0, 0); } while (0)
; #define PG8_LDA(dst, b, h) do { _Pragma("unroll") for (int m = 0; m < 4; ++m) _Pragma("unroll") for (int k = 0; k < 2; ++k) dst[m][k] = *(const PG8_LAS bf16x8*)(lds + PG8_SA(b, h) + aoff + m * 2048 + k * 1024); } while (0)
; template <class Epi, class Sched, bool ALIGN_EPI = false, bool SP2 = false>
; __device__ __forceinline__ void gemm_phase(PG8_LAS unsigned char* lds, const Gemm g, const Sched& S, const Epi& E) {
;     ...
;             PG8_LDA(At, 0, 1); PG8_STAGE(PG8_SB(0, 0), b2, voffB); PG8_STAGE(PG8_SB(0, 1), b2 + hstep, voffB); PG8_STAGE(PG8_SA(0, 0), a2, voffA);
	s_add_i32 m0, s86, 0x2000
	ds_read_b128 v[218:221], v207 offset:21504
	global_load_lds_dwordx4 v166, s[84:85]
	s_mov_b64 s[98:99], s[58:59]

; #define PG8_STAGE(bufoff, gbase, voff) do { _Pragma("unroll") for (int _i = 0; _i < 2; ++_i) \
;         __builtin_amdgcn_global_load_lds((const unsigned*)((const char*)(gbase) + (voff)[_i]), (PG8_LAS unsigned*)(lds + (bufoff) + ldsw + _i * 8192), 16, 0, 0); } while (0)
; #define PG8_LDA(dst, b, h) do { _Pragma("unroll") for (int m = 0; m < 4; ++m) _Pragma("unroll") for (int k = 0; k < 2; ++k) dst[m][k] = *(const PG8_LAS bf16x8*)(lds + PG8_SA(b, h) + aoff + m * 2048 + k * 1024); } while (0)
; #define PG8_MMA(ai, bj, At, Bt) do { __builtin_amdgcn_s_setprio(1); _Pragma("unroll") for (int m = 0; m < 4; ++m) _Pragma("unroll") for (int n = 0; n < 2; ++n) _Pragma("unroll") for (int k = 0; k < 2; ++k) \
;         acc[ai][bj][m][n] = __builtin_amdgcn_mfma_f32_16x16x32_bf16(Bt[n][k], At[m][k], acc[ai][bj][m][n], 0, 0, 0); __builtin_amdgcn_s_setprio(0); } while (0)
; #define PG8_WAIT_V(n) asm volatile("s_waitcnt vmcnt(" #n ")" ::: "memory")
; #define PG8_WAIT_L(n) asm volatile("s_waitcnt lgkmcnt(" #n ")" ::: "memory")
; #define PG8_BAR __builtin_amdgcn_s_barrier()
; #define PG8_SCHED __builtin_amdgcn_sched_barrier(0)
; template <class Epi, class Sched, bool ALIGN_EPI = false, bool SP2 = false>
; __device__ __forceinline__ void gemm_phase(PG8_LAS unsigned char* lds, const Gemm g, const Sched& S, const Epi& E) {
;     ...
;             PG8_LDA(At, 0, 1); PG8_STAGE(PG8_SB(0, 0), b2, voffB); PG8_STAGE(PG8_SB(0, 1), b2 + hstep, voffB); PG8_STAGE(PG8_SA(0, 0), a2, voffA);
;             PG8_WAIT_V(8); PG8_WAIT_L(0); PG8_BAR; PG8_MMA(1, 0, At, B0); PG8_MMA(1, 1, At, B1); PG8_BAR; PG8_SCHED;
	s_mov_b32 m0, s63
	ds_read_b128 v[222:225], v207 offset:22528
	global_load_lds_dwordx4 v160, s[58:59]
	s_mov_b32 m0, s64
	ds_read_b128 v[226:229], v207 offset:23552
	global_load_lds_dwordx4 v164, s[58:59]
	s_waitcnt vmcnt(8)
	s_waitcnt lgkmcnt(0)
	s_barrier
	s_setprio 1
	s_waitcnt lgkmcnt(0)
	v_mfma_f32_16x16x32_bf16 v[60:63], v[128:131], v[176:179], v[60:63]
	v_mfma_f32_16x16x32_bf16 v[56:59], v[136:139], v[176:179], v[56:59]
	v_mfma_f32_16x16x32_bf16 v[44:47], v[128:131], v[190:193], v[44:47]
	v_mfma_f32_16x16x32_bf16 v[40:43], v[136:139], v[190:193], v[40:43]
	v_mfma_f32_16x16x32_bf16 v[28:31], v[128:131], v[214:217], v[28:31]
	v_mfma_f32_16x16x32_bf16 v[24:27], v[136:139], v[214:217], v[24:27]
	v_mfma_f32_16x16x32_bf16 v[12:15], v[128:131], v[222:225], v[12:15]
	v_mfma_f32_16x16x32_bf16 v[8:11], v[136:139], v[222:225], v[8:11]
	v_mfma_f32_16x16x32_bf16 v[60:63], v[132:135], v[184:187], v[60:63]
	v_mfma_f32_16x16x32_bf16 v[56:59], v[140:143], v[184:187], v[56:59]
	v_mfma_f32_16x16x32_bf16 v[44:47], v[132:135], v[210:213], v[44:47]
	v_mfma_f32_16x16x32_bf16 v[40:43], v[140:143], v[210:213], v[40:43]
	v_mfma_f32_16x16x32_bf16 v[28:31], v[132:135], v[218:221], v[28:31]
	v_mfma_f32_16x16x32_bf16 v[24:27], v[140:143], v[218:221], v[24:27]
	v_mfma_f32_16x16x32_bf16 v[12:15], v[132:135], v[226:229], v[12:15]
	v_mfma_f32_16x16x32_bf16 v[8:11], v[140:143], v[226:229], v[8:11]


; #define PG8_STAGE(bufoff, gbase, voff) do { _Pragma("unroll") for (int _i = 0; _i < 2; ++_i) \
;         __builtin_amdgcn_global_load_lds((const unsigned*)((const char*)(gbase) + (voff)[_i]), (PG8_LAS unsigned*)(lds + (bufoff) + ldsw + _i * 8192), 16, 0, 0); } while (0)
; #define PG8_LDA(dst, b, h) do { _Pragma("unroll") for (int m = 0; m < 4; ++m) _Pragma("unroll") for (int k = 0; k < 2; ++k) dst[m][k] = *(const PG8_LAS bf16x8*)(lds + PG8_SA(b, h) + aoff + m * 2048 + k * 1024); } while (0)
; #define PG8_LDB(dst, b, h) do { _Pragma("unroll") for (int n = 0; n < 2; ++n) _Pragma("unroll") for (int k = 0; k < 2; ++k) dst[n][k] = *(const PG8_LAS bf16x8*)(lds + PG8_SB(b, h) + boff + n * 2048 + k * 1024); } while (0)
; #define PG8_MMA(ai, bj, At, Bt) do { __builtin_amdgcn_s_setprio(1); _Pragma("unroll") for (int m = 0; m < 4; ++m) _Pragma("unroll") for (int n = 0; n < 2; ++n) _Pragma("unroll") for (int k = 0; k < 2; ++k) \
;         acc[ai][bj][m][n] = __builtin_amdgcn_mfma_f32_16x16x32_bf16(Bt[n][k], At[m][k], acc[ai][bj][m][n], 0, 0, 0); __builtin_amdgcn_s_setprio(0); } while (0)
; #define PG8_WAIT_V(n) asm volatile("s_waitcnt vmcnt(" #n ")" ::: "memory")
; #define PG8_WAIT_L(n) asm volatile("s_waitcnt lgkmcnt(" #n ")" ::: "memory")
; #define PG8_BAR __builtin_amdgcn_s_barrier()
; #define PG8_SCHED __builtin_amdgcn_sched_barrier(0)
; template <class Epi, class Sched, bool ALIGN_EPI = false, bool SP2 = false>
; __device__ __forceinline__ void gemm_phase(PG8_LAS unsigned char* lds, const Gemm g, const Sched& S, const Epi& E) {
;     ...
;             PG8_WAIT_V(8); PG8_WAIT_L(0); PG8_BAR; PG8_MMA(1, 0, At, B0); PG8_MMA(1, 1, At, B1); PG8_BAR; PG8_SCHED;
;             PG8_LDB(B0, 1, 0); PG8_LDB(B1, 1, 1); PG8_SCHED; PG8_LDA(At, 1, 0); PG8_STAGE(PG8_SA(0, 1), a2 + hstep, voffA);
	v_mfma_f32_16x16x32_bf16 v[52:55], v[144:147], v[176:179], v[52:55]
	v_mfma_f32_16x16x32_bf16 v[48:51], v[152:155], v[176:179], v[48:51]
	v_mfma_f32_16x16x32_bf16 v[36:39], v[144:147], v[190:193], v[36:39]
	v_mfma_f32_16x16x32_bf16 v[32:35], v[152:155], v[190:193], v[32:35]
	v_mfma_f32_16x16x32_bf16 v[20:23], v[144:147], v[214:217], v[20:23]
	v_mfma_f32_16x16x32_bf16 v[16:19], v[152:155], v[214:217], v[16:19]
	v_mfma_f32_16x16x32_bf16 v[4:7], v[144:147], v[222:225], v[4:7]
	v_mfma_f32_16x16x32_bf16 v[0:3], v[152:155], v[222:225], v[0:3]
	v_mfma_f32_16x16x32_bf16 v[52:55], v[148:151], v[184:187], v[52:55]
	v_mfma_f32_16x16x32_bf16 v[48:51], v[156:159], v[184:187], v[48:51]
	v_mfma_f32_16x16x32_bf16 v[36:39], v[148:151], v[210:213], v[36:39]
	v_mfma_f32_16x16x32_bf16 v[32:35], v[156:159], v[210:213], v[32:35]
	v_mfma_f32_16x16x32_bf16 v[20:23], v[148:151], v[218:221], v[20:23]
	v_mfma_f32_16x16x32_bf16 v[16:19], v[156:159], v[218:221], v[16:19]
	v_mfma_f32_16x16x32_bf16 v[4:7], v[148:151], v[226:229], v[4:7]
	v_mfma_f32_16x16x32_bf16 v[0:3], v[156:159], v[226:229], v[0:3]
	s_setprio 0
	s_barrier
	s_add_i32 s84, 0, 0x18000
	s_add_i32 s85, 0, 0x1c000
	v_add_u32_e32 v140, s84, v189
	v_add_u32_e32 v156, s85, v189
	ds_read_b128 v[128:131], v140
	ds_read_b128 v[132:135], v140 offset:1024
	ds_read_b128 v[136:139], v140 offset:2048
	ds_read_b128 v[140:143], v140 offset:3072
	ds_read_b128 v[144:147], v156
	ds_read_b128 v[148:151], v156 offset:1024
	ds_read_b128 v[152:155], v156 offset:2048
	ds_read_b128 v[156:159], v156 offset:3072
	s_add_u32 s58, s58, 0x80000
	s_addc_u32 s59, s59, 0
	s_mov_b32 m0, s65

; #define PG8_STAGE(bufoff, gbase, voff) do { _Pragma("unroll") for (int _i = 0; _i < 2; ++_i) \
;         __builtin_amdgcn_global_load_lds((const unsigned*)((const char*)(gbase) + (voff)[_i]), (PG8_LAS unsigned*)(lds + (bufoff) + ldsw + _i * 8192), 16, 0, 0); } while (0)
; #define PG8_LDA(dst, b, h) do { _Pragma("unroll") for (int m = 0; m < 4; ++m) _Pragma("unroll") for (int k = 0; k < 2; ++k) dst[m][k] = *(const PG8_LAS bf16x8*)(lds + PG8_SA(b, h) + aoff + m * 2048 + k * 1024); } while (0)
; #define PG8_LDB(dst, b, h) do { _Pragma("unroll") for (int n = 0; n < 2; ++n) _Pragma("unroll") for (int k = 0; k < 2; ++k) dst[n][k] = *(const PG8_LAS bf16x8*)(lds + PG8_SB(b, h) + boff + n * 2048 + k * 1024); } while (0)
; #define PG8_SCHED __builtin_amdgcn_sched_barrier(0)
; template <class Epi, class Sched, bool ALIGN_EPI = false, bool SP2 = false>
; __device__ __forceinline__ void gemm_phase(PG8_LAS unsigned char* lds, const Gemm g, const Sched& S, const Epi& E) {
;     ...
;             PG8_LDB(B0, 1, 0); PG8_LDB(B1, 1, 1); PG8_SCHED; PG8_LDA(At, 1, 0); PG8_STAGE(PG8_SA(0, 1), a2 + hstep, voffA);
	ds_read_b128 v[176:179], v207 offset:32768
	ds_read_b128 v[184:187], v207 offset:33792
	ds_read_b128 v[190:193], v207 offset:34816
	ds_read_b128 v[210:213], v207 offset:35840
	ds_read_b128 v[214:217], v207 offset:36864
	ds_read_b128 v[218:221], v207 offset:37888
	ds_read_b128 v[222:225], v207 offset:38912

; #define PG8_STAGE(bufoff, gbase, voff) do { _Pragma("unroll") for (int _i = 0; _i < 2; ++_i) \
;         __builtin_amdgcn_global_load_lds((const unsigned*)((const char*)(gbase) + (voff)[_i]), (PG8_LAS unsigned*)(lds + (bufoff) + ldsw + _i * 8192), 16, 0, 0); } while (0)
; #define PG8_LDA(dst, b, h) do { _Pragma("unroll") for (int m = 0; m < 4; ++m) _Pragma("unroll") for (int k = 0; k < 2; ++k) dst[m][k] = *(const PG8_LAS bf16x8*)(lds + PG8_SA(b, h) + aoff + m * 2048 + k * 1024); } while (0)
; #define PG8_LDB(dst, b, h) do { _Pragma("unroll") for (int n = 0; n < 2; ++n) _Pragma("unroll") for (int k = 0; k < 2; ++k) dst[n][k] = *(const PG8_LAS bf16x8*)(lds + PG8_SB(b, h) + boff + n * 2048 + k * 1024); } while (0)
; #define PG8_SCHED __builtin_amdgcn_sched_barrier(0)
; template <class Epi, class Sched, bool ALIGN_EPI = false, bool SP2 = false>
; __device__ __forceinline__ void gemm_phase(PG8_LAS unsigned char* lds, const Gemm g, const Sched& S, const Epi& E) {
;     ...
;             PG8_LDB(B0, 1, 0); PG8_LDB(B1, 1, 1); PG8_SCHED; PG8_LDA(At, 1, 0); PG8_STAGE(PG8_SA(0, 1), a2 + hstep, voffA);
	global_load_lds_dwordx4 v160, s[58:59]

; #define PG8_STAGE(bufoff, gbase, voff) do { _Pragma("unroll") for (int _i = 0; _i < 2; ++_i) \
;         __builtin_amdgcn_global_load_lds((const unsigned*)((const char*)(gbase) + (voff)[_i]), (PG8_LAS unsigned*)(lds + (bufoff) + ldsw + _i * 8192), 16, 0, 0); } while (0)
; #define PG8_LDA(dst, b, h) do { _Pragma("unroll") for (int m = 0; m < 4; ++m) _Pragma("unroll") for (int k = 0; k < 2; ++k) dst[m][k] = *(const PG8_LAS bf16x8*)(lds + PG8_SA(b, h) + aoff + m * 2048 + k * 1024); } while (0)
; #define PG8_LDB(dst, b, h) do { _Pragma("unroll") for (int n = 0; n < 2; ++n) _Pragma("unroll") for (int k = 0; k < 2; ++k) dst[n][k] = *(const PG8_LAS bf16x8*)(lds + PG8_SB(b, h) + boff + n * 2048 + k * 1024); } while (0)
; #define PG8_MMA(ai, bj, At, Bt) do { __builtin_amdgcn_s_setprio(1); _Pragma("unroll") for (int m = 0; m < 4; ++m) _Pragma("unroll") for (int n = 0; n < 2; ++n) _Pragma("unroll") for (int k = 0; k < 2; ++k) \
;         acc[ai][bj][m][n] = __builtin_amdgcn_mfma_f32_16x16x32_bf16(Bt[n][k], At[m][k], acc[ai][bj][m][n], 0, 0, 0); __builtin_amdgcn_s_setprio(0); } while (0)
; #define PG8_WAIT_V(n) asm volatile("s_waitcnt vmcnt(" #n ")" ::: "memory")
; #define PG8_WAIT_L(n) asm volatile("s_waitcnt lgkmcnt(" #n ")" ::: "memory")
; #define PG8_BAR __builtin_amdgcn_s_barrier()
; #define PG8_SCHED __builtin_amdgcn_sched_barrier(0)
; template <class Epi, class Sched, bool ALIGN_EPI = false, bool SP2 = false>
; __device__ __forceinline__ void gemm_phase(PG8_LAS unsigned char* lds, const Gemm g, const Sched& S, const Epi& E) {
;     ...
;             PG8_LDB(B0, 1, 0); PG8_LDB(B1, 1, 1); PG8_SCHED; PG8_LDA(At, 1, 0); PG8_STAGE(PG8_SA(0, 1), a2 + hstep, voffA);
;             PG8_WAIT_V(8); PG8_WAIT_L(0); PG8_BAR; PG8_MMA(0, 0, At, B0); PG8_MMA(0, 1, At, B1); PG8_BAR; PG8_SCHED;
	s_mov_b32 m0, s67
	ds_read_b128 v[226:229], v207 offset:39936
	global_load_lds_dwordx4 v164, s[58:59]
	s_waitcnt vmcnt(8)
	s_waitcnt lgkmcnt(0)
	s_barrier
	s_setprio 1
	s_waitcnt lgkmcnt(0)
	v_mfma_f32_16x16x32_bf16 v[124:127], v[128:131], v[176:179], v[124:127]
	v_mfma_f32_16x16x32_bf16 v[120:123], v[136:139], v[176:179], v[120:123]
	v_mfma_f32_16x16x32_bf16 v[108:111], v[128:131], v[190:193], v[108:111]
	v_mfma_f32_16x16x32_bf16 v[104:107], v[136:139], v[190:193], v[104:107]
	v_mfma_f32_16x16x32_bf16 v[92:95], v[128:131], v[214:217], v[92:95]
	v_mfma_f32_16x16x32_bf16 v[88:91], v[136:139], v[214:217], v[88:91]
	v_mfma_f32_16x16x32_bf16 v[76:79], v[128:131], v[222:225], v[76:79]
	v_mfma_f32_16x16x32_bf16 v[72:75], v[136:139], v[222:225], v[72:75]
	v_mfma_f32_16x16x32_bf16 v[124:127], v[132:135], v[184:187], v[124:127]
	v_mfma_f32_16x16x32_bf16 v[120:123], v[140:143], v[184:187], v[120:123]
	v_mfma_f32_16x16x32_bf16 v[108:111], v[132:135], v[210:213], v[108:111]
	v_mfma_f32_16x16x32_bf16 v[104:107], v[140:143], v[210:213], v[104:107]
	v_mfma_f32_16x16x32_bf16 v[92:95], v[132:135], v[218:221], v[92:95]
	v_mfma_f32_16x16x32_bf16 v[88:91], v[140:143], v[218:221], v[88:91]
	v_mfma_f32_16x16x32_bf16 v[76:79], v[132:135], v[226:229], v[76:79]
	v_mfma_f32_16x16x32_bf16 v[72:75], v[140:143], v[226:229], v[72:75]


; #define PG8_STAGE(bufoff, gbase, voff) do { _Pragma("unroll") for (int _i = 0; _i < 2; ++_i) \
;         __builtin_amdgcn_global_load_lds((const unsigned*)((const char*)(gbase) + (voff)[_i]), (PG8_LAS unsigned*)(lds + (bufoff) + ldsw + _i * 8192), 16, 0, 0); } while (0)
; #define PG8_LDA(dst, b, h) do { _Pragma("unroll") for (int m = 0; m < 4; ++m) _Pragma("unroll") for (int k = 0; k < 2; ++k) dst[m][k] = *(const PG8_LAS bf16x8*)(lds + PG8_SA(b, h) + aoff + m * 2048 + k * 1024); } while (0)
; #define PG8_MMA(ai, bj, At, Bt) do { __builtin_amdgcn_s_setprio(1); _Pragma("unroll") for (int m = 0; m < 4; ++m) _Pragma("unroll") for (int n = 0; n < 2; ++n) _Pragma("unroll") for (int k = 0; k < 2; ++k) \
;         acc[ai][bj][m][n] = __builtin_amdgcn_mfma_f32_16x16x32_bf16(Bt[n][k], At[m][k], acc[ai][bj][m][n], 0, 0, 0); __builtin_amdgcn_s_setprio(0); } while (0)
; #define PG8_WAIT_V(n) asm volatile("s_waitcnt vmcnt(" #n ")" ::: "memory")
; #define PG8_WAIT_L(n) asm volatile("s_waitcnt lgkmcnt(" #n ")" ::: "memory")
; #define PG8_BAR __builtin_amdgcn_s_barrier()
; #define PG8_SCHED __builtin_amdgcn_sched_barrier(0)
; template <class Epi, class Sched, bool ALIGN_EPI = false, bool SP2 = false>
; __device__ __forceinline__ void gemm_phase(PG8_LAS unsigned char* lds, const Gemm g, const Sched& S, const Epi& E) {
;     ...
;             PG8_WAIT_V(8); PG8_WAIT_L(0); PG8_BAR; PG8_MMA(0, 0, At, B0); PG8_MMA(0, 1, At, B1); PG8_BAR; PG8_SCHED;
;             PG8_LDA(At, 1, 1); PG8_STAGE(PG8_SB(1, 0), b3, voffB); PG8_STAGE(PG8_SB(1, 1), b3 + hstep, voffB); PG8_STAGE(PG8_SA(1, 0), a3, voffA);
	v_mfma_f32_16x16x32_bf16 v[116:119], v[144:147], v[176:179], v[116:119]
	v_mfma_f32_16x16x32_bf16 v[112:115], v[152:155], v[176:179], v[112:115]
	v_mfma_f32_16x16x32_bf16 v[100:103], v[144:147], v[190:193], v[100:103]
	v_mfma_f32_16x16x32_bf16 v[96:99], v[152:155], v[190:193], v[96:99]
	v_mfma_f32_16x16x32_bf16 v[84:87], v[144:147], v[214:217], v[84:87]
	v_mfma_f32_16x16x32_bf16 v[80:83], v[152:155], v[214:217], v[80:83]
	v_mfma_f32_16x16x32_bf16 v[68:71], v[144:147], v[222:225], v[68:71]
	v_mfma_f32_16x16x32_bf16 v[64:67], v[152:155], v[222:225], v[64:67]
	v_mfma_f32_16x16x32_bf16 v[116:119], v[148:151], v[184:187], v[116:119]
	v_mfma_f32_16x16x32_bf16 v[112:115], v[156:159], v[184:187], v[112:115]
	v_mfma_f32_16x16x32_bf16 v[100:103], v[148:151], v[210:213], v[100:103]
	v_mfma_f32_16x16x32_bf16 v[96:99], v[156:159], v[210:213], v[96:99]
	v_mfma_f32_16x16x32_bf16 v[84:87], v[148:151], v[218:221], v[84:87]
	v_mfma_f32_16x16x32_bf16 v[80:83], v[156:159], v[218:221], v[80:83]
	v_mfma_f32_16x16x32_bf16 v[68:71], v[148:151], v[226:229], v[68:71]
	v_mfma_f32_16x16x32_bf16 v[64:67], v[156:159], v[226:229], v[64:67]
	s_setprio 0
	s_barrier
	s_add_i32 s58, s84, s62

; #define PG8_STAGE(bufoff, gbase, voff) do { _Pragma("unroll") for (int _i = 0; _i < 2; ++_i) \
;         __builtin_amdgcn_global_load_lds((const unsigned*)((const char*)(gbase) + (voff)[_i]), (PG8_LAS unsigned*)(lds + (bufoff) + ldsw + _i * 8192), 16, 0, 0); } while (0)
; #define PG8_LDA(dst, b, h) do { _Pragma("unroll") for (int m = 0; m < 4; ++m) _Pragma("unroll") for (int k = 0; k < 2; ++k) dst[m][k] = *(const PG8_LAS bf16x8*)(lds + PG8_SA(b, h) + aoff + m * 2048 + k * 1024); } while (0)
; template <class Epi, class Sched, bool ALIGN_EPI = false, bool SP2 = false>
; __device__ __forceinline__ void gemm_phase(PG8_LAS unsigned char* lds, const Gemm g, const Sched& S, const Epi& E) {
;     ...
;             PG8_LDA(At, 1, 1); PG8_STAGE(PG8_SB(1, 0), b3, voffB); PG8_STAGE(PG8_SB(1, 1), b3 + hstep, voffB); PG8_STAGE(PG8_SA(1, 0), a3, voffA);
	s_mov_b32 m0, s58
	ds_read_b128 v[176:179], v207 offset:49152
	ds_read_b128 v[184:187], v207 offset:50176
	ds_read_b128 v[190:193], v207 offset:51200
	ds_read_b128 v[210:213], v207 offset:52224


; #define PG8_STAGE(bufoff, gbase, voff) do { _Pragma("unroll") for (int _i = 0; _i < 2; ++_i) \
;         __builtin_amdgcn_global_load_lds((const unsigned*)((const char*)(gbase) + (voff)[_i]), (PG8_LAS unsigned*)(lds + (bufoff) + ldsw + _i * 8192), 16, 0, 0); } while (0)
; #define PG8_LDA(dst, b, h) do { _Pragma("unroll") for (int m = 0; m < 4; ++m) _Pragma("unroll") for (int k = 0; k < 2; ++k) dst[m][k] = *(const PG8_LAS bf16x8*)(lds + PG8_SA(b, h) + aoff + m * 2048 + k * 1024); } while (0)
; template <class Epi, class Sched, bool ALIGN_EPI = false, bool SP2 = false>
; __device__ __forceinline__ void gemm_phase(PG8_LAS unsigned char* lds, const Gemm g, const Sched& S, const Epi& E) {
;     ...
;             PG8_LDA(At, 1, 1); PG8_STAGE(PG8_SB(1, 0), b3, voffB); PG8_STAGE(PG8_SB(1, 1), b3 + hstep, voffB); PG8_STAGE(PG8_SA(1, 0), a3, voffA);
	global_load_lds_dwordx4 v250, s[96:97]
	s_add_i32 m0, s58, 0x2000
	s_add_u32 s12, s12, 0x80080

; #define PG8_STAGE(bufoff, gbase, voff) do { _Pragma("unroll") for (int _i = 0; _i < 2; ++_i) \
;         __builtin_amdgcn_global_load_lds((const unsigned*)((const char*)(gbase) + (voff)[_i]), (PG8_LAS unsigned*)(lds + (bufoff) + ldsw + _i * 8192), 16, 0, 0); } while (0)
; #define PG8_LDA(dst, b, h) do { _Pragma("unroll") for (int m = 0; m < 4; ++m) _Pragma("unroll") for (int k = 0; k < 2; ++k) dst[m][k] = *(const PG8_LAS bf16x8*)(lds + PG8_SA(b, h) + aoff + m * 2048 + k * 1024); } while (0)
; template <class Epi, class Sched, bool ALIGN_EPI = false, bool SP2 = false>
; __device__ __forceinline__ void gemm_phase(PG8_LAS unsigned char* lds, const Gemm g, const Sched& S, const Epi& E) {
;     ...
;             PG8_LDA(At, 1, 1); PG8_STAGE(PG8_SB(1, 0), b3, voffB); PG8_STAGE(PG8_SB(1, 1), b3 + hstep, voffB); PG8_STAGE(PG8_SA(1, 0), a3, voffA);
	s_addc_u32 s13, s13, 0
	s_add_i32 s58, s85, s62
	global_load_lds_dwordx4 v251, s[96:97]

; #define PG8_STAGE(bufoff, gbase, voff) do { _Pragma("unroll") for (int _i = 0; _i < 2; ++_i) \
;         __builtin_amdgcn_global_load_lds((const unsigned*)((const char*)(gbase) + (voff)[_i]), (PG8_LAS unsigned*)(lds + (bufoff) + ldsw + _i * 8192), 16, 0, 0); } while (0)
; #define PG8_LDA(dst, b, h) do { _Pragma("unroll") for (int m = 0; m < 4; ++m) _Pragma("unroll") for (int k = 0; k < 2; ++k) dst[m][k] = *(const PG8_LAS bf16x8*)(lds + PG8_SA(b, h) + aoff + m * 2048 + k * 1024); } while (0)
; template <class Epi, class Sched, bool ALIGN_EPI = false, bool SP2 = false>
; __device__ __forceinline__ void gemm_phase(PG8_LAS unsigned char* lds, const Gemm g, const Sched& S, const Epi& E) {
;     ...
;             PG8_LDA(At, 1, 1); PG8_STAGE(PG8_SB(1, 0), b3, voffB); PG8_STAGE(PG8_SB(1, 1), b3 + hstep, voffB); PG8_STAGE(PG8_SA(1, 0), a3, voffA);
	s_mov_b32 m0, s58
	ds_read_b128 v[214:217], v207 offset:53248
	global_load_lds_dwordx4 v162, s[12:13]

; #define PG8_STAGE(bufoff, gbase, voff) do { _Pragma("unroll") for (int _i = 0; _i < 2; ++_i) \
;         __builtin_amdgcn_global_load_lds((const unsigned*)((const char*)(gbase) + (voff)[_i]), (PG8_LAS unsigned*)(lds + (bufoff) + ldsw + _i * 8192), 16, 0, 0); } while (0)
; #define PG8_LDA(dst, b, h) do { _Pragma("unroll") for (int m = 0; m < 4; ++m) _Pragma("unroll") for (int k = 0; k < 2; ++k) dst[m][k] = *(const PG8_LAS bf16x8*)(lds + PG8_SA(b, h) + aoff + m * 2048 + k * 1024); } while (0)
; template <class Epi, class Sched, bool ALIGN_EPI = false, bool SP2 = false>
; __device__ __forceinline__ void gemm_phase(PG8_LAS unsigned char* lds, const Gemm g, const Sched& S, const Epi& E) {
;     ...
;             PG8_LDA(At, 1, 1); PG8_STAGE(PG8_SB(1, 0), b3, voffB); PG8_STAGE(PG8_SB(1, 1), b3 + hstep, voffB); PG8_STAGE(PG8_SA(1, 0), a3, voffA);
	s_add_i32 m0, s58, 0x2000
	ds_read_b128 v[218:221], v207 offset:54272
	global_load_lds_dwordx4 v166, s[12:13]

; #define PG8_STAGE(bufoff, gbase, voff) do { _Pragma("unroll") for (int _i = 0; _i < 2; ++_i) \
;         __builtin_amdgcn_global_load_lds((const unsigned*)((const char*)(gbase) + (voff)[_i]), (PG8_LAS unsigned*)(lds + (bufoff) + ldsw + _i * 8192), 16, 0, 0); } while (0)
; #define PG8_LDA(dst, b, h) do { _Pragma("unroll") for (int m = 0; m < 4; ++m) _Pragma("unroll") for (int k = 0; k < 2; ++k) dst[m][k] = *(const PG8_LAS bf16x8*)(lds + PG8_SA(b, h) + aoff + m * 2048 + k * 1024); } while (0)
; template <class Epi, class Sched, bool ALIGN_EPI = false, bool SP2 = false>
; __device__ __forceinline__ void gemm_phase(PG8_LAS unsigned char* lds, const Gemm g, const Sched& S, const Epi& E) {
;     ...
;             PG8_LDA(At, 1, 1); PG8_STAGE(PG8_SB(1, 0), b3, voffB); PG8_STAGE(PG8_SB(1, 1), b3 + hstep, voffB); PG8_STAGE(PG8_SA(1, 0), a3, voffA);
	s_mov_b32 m0, s69
	ds_read_b128 v[222:225], v207 offset:55296
	global_load_lds_dwordx4 v252, s[98:99]

; #define PG8_STAGE(bufoff, gbase, voff) do { _Pragma("unroll") for (int _i = 0; _i < 2; ++_i) \
;         __builtin_amdgcn_global_load_lds((const unsigned*)((const char*)(gbase) + (voff)[_i]), (PG8_LAS unsigned*)(lds + (bufoff) + ldsw + _i * 8192), 16, 0, 0); } while (0)
; #define PG8_LDA(dst, b, h) do { _Pragma("unroll") for (int m = 0; m < 4; ++m) _Pragma("unroll") for (int k = 0; k < 2; ++k) dst[m][k] = *(const PG8_LAS bf16x8*)(lds + PG8_SA(b, h) + aoff + m * 2048 + k * 1024); } while (0)
; #define PG8_MMA(ai, bj, At, Bt) do { __builtin_amdgcn_s_setprio(1); _Pragma("unroll") for (int m = 0; m < 4; ++m) _Pragma("unroll") for (int n = 0; n < 2; ++n) _Pragma("unroll") for (int k = 0; k < 2; ++k) \
;         acc[ai][bj][m][n] = __builtin_amdgcn_mfma_f32_16x16x32_bf16(Bt[n][k], At[m][k], acc[ai][bj][m][n], 0, 0, 0); __builtin_amdgcn_s_setprio(0); } while (0)
; #define PG8_WAIT_V(n) asm volatile("s_waitcnt vmcnt(" #n ")" ::: "memory")
; #define PG8_WAIT_L(n) asm volatile("s_waitcnt lgkmcnt(" #n ")" ::: "memory")
; #define PG8_BAR __builtin_amdgcn_s_barrier()
; #define PG8_SCHED __builtin_amdgcn_sched_barrier(0)
; template <class Epi, class Sched, bool ALIGN_EPI = false, bool SP2 = false>
; __device__ __forceinline__ void gemm_phase(PG8_LAS unsigned char* lds, const Gemm g, const Sched& S, const Epi& E) {
;     ...
;             PG8_LDA(At, 1, 1); PG8_STAGE(PG8_SB(1, 0), b3, voffB); PG8_STAGE(PG8_SB(1, 1), b3 + hstep, voffB); PG8_STAGE(PG8_SA(1, 0), a3, voffA);
;             PG8_WAIT_V(8); PG8_WAIT_L(0); PG8_BAR; PG8_MMA(1, 0, At, B0); PG8_MMA(1, 1, At, B1); PG8_BAR; PG8_SCHED;
	s_mov_b32 m0, s70
	ds_read_b128 v[226:229], v207 offset:56320
	global_load_lds_dwordx4 v253, s[98:99]
	s_waitcnt vmcnt(8)
	s_waitcnt lgkmcnt(0)
	s_barrier
	s_setprio 1
	s_waitcnt lgkmcnt(0)
	v_mfma_f32_16x16x32_bf16 v[60:63], v[128:131], v[176:179], v[60:63]
	v_mfma_f32_16x16x32_bf16 v[56:59], v[136:139], v[176:179], v[56:59]
	v_mfma_f32_16x16x32_bf16 v[44:47], v[128:131], v[190:193], v[44:47]
	v_mfma_f32_16x16x32_bf16 v[40:43], v[136:139], v[190:193], v[40:43]
	v_mfma_f32_16x16x32_bf16 v[28:31], v[128:131], v[214:217], v[28:31]
	v_mfma_f32_16x16x32_bf16 v[24:27], v[136:139], v[214:217], v[24:27]
	v_mfma_f32_16x16x32_bf16 v[12:15], v[128:131], v[222:225], v[12:15]
	v_mfma_f32_16x16x32_bf16 v[8:11], v[136:139], v[222:225], v[8:11]
	v_mfma_f32_16x16x32_bf16 v[60:63], v[132:135], v[184:187], v[60:63]
	v_mfma_f32_16x16x32_bf16 v[56:59], v[140:143], v[184:187], v[56:59]
	v_mfma_f32_16x16x32_bf16 v[44:47], v[132:135], v[210:213], v[44:47]
	v_mfma_f32_16x16x32_bf16 v[40:43], v[140:143], v[210:213], v[40:43]
	v_mfma_f32_16x16x32_bf16 v[28:31], v[132:135], v[218:221], v[28:31]
	v_mfma_f32_16x16x32_bf16 v[24:27], v[140:143], v[218:221], v[24:27]
	v_mfma_f32_16x16x32_bf16 v[12:15], v[132:135], v[226:229], v[12:15]
	v_mfma_f32_16x16x32_bf16 v[8:11], v[140:143], v[226:229], v[8:11]


; #define PG8_MMA(ai, bj, At, Bt) do { __builtin_amdgcn_s_setprio(1); _Pragma("unroll") for (int m = 0; m < 4; ++m) _Pragma("unroll") for (int n = 0; n < 2; ++n) _Pragma("unroll") for (int k = 0; k < 2; ++k) \
;         acc[ai][bj][m][n] = __builtin_amdgcn_mfma_f32_16x16x32_bf16(Bt[n][k], At[m][k], acc[ai][bj][m][n], 0, 0, 0); __builtin_amdgcn_s_setprio(0); } while (0)
; #define PG8_WAIT_V(n) asm volatile("s_waitcnt vmcnt(" #n ")" ::: "memory")
; #define PG8_WAIT_L(n) asm volatile("s_waitcnt lgkmcnt(" #n ")" ::: "memory")
; #define PG8_BAR __builtin_amdgcn_s_barrier()
; #define PG8_SCHED __builtin_amdgcn_sched_barrier(0)
; template <class Epi, class Sched, bool ALIGN_EPI = false, bool SP2 = false>
; __device__ __forceinline__ void gemm_phase(PG8_LAS unsigned char* lds, const Gemm g, const Sched& S, const Epi& E) {
;     ...
;         for (int t = 0; t < nt; t += 2) {
;             const bool last = (t == nt - 2);
;     ...
;             PG8_WAIT_V(8); PG8_WAIT_L(0); PG8_BAR; PG8_MMA(1, 0, At, B0); PG8_MMA(1, 1, At, B1); PG8_BAR; PG8_SCHED;
;     ...
;         if constexpr (ALIGN_EPI) { if (wr == 0) PG8_BAR; }
	v_mfma_f32_16x16x32_bf16 v[52:55], v[144:147], v[176:179], v[52:55]
	v_mfma_f32_16x16x32_bf16 v[48:51], v[152:155], v[176:179], v[48:51]
	v_mfma_f32_16x16x32_bf16 v[36:39], v[144:147], v[190:193], v[36:39]
	v_mfma_f32_16x16x32_bf16 v[32:35], v[152:155], v[190:193], v[32:35]
	v_mfma_f32_16x16x32_bf16 v[20:23], v[144:147], v[214:217], v[20:23]
	v_mfma_f32_16x16x32_bf16 v[16:19], v[152:155], v[214:217], v[16:19]
	v_mfma_f32_16x16x32_bf16 v[4:7], v[144:147], v[222:225], v[4:7]
	v_mfma_f32_16x16x32_bf16 v[0:3], v[152:155], v[222:225], v[0:3]
	v_mfma_f32_16x16x32_bf16 v[52:55], v[148:151], v[184:187], v[52:55]
	v_mfma_f32_16x16x32_bf16 v[48:51], v[156:159], v[184:187], v[48:51]
	v_mfma_f32_16x16x32_bf16 v[36:39], v[148:151], v[210:213], v[36:39]
	v_mfma_f32_16x16x32_bf16 v[32:35], v[156:159], v[210:213], v[32:35]
	v_mfma_f32_16x16x32_bf16 v[20:23], v[148:151], v[218:221], v[20:23]
	v_mfma_f32_16x16x32_bf16 v[16:19], v[156:159], v[218:221], v[16:19]
	v_mfma_f32_16x16x32_bf16 v[4:7], v[148:151], v[226:229], v[4:7]
	v_mfma_f32_16x16x32_bf16 v[0:3], v[156:159], v[226:229], v[0:3]
	s_setprio 0
	s_barrier
	s_add_i32 s83, s83, 2
	s_add_u32 s10, s10, 0x100
	s_addc_u32 s11, s11, 0
	s_add_u32 s81, s81, 0x100
	s_addc_u32 s82, s82, 0
	s_cmp_gt_u32 s83, 29
	s_cbranch_scc0 .LBB0_1034
	s_and_b64 vcc, exec, s[40:41]
	s_cbranch_vccz .LBB0_1037
	s_barrier

; #define PG8_STAGE(bufoff, gbase, voff) do { _Pragma("unroll") for (int _i = 0; _i < 2; ++_i) \
;         __builtin_amdgcn_global_load_lds((const unsigned*)((const char*)(gbase) + (voff)[_i]), (PG8_LAS unsigned*)(lds + (bufoff) + ldsw + _i * 8192), 16, 0, 0); } while (0)
; #define PG8_LDA(dst, b, h) do { _Pragma("unroll") for (int m = 0; m < 4; ++m) _Pragma("unroll") for (int k = 0; k < 2; ++k) dst[m][k] = *(const PG8_LAS bf16x8*)(lds + PG8_SA(b, h) + aoff + m * 2048 + k * 1024); } while (0)
; #define PG8_LDB(dst, b, h) do { _Pragma("unroll") for (int n = 0; n < 2; ++n) _Pragma("unroll") for (int k = 0; k < 2; ++k) dst[n][k] = *(const PG8_LAS bf16x8*)(lds + PG8_SB(b, h) + boff + n * 2048 + k * 1024); } while (0)
; #define PG8_SCHED __builtin_amdgcn_sched_barrier(0)
; template <class Epi, class Sched, bool ALIGN_EPI = false, bool SP2 = false>
; __device__ __forceinline__ void gemm_phase(PG8_LAS unsigned char* lds, const Gemm g, const Sched& S, const Epi& E) {
;     ...
;         for (int t = 0; t < nt; t += 2) {
;             const bool last = (t == nt - 2);
;             const char* a1 = cA + (size_t)(t + 1) * kstep;
;             const char* a2 = last ? nA : cA + (size_t)(t + 2) * kstep; const char* b2 = last ? nB : cB + (size_t)(t + 2) * kstep;
;             const char* a3 = a2 + kstep; const char* b3 = b2 + kstep;
;             if (last && has_next) S.a_ready(nxt);
;             if constexpr (SP2) {
;             PG8_LDB(B0, 0, 0); PG8_LDB(B1, 0, 1); PG8_SCHED; PG8_LDA(At, 0, 0); PG8_STAGE(PG8_SA(1, 1), a1 + hstep, voffA);
.LBB0_1114:
	ds_read_b128 v[96:99], v197
	ds_read_b128 v[100:103], v197 offset:1024
	ds_read_b128 v[104:107], v197 offset:2048
	ds_read_b128 v[112:115], v197 offset:3072
	ds_read_b128 v[144:147], v198
	ds_read_b128 v[148:151], v198 offset:1024
	ds_read_b128 v[152:155], v198 offset:2048
	ds_read_b128 v[172:175], v198 offset:3072
	s_add_u32 s50, s48, 0xffe00080
	s_addc_u32 s51, s49, -1
	s_cmpk_eq_i32 s73, 0x7c
	s_cselect_b32 s53, s43, s51
	s_cselect_b32 s52, s69, s50
	s_cselect_b32 s51, s41, s72
	s_cselect_b32 s50, s70, s71

; #define PG8_STAGE(bufoff, gbase, voff) do { _Pragma("unroll") for (int _i = 0; _i < 2; ++_i) \
;         __builtin_amdgcn_global_load_lds((const unsigned*)((const char*)(gbase) + (voff)[_i]), (PG8_LAS unsigned*)(lds + (bufoff) + ldsw + _i * 8192), 16, 0, 0); } while (0)
; #define PG8_LDA(dst, b, h) do { _Pragma("unroll") for (int m = 0; m < 4; ++m) _Pragma("unroll") for (int k = 0; k < 2; ++k) dst[m][k] = *(const PG8_LAS bf16x8*)(lds + PG8_SA(b, h) + aoff + m * 2048 + k * 1024); } while (0)
; #define PG8_LDB(dst, b, h) do { _Pragma("unroll") for (int n = 0; n < 2; ++n) _Pragma("unroll") for (int k = 0; k < 2; ++k) dst[n][k] = *(const PG8_LAS bf16x8*)(lds + PG8_SB(b, h) + boff + n * 2048 + k * 1024); } while (0)
; #define PG8_SCHED __builtin_amdgcn_sched_barrier(0)
; template <class Epi, class Sched, bool ALIGN_EPI = false, bool SP2 = false>
; __device__ __forceinline__ void gemm_phase(PG8_LAS unsigned char* lds, const Gemm g, const Sched& S, const Epi& E) {
;     ...
;             PG8_LDB(B0, 0, 0); PG8_LDB(B1, 0, 1); PG8_SCHED; PG8_LDA(At, 0, 0); PG8_STAGE(PG8_SA(1, 1), a1 + hstep, voffA);
	s_add_i32 m0, s56, 0xc000
	ds_read_b128 v[176:179], v199
	ds_read_b128 v[180:183], v199 offset:1024
	ds_read_b128 v[184:187], v199 offset:2048
	ds_read_b128 v[188:191], v199 offset:3072
	ds_read_b128 v[202:205], v199 offset:4096
	ds_read_b128 v[206:209], v199 offset:5120
	ds_read_b128 v[210:213], v199 offset:6144

; #define PG8_STAGE(bufoff, gbase, voff) do { _Pragma("unroll") for (int _i = 0; _i < 2; ++_i) \
;         __builtin_amdgcn_global_load_lds((const unsigned*)((const char*)(gbase) + (voff)[_i]), (PG8_LAS unsigned*)(lds + (bufoff) + ldsw + _i * 8192), 16, 0, 0); } while (0)
; #define PG8_LDA(dst, b, h) do { _Pragma("unroll") for (int m = 0; m < 4; ++m) _Pragma("unroll") for (int k = 0; k < 2; ++k) dst[m][k] = *(const PG8_LAS bf16x8*)(lds + PG8_SA(b, h) + aoff + m * 2048 + k * 1024); } while (0)
; #define PG8_LDB(dst, b, h) do { _Pragma("unroll") for (int n = 0; n < 2; ++n) _Pragma("unroll") for (int k = 0; k < 2; ++k) dst[n][k] = *(const PG8_LAS bf16x8*)(lds + PG8_SB(b, h) + boff + n * 2048 + k * 1024); } while (0)
; #define PG8_SCHED __builtin_amdgcn_sched_barrier(0)
; template <class Epi, class Sched, bool ALIGN_EPI = false, bool SP2 = false>
; __device__ __forceinline__ void gemm_phase(PG8_LAS unsigned char* lds, const Gemm g, const Sched& S, const Epi& E) {
;     ...
;             PG8_LDB(B0, 0, 0); PG8_LDB(B1, 0, 1); PG8_SCHED; PG8_LDA(At, 0, 0); PG8_STAGE(PG8_SA(1, 1), a1 + hstep, voffA);
	global_load_lds_dwordx4 v164, s[48:49]

; #define PG8_STAGE(bufoff, gbase, voff) do { _Pragma("unroll") for (int _i = 0; _i < 2; ++_i) \
;         __builtin_amdgcn_global_load_lds((const unsigned*)((const char*)(gbase) + (voff)[_i]), (PG8_LAS unsigned*)(lds + (bufoff) + ldsw + _i * 8192), 16, 0, 0); } while (0)
; #define PG8_LDA(dst, b, h) do { _Pragma("unroll") for (int m = 0; m < 4; ++m) _Pragma("unroll") for (int k = 0; k < 2; ++k) dst[m][k] = *(const PG8_LAS bf16x8*)(lds + PG8_SA(b, h) + aoff + m * 2048 + k * 1024); } while (0)
; #define PG8_LDB(dst, b, h) do { _Pragma("unroll") for (int n = 0; n < 2; ++n) _Pragma("unroll") for (int k = 0; k < 2; ++k) dst[n][k] = *(const PG8_LAS bf16x8*)(lds + PG8_SB(b, h) + boff + n * 2048 + k * 1024); } while (0)
; #define PG8_MMA(ai, bj, At, Bt) do { __builtin_amdgcn_s_setprio(1); _Pragma("unroll") for (int m = 0; m < 4; ++m) _Pragma("unroll") for (int n = 0; n < 2; ++n) _Pragma("unroll") for (int k = 0; k < 2; ++k) \
;         acc[ai][bj][m][n] = __builtin_amdgcn_mfma_f32_16x16x32_bf16(Bt[n][k], At[m][k], acc[ai][bj][m][n], 0, 0, 0); __builtin_amdgcn_s_setprio(0); } while (0)
; #define PG8_WAIT_V(n) asm volatile("s_waitcnt vmcnt(" #n ")" ::: "memory")
; #define PG8_WAIT_L(n) asm volatile("s_waitcnt lgkmcnt(" #n ")" ::: "memory")
; #define PG8_BAR __builtin_amdgcn_s_barrier()
; #define PG8_SCHED __builtin_amdgcn_sched_barrier(0)
; template <class Epi, class Sched, bool ALIGN_EPI = false, bool SP2 = false>
; __device__ __forceinline__ void gemm_phase(PG8_LAS unsigned char* lds, const Gemm g, const Sched& S, const Epi& E) {
;     ...
;             PG8_LDB(B0, 0, 0); PG8_LDB(B1, 0, 1); PG8_SCHED; PG8_LDA(At, 0, 0); PG8_STAGE(PG8_SA(1, 1), a1 + hstep, voffA);
;             PG8_WAIT_V(8); PG8_WAIT_L(0); PG8_BAR; PG8_MMA(0, 0, At, B0); PG8_MMA(0, 1, At, B1); PG8_BAR; PG8_SCHED;
	s_add_i32 m0, s56, 0xe000
	ds_read_b128 v[214:217], v199 offset:7168
	global_load_lds_dwordx4 v166, s[48:49]
	s_waitcnt vmcnt(8)
	s_waitcnt lgkmcnt(0)
	s_barrier
	s_setprio 1
	s_waitcnt lgkmcnt(0)
	v_mfma_f32_16x16x32_bf16 v[140:143], v[96:99], v[176:179], v[140:143]
	v_mfma_f32_16x16x32_bf16 v[136:139], v[104:107], v[176:179], v[136:139]
	v_mfma_f32_16x16x32_bf16 v[124:127], v[96:99], v[184:187], v[124:127]
	v_mfma_f32_16x16x32_bf16 v[120:123], v[104:107], v[184:187], v[120:123]
	v_mfma_f32_16x16x32_bf16 v[92:95], v[96:99], v[202:205], v[92:95]
	v_mfma_f32_16x16x32_bf16 v[88:91], v[104:107], v[202:205], v[88:91]
	v_mfma_f32_16x16x32_bf16 v[76:79], v[96:99], v[210:213], v[76:79]
	v_mfma_f32_16x16x32_bf16 v[72:75], v[104:107], v[210:213], v[72:75]
	v_mfma_f32_16x16x32_bf16 v[140:143], v[100:103], v[180:183], v[140:143]
	v_mfma_f32_16x16x32_bf16 v[136:139], v[112:115], v[180:183], v[136:139]
	v_mfma_f32_16x16x32_bf16 v[124:127], v[100:103], v[188:191], v[124:127]
	v_mfma_f32_16x16x32_bf16 v[120:123], v[112:115], v[188:191], v[120:123]
	v_mfma_f32_16x16x32_bf16 v[92:95], v[100:103], v[206:209], v[92:95]
	v_mfma_f32_16x16x32_bf16 v[88:91], v[112:115], v[206:209], v[88:91]
	v_mfma_f32_16x16x32_bf16 v[76:79], v[100:103], v[214:217], v[76:79]
	v_mfma_f32_16x16x32_bf16 v[72:75], v[112:115], v[214:217], v[72:75]


; #define PG8_STAGE(bufoff, gbase, voff) do { _Pragma("unroll") for (int _i = 0; _i < 2; ++_i) \
;         __builtin_amdgcn_global_load_lds((const unsigned*)((const char*)(gbase) + (voff)[_i]), (PG8_LAS unsigned*)(lds + (bufoff) + ldsw + _i * 8192), 16, 0, 0); } while (0)
; #define PG8_LDA(dst, b, h) do { _Pragma("unroll") for (int m = 0; m < 4; ++m) _Pragma("unroll") for (int k = 0; k < 2; ++k) dst[m][k] = *(const PG8_LAS bf16x8*)(lds + PG8_SA(b, h) + aoff + m * 2048 + k * 1024); } while (0)
; #define PG8_MMA(ai, bj, At, Bt) do { __builtin_amdgcn_s_setprio(1); _Pragma("unroll") for (int m = 0; m < 4; ++m) _Pragma("unroll") for (int n = 0; n < 2; ++n) _Pragma("unroll") for (int k = 0; k < 2; ++k) \
;         acc[ai][bj][m][n] = __builtin_amdgcn_mfma_f32_16x16x32_bf16(Bt[n][k], At[m][k], acc[ai][bj][m][n], 0, 0, 0); __builtin_amdgcn_s_setprio(0); } while (0)
; #define PG8_WAIT_V(n) asm volatile("s_waitcnt vmcnt(" #n ")" ::: "memory")
; #define PG8_WAIT_L(n) asm volatile("s_waitcnt lgkmcnt(" #n ")" ::: "memory")
; #define PG8_BAR __builtin_amdgcn_s_barrier()
; #define PG8_SCHED __builtin_amdgcn_sched_barrier(0)
; template <class Epi, class Sched, bool ALIGN_EPI = false, bool SP2 = false>
; __device__ __forceinline__ void gemm_phase(PG8_LAS unsigned char* lds, const Gemm g, const Sched& S, const Epi& E) {
;     ...
;             PG8_WAIT_V(8); PG8_WAIT_L(0); PG8_BAR; PG8_MMA(0, 0, At, B0); PG8_MMA(0, 1, At, B1); PG8_BAR; PG8_SCHED;
;             PG8_LDA(At, 0, 1); PG8_STAGE(PG8_SB(0, 0), b2, voffB); PG8_STAGE(PG8_SB(0, 1), b2 + hstep, voffB); PG8_STAGE(PG8_SA(0, 0), a2, voffA);
	v_mfma_f32_16x16x32_bf16 v[132:135], v[144:147], v[176:179], v[132:135]
	v_mfma_f32_16x16x32_bf16 v[128:131], v[152:155], v[176:179], v[128:131]
	v_mfma_f32_16x16x32_bf16 v[116:119], v[144:147], v[184:187], v[116:119]
	v_mfma_f32_16x16x32_bf16 v[108:111], v[152:155], v[184:187], v[108:111]
	v_mfma_f32_16x16x32_bf16 v[84:87], v[144:147], v[202:205], v[84:87]
	v_mfma_f32_16x16x32_bf16 v[80:83], v[152:155], v[202:205], v[80:83]
	v_mfma_f32_16x16x32_bf16 v[68:71], v[144:147], v[210:213], v[68:71]
	v_mfma_f32_16x16x32_bf16 v[64:67], v[152:155], v[210:213], v[64:67]
	v_mfma_f32_16x16x32_bf16 v[132:135], v[148:151], v[180:183], v[132:135]
	v_mfma_f32_16x16x32_bf16 v[128:131], v[172:175], v[180:183], v[128:131]
	v_mfma_f32_16x16x32_bf16 v[116:119], v[148:151], v[188:191], v[116:119]
	v_mfma_f32_16x16x32_bf16 v[108:111], v[172:175], v[188:191], v[108:111]
	v_mfma_f32_16x16x32_bf16 v[84:87], v[148:151], v[206:209], v[84:87]
	v_mfma_f32_16x16x32_bf16 v[80:83], v[172:175], v[206:209], v[80:83]
	v_mfma_f32_16x16x32_bf16 v[68:71], v[148:151], v[214:217], v[68:71]
	v_mfma_f32_16x16x32_bf16 v[64:67], v[172:175], v[214:217], v[64:67]
	s_setprio 0
	s_barrier
	s_add_i32 s74, s65, s55
	s_mov_b64 s[96:97], s[50:51]

; #define PG8_STAGE(bufoff, gbase, voff) do { _Pragma("unroll") for (int _i = 0; _i < 2; ++_i) \
;         __builtin_amdgcn_global_load_lds((const unsigned*)((const char*)(gbase) + (voff)[_i]), (PG8_LAS unsigned*)(lds + (bufoff) + ldsw + _i * 8192), 16, 0, 0); } while (0)
; #define PG8_LDA(dst, b, h) do { _Pragma("unroll") for (int m = 0; m < 4; ++m) _Pragma("unroll") for (int k = 0; k < 2; ++k) dst[m][k] = *(const PG8_LAS bf16x8*)(lds + PG8_SA(b, h) + aoff + m * 2048 + k * 1024); } while (0)
; template <class Epi, class Sched, bool ALIGN_EPI = false, bool SP2 = false>
; __device__ __forceinline__ void gemm_phase(PG8_LAS unsigned char* lds, const Gemm g, const Sched& S, const Epi& E) {
;     ...
;             PG8_LDA(At, 0, 1); PG8_STAGE(PG8_SB(0, 0), b2, voffB); PG8_STAGE(PG8_SB(0, 1), b2 + hstep, voffB); PG8_STAGE(PG8_SA(0, 0), a2, voffA);
	s_mov_b32 m0, s74
	ds_read_b128 v[176:179], v199 offset:16384
	ds_read_b128 v[180:183], v199 offset:17408
	ds_read_b128 v[184:187], v199 offset:18432
	ds_read_b128 v[188:191], v199 offset:19456


; #define PG8_STAGE(bufoff, gbase, voff) do { _Pragma("unroll") for (int _i = 0; _i < 2; ++_i) \
;         __builtin_amdgcn_global_load_lds((const unsigned*)((const char*)(gbase) + (voff)[_i]), (PG8_LAS unsigned*)(lds + (bufoff) + ldsw + _i * 8192), 16, 0, 0); } while (0)
; #define PG8_LDA(dst, b, h) do { _Pragma("unroll") for (int m = 0; m < 4; ++m) _Pragma("unroll") for (int k = 0; k < 2; ++k) dst[m][k] = *(const PG8_LAS bf16x8*)(lds + PG8_SA(b, h) + aoff + m * 2048 + k * 1024); } while (0)
; template <class Epi, class Sched, bool ALIGN_EPI = false, bool SP2 = false>
; __device__ __forceinline__ void gemm_phase(PG8_LAS unsigned char* lds, const Gemm g, const Sched& S, const Epi& E) {
;     ...
;             PG8_LDA(At, 0, 1); PG8_STAGE(PG8_SB(0, 0), b2, voffB); PG8_STAGE(PG8_SB(0, 1), b2 + hstep, voffB); PG8_STAGE(PG8_SA(0, 0), a2, voffA);
	global_load_lds_dwordx4 v158, s[50:51]
	s_add_i32 m0, s74, 0x2000
	s_add_u32 s74, s50, 0x200000

; #define PG8_STAGE(bufoff, gbase, voff) do { _Pragma("unroll") for (int _i = 0; _i < 2; ++_i) \
;         __builtin_amdgcn_global_load_lds((const unsigned*)((const char*)(gbase) + (voff)[_i]), (PG8_LAS unsigned*)(lds + (bufoff) + ldsw + _i * 8192), 16, 0, 0); } while (0)
; #define PG8_LDA(dst, b, h) do { _Pragma("unroll") for (int m = 0; m < 4; ++m) _Pragma("unroll") for (int k = 0; k < 2; ++k) dst[m][k] = *(const PG8_LAS bf16x8*)(lds + PG8_SA(b, h) + aoff + m * 2048 + k * 1024); } while (0)
; template <class Epi, class Sched, bool ALIGN_EPI = false, bool SP2 = false>
; __device__ __forceinline__ void gemm_phase(PG8_LAS unsigned char* lds, const Gemm g, const Sched& S, const Epi& E) {
;     ...
;             PG8_LDA(At, 0, 1); PG8_STAGE(PG8_SB(0, 0), b2, voffB); PG8_STAGE(PG8_SB(0, 1), b2 + hstep, voffB); PG8_STAGE(PG8_SA(0, 0), a2, voffA);
	s_addc_u32 s75, s51, 0
	s_add_i32 s76, s67, s55
	global_load_lds_dwordx4 v162, s[50:51]

; #define PG8_STAGE(bufoff, gbase, voff) do { _Pragma("unroll") for (int _i = 0; _i < 2; ++_i) \
;         __builtin_amdgcn_global_load_lds((const unsigned*)((const char*)(gbase) + (voff)[_i]), (PG8_LAS unsigned*)(lds + (bufoff) + ldsw + _i * 8192), 16, 0, 0); } while (0)
; #define PG8_LDA(dst, b, h) do { _Pragma("unroll") for (int m = 0; m < 4; ++m) _Pragma("unroll") for (int k = 0; k < 2; ++k) dst[m][k] = *(const PG8_LAS bf16x8*)(lds + PG8_SA(b, h) + aoff + m * 2048 + k * 1024); } while (0)
; template <class Epi, class Sched, bool ALIGN_EPI = false, bool SP2 = false>
; __device__ __forceinline__ void gemm_phase(PG8_LAS unsigned char* lds, const Gemm g, const Sched& S, const Epi& E) {
;     ...
;             PG8_LDA(At, 0, 1); PG8_STAGE(PG8_SB(0, 0), b2, voffB); PG8_STAGE(PG8_SB(0, 1), b2 + hstep, voffB); PG8_STAGE(PG8_SA(0, 0), a2, voffA);
	s_mov_b32 m0, s76
	ds_read_b128 v[202:205], v199 offset:20480
	global_load_lds_dwordx4 v158, s[74:75]

; #define PG8_STAGE(bufoff, gbase, voff) do { _Pragma("unroll") for (int _i = 0; _i < 2; ++_i) \
;         __builtin_amdgcn_global_load_lds((const unsigned*)((const char*)(gbase) + (voff)[_i]), (PG8_LAS unsigned*)(lds + (bufoff) + ldsw + _i * 8192), 16, 0, 0); } while (0)
; #define PG8_LDA(dst, b, h) do { _Pragma("unroll") for (int m = 0; m < 4; ++m) _Pragma("unroll") for (int k = 0; k < 2; ++k) dst[m][k] = *(const PG8_LAS bf16x8*)(lds + PG8_SA(b, h) + aoff + m * 2048 + k * 1024); } while (0)
; template <class Epi, class Sched, bool ALIGN_EPI = false, bool SP2 = false>
; __device__ __forceinline__ void gemm_phase(PG8_LAS unsigned char* lds, const Gemm g, const Sched& S, const Epi& E) {
;     ...
;             PG8_LDA(At, 0, 1); PG8_STAGE(PG8_SB(0, 0), b2, voffB); PG8_STAGE(PG8_SB(0, 1), b2 + hstep, voffB); PG8_STAGE(PG8_SA(0, 0), a2, voffA);
	s_add_i32 m0, s76, 0x2000
	ds_read_b128 v[206:209], v199 offset:21504
	global_load_lds_dwordx4 v162, s[74:75]
	s_mov_b64 s[98:99], s[52:53]

; #define PG8_STAGE(bufoff, gbase, voff) do { _Pragma("unroll") for (int _i = 0; _i < 2; ++_i) \
;         __builtin_amdgcn_global_load_lds((const unsigned*)((const char*)(gbase) + (voff)[_i]), (PG8_LAS unsigned*)(lds + (bufoff) + ldsw + _i * 8192), 16, 0, 0); } while (0)
; #define PG8_LDA(dst, b, h) do { _Pragma("unroll") for (int m = 0; m < 4; ++m) _Pragma("unroll") for (int k = 0; k < 2; ++k) dst[m][k] = *(const PG8_LAS bf16x8*)(lds + PG8_SA(b, h) + aoff + m * 2048 + k * 1024); } while (0)
; #define PG8_MMA(ai, bj, At, Bt) do { __builtin_amdgcn_s_setprio(1); _Pragma("unroll") for (int m = 0; m < 4; ++m) _Pragma("unroll") for (int n = 0; n < 2; ++n) _Pragma("unroll") for (int k = 0; k < 2; ++k) \
;         acc[ai][bj][m][n] = __builtin_amdgcn_mfma_f32_16x16x32_bf16(Bt[n][k], At[m][k], acc[ai][bj][m][n], 0, 0, 0); __builtin_amdgcn_s_setprio(0); } while (0)
; #define PG8_WAIT_V(n) asm volatile("s_waitcnt vmcnt(" #n ")" ::: "memory")
; #define PG8_WAIT_L(n) asm volatile("s_waitcnt lgkmcnt(" #n ")" ::: "memory")
; #define PG8_BAR __builtin_amdgcn_s_barrier()
; #define PG8_SCHED __builtin_amdgcn_sched_barrier(0)
; template <class Epi, class Sched, bool ALIGN_EPI = false, bool SP2 = false>
; __device__ __forceinline__ void gemm_phase(PG8_LAS unsigned char* lds, const Gemm g, const Sched& S, const Epi& E) {
;     ...
;             PG8_LDA(At, 0, 1); PG8_STAGE(PG8_SB(0, 0), b2, voffB); PG8_STAGE(PG8_SB(0, 1), b2 + hstep, voffB); PG8_STAGE(PG8_SA(0, 0), a2, voffA);
;             PG8_WAIT_V(8); PG8_WAIT_L(0); PG8_BAR; PG8_MMA(1, 0, At, B0); PG8_MMA(1, 1, At, B1); PG8_BAR; PG8_SCHED;
	s_mov_b32 m0, s56
	ds_read_b128 v[210:213], v199 offset:22528
	global_load_lds_dwordx4 v156, s[52:53]
	s_mov_b32 m0, s57
	ds_read_b128 v[214:217], v199 offset:23552
	global_load_lds_dwordx4 v160, s[52:53]
	s_waitcnt vmcnt(8)
	s_waitcnt lgkmcnt(0)
	s_barrier
	s_setprio 1
	s_waitcnt lgkmcnt(0)
	v_mfma_f32_16x16x32_bf16 v[60:63], v[96:99], v[176:179], v[60:63]
	v_mfma_f32_16x16x32_bf16 v[56:59], v[104:107], v[176:179], v[56:59]
	v_mfma_f32_16x16x32_bf16 v[44:47], v[96:99], v[184:187], v[44:47]
	v_mfma_f32_16x16x32_bf16 v[40:43], v[104:107], v[184:187], v[40:43]
	v_mfma_f32_16x16x32_bf16 v[28:31], v[96:99], v[202:205], v[28:31]
	v_mfma_f32_16x16x32_bf16 v[24:27], v[104:107], v[202:205], v[24:27]
	v_mfma_f32_16x16x32_bf16 v[12:15], v[96:99], v[210:213], v[12:15]
	v_mfma_f32_16x16x32_bf16 v[8:11], v[104:107], v[210:213], v[8:11]
	v_mfma_f32_16x16x32_bf16 v[60:63], v[100:103], v[180:183], v[60:63]
	v_mfma_f32_16x16x32_bf16 v[56:59], v[112:115], v[180:183], v[56:59]
	v_mfma_f32_16x16x32_bf16 v[44:47], v[100:103], v[188:191], v[44:47]
	v_mfma_f32_16x16x32_bf16 v[40:43], v[112:115], v[188:191], v[40:43]
	v_mfma_f32_16x16x32_bf16 v[28:31], v[100:103], v[206:209], v[28:31]
	v_mfma_f32_16x16x32_bf16 v[24:27], v[112:115], v[206:209], v[24:27]
	v_mfma_f32_16x16x32_bf16 v[12:15], v[100:103], v[214:217], v[12:15]
	v_mfma_f32_16x16x32_bf16 v[8:11], v[112:115], v[214:217], v[8:11]


; #define PG8_STAGE(bufoff, gbase, voff) do { _Pragma("unroll") for (int _i = 0; _i < 2; ++_i) \
;         __builtin_amdgcn_global_load_lds((const unsigned*)((const char*)(gbase) + (voff)[_i]), (PG8_LAS unsigned*)(lds + (bufoff) + ldsw + _i * 8192), 16, 0, 0); } while (0)
; #define PG8_LDA(dst, b, h) do { _Pragma("unroll") for (int m = 0; m < 4; ++m) _Pragma("unroll") for (int k = 0; k < 2; ++k) dst[m][k] = *(const PG8_LAS bf16x8*)(lds + PG8_SA(b, h) + aoff + m * 2048 + k * 1024); } while (0)
; #define PG8_LDB(dst, b, h) do { _Pragma("unroll") for (int n = 0; n < 2; ++n) _Pragma("unroll") for (int k = 0; k < 2; ++k) dst[n][k] = *(const PG8_LAS bf16x8*)(lds + PG8_SB(b, h) + boff + n * 2048 + k * 1024); } while (0)
; #define PG8_MMA(ai, bj, At, Bt) do { __builtin_amdgcn_s_setprio(1); _Pragma("unroll") for (int m = 0; m < 4; ++m) _Pragma("unroll") for (int n = 0; n < 2; ++n) _Pragma("unroll") for (int k = 0; k < 2; ++k) \
;         acc[ai][bj][m][n] = __builtin_amdgcn_mfma_f32_16x16x32_bf16(Bt[n][k], At[m][k], acc[ai][bj][m][n], 0, 0, 0); __builtin_amdgcn_s_setprio(0); } while (0)
; #define PG8_WAIT_V(n) asm volatile("s_waitcnt vmcnt(" #n ")" ::: "memory")
; #define PG8_WAIT_L(n) asm volatile("s_waitcnt lgkmcnt(" #n ")" ::: "memory")
; #define PG8_BAR __builtin_amdgcn_s_barrier()
; #define PG8_SCHED __builtin_amdgcn_sched_barrier(0)
; template <class Epi, class Sched, bool ALIGN_EPI = false, bool SP2 = false>
; __device__ __forceinline__ void gemm_phase(PG8_LAS unsigned char* lds, const Gemm g, const Sched& S, const Epi& E) {
;     ...
;             PG8_WAIT_V(8); PG8_WAIT_L(0); PG8_BAR; PG8_MMA(1, 0, At, B0); PG8_MMA(1, 1, At, B1); PG8_BAR; PG8_SCHED;
;             PG8_LDB(B0, 1, 0); PG8_LDB(B1, 1, 1); PG8_SCHED; PG8_LDA(At, 1, 0); PG8_STAGE(PG8_SA(0, 1), a2 + hstep, voffA);
	v_mfma_f32_16x16x32_bf16 v[52:55], v[144:147], v[176:179], v[52:55]
	v_mfma_f32_16x16x32_bf16 v[48:51], v[152:155], v[176:179], v[48:51]
	v_mfma_f32_16x16x32_bf16 v[36:39], v[144:147], v[184:187], v[36:39]
	v_mfma_f32_16x16x32_bf16 v[32:35], v[152:155], v[184:187], v[32:35]
	v_mfma_f32_16x16x32_bf16 v[20:23], v[144:147], v[202:205], v[20:23]
	v_mfma_f32_16x16x32_bf16 v[16:19], v[152:155], v[202:205], v[16:19]
	v_mfma_f32_16x16x32_bf16 v[4:7], v[144:147], v[210:213], v[4:7]
	v_mfma_f32_16x16x32_bf16 v[0:3], v[152:155], v[210:213], v[0:3]
	v_mfma_f32_16x16x32_bf16 v[52:55], v[148:151], v[180:183], v[52:55]
	v_mfma_f32_16x16x32_bf16 v[48:51], v[172:175], v[180:183], v[48:51]
	v_mfma_f32_16x16x32_bf16 v[36:39], v[148:151], v[188:191], v[36:39]
	v_mfma_f32_16x16x32_bf16 v[32:35], v[172:175], v[188:191], v[32:35]
	v_mfma_f32_16x16x32_bf16 v[20:23], v[148:151], v[206:209], v[20:23]
	v_mfma_f32_16x16x32_bf16 v[16:19], v[172:175], v[206:209], v[16:19]
	v_mfma_f32_16x16x32_bf16 v[4:7], v[148:151], v[214:217], v[4:7]
	v_mfma_f32_16x16x32_bf16 v[0:3], v[172:175], v[214:217], v[0:3]
	s_setprio 0
	s_barrier
	s_add_i32 s74, 0, 0x18000
	s_add_i32 s75, 0, 0x1c000
	v_add_u32_e32 v112, s74, v195
	v_add_u32_e32 v172, s75, v195
	ds_read_b128 v[96:99], v112
	ds_read_b128 v[100:103], v112 offset:1024
	ds_read_b128 v[104:107], v112 offset:2048
	ds_read_b128 v[112:115], v112 offset:3072
	ds_read_b128 v[144:147], v172
	ds_read_b128 v[148:151], v172 offset:1024
	ds_read_b128 v[152:155], v172 offset:2048
	ds_read_b128 v[172:175], v172 offset:3072
	s_add_u32 s52, s52, 0x200000
	s_addc_u32 s53, s53, 0
	s_mov_b32 m0, s58

; #define PG8_STAGE(bufoff, gbase, voff) do { _Pragma("unroll") for (int _i = 0; _i < 2; ++_i) \
;         __builtin_amdgcn_global_load_lds((const unsigned*)((const char*)(gbase) + (voff)[_i]), (PG8_LAS unsigned*)(lds + (bufoff) + ldsw + _i * 8192), 16, 0, 0); } while (0)
; #define PG8_LDA(dst, b, h) do { _Pragma("unroll") for (int m = 0; m < 4; ++m) _Pragma("unroll") for (int k = 0; k < 2; ++k) dst[m][k] = *(const PG8_LAS bf16x8*)(lds + PG8_SA(b, h) + aoff + m * 2048 + k * 1024); } while (0)
; #define PG8_LDB(dst, b, h) do { _Pragma("unroll") for (int n = 0; n < 2; ++n) _Pragma("unroll") for (int k = 0; k < 2; ++k) dst[n][k] = *(const PG8_LAS bf16x8*)(lds + PG8_SB(b, h) + boff + n * 2048 + k * 1024); } while (0)
; #define PG8_SCHED __builtin_amdgcn_sched_barrier(0)
; template <class Epi, class Sched, bool ALIGN_EPI = false, bool SP2 = false>
; __device__ __forceinline__ void gemm_phase(PG8_LAS unsigned char* lds, const Gemm g, const Sched& S, const Epi& E) {
;     ...
;             PG8_LDB(B0, 1, 0); PG8_LDB(B1, 1, 1); PG8_SCHED; PG8_LDA(At, 1, 0); PG8_STAGE(PG8_SA(0, 1), a2 + hstep, voffA);
	ds_read_b128 v[176:179], v199 offset:32768
	ds_read_b128 v[180:183], v199 offset:33792
	ds_read_b128 v[184:187], v199 offset:34816
	ds_read_b128 v[188:191], v199 offset:35840
	ds_read_b128 v[202:205], v199 offset:36864
	ds_read_b128 v[206:209], v199 offset:37888
	ds_read_b128 v[210:213], v199 offset:38912

; #define PG8_STAGE(bufoff, gbase, voff) do { _Pragma("unroll") for (int _i = 0; _i < 2; ++_i) \
;         __builtin_amdgcn_global_load_lds((const unsigned*)((const char*)(gbase) + (voff)[_i]), (PG8_LAS unsigned*)(lds + (bufoff) + ldsw + _i * 8192), 16, 0, 0); } while (0)
; #define PG8_LDA(dst, b, h) do { _Pragma("unroll") for (int m = 0; m < 4; ++m) _Pragma("unroll") for (int k = 0; k < 2; ++k) dst[m][k] = *(const PG8_LAS bf16x8*)(lds + PG8_SA(b, h) + aoff + m * 2048 + k * 1024); } while (0)
; #define PG8_LDB(dst, b, h) do { _Pragma("unroll") for (int n = 0; n < 2; ++n) _Pragma("unroll") for (int k = 0; k < 2; ++k) dst[n][k] = *(const PG8_LAS bf16x8*)(lds + PG8_SB(b, h) + boff + n * 2048 + k * 1024); } while (0)
; #define PG8_SCHED __builtin_amdgcn_sched_barrier(0)
; template <class Epi, class Sched, bool ALIGN_EPI = false, bool SP2 = false>
; __device__ __forceinline__ void gemm_phase(PG8_LAS unsigned char* lds, const Gemm g, const Sched& S, const Epi& E) {
;     ...
;             PG8_LDB(B0, 1, 0); PG8_LDB(B1, 1, 1); PG8_SCHED; PG8_LDA(At, 1, 0); PG8_STAGE(PG8_SA(0, 1), a2 + hstep, voffA);
	global_load_lds_dwordx4 v156, s[52:53]

; #define PG8_STAGE(bufoff, gbase, voff) do { _Pragma("unroll") for (int _i = 0; _i < 2; ++_i) \
;         __builtin_amdgcn_global_load_lds((const unsigned*)((const char*)(gbase) + (voff)[_i]), (PG8_LAS unsigned*)(lds + (bufoff) + ldsw + _i * 8192), 16, 0, 0); } while (0)
; #define PG8_LDA(dst, b, h) do { _Pragma("unroll") for (int m = 0; m < 4; ++m) _Pragma("unroll") for (int k = 0; k < 2; ++k) dst[m][k] = *(const PG8_LAS bf16x8*)(lds + PG8_SA(b, h) + aoff + m * 2048 + k * 1024); } while (0)
; #define PG8_LDB(dst, b, h) do { _Pragma("unroll") for (int n = 0; n < 2; ++n) _Pragma("unroll") for (int k = 0; k < 2; ++k) dst[n][k] = *(const PG8_LAS bf16x8*)(lds + PG8_SB(b, h) + boff + n * 2048 + k * 1024); } while (0)
; #define PG8_MMA(ai, bj, At, Bt) do { __builtin_amdgcn_s_setprio(1); _Pragma("unroll") for (int m = 0; m < 4; ++m) _Pragma("unroll") for (int n = 0; n < 2; ++n) _Pragma("unroll") for (int k = 0; k < 2; ++k) \
;         acc[ai][bj][m][n] = __builtin_amdgcn_mfma_f32_16x16x32_bf16(Bt[n][k], At[m][k], acc[ai][bj][m][n], 0, 0, 0); __builtin_amdgcn_s_setprio(0); } while (0)
; #define PG8_WAIT_V(n) asm volatile("s_waitcnt vmcnt(" #n ")" ::: "memory")
; #define PG8_WAIT_L(n) asm volatile("s_waitcnt lgkmcnt(" #n ")" ::: "memory")
; #define PG8_BAR __builtin_amdgcn_s_barrier()
; #define PG8_SCHED __builtin_amdgcn_sched_barrier(0)
; template <class Epi, class Sched, bool ALIGN_EPI = false, bool SP2 = false>
; __device__ __forceinline__ void gemm_phase(PG8_LAS unsigned char* lds, const Gemm g, const Sched& S, const Epi& E) {
;     ...
;             PG8_LDB(B0, 1, 0); PG8_LDB(B1, 1, 1); PG8_SCHED; PG8_LDA(At, 1, 0); PG8_STAGE(PG8_SA(0, 1), a2 + hstep, voffA);
;             PG8_WAIT_V(8); PG8_WAIT_L(0); PG8_BAR; PG8_MMA(0, 0, At, B0); PG8_MMA(0, 1, At, B1); PG8_BAR; PG8_SCHED;
	s_mov_b32 m0, s59
	ds_read_b128 v[214:217], v199 offset:39936
	global_load_lds_dwordx4 v160, s[52:53]
	s_waitcnt vmcnt(8)
	s_waitcnt lgkmcnt(0)
	s_barrier
	s_setprio 1
	s_waitcnt lgkmcnt(0)
	v_mfma_f32_16x16x32_bf16 v[140:143], v[96:99], v[176:179], v[140:143]
	v_mfma_f32_16x16x32_bf16 v[136:139], v[104:107], v[176:179], v[136:139]
	v_mfma_f32_16x16x32_bf16 v[124:127], v[96:99], v[184:187], v[124:127]
	v_mfma_f32_16x16x32_bf16 v[120:123], v[104:107], v[184:187], v[120:123]
	v_mfma_f32_16x16x32_bf16 v[92:95], v[96:99], v[202:205], v[92:95]
	v_mfma_f32_16x16x32_bf16 v[88:91], v[104:107], v[202:205], v[88:91]
	v_mfma_f32_16x16x32_bf16 v[76:79], v[96:99], v[210:213], v[76:79]
	v_mfma_f32_16x16x32_bf16 v[72:75], v[104:107], v[210:213], v[72:75]
	v_mfma_f32_16x16x32_bf16 v[140:143], v[100:103], v[180:183], v[140:143]
	v_mfma_f32_16x16x32_bf16 v[136:139], v[112:115], v[180:183], v[136:139]
	v_mfma_f32_16x16x32_bf16 v[124:127], v[100:103], v[188:191], v[124:127]
	v_mfma_f32_16x16x32_bf16 v[120:123], v[112:115], v[188:191], v[120:123]
	v_mfma_f32_16x16x32_bf16 v[92:95], v[100:103], v[206:209], v[92:95]
	v_mfma_f32_16x16x32_bf16 v[88:91], v[112:115], v[206:209], v[88:91]
	v_mfma_f32_16x16x32_bf16 v[76:79], v[100:103], v[214:217], v[76:79]
	v_mfma_f32_16x16x32_bf16 v[72:75], v[112:115], v[214:217], v[72:75]


; #define PG8_STAGE(bufoff, gbase, voff) do { _Pragma("unroll") for (int _i = 0; _i < 2; ++_i) \
;         __builtin_amdgcn_global_load_lds((const unsigned*)((const char*)(gbase) + (voff)[_i]), (PG8_LAS unsigned*)(lds + (bufoff) + ldsw + _i * 8192), 16, 0, 0); } while (0)
; #define PG8_LDA(dst, b, h) do { _Pragma("unroll") for (int m = 0; m < 4; ++m) _Pragma("unroll") for (int k = 0; k < 2; ++k) dst[m][k] = *(const PG8_LAS bf16x8*)(lds + PG8_SA(b, h) + aoff + m * 2048 + k * 1024); } while (0)
; #define PG8_MMA(ai, bj, At, Bt) do { __builtin_amdgcn_s_setprio(1); _Pragma("unroll") for (int m = 0; m < 4; ++m) _Pragma("unroll") for (int n = 0; n < 2; ++n) _Pragma("unroll") for (int k = 0; k < 2; ++k) \
;         acc[ai][bj][m][n] = __builtin_amdgcn_mfma_f32_16x16x32_bf16(Bt[n][k], At[m][k], acc[ai][bj][m][n], 0, 0, 0); __builtin_amdgcn_s_setprio(0); } while (0)
; #define PG8_WAIT_V(n) asm volatile("s_waitcnt vmcnt(" #n ")" ::: "memory")
; #define PG8_WAIT_L(n) asm volatile("s_waitcnt lgkmcnt(" #n ")" ::: "memory")
; #define PG8_BAR __builtin_amdgcn_s_barrier()
; #define PG8_SCHED __builtin_amdgcn_sched_barrier(0)
; template <class Epi, class Sched, bool ALIGN_EPI = false, bool SP2 = false>
; __device__ __forceinline__ void gemm_phase(PG8_LAS unsigned char* lds, const Gemm g, const Sched& S, const Epi& E) {
;     ...
;             PG8_WAIT_V(8); PG8_WAIT_L(0); PG8_BAR; PG8_MMA(0, 0, At, B0); PG8_MMA(0, 1, At, B1); PG8_BAR; PG8_SCHED;
;             PG8_LDA(At, 1, 1); PG8_STAGE(PG8_SB(1, 0), b3, voffB); PG8_STAGE(PG8_SB(1, 1), b3 + hstep, voffB); PG8_STAGE(PG8_SA(1, 0), a3, voffA);
	v_mfma_f32_16x16x32_bf16 v[132:135], v[144:147], v[176:179], v[132:135]
	v_mfma_f32_16x16x32_bf16 v[128:131], v[152:155], v[176:179], v[128:131]
	v_mfma_f32_16x16x32_bf16 v[116:119], v[144:147], v[184:187], v[116:119]
	v_mfma_f32_16x16x32_bf16 v[108:111], v[152:155], v[184:187], v[108:111]
	v_mfma_f32_16x16x32_bf16 v[84:87], v[144:147], v[202:205], v[84:87]
	v_mfma_f32_16x16x32_bf16 v[80:83], v[152:155], v[202:205], v[80:83]
	v_mfma_f32_16x16x32_bf16 v[68:71], v[144:147], v[210:213], v[68:71]
	v_mfma_f32_16x16x32_bf16 v[64:67], v[152:155], v[210:213], v[64:67]
	v_mfma_f32_16x16x32_bf16 v[132:135], v[148:151], v[180:183], v[132:135]
	v_mfma_f32_16x16x32_bf16 v[128:131], v[172:175], v[180:183], v[128:131]
	v_mfma_f32_16x16x32_bf16 v[116:119], v[148:151], v[188:191], v[116:119]
	v_mfma_f32_16x16x32_bf16 v[108:111], v[172:175], v[188:191], v[108:111]
	v_mfma_f32_16x16x32_bf16 v[84:87], v[148:151], v[206:209], v[84:87]
	v_mfma_f32_16x16x32_bf16 v[80:83], v[172:175], v[206:209], v[80:83]
	v_mfma_f32_16x16x32_bf16 v[68:71], v[148:151], v[214:217], v[68:71]
	v_mfma_f32_16x16x32_bf16 v[64:67], v[172:175], v[214:217], v[64:67]
	s_setprio 0
	s_barrier
	s_add_i32 s52, s74, s55

; #define PG8_STAGE(bufoff, gbase, voff) do { _Pragma("unroll") for (int _i = 0; _i < 2; ++_i) \
;         __builtin_amdgcn_global_load_lds((const unsigned*)((const char*)(gbase) + (voff)[_i]), (PG8_LAS unsigned*)(lds + (bufoff) + ldsw + _i * 8192), 16, 0, 0); } while (0)
; #define PG8_LDA(dst, b, h) do { _Pragma("unroll") for (int m = 0; m < 4; ++m) _Pragma("unroll") for (int k = 0; k < 2; ++k) dst[m][k] = *(const PG8_LAS bf16x8*)(lds + PG8_SA(b, h) + aoff + m * 2048 + k * 1024); } while (0)
; template <class Epi, class Sched, bool ALIGN_EPI = false, bool SP2 = false>
; __device__ __forceinline__ void gemm_phase(PG8_LAS unsigned char* lds, const Gemm g, const Sched& S, const Epi& E) {
;     ...
;             PG8_LDA(At, 1, 1); PG8_STAGE(PG8_SB(1, 0), b3, voffB); PG8_STAGE(PG8_SB(1, 1), b3 + hstep, voffB); PG8_STAGE(PG8_SA(1, 0), a3, voffA);
	s_mov_b32 m0, s52
	ds_read_b128 v[176:179], v199 offset:49152
	ds_read_b128 v[180:183], v199 offset:50176
	ds_read_b128 v[184:187], v199 offset:51200
	ds_read_b128 v[188:191], v199 offset:52224


; #define PG8_STAGE(bufoff, gbase, voff) do { _Pragma("unroll") for (int _i = 0; _i < 2; ++_i) \
;         __builtin_amdgcn_global_load_lds((const unsigned*)((const char*)(gbase) + (voff)[_i]), (PG8_LAS unsigned*)(lds + (bufoff) + ldsw + _i * 8192), 16, 0, 0); } while (0)
; #define PG8_LDA(dst, b, h) do { _Pragma("unroll") for (int m = 0; m < 4; ++m) _Pragma("unroll") for (int k = 0; k < 2; ++k) dst[m][k] = *(const PG8_LAS bf16x8*)(lds + PG8_SA(b, h) + aoff + m * 2048 + k * 1024); } while (0)
; template <class Epi, class Sched, bool ALIGN_EPI = false, bool SP2 = false>
; __device__ __forceinline__ void gemm_phase(PG8_LAS unsigned char* lds, const Gemm g, const Sched& S, const Epi& E) {
;     ...
;             PG8_LDA(At, 1, 1); PG8_STAGE(PG8_SB(1, 0), b3, voffB); PG8_STAGE(PG8_SB(1, 1), b3 + hstep, voffB); PG8_STAGE(PG8_SA(1, 0), a3, voffA);
	global_load_lds_dwordx4 v250, s[96:97]
	s_add_i32 m0, s52, 0x2000
	s_add_u32 s50, s50, 0x200080

; #define PG8_STAGE(bufoff, gbase, voff) do { _Pragma("unroll") for (int _i = 0; _i < 2; ++_i) \
;         __builtin_amdgcn_global_load_lds((const unsigned*)((const char*)(gbase) + (voff)[_i]), (PG8_LAS unsigned*)(lds + (bufoff) + ldsw + _i * 8192), 16, 0, 0); } while (0)
; #define PG8_LDA(dst, b, h) do { _Pragma("unroll") for (int m = 0; m < 4; ++m) _Pragma("unroll") for (int k = 0; k < 2; ++k) dst[m][k] = *(const PG8_LAS bf16x8*)(lds + PG8_SA(b, h) + aoff + m * 2048 + k * 1024); } while (0)
; template <class Epi, class Sched, bool ALIGN_EPI = false, bool SP2 = false>
; __device__ __forceinline__ void gemm_phase(PG8_LAS unsigned char* lds, const Gemm g, const Sched& S, const Epi& E) {
;     ...
;             PG8_LDA(At, 1, 1); PG8_STAGE(PG8_SB(1, 0), b3, voffB); PG8_STAGE(PG8_SB(1, 1), b3 + hstep, voffB); PG8_STAGE(PG8_SA(1, 0), a3, voffA);
	s_addc_u32 s51, s51, 0
	s_add_i32 s52, s75, s55
	global_load_lds_dwordx4 v251, s[96:97]

; #define PG8_STAGE(bufoff, gbase, voff) do { _Pragma("unroll") for (int _i = 0; _i < 2; ++_i) \
;         __builtin_amdgcn_global_load_lds((const unsigned*)((const char*)(gbase) + (voff)[_i]), (PG8_LAS unsigned*)(lds + (bufoff) + ldsw + _i * 8192), 16, 0, 0); } while (0)
; #define PG8_LDA(dst, b, h) do { _Pragma("unroll") for (int m = 0; m < 4; ++m) _Pragma("unroll") for (int k = 0; k < 2; ++k) dst[m][k] = *(const PG8_LAS bf16x8*)(lds + PG8_SA(b, h) + aoff + m * 2048 + k * 1024); } while (0)
; template <class Epi, class Sched, bool ALIGN_EPI = false, bool SP2 = false>
; __device__ __forceinline__ void gemm_phase(PG8_LAS unsigned char* lds, const Gemm g, const Sched& S, const Epi& E) {
;     ...
;             PG8_LDA(At, 1, 1); PG8_STAGE(PG8_SB(1, 0), b3, voffB); PG8_STAGE(PG8_SB(1, 1), b3 + hstep, voffB); PG8_STAGE(PG8_SA(1, 0), a3, voffA);
	s_mov_b32 m0, s52
	ds_read_b128 v[202:205], v199 offset:53248
	global_load_lds_dwordx4 v158, s[50:51]

; #define PG8_STAGE(bufoff, gbase, voff) do { _Pragma("unroll") for (int _i = 0; _i < 2; ++_i) \
;         __builtin_amdgcn_global_load_lds((const unsigned*)((const char*)(gbase) + (voff)[_i]), (PG8_LAS unsigned*)(lds + (bufoff) + ldsw + _i * 8192), 16, 0, 0); } while (0)
; #define PG8_LDA(dst, b, h) do { _Pragma("unroll") for (int m = 0; m < 4; ++m) _Pragma("unroll") for (int k = 0; k < 2; ++k) dst[m][k] = *(const PG8_LAS bf16x8*)(lds + PG8_SA(b, h) + aoff + m * 2048 + k * 1024); } while (0)
; template <class Epi, class Sched, bool ALIGN_EPI = false, bool SP2 = false>
; __device__ __forceinline__ void gemm_phase(PG8_LAS unsigned char* lds, const Gemm g, const Sched& S, const Epi& E) {
;     ...
;             PG8_LDA(At, 1, 1); PG8_STAGE(PG8_SB(1, 0), b3, voffB); PG8_STAGE(PG8_SB(1, 1), b3 + hstep, voffB); PG8_STAGE(PG8_SA(1, 0), a3, voffA);
	s_add_i32 m0, s52, 0x2000
	ds_read_b128 v[206:209], v199 offset:54272
	global_load_lds_dwordx4 v162, s[50:51]

; #define PG8_STAGE(bufoff, gbase, voff) do { _Pragma("unroll") for (int _i = 0; _i < 2; ++_i) \
;         __builtin_amdgcn_global_load_lds((const unsigned*)((const char*)(gbase) + (voff)[_i]), (PG8_LAS unsigned*)(lds + (bufoff) + ldsw + _i * 8192), 16, 0, 0); } while (0)
; #define PG8_LDA(dst, b, h) do { _Pragma("unroll") for (int m = 0; m < 4; ++m) _Pragma("unroll") for (int k = 0; k < 2; ++k) dst[m][k] = *(const PG8_LAS bf16x8*)(lds + PG8_SA(b, h) + aoff + m * 2048 + k * 1024); } while (0)
; template <class Epi, class Sched, bool ALIGN_EPI = false, bool SP2 = false>
; __device__ __forceinline__ void gemm_phase(PG8_LAS unsigned char* lds, const Gemm g, const Sched& S, const Epi& E) {
;     ...
;             PG8_LDA(At, 1, 1); PG8_STAGE(PG8_SB(1, 0), b3, voffB); PG8_STAGE(PG8_SB(1, 1), b3 + hstep, voffB); PG8_STAGE(PG8_SA(1, 0), a3, voffA);
	s_mov_b32 m0, s61
	ds_read_b128 v[210:213], v199 offset:55296
	global_load_lds_dwordx4 v252, s[98:99]

; #define PG8_STAGE(bufoff, gbase, voff) do { _Pragma("unroll") for (int _i = 0; _i < 2; ++_i) \
;         __builtin_amdgcn_global_load_lds((const unsigned*)((const char*)(gbase) + (voff)[_i]), (PG8_LAS unsigned*)(lds + (bufoff) + ldsw + _i * 8192), 16, 0, 0); } while (0)
; #define PG8_LDA(dst, b, h) do { _Pragma("unroll") for (int m = 0; m < 4; ++m) _Pragma("unroll") for (int k = 0; k < 2; ++k) dst[m][k] = *(const PG8_LAS bf16x8*)(lds + PG8_SA(b, h) + aoff + m * 2048 + k * 1024); } while (0)
; #define PG8_MMA(ai, bj, At, Bt) do { __builtin_amdgcn_s_setprio(1); _Pragma("unroll") for (int m = 0; m < 4; ++m) _Pragma("unroll") for (int n = 0; n < 2; ++n) _Pragma("unroll") for (int k = 0; k < 2; ++k) \
;         acc[ai][bj][m][n] = __builtin_amdgcn_mfma_f32_16x16x32_bf16(Bt[n][k], At[m][k], acc[ai][bj][m][n], 0, 0, 0); __builtin_amdgcn_s_setprio(0); } while (0)
; #define PG8_WAIT_V(n) asm volatile("s_waitcnt vmcnt(" #n ")" ::: "memory")
; #define PG8_WAIT_L(n) asm volatile("s_waitcnt lgkmcnt(" #n ")" ::: "memory")
; #define PG8_BAR __builtin_amdgcn_s_barrier()
; #define PG8_SCHED __builtin_amdgcn_sched_barrier(0)
; template <class Epi, class Sched, bool ALIGN_EPI = false, bool SP2 = false>
; __device__ __forceinline__ void gemm_phase(PG8_LAS unsigned char* lds, const Gemm g, const Sched& S, const Epi& E) {
;     ...
;             PG8_LDA(At, 1, 1); PG8_STAGE(PG8_SB(1, 0), b3, voffB); PG8_STAGE(PG8_SB(1, 1), b3 + hstep, voffB); PG8_STAGE(PG8_SA(1, 0), a3, voffA);
;             PG8_WAIT_V(8); PG8_WAIT_L(0); PG8_BAR; PG8_MMA(1, 0, At, B0); PG8_MMA(1, 1, At, B1); PG8_BAR; PG8_SCHED;
	s_mov_b32 m0, s62
	ds_read_b128 v[214:217], v199 offset:56320
	global_load_lds_dwordx4 v253, s[98:99]
	s_waitcnt vmcnt(8)
	s_waitcnt lgkmcnt(0)
	s_barrier
	s_setprio 1
	s_waitcnt lgkmcnt(0)
	v_mfma_f32_16x16x32_bf16 v[60:63], v[96:99], v[176:179], v[60:63]
	v_mfma_f32_16x16x32_bf16 v[56:59], v[104:107], v[176:179], v[56:59]
	v_mfma_f32_16x16x32_bf16 v[44:47], v[96:99], v[184:187], v[44:47]
	v_mfma_f32_16x16x32_bf16 v[40:43], v[104:107], v[184:187], v[40:43]
	v_mfma_f32_16x16x32_bf16 v[28:31], v[96:99], v[202:205], v[28:31]
	v_mfma_f32_16x16x32_bf16 v[24:27], v[104:107], v[202:205], v[24:27]
	v_mfma_f32_16x16x32_bf16 v[12:15], v[96:99], v[210:213], v[12:15]
	v_mfma_f32_16x16x32_bf16 v[8:11], v[104:107], v[210:213], v[8:11]
	v_mfma_f32_16x16x32_bf16 v[60:63], v[100:103], v[180:183], v[60:63]
	v_mfma_f32_16x16x32_bf16 v[56:59], v[112:115], v[180:183], v[56:59]
	v_mfma_f32_16x16x32_bf16 v[44:47], v[100:103], v[188:191], v[44:47]
	v_mfma_f32_16x16x32_bf16 v[40:43], v[112:115], v[188:191], v[40:43]
	v_mfma_f32_16x16x32_bf16 v[28:31], v[100:103], v[206:209], v[28:31]
	v_mfma_f32_16x16x32_bf16 v[24:27], v[112:115], v[206:209], v[24:27]
	v_mfma_f32_16x16x32_bf16 v[12:15], v[100:103], v[214:217], v[12:15]
	v_mfma_f32_16x16x32_bf16 v[8:11], v[112:115], v[214:217], v[8:11]


; #define PG8_MMA(ai, bj, At, Bt) do { __builtin_amdgcn_s_setprio(1); _Pragma("unroll") for (int m = 0; m < 4; ++m) _Pragma("unroll") for (int n = 0; n < 2; ++n) _Pragma("unroll") for (int k = 0; k < 2; ++k) \
;         acc[ai][bj][m][n] = __builtin_amdgcn_mfma_f32_16x16x32_bf16(Bt[n][k], At[m][k], acc[ai][bj][m][n], 0, 0, 0); __builtin_amdgcn_s_setprio(0); } while (0)
; #define PG8_WAIT_V(n) asm volatile("s_waitcnt vmcnt(" #n ")" ::: "memory")
; #define PG8_WAIT_L(n) asm volatile("s_waitcnt lgkmcnt(" #n ")" ::: "memory")
; #define PG8_BAR __builtin_amdgcn_s_barrier()
; #define PG8_SCHED __builtin_amdgcn_sched_barrier(0)
; template <class Epi, class Sched, bool ALIGN_EPI = false, bool SP2 = false>
; __device__ __forceinline__ void gemm_phase(PG8_LAS unsigned char* lds, const Gemm g, const Sched& S, const Epi& E) {
;     ...
;             PG8_WAIT_V(8); PG8_WAIT_L(0); PG8_BAR; PG8_MMA(1, 0, At, B0); PG8_MMA(1, 1, At, B1); PG8_BAR; PG8_SCHED;
;     ...
;         if constexpr (ALIGN_EPI) { if (wr == 0) PG8_BAR; }
	v_mfma_f32_16x16x32_bf16 v[52:55], v[144:147], v[176:179], v[52:55]
	v_mfma_f32_16x16x32_bf16 v[48:51], v[152:155], v[176:179], v[48:51]
	v_mfma_f32_16x16x32_bf16 v[36:39], v[144:147], v[184:187], v[36:39]
	v_mfma_f32_16x16x32_bf16 v[32:35], v[152:155], v[184:187], v[32:35]
	v_mfma_f32_16x16x32_bf16 v[20:23], v[144:147], v[202:205], v[20:23]
	v_mfma_f32_16x16x32_bf16 v[16:19], v[152:155], v[202:205], v[16:19]
	v_mfma_f32_16x16x32_bf16 v[4:7], v[144:147], v[210:213], v[4:7]
	v_mfma_f32_16x16x32_bf16 v[0:3], v[152:155], v[210:213], v[0:3]
	v_mfma_f32_16x16x32_bf16 v[52:55], v[148:151], v[180:183], v[52:55]
	v_mfma_f32_16x16x32_bf16 v[48:51], v[172:175], v[180:183], v[48:51]
	v_mfma_f32_16x16x32_bf16 v[36:39], v[148:151], v[188:191], v[36:39]
	v_mfma_f32_16x16x32_bf16 v[32:35], v[172:175], v[188:191], v[32:35]
	v_mfma_f32_16x16x32_bf16 v[20:23], v[148:151], v[206:209], v[20:23]
	v_mfma_f32_16x16x32_bf16 v[16:19], v[172:175], v[206:209], v[16:19]
	v_mfma_f32_16x16x32_bf16 v[4:7], v[148:151], v[214:217], v[4:7]
	v_mfma_f32_16x16x32_bf16 v[0:3], v[172:175], v[214:217], v[0:3]
	s_setprio 0
	s_barrier
	s_add_i32 s73, s73, 2
	s_add_u32 s48, s48, 0x100
	s_addc_u32 s49, s49, 0
	s_add_u32 s71, s71, 0x100
	s_addc_u32 s72, s72, 0
	s_cmpk_gt_u32 s73, 0x7d
	s_cbranch_scc0 .LBB0_1114
	s_and_b64 vcc, exec, s[34:35]
	s_cbranch_vccz .LBB0_1117
	s_barrier
